# speedup vs baseline: 1.0309x; 1.0224x over previous
.LBB0_86:
	s_ashr_i32 s37, s36, 31
	s_lshl_b64 s[36:37], s[36:37], 20
	s_add_u32 s36, s48, s36
	s_addc_u32 s37, s49, s37
	s_ashr_i32 s5, s4, 31
	v_lshlrev_b32_e32 v3, 6, v1
	s_lshl_b64 s[4:5], s[4:5], 20
	v_and_b32_e32 v2, 48, v1
	v_and_b32_e32 v4, 0x3c0, v3
	v_lshlrev_b32_e32 v1, 2, v1
	s_add_u32 s4, s46, s4
	v_or_b32_e32 v5, v4, v2
	v_and_b32_e32 v1, 32, v1
	v_lshlrev_b32_e32 v0, 13, v0
	s_mov_b32 s72, 0x18000
	s_addc_u32 s5, s47, s5
	v_and_b32_e32 v111, 0x6000, v0
	s_add_i32 s40, s1, 0x10000
	s_add_i32 s41, s1, 0x18000
	s_add_i32 s64, s1, 0x12000
	s_add_i32 s65, s1, 0x1a000
	s_add_i32 s68, s1, 0x14000
	s_add_i32 s69, s1, 0x1c000
	s_add_i32 s70, s1, 0x16000
	s_add_i32 s71, s1, 0x1e000
	v_bitop3_b32 v0, v5, s72, v1 bitop3:0xde
	s_mov_b32 s72, 0x10400
	v_bitop3_b32 v149, v5, s72, v1 bitop3:0xde
	s_add_u32 s72, s44, s2
	s_addc_u32 s73, s45, s3
	s_add_i32 s2, s74, s75
	s_ashr_i32 s3, s2, 31
	s_waitcnt vmcnt(0)
	s_lshl_b64 s[2:3], s[2:3], 20
	v_bitop3_b32 v110, v4, v1, v2 bitop3:0x36
	v_and_b32_e32 v112, 0xffffc000, v3
	s_add_u32 s74, s10, s2
	v_mov_b32_e32 v4, 0
	v_or_b32_e32 v113, 0x800, v112
	v_or_b32_e32 v114, 0x1000, v112
	v_or_b32_e32 v115, 0x1800, v112
	v_or_b32_e32 v116, 0x2000, v112
	v_or_b32_e32 v117, 0x2800, v112
	v_or_b32_e32 v118, 0x3000, v112
	v_or_b32_e32 v119, 0x3800, v112
	v_bitop3_b32 v145, v5, s33, v1 bitop3:0xde
	s_addc_u32 s75, s11, s3
	s_mov_b64 s[2:3], 0
	s_mov_b32 s76, 1
	v_add_u32_e32 v150, v0, v111
	v_mov_b32_e32 v5, v4
	v_mov_b32_e32 v6, v4
	v_mov_b32_e32 v7, v4
	v_mov_b32_e32 v72, v4
	v_mov_b32_e32 v73, v4
	v_mov_b32_e32 v74, v4
	v_mov_b32_e32 v75, v4
	v_mov_b32_e32 v12, v4
	v_mov_b32_e32 v13, v4
	v_mov_b32_e32 v14, v4
	v_mov_b32_e32 v15, v4
	v_mov_b32_e32 v76, v4
	v_mov_b32_e32 v77, v4
	v_mov_b32_e32 v78, v4
	v_mov_b32_e32 v79, v4
	v_mov_b32_e32 v16, v4
	v_mov_b32_e32 v17, v4
	v_mov_b32_e32 v18, v4
	v_mov_b32_e32 v19, v4
	v_mov_b32_e32 v80, v4
	v_mov_b32_e32 v81, v4
	v_mov_b32_e32 v82, v4
	v_mov_b32_e32 v83, v4
	v_mov_b32_e32 v20, v4
	v_mov_b32_e32 v21, v4
	v_mov_b32_e32 v22, v4
	v_mov_b32_e32 v23, v4
	v_mov_b32_e32 v84, v4
	v_mov_b32_e32 v85, v4
	v_mov_b32_e32 v86, v4
	v_mov_b32_e32 v87, v4
	v_mov_b32_e32 v24, v4
	v_mov_b32_e32 v25, v4
	v_mov_b32_e32 v26, v4
	v_mov_b32_e32 v27, v4
	v_mov_b32_e32 v88, v4
	v_mov_b32_e32 v89, v4
	v_mov_b32_e32 v90, v4
	v_mov_b32_e32 v91, v4
	v_mov_b32_e32 v28, v4
	v_mov_b32_e32 v29, v4
	v_mov_b32_e32 v30, v4
	v_mov_b32_e32 v31, v4
	v_mov_b32_e32 v92, v4
	v_mov_b32_e32 v93, v4
	v_mov_b32_e32 v94, v4
	v_mov_b32_e32 v95, v4
	v_mov_b32_e32 v32, v4
	v_mov_b32_e32 v33, v4
	v_mov_b32_e32 v34, v4
	v_mov_b32_e32 v35, v4
	v_mov_b32_e32 v96, v4
	v_mov_b32_e32 v97, v4
	v_mov_b32_e32 v98, v4
	v_mov_b32_e32 v99, v4
	v_mov_b32_e32 v36, v4
	v_mov_b32_e32 v37, v4
	v_mov_b32_e32 v38, v4
	v_mov_b32_e32 v39, v4
	v_mov_b32_e32 v100, v4
	v_mov_b32_e32 v101, v4
	v_mov_b32_e32 v102, v4
	v_mov_b32_e32 v103, v4
	v_mov_b32_e32 v40, v4
	v_mov_b32_e32 v41, v4
	v_mov_b32_e32 v42, v4
	v_mov_b32_e32 v43, v4
	v_mov_b32_e32 v120, v4
	v_mov_b32_e32 v121, v4
	v_mov_b32_e32 v122, v4
	v_mov_b32_e32 v123, v4
	v_mov_b32_e32 v44, v4
	v_mov_b32_e32 v45, v4
	v_mov_b32_e32 v46, v4
	v_mov_b32_e32 v47, v4
	v_mov_b32_e32 v124, v4
	v_mov_b32_e32 v125, v4
	v_mov_b32_e32 v126, v4
	v_mov_b32_e32 v127, v4
	v_mov_b32_e32 v48, v4
	v_mov_b32_e32 v49, v4
	v_mov_b32_e32 v50, v4
	v_mov_b32_e32 v51, v4
	v_mov_b32_e32 v128, v4
	v_mov_b32_e32 v129, v4
	v_mov_b32_e32 v130, v4
	v_mov_b32_e32 v131, v4
	v_mov_b32_e32 v52, v4
	v_mov_b32_e32 v53, v4
	v_mov_b32_e32 v54, v4
	v_mov_b32_e32 v55, v4
	v_mov_b32_e32 v132, v4
	v_mov_b32_e32 v133, v4
	v_mov_b32_e32 v134, v4
	v_mov_b32_e32 v135, v4
	v_mov_b32_e32 v56, v4
	v_mov_b32_e32 v57, v4
	v_mov_b32_e32 v58, v4
	v_mov_b32_e32 v59, v4
	v_mov_b32_e32 v136, v4
	v_mov_b32_e32 v137, v4
	v_mov_b32_e32 v138, v4
	v_mov_b32_e32 v139, v4
	v_mov_b32_e32 v60, v4
	v_mov_b32_e32 v61, v4
	v_mov_b32_e32 v62, v4
	v_mov_b32_e32 v63, v4
	v_mov_b32_e32 v140, v4
	v_mov_b32_e32 v141, v4
	v_mov_b32_e32 v142, v4
	v_mov_b32_e32 v143, v4
	v_mov_b32_e32 v64, v4
	v_mov_b32_e32 v65, v4
	v_mov_b32_e32 v66, v4
	v_mov_b32_e32 v67, v4
	v_mov_b32_e32 v0, v4
	v_mov_b32_e32 v1, v4
	v_mov_b32_e32 v2, v4
	v_mov_b32_e32 v3, v4
	v_mov_b32_e32 v68, v4
	v_mov_b32_e32 v69, v4
	v_mov_b32_e32 v70, v4
	v_mov_b32_e32 v71, v4
	v_mov_b32_e32 v8, v4
	v_mov_b32_e32 v9, v4
	v_mov_b32_e32 v10, v4
	v_mov_b32_e32 v11, v4
	s_waitcnt lgkmcnt(0)
	s_barrier
	s_add_u32 s77, s74, s2
	s_addc_u32 s82, s75, s3
	s_add_u32 s78, s77, 0x1b900080
	s_addc_u32 s79, s82, 0
	s_add_u32 s83, s72, s2
	s_addc_u32 s84, s73, s3
	s_add_u32 s80, s83, 0x3400080
	s_addc_u32 s81, s84, 0
	v_add_u32_e32 v151, v110, v111
	v_add_u32_e32 v189, v110, v112
	ds_read_b128 v[152:155], v151 offset:32768
	ds_read_b128 v[156:159], v189
	s_mov_b32 m0, s40
	s_nop 0
	global_load_lds_dwordx4 v104, s[78:79]
	ds_read_b128 v[160:163], v151 offset:34816
	s_mov_b32 m0, s41
	s_nop 0
	global_load_lds_dwordx4 v104, s[80:81]
	ds_read_b128 v[164:167], v189 offset:2048
	ds_read_b128 v[168:171], v151 offset:36864
	s_mov_b32 m0, s64
	s_nop 0
	global_load_lds_dwordx4 v106, s[78:79]
	ds_read_b128 v[172:175], v151 offset:38912
	ds_read_b128 v[176:179], v189 offset:4096
	ds_read_b128 v[180:183], v189 offset:6144
	s_branch .Lmy_rot_87
.LBB0_87:
	s_add_u32 s77, s74, s2
	s_addc_u32 s82, s75, s3
	s_add_u32 s78, s77, 0x1b900080
	s_addc_u32 s79, s82, 0
	s_add_u32 s83, s72, s2
	s_addc_u32 s84, s73, s3
	s_add_u32 s80, s83, 0x3400080
	s_addc_u32 s81, s84, 0
	v_add_u32_e32 v151, v110, v111
	v_add_u32_e32 v189, v110, v112
	ds_read_b128 v[152:155], v151 offset:32768
	ds_read_b128 v[156:159], v189
	s_mov_b32 m0, s40
	v_mfma_f32_16x16x32_bf16 v[76:79], v[160:163], v[176:179], v[76:79]
	global_load_lds_dwordx4 v104, s[78:79]
	v_mfma_f32_16x16x32_bf16 v[64:67], v[160:163], v[180:183], v[64:67]
	ds_read_b128 v[160:163], v151 offset:34816
	v_mfma_f32_16x16x32_bf16 v[12:15], v[164:167], v[176:179], v[12:15]
	s_mov_b32 m0, s41
	v_mfma_f32_16x16x32_bf16 v[0:3], v[164:167], v[180:183], v[0:3]
	global_load_lds_dwordx4 v104, s[80:81]
	ds_read_b128 v[164:167], v189 offset:2048
	v_mfma_f32_16x16x32_bf16 v[72:75], v[168:171], v[176:179], v[72:75]
	v_mfma_f32_16x16x32_bf16 v[68:71], v[168:171], v[180:183], v[68:71]
	ds_read_b128 v[168:171], v151 offset:36864
	s_mov_b32 m0, s64
	v_mfma_f32_16x16x32_bf16 v[4:7], v[172:175], v[176:179], v[4:7]
	global_load_lds_dwordx4 v106, s[78:79]
	v_mfma_f32_16x16x32_bf16 v[8:11], v[172:175], v[180:183], v[8:11]
	ds_read_b128 v[172:175], v151 offset:38912
	ds_read_b128 v[176:179], v189 offset:4096
	ds_read_b128 v[180:183], v189 offset:6144
.Lmy_rot_87:
	s_waitcnt lgkmcnt(6)
	v_mfma_f32_16x16x32_bf16 v[140:143], v[152:155], v[156:159], v[140:143]
	s_waitcnt lgkmcnt(5)
	s_mov_b32 m0, s65
	v_mfma_f32_16x16x32_bf16 v[60:63], v[160:163], v[156:159], v[60:63]
	global_load_lds_dwordx4 v106, s[80:81]
	s_waitcnt lgkmcnt(4)
	v_mfma_f32_16x16x32_bf16 v[132:135], v[152:155], v[164:167], v[132:135]
	v_mfma_f32_16x16x32_bf16 v[52:55], v[160:163], v[164:167], v[52:55]
	s_waitcnt lgkmcnt(3)
	s_mov_b32 m0, s68
	v_mfma_f32_16x16x32_bf16 v[136:139], v[168:171], v[156:159], v[136:139]
	global_load_lds_dwordx4 v108, s[78:79]
	v_mfma_f32_16x16x32_bf16 v[128:131], v[168:171], v[164:167], v[128:131]
	s_waitcnt lgkmcnt(2)
	v_mfma_f32_16x16x32_bf16 v[56:59], v[172:175], v[156:159], v[56:59]
	ds_read_b128 v[156:159], v189 offset:8192
	s_mov_b32 m0, s69
	v_mfma_f32_16x16x32_bf16 v[48:51], v[172:175], v[164:167], v[48:51]
	global_load_lds_dwordx4 v108, s[80:81]
	ds_read_b128 v[164:167], v189 offset:10240
	s_waitcnt lgkmcnt(3)
	v_mfma_f32_16x16x32_bf16 v[124:127], v[152:155], v[176:179], v[124:127]
	v_mfma_f32_16x16x32_bf16 v[44:47], v[160:163], v[176:179], v[44:47]
	s_mov_b32 m0, s70
	v_mfma_f32_16x16x32_bf16 v[120:123], v[168:171], v[176:179], v[120:123]
	global_load_lds_dwordx4 v146, s[78:79]
	v_mfma_f32_16x16x32_bf16 v[40:43], v[172:175], v[176:179], v[40:43]
	ds_read_b128 v[176:179], v189 offset:12288
	s_waitcnt lgkmcnt(3)
	v_mfma_f32_16x16x32_bf16 v[100:103], v[152:155], v[180:183], v[100:103]
	s_mov_b32 m0, s71
	v_mfma_f32_16x16x32_bf16 v[36:39], v[160:163], v[180:183], v[36:39]
	global_load_lds_dwordx4 v146, s[80:81]
	v_mfma_f32_16x16x32_bf16 v[96:99], v[168:171], v[180:183], v[96:99]
	v_mfma_f32_16x16x32_bf16 v[32:35], v[172:175], v[180:183], v[32:35]
	ds_read_b128 v[180:183], v189 offset:14336
	s_waitcnt lgkmcnt(3)
	v_mfma_f32_16x16x32_bf16 v[28:31], v[160:163], v[156:159], v[28:31]
	s_waitcnt lgkmcnt(2)
	v_mfma_f32_16x16x32_bf16 v[20:23], v[160:163], v[164:167], v[20:23]
	s_waitcnt lgkmcnt(1)
	v_mfma_f32_16x16x32_bf16 v[12:15], v[160:163], v[176:179], v[12:15]
	s_waitcnt lgkmcnt(0)
	v_mfma_f32_16x16x32_bf16 v[0:3], v[160:163], v[180:183], v[0:3]
	ds_read_b128 v[160:163], v151 offset:33792
	v_mfma_f32_16x16x32_bf16 v[92:95], v[152:155], v[156:159], v[92:95]
	v_mfma_f32_16x16x32_bf16 v[84:87], v[152:155], v[164:167], v[84:87]
	v_mfma_f32_16x16x32_bf16 v[76:79], v[152:155], v[176:179], v[76:79]
	v_mfma_f32_16x16x32_bf16 v[64:67], v[152:155], v[180:183], v[64:67]
	ds_read_b128 v[152:155], v189 offset:1024
	v_mfma_f32_16x16x32_bf16 v[80:83], v[168:171], v[164:167], v[80:83]
	v_mfma_f32_16x16x32_bf16 v[16:19], v[172:175], v[164:167], v[16:19]
	ds_read_b128 v[164:167], v151 offset:35840
	v_mfma_f32_16x16x32_bf16 v[88:91], v[168:171], v[156:159], v[88:91]
	v_mfma_f32_16x16x32_bf16 v[24:27], v[172:175], v[156:159], v[24:27]
	ds_read_b128 v[156:159], v189 offset:3072
	v_mfma_f32_16x16x32_bf16 v[72:75], v[168:171], v[176:179], v[72:75]
	v_mfma_f32_16x16x32_bf16 v[4:7], v[172:175], v[176:179], v[4:7]
	ds_read_b128 v[176:179], v189 offset:5120
	v_mfma_f32_16x16x32_bf16 v[68:71], v[168:171], v[180:183], v[68:71]
	ds_read_b128 v[168:171], v151 offset:37888
	v_mfma_f32_16x16x32_bf16 v[8:11], v[172:175], v[180:183], v[8:11]
	ds_read_b128 v[172:175], v151 offset:39936
	ds_read_b128 v[180:183], v189 offset:7168
	s_waitcnt lgkmcnt(6)
	v_mfma_f32_16x16x32_bf16 v[140:143], v[160:163], v[152:155], v[140:143]
	s_waitcnt lgkmcnt(5)
	v_mfma_f32_16x16x32_bf16 v[60:63], v[164:167], v[152:155], v[60:63]
	s_waitcnt lgkmcnt(4)
	v_mfma_f32_16x16x32_bf16 v[132:135], v[160:163], v[156:159], v[132:135]
	v_mfma_f32_16x16x32_bf16 v[52:55], v[164:167], v[156:159], v[52:55]
	s_waitcnt lgkmcnt(3)
	v_mfma_f32_16x16x32_bf16 v[124:127], v[160:163], v[176:179], v[124:127]
	v_mfma_f32_16x16x32_bf16 v[44:47], v[164:167], v[176:179], v[44:47]
	s_waitcnt lgkmcnt(2)
	v_mfma_f32_16x16x32_bf16 v[136:139], v[168:171], v[152:155], v[136:139]
	s_waitcnt lgkmcnt(1)
	v_mfma_f32_16x16x32_bf16 v[56:59], v[172:175], v[152:155], v[56:59]
	ds_read_b128 v[152:155], v189 offset:9216
	v_mfma_f32_16x16x32_bf16 v[128:131], v[168:171], v[156:159], v[128:131]
	v_mfma_f32_16x16x32_bf16 v[48:51], v[172:175], v[156:159], v[48:51]
	ds_read_b128 v[156:159], v189 offset:11264
	v_mfma_f32_16x16x32_bf16 v[120:123], v[168:171], v[176:179], v[120:123]
	v_mfma_f32_16x16x32_bf16 v[40:43], v[172:175], v[176:179], v[40:43]
	ds_read_b128 v[176:179], v189 offset:13312
	s_waitcnt lgkmcnt(3)
	v_mfma_f32_16x16x32_bf16 v[100:103], v[160:163], v[180:183], v[100:103]
	v_mfma_f32_16x16x32_bf16 v[36:39], v[164:167], v[180:183], v[36:39]
	v_mfma_f32_16x16x32_bf16 v[96:99], v[168:171], v[180:183], v[96:99]
	v_mfma_f32_16x16x32_bf16 v[32:35], v[172:175], v[180:183], v[32:35]
	ds_read_b128 v[180:183], v189 offset:15360
	s_waitcnt lgkmcnt(3)
	v_mfma_f32_16x16x32_bf16 v[92:95], v[160:163], v[152:155], v[92:95]
	v_mfma_f32_16x16x32_bf16 v[28:31], v[164:167], v[152:155], v[28:31]
	v_mfma_f32_16x16x32_bf16 v[88:91], v[168:171], v[152:155], v[88:91]
	v_mfma_f32_16x16x32_bf16 v[24:27], v[172:175], v[152:155], v[24:27]
	s_waitcnt lgkmcnt(2)
	v_mfma_f32_16x16x32_bf16 v[84:87], v[160:163], v[156:159], v[84:87]
	v_mfma_f32_16x16x32_bf16 v[20:23], v[164:167], v[156:159], v[20:23]
	v_mfma_f32_16x16x32_bf16 v[80:83], v[168:171], v[156:159], v[80:83]
	v_mfma_f32_16x16x32_bf16 v[16:19], v[172:175], v[156:159], v[16:19]
	s_add_u32 s77, s77, 0x1b900100
	s_addc_u32 s78, s82, 0
	s_add_u32 s80, s83, 0x3400100
	s_addc_u32 s81, s84, 0
	s_cmp_lt_u32 s76, 31
	s_cselect_b32 s79, s78, s37
	s_cselect_b32 s78, s77, s36
	s_waitcnt vmcnt(0)
	s_waitcnt lgkmcnt(0)
	s_barrier
	s_cselect_b32 s81, s81, s5
	s_cselect_b32 s80, s80, s4
	ds_read_b128 v[152:155], v150
	v_add_u32_e32 v151, v145, v112
	ds_read_b128 v[156:159], v151
	s_mov_b32 m0, s1
	v_mfma_f32_16x16x32_bf16 v[76:79], v[160:163], v[176:179], v[76:79]
	global_load_lds_dwordx4 v104, s[78:79]
	v_mfma_f32_16x16x32_bf16 v[64:67], v[160:163], v[180:183], v[64:67]
	ds_read_b128 v[160:163], v150 offset:2048
	v_mfma_f32_16x16x32_bf16 v[12:15], v[164:167], v[176:179], v[12:15]
	s_mov_b32 m0, s39
	v_mfma_f32_16x16x32_bf16 v[0:3], v[164:167], v[180:183], v[0:3]
	global_load_lds_dwordx4 v104, s[80:81]
	v_add_u32_e32 v151, v145, v113
	ds_read_b128 v[164:167], v151
	v_mfma_f32_16x16x32_bf16 v[72:75], v[168:171], v[176:179], v[72:75]
	v_mfma_f32_16x16x32_bf16 v[68:71], v[168:171], v[180:183], v[68:71]
	ds_read_b128 v[168:171], v150 offset:4096
	s_mov_b32 m0, s53
	v_mfma_f32_16x16x32_bf16 v[4:7], v[172:175], v[176:179], v[4:7]
	global_load_lds_dwordx4 v106, s[78:79]
	v_mfma_f32_16x16x32_bf16 v[8:11], v[172:175], v[180:183], v[8:11]
	ds_read_b128 v[172:175], v150 offset:6144
	v_add_u32_e32 v151, v145, v114
	ds_read_b128 v[176:179], v151
	v_add_u32_e32 v151, v145, v115
	ds_read_b128 v[180:183], v151
	s_waitcnt lgkmcnt(6)
	v_mfma_f32_16x16x32_bf16 v[140:143], v[152:155], v[156:159], v[140:143]
	s_waitcnt lgkmcnt(5)
	s_mov_b32 m0, s54
	v_mfma_f32_16x16x32_bf16 v[60:63], v[160:163], v[156:159], v[60:63]
	global_load_lds_dwordx4 v106, s[80:81]
	s_waitcnt lgkmcnt(4)
	v_mfma_f32_16x16x32_bf16 v[132:135], v[152:155], v[164:167], v[132:135]
	v_mfma_f32_16x16x32_bf16 v[52:55], v[160:163], v[164:167], v[52:55]
	s_waitcnt lgkmcnt(3)
	s_mov_b32 m0, s55
	v_mfma_f32_16x16x32_bf16 v[136:139], v[168:171], v[156:159], v[136:139]
	global_load_lds_dwordx4 v108, s[78:79]
	v_mfma_f32_16x16x32_bf16 v[128:131], v[168:171], v[164:167], v[128:131]
	s_waitcnt lgkmcnt(2)
	v_mfma_f32_16x16x32_bf16 v[56:59], v[172:175], v[156:159], v[56:59]
	v_add_u32_e32 v151, v145, v116
	ds_read_b128 v[156:159], v151
	s_mov_b32 m0, s58
	v_mfma_f32_16x16x32_bf16 v[48:51], v[172:175], v[164:167], v[48:51]
	global_load_lds_dwordx4 v108, s[80:81]
	v_add_u32_e32 v151, v145, v117
	ds_read_b128 v[164:167], v151
	s_waitcnt lgkmcnt(3)
	v_mfma_f32_16x16x32_bf16 v[124:127], v[152:155], v[176:179], v[124:127]
	v_mfma_f32_16x16x32_bf16 v[44:47], v[160:163], v[176:179], v[44:47]
	s_mov_b32 m0, s62
	v_mfma_f32_16x16x32_bf16 v[120:123], v[168:171], v[176:179], v[120:123]
	global_load_lds_dwordx4 v146, s[78:79]
	v_mfma_f32_16x16x32_bf16 v[40:43], v[172:175], v[176:179], v[40:43]
	v_add_u32_e32 v151, v145, v118
	ds_read_b128 v[176:179], v151
	s_waitcnt lgkmcnt(3)
	v_mfma_f32_16x16x32_bf16 v[100:103], v[152:155], v[180:183], v[100:103]
	s_mov_b32 m0, s63
	v_mfma_f32_16x16x32_bf16 v[36:39], v[160:163], v[180:183], v[36:39]
	global_load_lds_dwordx4 v146, s[80:81]
	v_mfma_f32_16x16x32_bf16 v[96:99], v[168:171], v[180:183], v[96:99]
	v_mfma_f32_16x16x32_bf16 v[32:35], v[172:175], v[180:183], v[32:35]
	v_add_u32_e32 v151, v145, v119
	ds_read_b128 v[180:183], v151
	s_waitcnt lgkmcnt(3)
	v_mfma_f32_16x16x32_bf16 v[28:31], v[160:163], v[156:159], v[28:31]
	s_waitcnt lgkmcnt(2)
	v_mfma_f32_16x16x32_bf16 v[20:23], v[160:163], v[164:167], v[20:23]
	s_waitcnt lgkmcnt(1)
	v_mfma_f32_16x16x32_bf16 v[12:15], v[160:163], v[176:179], v[12:15]
	s_waitcnt lgkmcnt(0)
	v_mfma_f32_16x16x32_bf16 v[0:3], v[160:163], v[180:183], v[0:3]
	ds_read_b128 v[160:163], v150 offset:1024
	v_mfma_f32_16x16x32_bf16 v[92:95], v[152:155], v[156:159], v[92:95]
	v_mfma_f32_16x16x32_bf16 v[84:87], v[152:155], v[164:167], v[84:87]
	v_mfma_f32_16x16x32_bf16 v[76:79], v[152:155], v[176:179], v[76:79]
	v_mfma_f32_16x16x32_bf16 v[64:67], v[152:155], v[180:183], v[64:67]
	v_add_u32_e32 v151, v149, v112
	ds_read_b128 v[152:155], v151
	v_mfma_f32_16x16x32_bf16 v[80:83], v[168:171], v[164:167], v[80:83]
	v_mfma_f32_16x16x32_bf16 v[16:19], v[172:175], v[164:167], v[16:19]
	ds_read_b128 v[164:167], v150 offset:3072
	v_mfma_f32_16x16x32_bf16 v[88:91], v[168:171], v[156:159], v[88:91]
	v_mfma_f32_16x16x32_bf16 v[24:27], v[172:175], v[156:159], v[24:27]
	v_add_u32_e32 v151, v149, v113
	ds_read_b128 v[156:159], v151
	v_mfma_f32_16x16x32_bf16 v[72:75], v[168:171], v[176:179], v[72:75]
	v_mfma_f32_16x16x32_bf16 v[4:7], v[172:175], v[176:179], v[4:7]
	v_add_u32_e32 v151, v149, v114
	ds_read_b128 v[176:179], v151
	v_mfma_f32_16x16x32_bf16 v[68:71], v[168:171], v[180:183], v[68:71]
	ds_read_b128 v[168:171], v150 offset:5120
	v_mfma_f32_16x16x32_bf16 v[8:11], v[172:175], v[180:183], v[8:11]
	ds_read_b128 v[172:175], v150 offset:7168
	v_add_u32_e32 v151, v149, v115
	ds_read_b128 v[180:183], v151
	s_waitcnt lgkmcnt(6)
	v_mfma_f32_16x16x32_bf16 v[140:143], v[160:163], v[152:155], v[140:143]
	s_waitcnt lgkmcnt(5)
	v_mfma_f32_16x16x32_bf16 v[60:63], v[164:167], v[152:155], v[60:63]
	s_waitcnt lgkmcnt(4)
	v_mfma_f32_16x16x32_bf16 v[132:135], v[160:163], v[156:159], v[132:135]
	v_mfma_f32_16x16x32_bf16 v[52:55], v[164:167], v[156:159], v[52:55]
	s_waitcnt lgkmcnt(3)
	v_mfma_f32_16x16x32_bf16 v[124:127], v[160:163], v[176:179], v[124:127]
	v_mfma_f32_16x16x32_bf16 v[44:47], v[164:167], v[176:179], v[44:47]
	s_waitcnt lgkmcnt(2)
	v_mfma_f32_16x16x32_bf16 v[136:139], v[168:171], v[152:155], v[136:139]
	s_waitcnt lgkmcnt(1)
	v_mfma_f32_16x16x32_bf16 v[56:59], v[172:175], v[152:155], v[56:59]
	v_add_u32_e32 v151, v149, v116
	ds_read_b128 v[152:155], v151
	v_mfma_f32_16x16x32_bf16 v[128:131], v[168:171], v[156:159], v[128:131]
	v_mfma_f32_16x16x32_bf16 v[48:51], v[172:175], v[156:159], v[48:51]
	v_add_u32_e32 v151, v149, v117
	ds_read_b128 v[156:159], v151
	v_mfma_f32_16x16x32_bf16 v[120:123], v[168:171], v[176:179], v[120:123]
	v_mfma_f32_16x16x32_bf16 v[40:43], v[172:175], v[176:179], v[40:43]
	v_add_u32_e32 v151, v149, v118
	ds_read_b128 v[176:179], v151
	s_waitcnt lgkmcnt(3)
	v_mfma_f32_16x16x32_bf16 v[100:103], v[160:163], v[180:183], v[100:103]
	v_mfma_f32_16x16x32_bf16 v[36:39], v[164:167], v[180:183], v[36:39]
	v_mfma_f32_16x16x32_bf16 v[96:99], v[168:171], v[180:183], v[96:99]
	v_mfma_f32_16x16x32_bf16 v[32:35], v[172:175], v[180:183], v[32:35]
	v_add_u32_e32 v151, v149, v119
	ds_read_b128 v[180:183], v151
	s_waitcnt lgkmcnt(3)
	v_mfma_f32_16x16x32_bf16 v[92:95], v[160:163], v[152:155], v[92:95]
	v_mfma_f32_16x16x32_bf16 v[28:31], v[164:167], v[152:155], v[28:31]
	v_mfma_f32_16x16x32_bf16 v[88:91], v[168:171], v[152:155], v[88:91]
	v_mfma_f32_16x16x32_bf16 v[24:27], v[172:175], v[152:155], v[24:27]
	s_waitcnt lgkmcnt(2)
	v_mfma_f32_16x16x32_bf16 v[84:87], v[160:163], v[156:159], v[84:87]
	v_mfma_f32_16x16x32_bf16 v[20:23], v[164:167], v[156:159], v[20:23]
	v_mfma_f32_16x16x32_bf16 v[80:83], v[168:171], v[156:159], v[80:83]
	v_mfma_f32_16x16x32_bf16 v[16:19], v[172:175], v[156:159], v[16:19]
	s_waitcnt vmcnt(0)
	s_add_u32 s2, s2, 0x100
	s_addc_u32 s3, s3, 0
	s_add_i32 s76, s76, 2
	s_cmpk_lg_i32 s2, 0x1000
	s_waitcnt lgkmcnt(0)
	s_barrier
	s_cbranch_scc1 .LBB0_87
	v_mfma_f32_16x16x32_bf16 v[76:79], v[160:163], v[176:179], v[76:79]
	v_mfma_f32_16x16x32_bf16 v[64:67], v[160:163], v[180:183], v[64:67]
	v_mfma_f32_16x16x32_bf16 v[12:15], v[164:167], v[176:179], v[12:15]
	v_mfma_f32_16x16x32_bf16 v[0:3], v[164:167], v[180:183], v[0:3]
	v_mfma_f32_16x16x32_bf16 v[72:75], v[168:171], v[176:179], v[72:75]
	v_mfma_f32_16x16x32_bf16 v[68:71], v[168:171], v[180:183], v[68:71]
	v_mfma_f32_16x16x32_bf16 v[4:7], v[172:175], v[176:179], v[4:7]
	v_mfma_f32_16x16x32_bf16 v[8:11], v[172:175], v[180:183], v[8:11]
	s_nop 15
	s_nop 15
	v_mov_b32_e32 v145, v184
	s_movk_i32 s1, 0x100
	v_and_b32_e32 v163, 15, v145
	v_cmp_gt_u32_e64 s[2:3], s1, v145
	v_cmp_lt_u32_e32 vcc, 13, v163
	s_and_b64 s[4:5], s[2:3], vcc
	s_xor_b64 s[4:5], s[4:5], -1
	v_lshlrev_b32_e32 v149, 6, v163
	s_and_saveexec_b64 s[36:37], s[4:5]
	s_xor_b64 s[4:5], exec, s[36:37]
	v_lshlrev_b32_e32 v149, 6, v163
	s_or_saveexec_b64 s[4:5], s[4:5]
	v_bfe_u32 v150, v145, 4, 2
	v_readlane_b32 s68, v253, 18
	v_readlane_b32 s75, v253, 20
	s_xor_b64 exec, exec, s[4:5]
	s_cbranch_execz .LBB0_92
	v_mov_b32_e32 v104, 0x211c0
	v_lshl_or_b32 v104, v163, 2, v104
	ds_read_b32 v108, v104
	v_and_b32_e32 v104, 0xc0, v145
	v_lshl_add_u32 v104, v104, 2, v149
	v_lshl_or_b32 v109, v150, 4, v104
	v_add_u32_e32 v110, 0x1fc80, v109
	s_waitcnt lgkmcnt(0)
	v_pk_mul_f32 v[104:105], v[64:65], v[108:109] op_sel_hi:[1,0]
	v_pk_mul_f32 v[106:107], v[66:67], v[108:109] op_sel_hi:[1,0]
	v_add_u32_e32 v109, 0x1fd00, v109
	ds_write_b128 v110, v[104:107]
	v_pk_mul_f32 v[104:105], v[0:1], v[108:109] op_sel_hi:[1,0]
	v_pk_mul_f32 v[106:107], v[2:3], v[108:109] op_sel_hi:[1,0]
	ds_write_b128 v109, v[104:107]

.LBB0_154:
	s_ashr_i32 s21, s20, 31
	s_lshl_b64 s[20:21], s[20:21], 20
	s_add_u32 s20, s26, s20
	s_addc_u32 s21, s27, s21
	s_ashr_i32 s23, s22, 31
	s_lshl_b64 s[22:23], s[22:23], 20
	s_add_u32 s22, s8, s22
	s_addc_u32 s23, s9, s23
	s_add_u32 s44, s16, 0x80
	v_and_b32_e32 v8, 48, v7
	v_lshlrev_b32_e32 v9, 6, v7
	v_lshlrev_b32_e32 v7, 2, v7
	s_addc_u32 s45, s17, 0
	v_and_b32_e32 v10, 0x3c0, v9
	v_and_b32_e32 v149, 32, v7
	s_add_u32 s46, s18, 0x80
	v_or_b32_e32 v145, v10, v8
	v_bitop3_b32 v12, v10, v149, v8 bitop3:0x36
	s_waitcnt vmcnt(0)
	s_barrier
	v_lshlrev_b32_e32 v8, 13, v6
	s_addc_u32 s47, s19, 0
	s_add_i32 s25, s1, 0x10000
	v_lshl_add_u64 v[6:7], s[44:45], 0, v[0:1]
	s_mov_b32 s39, m0
	s_mov_b32 m0, s25
	s_nop 0
	global_load_lds_dwordx4 v[6:7], off
	s_mov_b32 m0, s39
	s_add_i32 s24, s1, 0x18000
	v_lshl_add_u64 v[6:7], s[46:47], 0, v[0:1]
	s_mov_b32 s39, m0
	s_mov_b32 m0, s24
	s_nop 0
	global_load_lds_dwordx4 v[6:7], off
	s_mov_b32 m0, s39
	v_lshl_add_u64 v[6:7], s[44:45], 0, v[2:3]
	s_add_i32 s39, s1, 0x12000
	s_mov_b32 s40, m0
	s_mov_b32 m0, s39
	s_nop 0
	global_load_lds_dwordx4 v[6:7], off
	s_mov_b32 m0, s40
	v_lshl_add_u64 v[6:7], s[46:47], 0, v[2:3]
	s_add_i32 s40, s1, 0x1a000
	s_mov_b32 s41, m0
	s_mov_b32 m0, s40
	s_nop 0
	global_load_lds_dwordx4 v[6:7], off
	s_mov_b32 m0, s41
	v_lshl_add_u64 v[6:7], s[44:45], 0, v[4:5]
	s_add_i32 s41, s1, 0x14000
	s_mov_b32 s42, m0
	s_mov_b32 m0, s41
	s_nop 0
	global_load_lds_dwordx4 v[6:7], off
	s_mov_b32 m0, s42
	v_lshl_add_u64 v[6:7], s[46:47], 0, v[4:5]
	s_add_i32 s42, s1, 0x1c000
	s_mov_b32 s43, m0
	s_mov_b32 m0, s42
	s_nop 0
	global_load_lds_dwordx4 v[6:7], off
	s_mov_b32 m0, s43
	v_lshl_add_u64 v[6:7], s[44:45], 0, v[146:147]
	s_add_i32 s43, s1, 0x16000
	s_mov_b32 s44, m0
	s_mov_b32 m0, s43
	s_nop 0
	global_load_lds_dwordx4 v[6:7], off
	s_mov_b32 m0, s44
	v_lshl_add_u64 v[6:7], s[46:47], 0, v[146:147]
	s_add_i32 s44, s1, 0x1e000
	s_mov_b32 s45, m0
	s_mov_b32 m0, s44
	s_nop 0
	global_load_lds_dwordx4 v[6:7], off
	s_mov_b32 m0, s45
	v_and_b32_e32 v182, 0xffffc000, v9
	v_or_b32_e32 v183, 0x800, v182
	v_or_b32_e32 v189, 0x1000, v182
	v_or_b32_e32 v199, 0x1800, v182
	v_or_b32_e32 v200, 0x2000, v182
	v_or_b32_e32 v201, 0x2800, v182
	v_or_b32_e32 v203, 0x3000, v182
	v_or_b32_e32 v206, 0x3800, v182
	s_movk_i32 s45, 0x6000
	v_and_or_b32 v7, v8, s45, v12
	ds_read_b128 v[8:11], v7 offset:32768
	v_or_b32_e32 v6, v12, v182
	ds_read_b128 v[12:15], v7 offset:34816
	ds_read_b128 v[16:19], v7 offset:36864
	ds_read_b128 v[24:27], v7 offset:38912
	ds_read_b128 v[20:23], v6
	ds_read_b128 v[28:31], v6 offset:2048
	ds_read_b128 v[32:35], v6 offset:4096
	ds_read_b128 v[36:39], v6 offset:6144
	s_waitcnt lgkmcnt(3)
	v_mfma_f32_16x16x32_bf16 v[40:43], v[8:11], v[20:23], 0
	v_mfma_f32_16x16x32_bf16 v[44:47], v[12:15], v[20:23], 0
	v_mfma_f32_16x16x32_bf16 v[48:51], v[16:19], v[20:23], 0
	v_mfma_f32_16x16x32_bf16 v[20:23], v[24:27], v[20:23], 0
	ds_read_b128 v[52:55], v6 offset:8192
	s_waitcnt lgkmcnt(3)
	v_mfma_f32_16x16x32_bf16 v[56:59], v[8:11], v[28:31], 0
	v_mfma_f32_16x16x32_bf16 v[60:63], v[12:15], v[28:31], 0
	v_mfma_f32_16x16x32_bf16 v[64:67], v[16:19], v[28:31], 0
	v_mfma_f32_16x16x32_bf16 v[28:31], v[24:27], v[28:31], 0
	ds_read_b128 v[68:71], v6 offset:10240
	s_waitcnt lgkmcnt(3)
	v_mfma_f32_16x16x32_bf16 v[72:75], v[8:11], v[32:35], 0
	v_mfma_f32_16x16x32_bf16 v[76:79], v[12:15], v[32:35], 0
	v_mfma_f32_16x16x32_bf16 v[80:83], v[16:19], v[32:35], 0
	v_mfma_f32_16x16x32_bf16 v[32:35], v[24:27], v[32:35], 0
	ds_read_b128 v[84:87], v6 offset:12288
	s_waitcnt lgkmcnt(3)
	v_mfma_f32_16x16x32_bf16 v[88:91], v[8:11], v[36:39], 0
	v_mfma_f32_16x16x32_bf16 v[92:95], v[12:15], v[36:39], 0
	v_mfma_f32_16x16x32_bf16 v[96:99], v[16:19], v[36:39], 0
	v_mfma_f32_16x16x32_bf16 v[36:39], v[24:27], v[36:39], 0
	ds_read_b128 v[100:103], v6 offset:14336
	s_waitcnt lgkmcnt(3)
	v_mfma_f32_16x16x32_bf16 v[104:107], v[8:11], v[52:55], 0
	v_mfma_f32_16x16x32_bf16 v[108:111], v[12:15], v[52:55], 0
	v_mfma_f32_16x16x32_bf16 v[112:115], v[16:19], v[52:55], 0
	v_mfma_f32_16x16x32_bf16 v[52:55], v[24:27], v[52:55], 0
	s_waitcnt lgkmcnt(2)
	v_mfma_f32_16x16x32_bf16 v[116:119], v[8:11], v[68:71], 0
	v_mfma_f32_16x16x32_bf16 v[120:123], v[12:15], v[68:71], 0
	v_mfma_f32_16x16x32_bf16 v[124:127], v[16:19], v[68:71], 0
	v_mfma_f32_16x16x32_bf16 v[68:71], v[24:27], v[68:71], 0
	s_waitcnt lgkmcnt(1)
	v_mfma_f32_16x16x32_bf16 v[128:131], v[8:11], v[84:87], 0
	v_mfma_f32_16x16x32_bf16 v[132:135], v[12:15], v[84:87], 0
	v_mfma_f32_16x16x32_bf16 v[136:139], v[16:19], v[84:87], 0
	v_mfma_f32_16x16x32_bf16 v[84:87], v[24:27], v[84:87], 0
	s_waitcnt lgkmcnt(0)
	v_mfma_f32_16x16x32_bf16 v[8:11], v[8:11], v[100:103], 0
	v_mfma_f32_16x16x32_bf16 v[12:15], v[12:15], v[100:103], 0
	v_mfma_f32_16x16x32_bf16 v[16:19], v[16:19], v[100:103], 0
	v_mfma_f32_16x16x32_bf16 v[24:27], v[24:27], v[100:103], 0
	ds_read_b128 v[100:103], v7 offset:33792
	ds_read_b128 v[140:143], v7 offset:35840
	ds_read_b128 v[150:153], v7 offset:37888
	ds_read_b128 v[158:161], v7 offset:39936
	ds_read_b128 v[154:157], v6 offset:1024
	ds_read_b128 v[162:165], v6 offset:3072
	ds_read_b128 v[166:169], v6 offset:5120
	ds_read_b128 v[170:173], v6 offset:7168
	s_waitcnt lgkmcnt(3)
	v_mfma_f32_16x16x32_bf16 v[40:43], v[100:103], v[154:157], v[40:43]
	v_mfma_f32_16x16x32_bf16 v[44:47], v[140:143], v[154:157], v[44:47]
	v_mfma_f32_16x16x32_bf16 v[48:51], v[150:153], v[154:157], v[48:51]
	v_mfma_f32_16x16x32_bf16 v[20:23], v[158:161], v[154:157], v[20:23]
	ds_read_b128 v[154:157], v6 offset:9216
	s_waitcnt lgkmcnt(3)
	v_mfma_f32_16x16x32_bf16 v[56:59], v[100:103], v[162:165], v[56:59]
	v_mfma_f32_16x16x32_bf16 v[60:63], v[140:143], v[162:165], v[60:63]
	v_mfma_f32_16x16x32_bf16 v[64:67], v[150:153], v[162:165], v[64:67]
	v_mfma_f32_16x16x32_bf16 v[28:31], v[158:161], v[162:165], v[28:31]
	ds_read_b128 v[162:165], v6 offset:11264
	s_waitcnt lgkmcnt(3)
	v_mfma_f32_16x16x32_bf16 v[72:75], v[100:103], v[166:169], v[72:75]
	v_mfma_f32_16x16x32_bf16 v[76:79], v[140:143], v[166:169], v[76:79]
	v_mfma_f32_16x16x32_bf16 v[80:83], v[150:153], v[166:169], v[80:83]
	v_mfma_f32_16x16x32_bf16 v[32:35], v[158:161], v[166:169], v[32:35]
	ds_read_b128 v[166:169], v6 offset:13312
	s_waitcnt lgkmcnt(3)
	v_mfma_f32_16x16x32_bf16 v[88:91], v[100:103], v[170:173], v[88:91]
	v_mfma_f32_16x16x32_bf16 v[92:95], v[140:143], v[170:173], v[92:95]
	v_mfma_f32_16x16x32_bf16 v[96:99], v[150:153], v[170:173], v[96:99]
	v_mfma_f32_16x16x32_bf16 v[36:39], v[158:161], v[170:173], v[36:39]
	ds_read_b128 v[170:173], v6 offset:15360
	s_waitcnt lgkmcnt(3)
	v_mfma_f32_16x16x32_bf16 v[104:107], v[100:103], v[154:157], v[104:107]
	v_mfma_f32_16x16x32_bf16 v[108:111], v[140:143], v[154:157], v[108:111]
	v_mfma_f32_16x16x32_bf16 v[112:115], v[150:153], v[154:157], v[112:115]
	v_mfma_f32_16x16x32_bf16 v[52:55], v[158:161], v[154:157], v[52:55]
	s_waitcnt lgkmcnt(2)
	v_mfma_f32_16x16x32_bf16 v[116:119], v[100:103], v[162:165], v[116:119]
	v_mfma_f32_16x16x32_bf16 v[120:123], v[140:143], v[162:165], v[120:123]
	v_mfma_f32_16x16x32_bf16 v[124:127], v[150:153], v[162:165], v[124:127]
	v_mfma_f32_16x16x32_bf16 v[68:71], v[158:161], v[162:165], v[68:71]
	s_waitcnt lgkmcnt(1)
	v_mfma_f32_16x16x32_bf16 v[128:131], v[100:103], v[166:169], v[128:131]
	v_mfma_f32_16x16x32_bf16 v[132:135], v[140:143], v[166:169], v[132:135]
	v_mfma_f32_16x16x32_bf16 v[136:139], v[150:153], v[166:169], v[136:139]
	v_mfma_f32_16x16x32_bf16 v[84:87], v[158:161], v[166:169], v[84:87]
	s_waitcnt lgkmcnt(0)
	v_mfma_f32_16x16x32_bf16 v[100:103], v[100:103], v[170:173], v[8:11]
	v_mfma_f32_16x16x32_bf16 v[150:153], v[150:153], v[170:173], v[16:19]
	v_mfma_f32_16x16x32_bf16 v[24:27], v[158:161], v[170:173], v[24:27]
	v_mfma_f32_16x16x32_bf16 v[140:143], v[140:143], v[170:173], v[12:15]
	s_add_u32 s46, s16, 0x100
	s_addc_u32 s47, s17, 0
	s_add_u32 s48, s18, 0x100
	s_waitcnt vmcnt(0)
	s_barrier
	s_addc_u32 s49, s19, 0
	v_lshl_add_u64 v[8:9], s[46:47], 0, v[0:1]
	s_mov_b32 s45, m0
	s_mov_b32 m0, s1
	s_nop 0
	global_load_lds_dwordx4 v[8:9], off
	s_mov_b32 m0, s45
	v_lshl_add_u64 v[8:9], s[48:49], 0, v[0:1]
	s_mov_b32 s45, m0
	s_mov_b32 m0, s30
	s_nop 0
	global_load_lds_dwordx4 v[8:9], off
	s_mov_b32 m0, s45
	v_lshl_add_u64 v[8:9], s[46:47], 0, v[2:3]
	s_mov_b32 s45, m0
	s_mov_b32 m0, s31
	s_nop 0
	global_load_lds_dwordx4 v[8:9], off
	s_mov_b32 m0, s45
	v_lshl_add_u64 v[8:9], s[48:49], 0, v[2:3]
	s_mov_b32 s45, m0
	s_mov_b32 m0, s34
	s_nop 0
	global_load_lds_dwordx4 v[8:9], off
	s_mov_b32 m0, s45
	v_lshl_add_u64 v[8:9], s[46:47], 0, v[4:5]
	s_mov_b32 s45, m0
	s_mov_b32 m0, s35
	s_nop 0
	global_load_lds_dwordx4 v[8:9], off
	s_mov_b32 m0, s45
	v_lshl_add_u64 v[8:9], s[48:49], 0, v[4:5]
	s_mov_b32 s45, m0
	s_mov_b32 m0, s36
	s_nop 0
	global_load_lds_dwordx4 v[8:9], off
	s_mov_b32 m0, s45
	v_lshl_add_u64 v[8:9], s[46:47], 0, v[146:147]
	s_mov_b32 s45, m0
	s_mov_b32 m0, s37
	s_nop 0
	global_load_lds_dwordx4 v[8:9], off
	s_mov_b32 m0, s45
	v_lshl_add_u64 v[8:9], s[48:49], 0, v[146:147]
	s_mov_b32 s45, m0
	s_mov_b32 m0, s38
	s_nop 0
	global_load_lds_dwordx4 v[8:9], off
	s_mov_b32 m0, s45
	v_or_b32_e32 v8, 0x18000, v7
	v_or_b32_e32 v9, 0x18800, v7
	v_or_b32_e32 v11, 0x19000, v7
	v_or_b32_e32 v10, 0x19800, v7
	ds_read_b128 v[154:157], v8
	ds_read_b128 v[158:161], v9
	ds_read_b128 v[162:165], v11
	ds_read_b128 v[166:169], v10
	v_bitop3_b32 v207, v145, s33, v149 bitop3:0xde
	v_add_u32_e32 v12, v207, v182
	ds_read_b128 v[16:19], v12
	v_add_u32_e32 v13, v207, v183
	v_add_u32_e32 v14, v207, v189
	v_add_u32_e32 v15, v207, v199
	ds_read_b128 v[170:173], v13
	ds_read_b128 v[174:177], v14
	ds_read_b128 v[178:181], v15
	s_waitcnt lgkmcnt(3)
	v_mfma_f32_16x16x32_bf16 v[40:43], v[154:157], v[16:19], v[40:43]
	v_mfma_f32_16x16x32_bf16 v[44:47], v[158:161], v[16:19], v[44:47]
	v_mfma_f32_16x16x32_bf16 v[48:51], v[162:165], v[16:19], v[48:51]
	v_mfma_f32_16x16x32_bf16 v[214:217], v[166:169], v[16:19], v[20:23]
	v_add_u32_e32 v16, v207, v200
	v_add_u32_e32 v17, v207, v201
	v_add_u32_e32 v18, v207, v203
	v_add_u32_e32 v19, v207, v206
	ds_read_b128 v[20:23], v16
	s_waitcnt lgkmcnt(3)
	v_mfma_f32_16x16x32_bf16 v[56:59], v[154:157], v[170:173], v[56:59]
	v_mfma_f32_16x16x32_bf16 v[60:63], v[158:161], v[170:173], v[60:63]
	v_mfma_f32_16x16x32_bf16 v[64:67], v[162:165], v[170:173], v[64:67]
	v_mfma_f32_16x16x32_bf16 v[170:173], v[166:169], v[170:173], v[28:31]
	s_nop 2
	ds_read_b128 v[28:31], v17
	s_waitcnt lgkmcnt(3)
	v_mfma_f32_16x16x32_bf16 v[72:75], v[154:157], v[174:177], v[72:75]
	v_mfma_f32_16x16x32_bf16 v[76:79], v[158:161], v[174:177], v[76:79]
	v_mfma_f32_16x16x32_bf16 v[80:83], v[162:165], v[174:177], v[80:83]
	v_mfma_f32_16x16x32_bf16 v[32:35], v[166:169], v[174:177], v[32:35]
	ds_read_b128 v[174:177], v18
	s_waitcnt lgkmcnt(3)
	v_mfma_f32_16x16x32_bf16 v[88:91], v[154:157], v[178:181], v[88:91]
	v_mfma_f32_16x16x32_bf16 v[92:95], v[158:161], v[178:181], v[92:95]
	v_mfma_f32_16x16x32_bf16 v[96:99], v[162:165], v[178:181], v[96:99]
	v_mfma_f32_16x16x32_bf16 v[36:39], v[166:169], v[178:181], v[36:39]
	ds_read_b128 v[178:181], v19
	s_waitcnt lgkmcnt(3)
	v_mfma_f32_16x16x32_bf16 v[104:107], v[154:157], v[20:23], v[104:107]
	v_mfma_f32_16x16x32_bf16 v[108:111], v[158:161], v[20:23], v[108:111]
	v_mfma_f32_16x16x32_bf16 v[112:115], v[162:165], v[20:23], v[112:115]
	v_mfma_f32_16x16x32_bf16 v[52:55], v[166:169], v[20:23], v[52:55]
	s_waitcnt lgkmcnt(2)
	v_mfma_f32_16x16x32_bf16 v[116:119], v[154:157], v[28:31], v[116:119]
	v_mfma_f32_16x16x32_bf16 v[120:123], v[158:161], v[28:31], v[120:123]
	v_mfma_f32_16x16x32_bf16 v[124:127], v[162:165], v[28:31], v[124:127]
	v_mfma_f32_16x16x32_bf16 v[68:71], v[166:169], v[28:31], v[68:71]
	s_waitcnt lgkmcnt(1)
	v_mfma_f32_16x16x32_bf16 v[128:131], v[154:157], v[174:177], v[128:131]
	v_mfma_f32_16x16x32_bf16 v[132:135], v[158:161], v[174:177], v[132:135]
	v_mfma_f32_16x16x32_bf16 v[84:87], v[166:169], v[174:177], v[84:87]
	s_waitcnt lgkmcnt(0)
	v_mfma_f32_16x16x32_bf16 v[100:103], v[154:157], v[178:181], v[100:103]
	v_mfma_f32_16x16x32_bf16 v[150:153], v[162:165], v[178:181], v[150:153]
	v_mfma_f32_16x16x32_bf16 v[154:157], v[166:169], v[178:181], v[24:27]
	v_mfma_f32_16x16x32_bf16 v[136:139], v[162:165], v[174:177], v[136:139]
	v_mfma_f32_16x16x32_bf16 v[140:143], v[158:161], v[178:181], v[140:143]
	v_or_b32_e32 v20, 0x18400, v7
	v_or_b32_e32 v21, 0x18c00, v7
	v_or_b32_e32 v23, 0x19400, v7
	v_or_b32_e32 v22, 0x19c00, v7
	ds_read_b128 v[158:161], v20
	ds_read_b128 v[162:165], v21
	ds_read_b128 v[166:169], v23
	ds_read_b128 v[174:177], v22
	s_mov_b32 s45, 0x10400
	v_bitop3_b32 v145, v145, s45, v149 bitop3:0xde
	v_add_u32_e32 v24, v145, v182
	ds_read_b128 v[28:31], v24
	v_add_u32_e32 v25, v145, v183
	v_add_u32_e32 v26, v145, v189
	v_add_u32_e32 v27, v145, v199
	ds_read_b128 v[178:181], v25
	ds_read_b128 v[218:221], v26
	ds_read_b128 v[222:225], v27
	s_waitcnt lgkmcnt(3)
	v_mfma_f32_16x16x32_bf16 v[40:43], v[158:161], v[28:31], v[40:43]
	v_mfma_f32_16x16x32_bf16 v[44:47], v[162:165], v[28:31], v[44:47]
	v_mfma_f32_16x16x32_bf16 v[48:51], v[166:169], v[28:31], v[48:51]
	v_mfma_f32_16x16x32_bf16 v[214:217], v[174:177], v[28:31], v[214:217]
	v_add_u32_e32 v28, v145, v200
	v_add_u32_e32 v29, v145, v201
	v_add_u32_e32 v30, v145, v203
	v_add_u32_e32 v31, v145, v206
	ds_read_b128 v[226:229], v28
	s_waitcnt lgkmcnt(3)
	v_mfma_f32_16x16x32_bf16 v[56:59], v[158:161], v[178:181], v[56:59]
	v_mfma_f32_16x16x32_bf16 v[60:63], v[162:165], v[178:181], v[60:63]
	v_mfma_f32_16x16x32_bf16 v[64:67], v[166:169], v[178:181], v[64:67]
	v_mfma_f32_16x16x32_bf16 v[170:173], v[174:177], v[178:181], v[170:173]
	ds_read_b128 v[178:181], v29
	s_waitcnt lgkmcnt(3)
	v_mfma_f32_16x16x32_bf16 v[72:75], v[158:161], v[218:221], v[72:75]
	v_mfma_f32_16x16x32_bf16 v[76:79], v[162:165], v[218:221], v[76:79]
	v_mfma_f32_16x16x32_bf16 v[80:83], v[166:169], v[218:221], v[80:83]
	v_mfma_f32_16x16x32_bf16 v[32:35], v[174:177], v[218:221], v[32:35]
	ds_read_b128 v[218:221], v30
	s_waitcnt lgkmcnt(3)
	v_mfma_f32_16x16x32_bf16 v[88:91], v[158:161], v[222:225], v[88:91]
	v_mfma_f32_16x16x32_bf16 v[92:95], v[162:165], v[222:225], v[92:95]
	v_mfma_f32_16x16x32_bf16 v[96:99], v[166:169], v[222:225], v[96:99]
	v_mfma_f32_16x16x32_bf16 v[36:39], v[174:177], v[222:225], v[36:39]
	ds_read_b128 v[222:225], v31
	s_waitcnt lgkmcnt(3)
	v_mfma_f32_16x16x32_bf16 v[104:107], v[158:161], v[226:229], v[104:107]
	v_mfma_f32_16x16x32_bf16 v[108:111], v[162:165], v[226:229], v[108:111]
	v_mfma_f32_16x16x32_bf16 v[112:115], v[166:169], v[226:229], v[112:115]
	v_mfma_f32_16x16x32_bf16 v[52:55], v[174:177], v[226:229], v[52:55]
	s_waitcnt lgkmcnt(2)
	v_mfma_f32_16x16x32_bf16 v[116:119], v[158:161], v[178:181], v[116:119]
	v_mfma_f32_16x16x32_bf16 v[120:123], v[162:165], v[178:181], v[120:123]
	v_mfma_f32_16x16x32_bf16 v[124:127], v[166:169], v[178:181], v[124:127]
	v_mfma_f32_16x16x32_bf16 v[68:71], v[174:177], v[178:181], v[68:71]
	s_waitcnt lgkmcnt(1)
	v_mfma_f32_16x16x32_bf16 v[132:135], v[162:165], v[218:221], v[132:135]
	v_mfma_f32_16x16x32_bf16 v[84:87], v[174:177], v[218:221], v[84:87]
	s_waitcnt lgkmcnt(0)
	v_mfma_f32_16x16x32_bf16 v[100:103], v[158:161], v[222:225], v[100:103]
	v_mfma_f32_16x16x32_bf16 v[150:153], v[166:169], v[222:225], v[150:153]
	v_mfma_f32_16x16x32_bf16 v[154:157], v[174:177], v[222:225], v[154:157]
	v_mfma_f32_16x16x32_bf16 v[128:131], v[158:161], v[218:221], v[128:131]
	v_mfma_f32_16x16x32_bf16 v[136:139], v[166:169], v[218:221], v[136:139]
	v_mfma_f32_16x16x32_bf16 v[140:143], v[162:165], v[222:225], v[140:143]
	s_add_u32 s46, s16, 0x180
	s_addc_u32 s47, s17, 0
	s_add_u32 s48, s18, 0x180
	s_waitcnt vmcnt(0)
	s_barrier
	s_addc_u32 s49, s19, 0
	v_lshl_add_u64 v[158:159], s[46:47], 0, v[0:1]
	s_mov_b32 s45, m0
	s_mov_b32 m0, s25
	s_nop 0
	global_load_lds_dwordx4 v[158:159], off
	s_mov_b32 m0, s45
	v_lshl_add_u64 v[158:159], s[48:49], 0, v[0:1]
	s_mov_b32 s45, m0
	s_mov_b32 m0, s24
	s_nop 0
	global_load_lds_dwordx4 v[158:159], off
	s_mov_b32 m0, s45
	v_lshl_add_u64 v[158:159], s[46:47], 0, v[2:3]
	s_mov_b32 s45, m0
	s_mov_b32 m0, s39
	s_nop 0
	global_load_lds_dwordx4 v[158:159], off
	s_mov_b32 m0, s45
	v_lshl_add_u64 v[158:159], s[48:49], 0, v[2:3]
	s_mov_b32 s45, m0
	s_mov_b32 m0, s40
	s_nop 0
	global_load_lds_dwordx4 v[158:159], off
	s_mov_b32 m0, s45
	v_lshl_add_u64 v[158:159], s[46:47], 0, v[4:5]
	s_mov_b32 s45, m0
	s_mov_b32 m0, s41
	s_nop 0
	global_load_lds_dwordx4 v[158:159], off
	s_mov_b32 m0, s45
	v_lshl_add_u64 v[158:159], s[48:49], 0, v[4:5]
	s_mov_b32 s45, m0
	s_mov_b32 m0, s42
	s_nop 0
	global_load_lds_dwordx4 v[158:159], off
	s_mov_b32 m0, s45
	v_lshl_add_u64 v[158:159], s[46:47], 0, v[146:147]
	s_mov_b32 s45, m0
	s_mov_b32 m0, s43
	s_nop 0
	global_load_lds_dwordx4 v[158:159], off
	s_mov_b32 m0, s45
	v_lshl_add_u64 v[158:159], s[48:49], 0, v[146:147]
	s_mov_b32 s45, m0
	s_mov_b32 m0, s44
	s_nop 0
	global_load_lds_dwordx4 v[158:159], off
	s_mov_b32 m0, s45
	ds_read_b128 v[158:161], v7 offset:32768
	ds_read_b128 v[162:165], v7 offset:34816
	ds_read_b128 v[166:169], v7 offset:36864
	ds_read_b128 v[178:181], v7 offset:38912
	ds_read_b128 v[174:177], v6
	ds_read_b128 v[218:221], v6 offset:2048
	ds_read_b128 v[222:225], v6 offset:4096
	ds_read_b128 v[226:229], v6 offset:6144
	s_waitcnt lgkmcnt(3)
	v_mfma_f32_16x16x32_bf16 v[40:43], v[158:161], v[174:177], v[40:43]
	v_mfma_f32_16x16x32_bf16 v[44:47], v[162:165], v[174:177], v[44:47]
	v_mfma_f32_16x16x32_bf16 v[48:51], v[166:169], v[174:177], v[48:51]
	v_mfma_f32_16x16x32_bf16 v[174:177], v[178:181], v[174:177], v[214:217]
	s_nop 2
	ds_read_b128 v[214:217], v6 offset:8192
	s_waitcnt lgkmcnt(3)
	v_mfma_f32_16x16x32_bf16 v[56:59], v[158:161], v[218:221], v[56:59]
	v_mfma_f32_16x16x32_bf16 v[60:63], v[162:165], v[218:221], v[60:63]
	v_mfma_f32_16x16x32_bf16 v[64:67], v[166:169], v[218:221], v[64:67]
	v_mfma_f32_16x16x32_bf16 v[170:173], v[178:181], v[218:221], v[170:173]
	ds_read_b128 v[218:221], v6 offset:10240
	s_waitcnt lgkmcnt(3)
	v_mfma_f32_16x16x32_bf16 v[72:75], v[158:161], v[222:225], v[72:75]
	v_mfma_f32_16x16x32_bf16 v[76:79], v[162:165], v[222:225], v[76:79]
	v_mfma_f32_16x16x32_bf16 v[80:83], v[166:169], v[222:225], v[80:83]
	v_mfma_f32_16x16x32_bf16 v[32:35], v[178:181], v[222:225], v[32:35]
	ds_read_b128 v[222:225], v6 offset:12288
	s_waitcnt lgkmcnt(3)
	v_mfma_f32_16x16x32_bf16 v[88:91], v[158:161], v[226:229], v[88:91]
	v_mfma_f32_16x16x32_bf16 v[92:95], v[162:165], v[226:229], v[92:95]
	v_mfma_f32_16x16x32_bf16 v[96:99], v[166:169], v[226:229], v[96:99]
	v_mfma_f32_16x16x32_bf16 v[36:39], v[178:181], v[226:229], v[36:39]
	ds_read_b128 v[226:229], v6 offset:14336
	s_waitcnt lgkmcnt(3)
	v_mfma_f32_16x16x32_bf16 v[104:107], v[158:161], v[214:217], v[104:107]
	v_mfma_f32_16x16x32_bf16 v[108:111], v[162:165], v[214:217], v[108:111]
	v_mfma_f32_16x16x32_bf16 v[112:115], v[166:169], v[214:217], v[112:115]
	v_mfma_f32_16x16x32_bf16 v[52:55], v[178:181], v[214:217], v[52:55]
	s_waitcnt lgkmcnt(2)
	v_mfma_f32_16x16x32_bf16 v[116:119], v[158:161], v[218:221], v[116:119]
	v_mfma_f32_16x16x32_bf16 v[120:123], v[162:165], v[218:221], v[120:123]
	v_mfma_f32_16x16x32_bf16 v[124:127], v[166:169], v[218:221], v[124:127]
	v_mfma_f32_16x16x32_bf16 v[68:71], v[178:181], v[218:221], v[68:71]
	s_waitcnt lgkmcnt(1)
	v_mfma_f32_16x16x32_bf16 v[132:135], v[162:165], v[222:225], v[132:135]
	v_mfma_f32_16x16x32_bf16 v[84:87], v[178:181], v[222:225], v[84:87]
	s_waitcnt lgkmcnt(0)
	v_mfma_f32_16x16x32_bf16 v[100:103], v[158:161], v[226:229], v[100:103]
	v_mfma_f32_16x16x32_bf16 v[150:153], v[166:169], v[226:229], v[150:153]
	v_mfma_f32_16x16x32_bf16 v[154:157], v[178:181], v[226:229], v[154:157]
	v_mfma_f32_16x16x32_bf16 v[128:131], v[158:161], v[222:225], v[128:131]
	v_mfma_f32_16x16x32_bf16 v[136:139], v[166:169], v[222:225], v[136:139]
	v_mfma_f32_16x16x32_bf16 v[140:143], v[162:165], v[226:229], v[140:143]
	ds_read_b128 v[158:161], v7 offset:33792
	ds_read_b128 v[162:165], v7 offset:35840
	ds_read_b128 v[166:169], v7 offset:37888
	ds_read_b128 v[214:217], v7 offset:39936
	ds_read_b128 v[178:181], v6 offset:1024
	ds_read_b128 v[218:221], v6 offset:3072
	ds_read_b128 v[222:225], v6 offset:5120
	ds_read_b128 v[226:229], v6 offset:7168
	s_waitcnt lgkmcnt(3)
	v_mfma_f32_16x16x32_bf16 v[40:43], v[158:161], v[178:181], v[40:43]
	v_mfma_f32_16x16x32_bf16 v[44:47], v[162:165], v[178:181], v[44:47]
	v_mfma_f32_16x16x32_bf16 v[48:51], v[166:169], v[178:181], v[48:51]
	v_mfma_f32_16x16x32_bf16 v[174:177], v[214:217], v[178:181], v[174:177]
	ds_read_b128 v[178:181], v6 offset:9216
	s_waitcnt lgkmcnt(3)
	v_mfma_f32_16x16x32_bf16 v[56:59], v[158:161], v[218:221], v[56:59]
	v_mfma_f32_16x16x32_bf16 v[60:63], v[162:165], v[218:221], v[60:63]
	v_mfma_f32_16x16x32_bf16 v[64:67], v[166:169], v[218:221], v[64:67]
	v_mfma_f32_16x16x32_bf16 v[170:173], v[214:217], v[218:221], v[170:173]
	ds_read_b128 v[218:221], v6 offset:11264
	s_waitcnt lgkmcnt(3)
	v_mfma_f32_16x16x32_bf16 v[72:75], v[158:161], v[222:225], v[72:75]
	v_mfma_f32_16x16x32_bf16 v[76:79], v[162:165], v[222:225], v[76:79]
	v_mfma_f32_16x16x32_bf16 v[80:83], v[166:169], v[222:225], v[80:83]
	v_mfma_f32_16x16x32_bf16 v[32:35], v[214:217], v[222:225], v[32:35]
	ds_read_b128 v[222:225], v6 offset:13312
	s_waitcnt lgkmcnt(3)
	v_mfma_f32_16x16x32_bf16 v[88:91], v[158:161], v[226:229], v[88:91]
	v_mfma_f32_16x16x32_bf16 v[92:95], v[162:165], v[226:229], v[92:95]
	v_mfma_f32_16x16x32_bf16 v[96:99], v[166:169], v[226:229], v[96:99]
	v_mfma_f32_16x16x32_bf16 v[36:39], v[214:217], v[226:229], v[36:39]
	ds_read_b128 v[226:229], v6 offset:15360
	s_waitcnt lgkmcnt(3)
	v_mfma_f32_16x16x32_bf16 v[104:107], v[158:161], v[178:181], v[104:107]
	v_mfma_f32_16x16x32_bf16 v[108:111], v[162:165], v[178:181], v[108:111]
	v_mfma_f32_16x16x32_bf16 v[112:115], v[166:169], v[178:181], v[112:115]
	v_mfma_f32_16x16x32_bf16 v[52:55], v[214:217], v[178:181], v[52:55]
	s_waitcnt lgkmcnt(2)
	v_mfma_f32_16x16x32_bf16 v[116:119], v[158:161], v[218:221], v[116:119]
	v_mfma_f32_16x16x32_bf16 v[120:123], v[162:165], v[218:221], v[120:123]
	v_mfma_f32_16x16x32_bf16 v[124:127], v[166:169], v[218:221], v[124:127]
	v_mfma_f32_16x16x32_bf16 v[68:71], v[214:217], v[218:221], v[68:71]
	s_waitcnt lgkmcnt(1)
	v_mfma_f32_16x16x32_bf16 v[132:135], v[162:165], v[222:225], v[132:135]
	v_mfma_f32_16x16x32_bf16 v[84:87], v[214:217], v[222:225], v[84:87]
	s_waitcnt lgkmcnt(0)
	v_mfma_f32_16x16x32_bf16 v[100:103], v[158:161], v[226:229], v[100:103]
	v_mfma_f32_16x16x32_bf16 v[150:153], v[166:169], v[226:229], v[150:153]
	v_mfma_f32_16x16x32_bf16 v[154:157], v[214:217], v[226:229], v[154:157]
	v_mfma_f32_16x16x32_bf16 v[128:131], v[158:161], v[222:225], v[128:131]
	v_mfma_f32_16x16x32_bf16 v[136:139], v[166:169], v[222:225], v[136:139]
	v_mfma_f32_16x16x32_bf16 v[140:143], v[162:165], v[226:229], v[140:143]
	s_add_u32 s46, s16, 0x200
	s_addc_u32 s47, s17, 0
	s_add_u32 s48, s18, 0x200
	s_waitcnt vmcnt(0)
	s_barrier
	s_addc_u32 s49, s19, 0
	s_mov_b32 s45, 0x280
	ds_read_b128 v[158:161], v8
	ds_read_b128 v[162:165], v12
	s_mov_b32 m0, s1
	s_nop 0
	global_load_lds_dwordx4 v0, s[46:47]
	ds_read_b128 v[166:169], v9
	s_mov_b32 m0, s30
	s_nop 0
	global_load_lds_dwordx4 v0, s[48:49]
	ds_read_b128 v[178:181], v13
	ds_read_b128 v[214:217], v11
	s_mov_b32 m0, s31
	s_nop 0
	global_load_lds_dwordx4 v2, s[46:47]
	ds_read_b128 v[218:221], v10
	ds_read_b128 v[222:225], v14
	ds_read_b128 v[226:229], v15
	s_branch .Lmy_rot_r_r2b
.Lmy_rr_r2b:
	ds_read_b128 v[158:161], v8
	ds_read_b128 v[162:165], v12
	s_mov_b32 m0, s1
	v_mfma_f32_16x16x32_bf16 v[128:131], v[166:169], v[222:225], v[128:131]
	global_load_lds_dwordx4 v0, s[46:47]
	v_mfma_f32_16x16x32_bf16 v[100:103], v[166:169], v[226:229], v[100:103]
	ds_read_b128 v[166:169], v9
	v_mfma_f32_16x16x32_bf16 v[132:135], v[178:181], v[222:225], v[132:135]
	s_mov_b32 m0, s30
	v_mfma_f32_16x16x32_bf16 v[140:143], v[178:181], v[226:229], v[140:143]
	global_load_lds_dwordx4 v0, s[48:49]
	ds_read_b128 v[178:181], v13
	v_mfma_f32_16x16x32_bf16 v[136:139], v[214:217], v[222:225], v[136:139]
	v_mfma_f32_16x16x32_bf16 v[150:153], v[214:217], v[226:229], v[150:153]
	ds_read_b128 v[214:217], v11
	s_mov_b32 m0, s31
	v_mfma_f32_16x16x32_bf16 v[84:87], v[218:221], v[222:225], v[84:87]
	global_load_lds_dwordx4 v2, s[46:47]
	v_mfma_f32_16x16x32_bf16 v[154:157], v[218:221], v[226:229], v[154:157]
	ds_read_b128 v[218:221], v10
	ds_read_b128 v[222:225], v14
	ds_read_b128 v[226:229], v15
.Lmy_rot_r_r2b:
	s_waitcnt lgkmcnt(6)
	v_mfma_f32_16x16x32_bf16 v[40:43], v[158:161], v[162:165], v[40:43]
	s_waitcnt lgkmcnt(5)
	s_mov_b32 m0, s34
	v_mfma_f32_16x16x32_bf16 v[44:47], v[166:169], v[162:165], v[44:47]
	global_load_lds_dwordx4 v2, s[48:49]
	s_waitcnt lgkmcnt(4)
	v_mfma_f32_16x16x32_bf16 v[56:59], v[158:161], v[178:181], v[56:59]
	v_mfma_f32_16x16x32_bf16 v[60:63], v[166:169], v[178:181], v[60:63]
	s_waitcnt lgkmcnt(3)
	s_mov_b32 m0, s35
	v_mfma_f32_16x16x32_bf16 v[48:51], v[214:217], v[162:165], v[48:51]
	global_load_lds_dwordx4 v4, s[46:47]
	v_mfma_f32_16x16x32_bf16 v[64:67], v[214:217], v[178:181], v[64:67]
	s_waitcnt lgkmcnt(2)
	v_mfma_f32_16x16x32_bf16 v[174:177], v[218:221], v[162:165], v[174:177]
	ds_read_b128 v[162:165], v16
	s_mov_b32 m0, s36
	v_mfma_f32_16x16x32_bf16 v[170:173], v[218:221], v[178:181], v[170:173]
	global_load_lds_dwordx4 v4, s[48:49]
	ds_read_b128 v[178:181], v17
	s_waitcnt lgkmcnt(3)
	v_mfma_f32_16x16x32_bf16 v[72:75], v[158:161], v[222:225], v[72:75]
	v_mfma_f32_16x16x32_bf16 v[76:79], v[166:169], v[222:225], v[76:79]
	s_mov_b32 m0, s37
	v_mfma_f32_16x16x32_bf16 v[80:83], v[214:217], v[222:225], v[80:83]
	global_load_lds_dwordx4 v146, s[46:47]
	v_mfma_f32_16x16x32_bf16 v[32:35], v[218:221], v[222:225], v[32:35]
	ds_read_b128 v[222:225], v18
	s_waitcnt lgkmcnt(3)
	v_mfma_f32_16x16x32_bf16 v[88:91], v[158:161], v[226:229], v[88:91]
	s_mov_b32 m0, s38
	v_mfma_f32_16x16x32_bf16 v[92:95], v[166:169], v[226:229], v[92:95]
	global_load_lds_dwordx4 v146, s[48:49]
	v_mfma_f32_16x16x32_bf16 v[96:99], v[214:217], v[226:229], v[96:99]
	v_mfma_f32_16x16x32_bf16 v[36:39], v[218:221], v[226:229], v[36:39]
	ds_read_b128 v[226:229], v19
	s_waitcnt lgkmcnt(3)
	v_mfma_f32_16x16x32_bf16 v[108:111], v[166:169], v[162:165], v[108:111]
	s_waitcnt lgkmcnt(2)
	v_mfma_f32_16x16x32_bf16 v[120:123], v[166:169], v[178:181], v[120:123]
	s_waitcnt lgkmcnt(1)
	v_mfma_f32_16x16x32_bf16 v[132:135], v[166:169], v[222:225], v[132:135]
	s_waitcnt lgkmcnt(0)
	v_mfma_f32_16x16x32_bf16 v[140:143], v[166:169], v[226:229], v[140:143]
	ds_read_b128 v[166:169], v20
	v_mfma_f32_16x16x32_bf16 v[104:107], v[158:161], v[162:165], v[104:107]
	v_mfma_f32_16x16x32_bf16 v[116:119], v[158:161], v[178:181], v[116:119]
	v_mfma_f32_16x16x32_bf16 v[128:131], v[158:161], v[222:225], v[128:131]
	v_mfma_f32_16x16x32_bf16 v[100:103], v[158:161], v[226:229], v[100:103]
	ds_read_b128 v[158:161], v24
	v_mfma_f32_16x16x32_bf16 v[124:127], v[214:217], v[178:181], v[124:127]
	v_mfma_f32_16x16x32_bf16 v[68:71], v[218:221], v[178:181], v[68:71]
	ds_read_b128 v[178:181], v21
	v_mfma_f32_16x16x32_bf16 v[112:115], v[214:217], v[162:165], v[112:115]
	v_mfma_f32_16x16x32_bf16 v[52:55], v[218:221], v[162:165], v[52:55]
	ds_read_b128 v[162:165], v25
	v_mfma_f32_16x16x32_bf16 v[136:139], v[214:217], v[222:225], v[136:139]
	v_mfma_f32_16x16x32_bf16 v[84:87], v[218:221], v[222:225], v[84:87]
	ds_read_b128 v[222:225], v26
	v_mfma_f32_16x16x32_bf16 v[150:153], v[214:217], v[226:229], v[150:153]
	ds_read_b128 v[214:217], v23
	v_mfma_f32_16x16x32_bf16 v[154:157], v[218:221], v[226:229], v[154:157]
	ds_read_b128 v[218:221], v22
	ds_read_b128 v[226:229], v27
	s_waitcnt lgkmcnt(6)
	v_mfma_f32_16x16x32_bf16 v[40:43], v[166:169], v[158:161], v[40:43]
	s_waitcnt lgkmcnt(5)
	v_mfma_f32_16x16x32_bf16 v[44:47], v[178:181], v[158:161], v[44:47]
	s_waitcnt lgkmcnt(4)
	v_mfma_f32_16x16x32_bf16 v[56:59], v[166:169], v[162:165], v[56:59]
	v_mfma_f32_16x16x32_bf16 v[60:63], v[178:181], v[162:165], v[60:63]
	s_waitcnt lgkmcnt(3)
	v_mfma_f32_16x16x32_bf16 v[72:75], v[166:169], v[222:225], v[72:75]
	v_mfma_f32_16x16x32_bf16 v[76:79], v[178:181], v[222:225], v[76:79]
	s_waitcnt lgkmcnt(2)
	v_mfma_f32_16x16x32_bf16 v[48:51], v[214:217], v[158:161], v[48:51]
	s_waitcnt lgkmcnt(1)
	v_mfma_f32_16x16x32_bf16 v[174:177], v[218:221], v[158:161], v[174:177]
	ds_read_b128 v[158:161], v28
	v_mfma_f32_16x16x32_bf16 v[64:67], v[214:217], v[162:165], v[64:67]
	v_mfma_f32_16x16x32_bf16 v[170:173], v[218:221], v[162:165], v[170:173]
	ds_read_b128 v[162:165], v29
	v_mfma_f32_16x16x32_bf16 v[80:83], v[214:217], v[222:225], v[80:83]
	v_mfma_f32_16x16x32_bf16 v[32:35], v[218:221], v[222:225], v[32:35]
	ds_read_b128 v[222:225], v30
	s_waitcnt lgkmcnt(3)
	v_mfma_f32_16x16x32_bf16 v[88:91], v[166:169], v[226:229], v[88:91]
	v_mfma_f32_16x16x32_bf16 v[92:95], v[178:181], v[226:229], v[92:95]
	v_mfma_f32_16x16x32_bf16 v[96:99], v[214:217], v[226:229], v[96:99]
	v_mfma_f32_16x16x32_bf16 v[36:39], v[218:221], v[226:229], v[36:39]
	ds_read_b128 v[226:229], v31
	s_waitcnt lgkmcnt(3)
	v_mfma_f32_16x16x32_bf16 v[104:107], v[166:169], v[158:161], v[104:107]
	v_mfma_f32_16x16x32_bf16 v[108:111], v[178:181], v[158:161], v[108:111]
	v_mfma_f32_16x16x32_bf16 v[112:115], v[214:217], v[158:161], v[112:115]
	v_mfma_f32_16x16x32_bf16 v[52:55], v[218:221], v[158:161], v[52:55]
	s_waitcnt lgkmcnt(2)
	v_mfma_f32_16x16x32_bf16 v[116:119], v[166:169], v[162:165], v[116:119]
	v_mfma_f32_16x16x32_bf16 v[120:123], v[178:181], v[162:165], v[120:123]
	v_mfma_f32_16x16x32_bf16 v[124:127], v[214:217], v[162:165], v[124:127]
	v_mfma_f32_16x16x32_bf16 v[68:71], v[218:221], v[162:165], v[68:71]
	s_add_u32 s46, s16, s45
	s_addc_u32 s47, s17, 0
	s_add_u32 s48, s18, s45
	s_addc_u32 s49, s19, 0
	s_add_u32 s45, s45, 0x80
	s_waitcnt vmcnt(0)
	s_waitcnt lgkmcnt(0)
	s_barrier
	ds_read_b128 v[158:161], v7 offset:32768
	ds_read_b128 v[162:165], v6
	s_mov_b32 m0, s25
	v_mfma_f32_16x16x32_bf16 v[128:131], v[166:169], v[222:225], v[128:131]
	global_load_lds_dwordx4 v0, s[46:47]
	v_mfma_f32_16x16x32_bf16 v[100:103], v[166:169], v[226:229], v[100:103]
	ds_read_b128 v[166:169], v7 offset:34816
	v_mfma_f32_16x16x32_bf16 v[132:135], v[178:181], v[222:225], v[132:135]
	s_mov_b32 m0, s24
	v_mfma_f32_16x16x32_bf16 v[140:143], v[178:181], v[226:229], v[140:143]
	global_load_lds_dwordx4 v0, s[48:49]
	ds_read_b128 v[178:181], v6 offset:2048
	v_mfma_f32_16x16x32_bf16 v[136:139], v[214:217], v[222:225], v[136:139]
	v_mfma_f32_16x16x32_bf16 v[150:153], v[214:217], v[226:229], v[150:153]
	ds_read_b128 v[214:217], v7 offset:36864
	s_mov_b32 m0, s39
	v_mfma_f32_16x16x32_bf16 v[84:87], v[218:221], v[222:225], v[84:87]
	global_load_lds_dwordx4 v2, s[46:47]
	v_mfma_f32_16x16x32_bf16 v[154:157], v[218:221], v[226:229], v[154:157]
	ds_read_b128 v[218:221], v7 offset:38912
	ds_read_b128 v[222:225], v6 offset:4096
	ds_read_b128 v[226:229], v6 offset:6144
	s_waitcnt lgkmcnt(6)
	v_mfma_f32_16x16x32_bf16 v[40:43], v[158:161], v[162:165], v[40:43]
	s_waitcnt lgkmcnt(5)
	s_mov_b32 m0, s40
	v_mfma_f32_16x16x32_bf16 v[44:47], v[166:169], v[162:165], v[44:47]
	global_load_lds_dwordx4 v2, s[48:49]
	s_waitcnt lgkmcnt(4)
	v_mfma_f32_16x16x32_bf16 v[56:59], v[158:161], v[178:181], v[56:59]
	v_mfma_f32_16x16x32_bf16 v[60:63], v[166:169], v[178:181], v[60:63]
	s_waitcnt lgkmcnt(3)
	s_mov_b32 m0, s41
	v_mfma_f32_16x16x32_bf16 v[48:51], v[214:217], v[162:165], v[48:51]
	global_load_lds_dwordx4 v4, s[46:47]
	v_mfma_f32_16x16x32_bf16 v[64:67], v[214:217], v[178:181], v[64:67]
	s_waitcnt lgkmcnt(2)
	v_mfma_f32_16x16x32_bf16 v[174:177], v[218:221], v[162:165], v[174:177]
	ds_read_b128 v[162:165], v6 offset:8192
	s_mov_b32 m0, s42
	v_mfma_f32_16x16x32_bf16 v[170:173], v[218:221], v[178:181], v[170:173]
	global_load_lds_dwordx4 v4, s[48:49]
	ds_read_b128 v[178:181], v6 offset:10240
	s_waitcnt lgkmcnt(3)
	v_mfma_f32_16x16x32_bf16 v[72:75], v[158:161], v[222:225], v[72:75]
	v_mfma_f32_16x16x32_bf16 v[76:79], v[166:169], v[222:225], v[76:79]
	s_mov_b32 m0, s43
	v_mfma_f32_16x16x32_bf16 v[80:83], v[214:217], v[222:225], v[80:83]
	global_load_lds_dwordx4 v146, s[46:47]
	v_mfma_f32_16x16x32_bf16 v[32:35], v[218:221], v[222:225], v[32:35]
	ds_read_b128 v[222:225], v6 offset:12288
	s_waitcnt lgkmcnt(3)
	v_mfma_f32_16x16x32_bf16 v[88:91], v[158:161], v[226:229], v[88:91]
	s_mov_b32 m0, s44
	v_mfma_f32_16x16x32_bf16 v[92:95], v[166:169], v[226:229], v[92:95]
	global_load_lds_dwordx4 v146, s[48:49]
	v_mfma_f32_16x16x32_bf16 v[96:99], v[214:217], v[226:229], v[96:99]
	v_mfma_f32_16x16x32_bf16 v[36:39], v[218:221], v[226:229], v[36:39]
	ds_read_b128 v[226:229], v6 offset:14336
	s_waitcnt lgkmcnt(3)
	v_mfma_f32_16x16x32_bf16 v[108:111], v[166:169], v[162:165], v[108:111]
	s_waitcnt lgkmcnt(2)
	v_mfma_f32_16x16x32_bf16 v[120:123], v[166:169], v[178:181], v[120:123]
	s_waitcnt lgkmcnt(1)
	v_mfma_f32_16x16x32_bf16 v[132:135], v[166:169], v[222:225], v[132:135]
	s_waitcnt lgkmcnt(0)
	v_mfma_f32_16x16x32_bf16 v[140:143], v[166:169], v[226:229], v[140:143]
	ds_read_b128 v[166:169], v7 offset:33792
	v_mfma_f32_16x16x32_bf16 v[104:107], v[158:161], v[162:165], v[104:107]
	v_mfma_f32_16x16x32_bf16 v[116:119], v[158:161], v[178:181], v[116:119]
	v_mfma_f32_16x16x32_bf16 v[128:131], v[158:161], v[222:225], v[128:131]
	v_mfma_f32_16x16x32_bf16 v[100:103], v[158:161], v[226:229], v[100:103]
	ds_read_b128 v[158:161], v6 offset:1024
	v_mfma_f32_16x16x32_bf16 v[124:127], v[214:217], v[178:181], v[124:127]
	v_mfma_f32_16x16x32_bf16 v[68:71], v[218:221], v[178:181], v[68:71]
	ds_read_b128 v[178:181], v7 offset:35840
	v_mfma_f32_16x16x32_bf16 v[112:115], v[214:217], v[162:165], v[112:115]
	v_mfma_f32_16x16x32_bf16 v[52:55], v[218:221], v[162:165], v[52:55]
	ds_read_b128 v[162:165], v6 offset:3072
	v_mfma_f32_16x16x32_bf16 v[136:139], v[214:217], v[222:225], v[136:139]
	v_mfma_f32_16x16x32_bf16 v[84:87], v[218:221], v[222:225], v[84:87]
	ds_read_b128 v[222:225], v6 offset:5120
	v_mfma_f32_16x16x32_bf16 v[150:153], v[214:217], v[226:229], v[150:153]
	ds_read_b128 v[214:217], v7 offset:37888
	v_mfma_f32_16x16x32_bf16 v[154:157], v[218:221], v[226:229], v[154:157]
	ds_read_b128 v[218:221], v7 offset:39936
	ds_read_b128 v[226:229], v6 offset:7168
	s_waitcnt lgkmcnt(6)
	v_mfma_f32_16x16x32_bf16 v[40:43], v[166:169], v[158:161], v[40:43]
	s_waitcnt lgkmcnt(5)
	v_mfma_f32_16x16x32_bf16 v[44:47], v[178:181], v[158:161], v[44:47]
	s_waitcnt lgkmcnt(4)
	v_mfma_f32_16x16x32_bf16 v[56:59], v[166:169], v[162:165], v[56:59]
	v_mfma_f32_16x16x32_bf16 v[60:63], v[178:181], v[162:165], v[60:63]
	s_waitcnt lgkmcnt(3)
	v_mfma_f32_16x16x32_bf16 v[72:75], v[166:169], v[222:225], v[72:75]
	v_mfma_f32_16x16x32_bf16 v[76:79], v[178:181], v[222:225], v[76:79]
	s_waitcnt lgkmcnt(2)
	v_mfma_f32_16x16x32_bf16 v[48:51], v[214:217], v[158:161], v[48:51]
	s_waitcnt lgkmcnt(1)
	v_mfma_f32_16x16x32_bf16 v[174:177], v[218:221], v[158:161], v[174:177]
	ds_read_b128 v[158:161], v6 offset:9216
	v_mfma_f32_16x16x32_bf16 v[64:67], v[214:217], v[162:165], v[64:67]
	v_mfma_f32_16x16x32_bf16 v[170:173], v[218:221], v[162:165], v[170:173]
	ds_read_b128 v[162:165], v6 offset:11264
	v_mfma_f32_16x16x32_bf16 v[80:83], v[214:217], v[222:225], v[80:83]
	v_mfma_f32_16x16x32_bf16 v[32:35], v[218:221], v[222:225], v[32:35]
	ds_read_b128 v[222:225], v6 offset:13312
	s_waitcnt lgkmcnt(3)
	v_mfma_f32_16x16x32_bf16 v[88:91], v[166:169], v[226:229], v[88:91]
	v_mfma_f32_16x16x32_bf16 v[92:95], v[178:181], v[226:229], v[92:95]
	v_mfma_f32_16x16x32_bf16 v[96:99], v[214:217], v[226:229], v[96:99]
	v_mfma_f32_16x16x32_bf16 v[36:39], v[218:221], v[226:229], v[36:39]
	ds_read_b128 v[226:229], v6 offset:15360
	s_waitcnt lgkmcnt(3)
	v_mfma_f32_16x16x32_bf16 v[104:107], v[166:169], v[158:161], v[104:107]
	v_mfma_f32_16x16x32_bf16 v[108:111], v[178:181], v[158:161], v[108:111]
	v_mfma_f32_16x16x32_bf16 v[112:115], v[214:217], v[158:161], v[112:115]
	v_mfma_f32_16x16x32_bf16 v[52:55], v[218:221], v[158:161], v[52:55]
	s_waitcnt lgkmcnt(2)
	v_mfma_f32_16x16x32_bf16 v[116:119], v[166:169], v[162:165], v[116:119]
	v_mfma_f32_16x16x32_bf16 v[120:123], v[178:181], v[162:165], v[120:123]
	v_mfma_f32_16x16x32_bf16 v[124:127], v[214:217], v[162:165], v[124:127]
	v_mfma_f32_16x16x32_bf16 v[68:71], v[218:221], v[162:165], v[68:71]
	s_add_u32 s46, s16, s45
	s_addc_u32 s47, s17, 0
	s_add_u32 s48, s18, s45
	s_addc_u32 s49, s19, 0
	s_add_u32 s45, s45, 0x80
	s_cmp_lg_u32 s45, 0xf80
	s_waitcnt vmcnt(0)
	s_waitcnt lgkmcnt(0)
	s_barrier
	s_cbranch_scc1 .Lmy_rr_r2b
	v_mfma_f32_16x16x32_bf16 v[128:131], v[166:169], v[222:225], v[128:131]
	v_mfma_f32_16x16x32_bf16 v[100:103], v[166:169], v[226:229], v[100:103]
	v_mfma_f32_16x16x32_bf16 v[132:135], v[178:181], v[222:225], v[132:135]
	v_mfma_f32_16x16x32_bf16 v[140:143], v[178:181], v[226:229], v[140:143]
	v_mfma_f32_16x16x32_bf16 v[136:139], v[214:217], v[222:225], v[136:139]
	v_mfma_f32_16x16x32_bf16 v[150:153], v[214:217], v[226:229], v[150:153]
	v_mfma_f32_16x16x32_bf16 v[84:87], v[218:221], v[222:225], v[84:87]
	v_mfma_f32_16x16x32_bf16 v[154:157], v[218:221], v[226:229], v[154:157]
	s_nop 15
	s_nop 15
	v_lshl_add_u64 v[158:159], s[46:47], 0, v[0:1]
	s_mov_b32 s45, m0
	s_mov_b32 m0, s1
	s_nop 0
	global_load_lds_dwordx4 v[158:159], off
	s_mov_b32 m0, s45
	v_lshl_add_u64 v[158:159], s[48:49], 0, v[0:1]
	s_mov_b32 s45, m0
	s_mov_b32 m0, s30
	s_nop 0
	global_load_lds_dwordx4 v[158:159], off
	s_mov_b32 m0, s45
	v_lshl_add_u64 v[158:159], s[46:47], 0, v[2:3]
	s_mov_b32 s45, m0
	s_mov_b32 m0, s31
	s_nop 0
	global_load_lds_dwordx4 v[158:159], off
	s_mov_b32 m0, s45
	v_lshl_add_u64 v[158:159], s[48:49], 0, v[2:3]
	s_mov_b32 s45, m0
	s_mov_b32 m0, s34
	s_nop 0
	global_load_lds_dwordx4 v[158:159], off
	s_mov_b32 m0, s45
	v_lshl_add_u64 v[158:159], s[46:47], 0, v[4:5]
	s_mov_b32 s45, m0
	s_mov_b32 m0, s35
	s_nop 0
	global_load_lds_dwordx4 v[158:159], off
	s_mov_b32 m0, s45
	v_lshl_add_u64 v[158:159], s[48:49], 0, v[4:5]
	s_mov_b32 s45, m0
	s_mov_b32 m0, s36
	s_nop 0
	global_load_lds_dwordx4 v[158:159], off
	s_mov_b32 m0, s45
	v_lshl_add_u64 v[158:159], s[46:47], 0, v[146:147]
	s_mov_b32 s45, m0
	s_mov_b32 m0, s37
	s_nop 0
	global_load_lds_dwordx4 v[158:159], off
	s_mov_b32 m0, s45
	v_lshl_add_u64 v[158:159], s[48:49], 0, v[146:147]
	s_mov_b32 s45, m0
	s_mov_b32 m0, s38
	s_nop 0
	global_load_lds_dwordx4 v[158:159], off
	s_mov_b32 m0, s45
	ds_read_b128 v[158:161], v8
	ds_read_b128 v[162:165], v9
	ds_read_b128 v[166:169], v11
	ds_read_b128 v[214:217], v10
	ds_read_b128 v[178:181], v12
	ds_read_b128 v[218:221], v13
	ds_read_b128 v[222:225], v14
	ds_read_b128 v[226:229], v15
	s_waitcnt lgkmcnt(3)
	v_mfma_f32_16x16x32_bf16 v[40:43], v[158:161], v[178:181], v[40:43]
	v_mfma_f32_16x16x32_bf16 v[44:47], v[162:165], v[178:181], v[44:47]
	v_mfma_f32_16x16x32_bf16 v[48:51], v[166:169], v[178:181], v[48:51]
	v_mfma_f32_16x16x32_bf16 v[174:177], v[214:217], v[178:181], v[174:177]
	ds_read_b128 v[178:181], v16
	s_waitcnt lgkmcnt(3)
	v_mfma_f32_16x16x32_bf16 v[56:59], v[158:161], v[218:221], v[56:59]
	v_mfma_f32_16x16x32_bf16 v[60:63], v[162:165], v[218:221], v[60:63]
	v_mfma_f32_16x16x32_bf16 v[64:67], v[166:169], v[218:221], v[64:67]
	v_mfma_f32_16x16x32_bf16 v[170:173], v[214:217], v[218:221], v[170:173]
	ds_read_b128 v[218:221], v17
	s_waitcnt lgkmcnt(3)
	v_mfma_f32_16x16x32_bf16 v[72:75], v[158:161], v[222:225], v[72:75]
	v_mfma_f32_16x16x32_bf16 v[76:79], v[162:165], v[222:225], v[76:79]
	v_mfma_f32_16x16x32_bf16 v[80:83], v[166:169], v[222:225], v[80:83]
	v_mfma_f32_16x16x32_bf16 v[32:35], v[214:217], v[222:225], v[32:35]
	ds_read_b128 v[222:225], v18
	s_waitcnt lgkmcnt(3)
	v_mfma_f32_16x16x32_bf16 v[88:91], v[158:161], v[226:229], v[88:91]
	v_mfma_f32_16x16x32_bf16 v[92:95], v[162:165], v[226:229], v[92:95]
	v_mfma_f32_16x16x32_bf16 v[96:99], v[166:169], v[226:229], v[96:99]
	v_mfma_f32_16x16x32_bf16 v[36:39], v[214:217], v[226:229], v[36:39]
	ds_read_b128 v[226:229], v19
	s_waitcnt lgkmcnt(3)
	v_mfma_f32_16x16x32_bf16 v[104:107], v[158:161], v[178:181], v[104:107]
	v_mfma_f32_16x16x32_bf16 v[108:111], v[162:165], v[178:181], v[108:111]
	v_mfma_f32_16x16x32_bf16 v[112:115], v[166:169], v[178:181], v[112:115]
	v_mfma_f32_16x16x32_bf16 v[52:55], v[214:217], v[178:181], v[52:55]
	s_waitcnt lgkmcnt(2)
	v_mfma_f32_16x16x32_bf16 v[116:119], v[158:161], v[218:221], v[116:119]
	v_mfma_f32_16x16x32_bf16 v[120:123], v[162:165], v[218:221], v[120:123]
	v_mfma_f32_16x16x32_bf16 v[124:127], v[166:169], v[218:221], v[124:127]
	v_mfma_f32_16x16x32_bf16 v[68:71], v[214:217], v[218:221], v[68:71]
	s_waitcnt lgkmcnt(1)
	v_mfma_f32_16x16x32_bf16 v[132:135], v[162:165], v[222:225], v[132:135]
	v_mfma_f32_16x16x32_bf16 v[84:87], v[214:217], v[222:225], v[84:87]
	s_waitcnt lgkmcnt(0)
	v_mfma_f32_16x16x32_bf16 v[100:103], v[158:161], v[226:229], v[100:103]
	v_mfma_f32_16x16x32_bf16 v[150:153], v[166:169], v[226:229], v[150:153]
	v_mfma_f32_16x16x32_bf16 v[154:157], v[214:217], v[226:229], v[154:157]
	v_mfma_f32_16x16x32_bf16 v[128:131], v[158:161], v[222:225], v[128:131]
	v_mfma_f32_16x16x32_bf16 v[136:139], v[166:169], v[222:225], v[136:139]
	v_mfma_f32_16x16x32_bf16 v[140:143], v[162:165], v[226:229], v[140:143]
	ds_read_b128 v[158:161], v20
	ds_read_b128 v[162:165], v21
	ds_read_b128 v[166:169], v23
	ds_read_b128 v[214:217], v22
	ds_read_b128 v[178:181], v24
	ds_read_b128 v[218:221], v25
	ds_read_b128 v[222:225], v26
	ds_read_b128 v[226:229], v27
	s_waitcnt lgkmcnt(3)
	v_mfma_f32_16x16x32_bf16 v[40:43], v[158:161], v[178:181], v[40:43]
	v_mfma_f32_16x16x32_bf16 v[44:47], v[162:165], v[178:181], v[44:47]
	v_mfma_f32_16x16x32_bf16 v[48:51], v[166:169], v[178:181], v[48:51]
	v_mfma_f32_16x16x32_bf16 v[174:177], v[214:217], v[178:181], v[174:177]
	ds_read_b128 v[178:181], v28
	s_waitcnt lgkmcnt(3)
	v_mfma_f32_16x16x32_bf16 v[56:59], v[158:161], v[218:221], v[56:59]
	v_mfma_f32_16x16x32_bf16 v[60:63], v[162:165], v[218:221], v[60:63]
	v_mfma_f32_16x16x32_bf16 v[64:67], v[166:169], v[218:221], v[64:67]
	v_mfma_f32_16x16x32_bf16 v[170:173], v[214:217], v[218:221], v[170:173]
	ds_read_b128 v[218:221], v29
	s_waitcnt lgkmcnt(3)
	v_mfma_f32_16x16x32_bf16 v[72:75], v[158:161], v[222:225], v[72:75]
	v_mfma_f32_16x16x32_bf16 v[76:79], v[162:165], v[222:225], v[76:79]
	v_mfma_f32_16x16x32_bf16 v[80:83], v[166:169], v[222:225], v[80:83]
	v_mfma_f32_16x16x32_bf16 v[32:35], v[214:217], v[222:225], v[32:35]
	ds_read_b128 v[222:225], v30
	s_waitcnt lgkmcnt(3)
	v_mfma_f32_16x16x32_bf16 v[88:91], v[158:161], v[226:229], v[88:91]
	v_mfma_f32_16x16x32_bf16 v[92:95], v[162:165], v[226:229], v[92:95]
	v_mfma_f32_16x16x32_bf16 v[96:99], v[166:169], v[226:229], v[96:99]
	v_mfma_f32_16x16x32_bf16 v[36:39], v[214:217], v[226:229], v[36:39]
	ds_read_b128 v[226:229], v31
	s_waitcnt lgkmcnt(3)
	v_mfma_f32_16x16x32_bf16 v[104:107], v[158:161], v[178:181], v[104:107]
	v_mfma_f32_16x16x32_bf16 v[108:111], v[162:165], v[178:181], v[108:111]
	v_mfma_f32_16x16x32_bf16 v[112:115], v[166:169], v[178:181], v[112:115]
	v_mfma_f32_16x16x32_bf16 v[52:55], v[214:217], v[178:181], v[52:55]
	s_waitcnt lgkmcnt(2)
	v_mfma_f32_16x16x32_bf16 v[116:119], v[158:161], v[218:221], v[116:119]
	v_mfma_f32_16x16x32_bf16 v[120:123], v[162:165], v[218:221], v[120:123]
	v_mfma_f32_16x16x32_bf16 v[124:127], v[166:169], v[218:221], v[124:127]
	v_mfma_f32_16x16x32_bf16 v[68:71], v[214:217], v[218:221], v[68:71]
	s_waitcnt lgkmcnt(1)
	v_mfma_f32_16x16x32_bf16 v[132:135], v[162:165], v[222:225], v[132:135]
	v_mfma_f32_16x16x32_bf16 v[84:87], v[214:217], v[222:225], v[84:87]
	s_waitcnt lgkmcnt(0)
	v_mfma_f32_16x16x32_bf16 v[100:103], v[158:161], v[226:229], v[100:103]
	v_mfma_f32_16x16x32_bf16 v[150:153], v[166:169], v[226:229], v[150:153]
	v_mfma_f32_16x16x32_bf16 v[154:157], v[214:217], v[226:229], v[154:157]
	v_mfma_f32_16x16x32_bf16 v[128:131], v[158:161], v[222:225], v[128:131]
	v_mfma_f32_16x16x32_bf16 v[136:139], v[166:169], v[222:225], v[136:139]
	v_mfma_f32_16x16x32_bf16 v[140:143], v[162:165], v[226:229], v[140:143]
	s_add_u32 s16, s16, 0xf80
	s_addc_u32 s17, s17, 0
	s_add_u32 s18, s18, 0xf80
	s_waitcnt vmcnt(0)
	s_barrier
	s_addc_u32 s19, s19, 0
	v_lshl_add_u64 v[158:159], s[16:17], 0, v[0:1]
	s_mov_b32 s45, m0
	s_mov_b32 m0, s25
	s_nop 0
	global_load_lds_dwordx4 v[158:159], off
	s_mov_b32 m0, s45
	v_lshl_add_u64 v[158:159], s[18:19], 0, v[0:1]
	s_mov_b32 s25, m0
	s_mov_b32 m0, s24
	s_nop 0
	global_load_lds_dwordx4 v[158:159], off
	s_mov_b32 m0, s25
	v_lshl_add_u64 v[158:159], s[16:17], 0, v[2:3]
	s_mov_b32 s24, m0
	s_mov_b32 m0, s39
	s_nop 0
	global_load_lds_dwordx4 v[158:159], off
	s_mov_b32 m0, s24
	v_lshl_add_u64 v[158:159], s[18:19], 0, v[2:3]
	s_mov_b32 s24, m0
	s_mov_b32 m0, s40
	s_nop 0
	global_load_lds_dwordx4 v[158:159], off
	s_mov_b32 m0, s24
	v_lshl_add_u64 v[158:159], s[16:17], 0, v[4:5]
	s_mov_b32 s24, m0
	s_mov_b32 m0, s41
	s_nop 0
	global_load_lds_dwordx4 v[158:159], off
	s_mov_b32 m0, s24
	v_lshl_add_u64 v[158:159], s[18:19], 0, v[4:5]
	s_mov_b32 s24, m0
	s_mov_b32 m0, s42
	s_nop 0
	global_load_lds_dwordx4 v[158:159], off
	s_mov_b32 m0, s24
	v_lshl_add_u64 v[158:159], s[16:17], 0, v[146:147]
	s_mov_b32 s16, m0
	s_mov_b32 m0, s43
	s_nop 0
	global_load_lds_dwordx4 v[158:159], off
	s_mov_b32 m0, s16
	v_lshl_add_u64 v[158:159], s[18:19], 0, v[146:147]
	s_mov_b32 s16, m0
	s_mov_b32 m0, s44
	s_nop 0
	global_load_lds_dwordx4 v[158:159], off
	s_mov_b32 m0, s16
	ds_read_b128 v[158:161], v7 offset:32768
	ds_read_b128 v[162:165], v7 offset:34816
	ds_read_b128 v[166:169], v7 offset:36864
	ds_read_b128 v[214:217], v7 offset:38912
	ds_read_b128 v[178:181], v6
	ds_read_b128 v[218:221], v6 offset:2048
	ds_read_b128 v[222:225], v6 offset:4096
	ds_read_b128 v[226:229], v6 offset:6144
	s_waitcnt lgkmcnt(3)
	v_mfma_f32_16x16x32_bf16 v[40:43], v[158:161], v[178:181], v[40:43]
	v_mfma_f32_16x16x32_bf16 v[44:47], v[162:165], v[178:181], v[44:47]
	v_mfma_f32_16x16x32_bf16 v[48:51], v[166:169], v[178:181], v[48:51]
	v_mfma_f32_16x16x32_bf16 v[174:177], v[214:217], v[178:181], v[174:177]
	ds_read_b128 v[178:181], v6 offset:8192
	s_waitcnt lgkmcnt(3)
	v_mfma_f32_16x16x32_bf16 v[56:59], v[158:161], v[218:221], v[56:59]
	v_mfma_f32_16x16x32_bf16 v[60:63], v[162:165], v[218:221], v[60:63]
	v_mfma_f32_16x16x32_bf16 v[64:67], v[166:169], v[218:221], v[64:67]
	v_mfma_f32_16x16x32_bf16 v[170:173], v[214:217], v[218:221], v[170:173]
	ds_read_b128 v[218:221], v6 offset:10240
	s_waitcnt lgkmcnt(3)
	v_mfma_f32_16x16x32_bf16 v[72:75], v[158:161], v[222:225], v[72:75]
	v_mfma_f32_16x16x32_bf16 v[76:79], v[162:165], v[222:225], v[76:79]
	v_mfma_f32_16x16x32_bf16 v[80:83], v[166:169], v[222:225], v[80:83]
	v_mfma_f32_16x16x32_bf16 v[32:35], v[214:217], v[222:225], v[32:35]
	ds_read_b128 v[222:225], v6 offset:12288
	s_waitcnt lgkmcnt(3)
	v_mfma_f32_16x16x32_bf16 v[88:91], v[158:161], v[226:229], v[88:91]
	v_mfma_f32_16x16x32_bf16 v[92:95], v[162:165], v[226:229], v[92:95]
	v_mfma_f32_16x16x32_bf16 v[96:99], v[166:169], v[226:229], v[96:99]
	v_mfma_f32_16x16x32_bf16 v[36:39], v[214:217], v[226:229], v[36:39]
	ds_read_b128 v[226:229], v6 offset:14336
	s_waitcnt lgkmcnt(3)
	v_mfma_f32_16x16x32_bf16 v[104:107], v[158:161], v[178:181], v[104:107]
	v_mfma_f32_16x16x32_bf16 v[108:111], v[162:165], v[178:181], v[108:111]
	v_mfma_f32_16x16x32_bf16 v[112:115], v[166:169], v[178:181], v[112:115]
	v_mfma_f32_16x16x32_bf16 v[52:55], v[214:217], v[178:181], v[52:55]
	s_waitcnt lgkmcnt(2)
	v_mfma_f32_16x16x32_bf16 v[116:119], v[158:161], v[218:221], v[116:119]
	v_mfma_f32_16x16x32_bf16 v[120:123], v[162:165], v[218:221], v[120:123]
	v_mfma_f32_16x16x32_bf16 v[124:127], v[166:169], v[218:221], v[124:127]
	v_mfma_f32_16x16x32_bf16 v[68:71], v[214:217], v[218:221], v[68:71]
	s_waitcnt lgkmcnt(1)
	v_mfma_f32_16x16x32_bf16 v[132:135], v[162:165], v[222:225], v[132:135]
	v_mfma_f32_16x16x32_bf16 v[84:87], v[214:217], v[222:225], v[84:87]
	s_waitcnt lgkmcnt(0)
	v_mfma_f32_16x16x32_bf16 v[100:103], v[158:161], v[226:229], v[100:103]
	v_mfma_f32_16x16x32_bf16 v[150:153], v[166:169], v[226:229], v[150:153]
	v_mfma_f32_16x16x32_bf16 v[154:157], v[214:217], v[226:229], v[154:157]
	v_mfma_f32_16x16x32_bf16 v[128:131], v[158:161], v[222:225], v[128:131]
	v_mfma_f32_16x16x32_bf16 v[136:139], v[166:169], v[222:225], v[136:139]
	v_mfma_f32_16x16x32_bf16 v[140:143], v[162:165], v[226:229], v[140:143]
	ds_read_b128 v[158:161], v7 offset:33792
	ds_read_b128 v[162:165], v7 offset:35840
	ds_read_b128 v[166:169], v7 offset:37888
	ds_read_b128 v[214:217], v7 offset:39936
	ds_read_b128 v[178:181], v6 offset:1024
	ds_read_b128 v[218:221], v6 offset:3072
	ds_read_b128 v[222:225], v6 offset:5120
	ds_read_b128 v[226:229], v6 offset:7168
	s_waitcnt lgkmcnt(3)
	v_mfma_f32_16x16x32_bf16 v[40:43], v[158:161], v[178:181], v[40:43]
	v_mfma_f32_16x16x32_bf16 v[44:47], v[162:165], v[178:181], v[44:47]
	v_mfma_f32_16x16x32_bf16 v[48:51], v[166:169], v[178:181], v[48:51]
	v_mfma_f32_16x16x32_bf16 v[174:177], v[214:217], v[178:181], v[174:177]
	ds_read_b128 v[178:181], v6 offset:9216
	s_waitcnt lgkmcnt(3)
	v_mfma_f32_16x16x32_bf16 v[56:59], v[158:161], v[218:221], v[56:59]
	v_mfma_f32_16x16x32_bf16 v[60:63], v[162:165], v[218:221], v[60:63]
	v_mfma_f32_16x16x32_bf16 v[64:67], v[166:169], v[218:221], v[64:67]
	v_mfma_f32_16x16x32_bf16 v[170:173], v[214:217], v[218:221], v[170:173]
	ds_read_b128 v[218:221], v6 offset:11264
	s_waitcnt lgkmcnt(3)
	v_mfma_f32_16x16x32_bf16 v[72:75], v[158:161], v[222:225], v[72:75]
	v_mfma_f32_16x16x32_bf16 v[76:79], v[162:165], v[222:225], v[76:79]
	v_mfma_f32_16x16x32_bf16 v[80:83], v[166:169], v[222:225], v[80:83]
	v_mfma_f32_16x16x32_bf16 v[32:35], v[214:217], v[222:225], v[32:35]
	ds_read_b128 v[222:225], v6 offset:13312
	s_waitcnt lgkmcnt(3)
	v_mfma_f32_16x16x32_bf16 v[88:91], v[158:161], v[226:229], v[88:91]
	v_mfma_f32_16x16x32_bf16 v[92:95], v[162:165], v[226:229], v[92:95]
	v_mfma_f32_16x16x32_bf16 v[96:99], v[166:169], v[226:229], v[96:99]
	v_mfma_f32_16x16x32_bf16 v[36:39], v[214:217], v[226:229], v[36:39]
	ds_read_b128 v[226:229], v6 offset:15360
	s_waitcnt lgkmcnt(3)
	v_mfma_f32_16x16x32_bf16 v[104:107], v[158:161], v[178:181], v[104:107]
	v_mfma_f32_16x16x32_bf16 v[108:111], v[162:165], v[178:181], v[108:111]
	v_mfma_f32_16x16x32_bf16 v[112:115], v[166:169], v[178:181], v[112:115]
	v_mfma_f32_16x16x32_bf16 v[52:55], v[214:217], v[178:181], v[52:55]
	s_waitcnt lgkmcnt(2)
	v_mfma_f32_16x16x32_bf16 v[116:119], v[158:161], v[218:221], v[116:119]
	v_mfma_f32_16x16x32_bf16 v[120:123], v[162:165], v[218:221], v[120:123]
	v_mfma_f32_16x16x32_bf16 v[124:127], v[166:169], v[218:221], v[124:127]
	v_mfma_f32_16x16x32_bf16 v[68:71], v[214:217], v[218:221], v[68:71]
	s_waitcnt lgkmcnt(1)
	v_mfma_f32_16x16x32_bf16 v[132:135], v[162:165], v[222:225], v[132:135]
	v_mfma_f32_16x16x32_bf16 v[84:87], v[214:217], v[222:225], v[84:87]
	s_waitcnt lgkmcnt(0)
	v_mfma_f32_16x16x32_bf16 v[100:103], v[158:161], v[226:229], v[100:103]
	v_mfma_f32_16x16x32_bf16 v[150:153], v[166:169], v[226:229], v[150:153]
	v_mfma_f32_16x16x32_bf16 v[154:157], v[214:217], v[226:229], v[154:157]
	v_mfma_f32_16x16x32_bf16 v[128:131], v[158:161], v[222:225], v[128:131]
	v_mfma_f32_16x16x32_bf16 v[136:139], v[166:169], v[222:225], v[136:139]
	v_mfma_f32_16x16x32_bf16 v[140:143], v[162:165], v[226:229], v[140:143]
	s_waitcnt vmcnt(0)
	s_barrier
	v_lshl_add_u64 v[6:7], s[20:21], 0, v[0:1]
	s_mov_b32 s16, m0
	s_mov_b32 m0, s1
	s_nop 0
	global_load_lds_dwordx4 v[6:7], off
	s_mov_b32 m0, s16
	v_lshl_add_u64 v[0:1], s[22:23], 0, v[0:1]
	s_mov_b32 s1, m0
	s_mov_b32 m0, s30
	s_nop 0
	global_load_lds_dwordx4 v[0:1], off
	s_mov_b32 m0, s1
	v_lshl_add_u64 v[0:1], s[20:21], 0, v[2:3]
	s_mov_b32 s1, m0
	s_mov_b32 m0, s31
	s_nop 0
	global_load_lds_dwordx4 v[0:1], off
	s_mov_b32 m0, s1
	v_lshl_add_u64 v[0:1], s[22:23], 0, v[2:3]
	s_mov_b32 s1, m0
	s_mov_b32 m0, s34
	s_nop 0
	global_load_lds_dwordx4 v[0:1], off
	s_mov_b32 m0, s1
	v_lshl_add_u64 v[0:1], s[20:21], 0, v[4:5]
	s_mov_b32 s1, m0
	s_mov_b32 m0, s35
	s_nop 0
	global_load_lds_dwordx4 v[0:1], off
	s_mov_b32 m0, s1
	v_lshl_add_u64 v[0:1], s[22:23], 0, v[4:5]
	s_mov_b32 s1, m0
	s_mov_b32 m0, s36
	s_nop 0
	global_load_lds_dwordx4 v[0:1], off
	s_mov_b32 m0, s1
	v_lshl_add_u64 v[0:1], s[20:21], 0, v[146:147]
	s_mov_b32 s1, m0
	s_mov_b32 m0, s37
	s_nop 0
	global_load_lds_dwordx4 v[0:1], off
	s_mov_b32 m0, s1
	v_lshl_add_u64 v[0:1], s[22:23], 0, v[146:147]
	s_mov_b32 s1, m0
	s_mov_b32 m0, s38
	s_nop 0
	global_load_lds_dwordx4 v[0:1], off
	s_mov_b32 m0, s1
	ds_read_b128 v[0:3], v8
	ds_read_b128 v[4:7], v9
	ds_read_b128 v[158:161], v11
	ds_read_b128 v[8:11], v10
	ds_read_b128 v[162:165], v12
	ds_read_b128 v[166:169], v13
	ds_read_b128 v[178:181], v14
	ds_read_b128 v[12:15], v15
	s_waitcnt lgkmcnt(3)
	v_mfma_f32_16x16x32_bf16 v[40:43], v[0:3], v[162:165], v[40:43]
	v_mfma_f32_16x16x32_bf16 v[44:47], v[4:7], v[162:165], v[44:47]
	v_mfma_f32_16x16x32_bf16 v[48:51], v[158:161], v[162:165], v[48:51]
	v_mfma_f32_16x16x32_bf16 v[162:165], v[8:11], v[162:165], v[174:177]
	s_nop 2
	ds_read_b128 v[174:177], v16
	s_waitcnt lgkmcnt(3)
	v_mfma_f32_16x16x32_bf16 v[56:59], v[0:3], v[166:169], v[56:59]
	v_mfma_f32_16x16x32_bf16 v[60:63], v[4:7], v[166:169], v[60:63]
	v_mfma_f32_16x16x32_bf16 v[64:67], v[158:161], v[166:169], v[64:67]
	v_mfma_f32_16x16x32_bf16 v[166:169], v[8:11], v[166:169], v[170:173]
	s_nop 2
	ds_read_b128 v[170:173], v17
	s_waitcnt lgkmcnt(3)
	v_mfma_f32_16x16x32_bf16 v[72:75], v[0:3], v[178:181], v[72:75]
	v_mfma_f32_16x16x32_bf16 v[76:79], v[4:7], v[178:181], v[76:79]
	v_mfma_f32_16x16x32_bf16 v[80:83], v[158:161], v[178:181], v[80:83]
	v_mfma_f32_16x16x32_bf16 v[32:35], v[8:11], v[178:181], v[32:35]
	ds_read_b128 v[178:181], v18
	s_waitcnt lgkmcnt(3)
	v_mfma_f32_16x16x32_bf16 v[214:217], v[0:3], v[12:15], v[88:91]
	v_mfma_f32_16x16x32_bf16 v[218:221], v[4:7], v[12:15], v[92:95]
	v_mfma_f32_16x16x32_bf16 v[222:225], v[158:161], v[12:15], v[96:99]
	v_mfma_f32_16x16x32_bf16 v[12:15], v[8:11], v[12:15], v[36:39]
	ds_read_b128 v[16:19], v19
	s_waitcnt lgkmcnt(3)
	v_mfma_f32_16x16x32_bf16 v[36:39], v[0:3], v[174:177], v[104:107]
	v_mfma_f32_16x16x32_bf16 v[226:229], v[4:7], v[174:177], v[108:111]
	v_mfma_f32_16x16x32_bf16 v[112:115], v[158:161], v[174:177], v[112:115]
	s_waitcnt lgkmcnt(2)
	v_mfma_f32_16x16x32_bf16 v[116:119], v[0:3], v[170:173], v[116:119]
	v_mfma_f32_16x16x32_bf16 v[120:123], v[4:7], v[170:173], v[120:123]
	v_mfma_f32_16x16x32_bf16 v[124:127], v[158:161], v[170:173], v[124:127]
	s_waitcnt lgkmcnt(1)
	v_mfma_f32_16x16x32_bf16 v[128:131], v[0:3], v[178:181], v[128:131]
	v_mfma_f32_16x16x32_bf16 v[132:135], v[4:7], v[178:181], v[132:135]
	s_waitcnt lgkmcnt(0)
	v_mfma_f32_16x16x32_bf16 v[0:3], v[0:3], v[16:19], v[100:103]
	v_mfma_f32_16x16x32_bf16 v[4:7], v[4:7], v[16:19], v[140:143]
	v_mfma_f32_16x16x32_bf16 v[140:143], v[158:161], v[16:19], v[150:153]
	v_mfma_f32_16x16x32_bf16 v[150:153], v[8:11], v[16:19], v[154:157]
	v_mfma_f32_16x16x32_bf16 v[174:177], v[8:11], v[174:177], v[52:55]
	v_mfma_f32_16x16x32_bf16 v[170:173], v[8:11], v[170:173], v[68:71]
	v_mfma_f32_16x16x32_bf16 v[136:139], v[158:161], v[178:181], v[136:139]
	v_mfma_f32_16x16x32_bf16 v[178:181], v[8:11], v[178:181], v[84:87]
	ds_read_b128 v[8:11], v20
	ds_read_b128 v[154:157], v21
	ds_read_b128 v[158:161], v23
	ds_read_b128 v[230:233], v22
	ds_read_b128 v[16:19], v24
	ds_read_b128 v[20:23], v25
	ds_read_b128 v[52:55], v26
	ds_read_b128 v[24:27], v27
	s_waitcnt lgkmcnt(3)
	v_mfma_f32_16x16x32_bf16 v[234:237], v[8:11], v[16:19], v[40:43]
	v_mfma_f32_16x16x32_bf16 v[238:241], v[154:157], v[16:19], v[44:47]
	v_mfma_f32_16x16x32_bf16 v[242:245], v[158:161], v[16:19], v[48:51]
	v_mfma_f32_16x16x32_bf16 v[162:165], v[230:233], v[16:19], v[162:165]
	ds_read_b128 v[16:19], v28
	s_waitcnt lgkmcnt(3)
	v_mfma_f32_16x16x32_bf16 v[108:111], v[8:11], v[20:23], v[56:59]
	v_mfma_f32_16x16x32_bf16 v[104:107], v[154:157], v[20:23], v[60:63]
	v_mfma_f32_16x16x32_bf16 v[100:103], v[158:161], v[20:23], v[64:67]
	v_mfma_f32_16x16x32_bf16 v[96:99], v[230:233], v[20:23], v[166:169]
	ds_read_b128 v[20:23], v29
	s_waitcnt lgkmcnt(3)
	v_mfma_f32_16x16x32_bf16 v[92:95], v[8:11], v[52:55], v[72:75]
	v_mfma_f32_16x16x32_bf16 v[88:91], v[154:157], v[52:55], v[76:79]
	v_mfma_f32_16x16x32_bf16 v[84:87], v[158:161], v[52:55], v[80:83]
	v_mfma_f32_16x16x32_bf16 v[80:83], v[230:233], v[52:55], v[32:35]
	ds_read_b128 v[166:169], v30
	s_waitcnt lgkmcnt(3)
	v_mfma_f32_16x16x32_bf16 v[76:79], v[8:11], v[24:27], v[214:217]
	v_mfma_f32_16x16x32_bf16 v[72:75], v[154:157], v[24:27], v[218:221]
	v_mfma_f32_16x16x32_bf16 v[68:71], v[158:161], v[24:27], v[222:225]
	v_mfma_f32_16x16x32_bf16 v[64:67], v[230:233], v[24:27], v[12:15]
	ds_read_b128 v[214:217], v31
	s_waitcnt lgkmcnt(3)
	v_mfma_f32_16x16x32_bf16 v[60:63], v[8:11], v[16:19], v[36:39]
	v_mfma_f32_16x16x32_bf16 v[56:59], v[154:157], v[16:19], v[226:229]
	v_mfma_f32_16x16x32_bf16 v[52:55], v[158:161], v[16:19], v[112:115]
	v_mfma_f32_16x16x32_bf16 v[48:51], v[230:233], v[16:19], v[174:177]
	s_waitcnt lgkmcnt(2)
	v_mfma_f32_16x16x32_bf16 v[44:47], v[8:11], v[20:23], v[116:119]
	v_mfma_f32_16x16x32_bf16 v[40:43], v[154:157], v[20:23], v[120:123]
	v_mfma_f32_16x16x32_bf16 v[36:39], v[158:161], v[20:23], v[124:127]
	v_mfma_f32_16x16x32_bf16 v[32:35], v[230:233], v[20:23], v[170:173]
	s_waitcnt lgkmcnt(1)
	v_mfma_f32_16x16x32_bf16 v[28:31], v[8:11], v[166:169], v[128:131]
	v_mfma_f32_16x16x32_bf16 v[24:27], v[154:157], v[166:169], v[132:135]
	v_mfma_f32_16x16x32_bf16 v[20:23], v[158:161], v[166:169], v[136:139]
	v_mfma_f32_16x16x32_bf16 v[16:19], v[230:233], v[166:169], v[178:181]
	s_waitcnt lgkmcnt(0)
	v_mfma_f32_16x16x32_bf16 v[12:15], v[8:11], v[214:217], v[0:3]
	v_mfma_f32_16x16x32_bf16 v[8:11], v[154:157], v[214:217], v[4:7]
	v_mfma_f32_16x16x32_bf16 v[4:7], v[158:161], v[214:217], v[140:143]
	v_mfma_f32_16x16x32_bf16 v[0:3], v[230:233], v[214:217], v[150:153]
	v_mov_b32_e32 v145, v184
	s_waitcnt vmcnt(0)
	s_barrier
	s_lshl_b32 s18, s0, 8
	s_lshl_b32 s16, s14, 8
	v_and_b32_e32 v151, 15, v145
	v_ashrrev_i32_e32 v112, 1, v145
	v_and_b32_e32 v153, 0xffffff80, v112
	v_or_b32_e32 v112, s18, v151
	v_add_u32_e32 v112, v112, v153
	v_ashrrev_i32_e32 v113, 31, v112
	v_lshlrev_b64 v[112:113], 13, v[112:113]
	v_bfe_u32 v150, v145, 6, 2
	v_lshl_add_u64 v[112:113], s[2:3], 0, v[112:113]
	s_ashr_i32 s17, s16, 31
	v_bfe_u32 v152, v145, 4, 2
	v_lshl_add_u64 v[112:113], s[16:17], 2, v[112:113]
	v_lshlrev_b32_e32 v146, 8, v150
	v_lshl_add_u64 v[112:113], v[112:113], 0, v[146:147]
	v_lshlrev_b32_e32 v146, 4, v152
	v_lshl_add_u64 v[154:155], v[112:113], 0, v[146:147]
	global_load_dwordx4 v[120:123], v[154:155], off offset:192
	global_load_dwordx4 v[128:131], v[154:155], off offset:128
	global_load_dwordx4 v[136:139], v[154:155], off offset:64
	global_load_dwordx4 v[140:143], v[154:155], off
	v_add_co_u32_e32 v112, vcc, s66, v154
	v_lshlrev_b32_e32 v158, 2, v152
	s_nop 0
	v_addc_co_u32_e32 v113, vcc, 0, v155, vcc
	global_load_dwordx4 v[132:135], v[112:113], off
	global_load_dwordx4 v[124:127], v[112:113], off offset:64
	global_load_dwordx4 v[116:119], v[112:113], off offset:128
	v_cmp_lt_i32_e32 vcc, v188, v186
	global_load_dwordx4 v[112:115], v[112:113], off offset:192
	v_cmp_eq_u32_e64 s[0:1], 0, v152
	v_cndmask_b32_e32 v146, v185, v188, vcc
	v_cmp_lt_i32_e32 vcc, v187, v186
	v_lshlrev_b32_e32 v149, 2, v146
	v_lshlrev_b32_e32 v157, 6, v150
	v_cndmask_b32_e32 v156, v185, v187, vcc
	v_lshlrev_b32_e32 v146, 2, v156
	v_or_b32_e32 v156, v153, v151
	v_add_u32_e32 v152, s18, v156
	v_ashrrev_i32_e32 v153, 31, v152
	v_lshl_or_b32 v182, v150, 10, v204
	v_or3_b32 v150, v157, s16, v158
	v_lshlrev_b64 v[158:159], 13, v[152:153]
	v_ashrrev_i32_e32 v151, 31, v150
	v_lshlrev_b64 v[160:161], 12, v[152:153]
	v_lshl_add_u64 v[158:159], s[2:3], 0, v[158:159]
	v_lshl_add_u64 v[160:161], s[4:5], 0, v[160:161]
	v_lshl_add_u64 v[166:167], v[150:151], 2, v[158:159]
	v_lshl_add_u64 v[168:169], v[150:151], 1, v[160:161]
	s_waitcnt vmcnt(7)
	v_pk_add_f32 v[158:159], v[162:163], v[120:121]
	s_waitcnt vmcnt(6)
	v_pk_add_f32 v[120:121], v[242:243], v[128:129]
	s_waitcnt vmcnt(5)
	v_pk_add_f32 v[128:129], v[238:239], v[136:137]
	s_waitcnt vmcnt(4)
	v_pk_add_f32 v[136:137], v[234:235], v[140:141]
	v_pk_add_f32 v[160:161], v[164:165], v[122:123]
	v_pk_add_f32 v[122:123], v[244:245], v[130:131]
	v_pk_add_f32 v[130:131], v[240:241], v[138:139]
	v_pk_add_f32 v[138:139], v[236:237], v[142:143]
	v_pk_mul_f32 v[172:173], v[128:129], v[128:129]
	v_pk_mul_f32 v[178:179], v[136:137], v[136:137]
	v_pk_mul_f32 v[162:163], v[120:121], v[120:121]
	v_pk_mul_f32 v[174:175], v[130:131], v[130:131]
	v_cvt_pk_bf16_f32 v176, v136, v137
	v_pk_mul_f32 v[180:181], v[138:139], v[138:139]
	global_store_dwordx4 v[166:167], v[136:139], off
	v_add_f32_e32 v153, v172, v173
	v_add_f32_e32 v157, v178, v179
	v_pk_mul_f32 v[136:137], v[158:159], v[158:159]
	v_pk_mul_f32 v[164:165], v[122:123], v[122:123]
	v_cvt_pk_bf16_f32 v177, v138, v139
	v_pk_mul_f32 v[138:139], v[160:161], v[160:161]
	v_add_f32_e32 v162, v162, v163
	v_add_f32_e32 v136, v136, v137
	v_add_f32_e32 v137, v174, v153
	v_add_f32_e32 v153, v180, v157
	v_add_f32_e32 v157, v164, v162
	v_add_f32_e32 v136, v138, v136
	v_add_f32_e32 v137, v175, v137
	v_add_f32_e32 v138, v181, v153
	v_add_f32_e32 v153, v165, v157
	v_add_f32_e32 v137, v138, v137
	v_add_f32_e32 v137, v137, v153
	v_add_f32_e32 v136, v139, v136
	v_add_f32_e32 v136, v137, v136
	ds_bpermute_b32 v137, v149, v136
	v_cvt_pk_bf16_f32 v170, v128, v129
	v_cvt_pk_bf16_f32 v171, v130, v131
	v_cvt_pk_bf16_f32 v142, v120, v121
	global_store_dwordx2 v[168:169], v[176:177], off
	global_store_dwordx4 v[166:167], v[128:131], off offset:64
	global_store_dwordx2 v[168:169], v[170:171], off offset:32
	global_store_dwordx4 v[166:167], v[120:123], off offset:128
	v_cvt_pk_bf16_f32 v140, v158, v159
	v_cvt_pk_bf16_f32 v141, v160, v161
	s_waitcnt lgkmcnt(0)
	v_add_f32_e32 v120, v136, v137
	ds_bpermute_b32 v121, v146, v120
	v_cvt_pk_bf16_f32 v143, v122, v123
	v_lshl_add_u32 v153, v156, 2, v182
	global_store_dwordx2 v[168:169], v[142:143], off offset:64
	global_store_dwordx4 v[166:167], v[158:161], off offset:192
	global_store_dwordx2 v[168:169], v[140:141], off offset:96
	s_and_saveexec_b64 s[16:17], s[0:1]
	s_cbranch_execz .LBB0_156
	s_waitcnt lgkmcnt(0)
	v_add_f32_e32 v120, v120, v121
	ds_write_b32 v153, v120

.LBB0_252:
	s_mul_i32 s16, s19, 0x300000
	s_mul_hi_i32 s17, s19, 0x300000
	s_add_u32 s16, s22, s16
	s_addc_u32 s17, s23, s17
	s_mul_hi_i32 s19, s18, 0x300000
	s_mul_i32 s18, s18, 0x300000
	s_add_u32 s18, s24, s18
	s_addc_u32 s19, s25, s19
	s_add_u32 s44, s0, 0x80
	v_and_b32_e32 v8, 48, v7
	v_lshlrev_b32_e32 v9, 6, v7
	v_lshlrev_b32_e32 v7, 2, v7
	s_addc_u32 s45, s1, 0
	v_and_b32_e32 v10, 0x3c0, v9
	v_and_b32_e32 v149, 32, v7
	s_add_u32 s46, s14, 0x80
	v_or_b32_e32 v145, v10, v8
	v_bitop3_b32 v12, v10, v149, v8 bitop3:0x36
	s_waitcnt vmcnt(0)
	s_barrier
	v_lshlrev_b32_e32 v8, 13, v6
	s_addc_u32 s47, s15, 0
	s_add_i32 s38, s27, 0x10000
	v_lshl_add_u64 v[6:7], s[44:45], 0, v[0:1]
	s_mov_b32 s39, m0
	s_mov_b32 m0, s38
	s_nop 0
	global_load_lds_dwordx4 v[6:7], off
	s_mov_b32 m0, s39
	s_add_i32 s37, s27, 0x18000
	v_lshl_add_u64 v[6:7], s[46:47], 0, v[0:1]
	s_mov_b32 s39, m0
	s_mov_b32 m0, s37
	s_nop 0
	global_load_lds_dwordx4 v[6:7], off
	s_mov_b32 m0, s39
	v_lshl_add_u64 v[6:7], s[44:45], 0, v[2:3]
	s_add_i32 s39, s27, 0x12000
	s_mov_b32 s40, m0
	s_mov_b32 m0, s39
	s_nop 0
	global_load_lds_dwordx4 v[6:7], off
	s_mov_b32 m0, s40
	v_lshl_add_u64 v[6:7], s[46:47], 0, v[2:3]
	s_add_i32 s40, s27, 0x1a000
	s_mov_b32 s41, m0
	s_mov_b32 m0, s40
	s_nop 0
	global_load_lds_dwordx4 v[6:7], off
	s_mov_b32 m0, s41
	v_lshl_add_u64 v[6:7], s[44:45], 0, v[4:5]
	s_add_i32 s41, s27, 0x14000
	s_mov_b32 s42, m0
	s_mov_b32 m0, s41
	s_nop 0
	global_load_lds_dwordx4 v[6:7], off
	s_mov_b32 m0, s42
	v_lshl_add_u64 v[6:7], s[46:47], 0, v[4:5]
	s_add_i32 s42, s27, 0x1c000
	s_mov_b32 s43, m0
	s_mov_b32 m0, s42
	s_nop 0
	global_load_lds_dwordx4 v[6:7], off
	s_mov_b32 m0, s43
	v_lshl_add_u64 v[6:7], s[44:45], 0, v[146:147]
	s_add_i32 s43, s27, 0x16000
	s_mov_b32 s44, m0
	s_mov_b32 m0, s43
	s_nop 0
	global_load_lds_dwordx4 v[6:7], off
	s_mov_b32 m0, s44
	v_lshl_add_u64 v[6:7], s[46:47], 0, v[146:147]
	s_add_i32 s44, s27, 0x1e000
	s_mov_b32 s45, m0
	s_mov_b32 m0, s44
	s_nop 0
	global_load_lds_dwordx4 v[6:7], off
	s_mov_b32 m0, s45
	v_and_b32_e32 v182, 0xffffc000, v9
	v_or_b32_e32 v183, 0x800, v182
	v_or_b32_e32 v189, 0x1000, v182
	v_or_b32_e32 v199, 0x1800, v182
	v_or_b32_e32 v200, 0x2000, v182
	v_or_b32_e32 v201, 0x2800, v182
	v_or_b32_e32 v203, 0x3000, v182
	v_or_b32_e32 v206, 0x3800, v182
	s_movk_i32 s45, 0x6000
	v_and_or_b32 v7, v8, s45, v12
	ds_read_b128 v[8:11], v7 offset:32768
	v_or_b32_e32 v6, v12, v182
	ds_read_b128 v[12:15], v7 offset:34816
	ds_read_b128 v[16:19], v7 offset:36864
	ds_read_b128 v[24:27], v7 offset:38912
	ds_read_b128 v[20:23], v6
	ds_read_b128 v[28:31], v6 offset:2048
	ds_read_b128 v[32:35], v6 offset:4096
	ds_read_b128 v[36:39], v6 offset:6144
	s_waitcnt lgkmcnt(3)
	v_mfma_f32_16x16x32_bf16 v[40:43], v[8:11], v[20:23], 0
	v_mfma_f32_16x16x32_bf16 v[44:47], v[12:15], v[20:23], 0
	v_mfma_f32_16x16x32_bf16 v[48:51], v[16:19], v[20:23], 0
	v_mfma_f32_16x16x32_bf16 v[20:23], v[24:27], v[20:23], 0
	ds_read_b128 v[52:55], v6 offset:8192
	s_waitcnt lgkmcnt(3)
	v_mfma_f32_16x16x32_bf16 v[56:59], v[8:11], v[28:31], 0
	v_mfma_f32_16x16x32_bf16 v[60:63], v[12:15], v[28:31], 0
	v_mfma_f32_16x16x32_bf16 v[64:67], v[16:19], v[28:31], 0
	v_mfma_f32_16x16x32_bf16 v[28:31], v[24:27], v[28:31], 0
	ds_read_b128 v[68:71], v6 offset:10240
	s_waitcnt lgkmcnt(3)
	v_mfma_f32_16x16x32_bf16 v[72:75], v[8:11], v[32:35], 0
	v_mfma_f32_16x16x32_bf16 v[76:79], v[12:15], v[32:35], 0
	v_mfma_f32_16x16x32_bf16 v[80:83], v[16:19], v[32:35], 0
	v_mfma_f32_16x16x32_bf16 v[32:35], v[24:27], v[32:35], 0
	ds_read_b128 v[84:87], v6 offset:12288
	s_waitcnt lgkmcnt(3)
	v_mfma_f32_16x16x32_bf16 v[88:91], v[8:11], v[36:39], 0
	v_mfma_f32_16x16x32_bf16 v[92:95], v[12:15], v[36:39], 0
	v_mfma_f32_16x16x32_bf16 v[96:99], v[16:19], v[36:39], 0
	v_mfma_f32_16x16x32_bf16 v[36:39], v[24:27], v[36:39], 0
	ds_read_b128 v[100:103], v6 offset:14336
	s_waitcnt lgkmcnt(3)
	v_mfma_f32_16x16x32_bf16 v[104:107], v[8:11], v[52:55], 0
	v_mfma_f32_16x16x32_bf16 v[108:111], v[12:15], v[52:55], 0
	v_mfma_f32_16x16x32_bf16 v[112:115], v[16:19], v[52:55], 0
	v_mfma_f32_16x16x32_bf16 v[52:55], v[24:27], v[52:55], 0
	s_waitcnt lgkmcnt(2)
	v_mfma_f32_16x16x32_bf16 v[116:119], v[8:11], v[68:71], 0
	v_mfma_f32_16x16x32_bf16 v[120:123], v[12:15], v[68:71], 0
	v_mfma_f32_16x16x32_bf16 v[124:127], v[16:19], v[68:71], 0
	v_mfma_f32_16x16x32_bf16 v[68:71], v[24:27], v[68:71], 0
	s_waitcnt lgkmcnt(1)
	v_mfma_f32_16x16x32_bf16 v[128:131], v[8:11], v[84:87], 0
	v_mfma_f32_16x16x32_bf16 v[132:135], v[12:15], v[84:87], 0
	v_mfma_f32_16x16x32_bf16 v[136:139], v[16:19], v[84:87], 0
	v_mfma_f32_16x16x32_bf16 v[84:87], v[24:27], v[84:87], 0
	s_waitcnt lgkmcnt(0)
	v_mfma_f32_16x16x32_bf16 v[8:11], v[8:11], v[100:103], 0
	v_mfma_f32_16x16x32_bf16 v[12:15], v[12:15], v[100:103], 0
	v_mfma_f32_16x16x32_bf16 v[16:19], v[16:19], v[100:103], 0
	v_mfma_f32_16x16x32_bf16 v[24:27], v[24:27], v[100:103], 0
	ds_read_b128 v[100:103], v7 offset:33792
	ds_read_b128 v[140:143], v7 offset:35840
	ds_read_b128 v[150:153], v7 offset:37888
	ds_read_b128 v[158:161], v7 offset:39936
	ds_read_b128 v[154:157], v6 offset:1024
	ds_read_b128 v[162:165], v6 offset:3072
	ds_read_b128 v[166:169], v6 offset:5120
	ds_read_b128 v[170:173], v6 offset:7168
	s_waitcnt lgkmcnt(3)
	v_mfma_f32_16x16x32_bf16 v[40:43], v[100:103], v[154:157], v[40:43]
	v_mfma_f32_16x16x32_bf16 v[44:47], v[140:143], v[154:157], v[44:47]
	v_mfma_f32_16x16x32_bf16 v[48:51], v[150:153], v[154:157], v[48:51]
	v_mfma_f32_16x16x32_bf16 v[20:23], v[158:161], v[154:157], v[20:23]
	ds_read_b128 v[154:157], v6 offset:9216
	s_waitcnt lgkmcnt(3)
	v_mfma_f32_16x16x32_bf16 v[56:59], v[100:103], v[162:165], v[56:59]
	v_mfma_f32_16x16x32_bf16 v[60:63], v[140:143], v[162:165], v[60:63]
	v_mfma_f32_16x16x32_bf16 v[64:67], v[150:153], v[162:165], v[64:67]
	v_mfma_f32_16x16x32_bf16 v[28:31], v[158:161], v[162:165], v[28:31]
	ds_read_b128 v[162:165], v6 offset:11264
	s_waitcnt lgkmcnt(3)
	v_mfma_f32_16x16x32_bf16 v[72:75], v[100:103], v[166:169], v[72:75]
	v_mfma_f32_16x16x32_bf16 v[76:79], v[140:143], v[166:169], v[76:79]
	v_mfma_f32_16x16x32_bf16 v[80:83], v[150:153], v[166:169], v[80:83]
	v_mfma_f32_16x16x32_bf16 v[32:35], v[158:161], v[166:169], v[32:35]
	ds_read_b128 v[166:169], v6 offset:13312
	s_waitcnt lgkmcnt(3)
	v_mfma_f32_16x16x32_bf16 v[88:91], v[100:103], v[170:173], v[88:91]
	v_mfma_f32_16x16x32_bf16 v[92:95], v[140:143], v[170:173], v[92:95]
	v_mfma_f32_16x16x32_bf16 v[96:99], v[150:153], v[170:173], v[96:99]
	v_mfma_f32_16x16x32_bf16 v[36:39], v[158:161], v[170:173], v[36:39]
	ds_read_b128 v[170:173], v6 offset:15360
	s_waitcnt lgkmcnt(3)
	v_mfma_f32_16x16x32_bf16 v[104:107], v[100:103], v[154:157], v[104:107]
	v_mfma_f32_16x16x32_bf16 v[108:111], v[140:143], v[154:157], v[108:111]
	v_mfma_f32_16x16x32_bf16 v[112:115], v[150:153], v[154:157], v[112:115]
	v_mfma_f32_16x16x32_bf16 v[52:55], v[158:161], v[154:157], v[52:55]
	s_waitcnt lgkmcnt(2)
	v_mfma_f32_16x16x32_bf16 v[116:119], v[100:103], v[162:165], v[116:119]
	v_mfma_f32_16x16x32_bf16 v[120:123], v[140:143], v[162:165], v[120:123]
	v_mfma_f32_16x16x32_bf16 v[124:127], v[150:153], v[162:165], v[124:127]
	v_mfma_f32_16x16x32_bf16 v[68:71], v[158:161], v[162:165], v[68:71]
	s_waitcnt lgkmcnt(1)
	v_mfma_f32_16x16x32_bf16 v[128:131], v[100:103], v[166:169], v[128:131]
	v_mfma_f32_16x16x32_bf16 v[132:135], v[140:143], v[166:169], v[132:135]
	v_mfma_f32_16x16x32_bf16 v[136:139], v[150:153], v[166:169], v[136:139]
	v_mfma_f32_16x16x32_bf16 v[84:87], v[158:161], v[166:169], v[84:87]
	s_waitcnt lgkmcnt(0)
	v_mfma_f32_16x16x32_bf16 v[100:103], v[100:103], v[170:173], v[8:11]
	v_mfma_f32_16x16x32_bf16 v[150:153], v[150:153], v[170:173], v[16:19]
	v_mfma_f32_16x16x32_bf16 v[24:27], v[158:161], v[170:173], v[24:27]
	v_mfma_f32_16x16x32_bf16 v[140:143], v[140:143], v[170:173], v[12:15]
	s_add_u32 s46, s0, 0x100
	s_addc_u32 s47, s1, 0
	s_add_u32 s48, s14, 0x100
	s_waitcnt vmcnt(0)
	s_barrier
	s_addc_u32 s49, s15, 0
	v_lshl_add_u64 v[8:9], s[46:47], 0, v[0:1]
	s_mov_b32 s45, m0
	s_mov_b32 m0, s27
	s_nop 0
	global_load_lds_dwordx4 v[8:9], off
	s_mov_b32 m0, s45
	v_lshl_add_u64 v[8:9], s[48:49], 0, v[0:1]
	s_mov_b32 s45, m0
	s_mov_b32 m0, s28
	s_nop 0
	global_load_lds_dwordx4 v[8:9], off
	s_mov_b32 m0, s45
	v_lshl_add_u64 v[8:9], s[46:47], 0, v[2:3]
	s_mov_b32 s45, m0
	s_mov_b32 m0, s29
	s_nop 0
	global_load_lds_dwordx4 v[8:9], off
	s_mov_b32 m0, s45
	v_lshl_add_u64 v[8:9], s[48:49], 0, v[2:3]
	s_mov_b32 s45, m0
	s_mov_b32 m0, s30
	s_nop 0
	global_load_lds_dwordx4 v[8:9], off
	s_mov_b32 m0, s45
	v_lshl_add_u64 v[8:9], s[46:47], 0, v[4:5]
	s_mov_b32 s45, m0
	s_mov_b32 m0, s31
	s_nop 0
	global_load_lds_dwordx4 v[8:9], off
	s_mov_b32 m0, s45
	v_lshl_add_u64 v[8:9], s[48:49], 0, v[4:5]
	s_mov_b32 s45, m0
	s_mov_b32 m0, s34
	s_nop 0
	global_load_lds_dwordx4 v[8:9], off
	s_mov_b32 m0, s45
	v_lshl_add_u64 v[8:9], s[46:47], 0, v[146:147]
	s_mov_b32 s45, m0
	s_mov_b32 m0, s35
	s_nop 0
	global_load_lds_dwordx4 v[8:9], off
	s_mov_b32 m0, s45
	v_lshl_add_u64 v[8:9], s[48:49], 0, v[146:147]
	s_mov_b32 s45, m0
	s_mov_b32 m0, s36
	s_nop 0
	global_load_lds_dwordx4 v[8:9], off
	s_mov_b32 m0, s45
	v_or_b32_e32 v8, 0x18000, v7
	v_or_b32_e32 v9, 0x18800, v7
	v_or_b32_e32 v11, 0x19000, v7
	v_or_b32_e32 v10, 0x19800, v7
	ds_read_b128 v[154:157], v8
	ds_read_b128 v[158:161], v9
	ds_read_b128 v[162:165], v11
	ds_read_b128 v[166:169], v10
	v_bitop3_b32 v207, v145, s33, v149 bitop3:0xde
	v_add_u32_e32 v12, v207, v182
	ds_read_b128 v[16:19], v12
	v_add_u32_e32 v13, v207, v183
	v_add_u32_e32 v14, v207, v189
	v_add_u32_e32 v15, v207, v199
	ds_read_b128 v[170:173], v13
	ds_read_b128 v[174:177], v14
	ds_read_b128 v[178:181], v15
	s_waitcnt lgkmcnt(3)
	v_mfma_f32_16x16x32_bf16 v[40:43], v[154:157], v[16:19], v[40:43]
	v_mfma_f32_16x16x32_bf16 v[44:47], v[158:161], v[16:19], v[44:47]
	v_mfma_f32_16x16x32_bf16 v[48:51], v[162:165], v[16:19], v[48:51]
	v_mfma_f32_16x16x32_bf16 v[214:217], v[166:169], v[16:19], v[20:23]
	v_add_u32_e32 v16, v207, v200
	v_add_u32_e32 v17, v207, v201
	v_add_u32_e32 v18, v207, v203
	v_add_u32_e32 v19, v207, v206
	ds_read_b128 v[20:23], v16
	s_waitcnt lgkmcnt(3)
	v_mfma_f32_16x16x32_bf16 v[56:59], v[154:157], v[170:173], v[56:59]
	v_mfma_f32_16x16x32_bf16 v[60:63], v[158:161], v[170:173], v[60:63]
	v_mfma_f32_16x16x32_bf16 v[64:67], v[162:165], v[170:173], v[64:67]
	v_mfma_f32_16x16x32_bf16 v[170:173], v[166:169], v[170:173], v[28:31]
	s_nop 2
	ds_read_b128 v[28:31], v17
	s_waitcnt lgkmcnt(3)
	v_mfma_f32_16x16x32_bf16 v[72:75], v[154:157], v[174:177], v[72:75]
	v_mfma_f32_16x16x32_bf16 v[76:79], v[158:161], v[174:177], v[76:79]
	v_mfma_f32_16x16x32_bf16 v[80:83], v[162:165], v[174:177], v[80:83]
	v_mfma_f32_16x16x32_bf16 v[32:35], v[166:169], v[174:177], v[32:35]
	ds_read_b128 v[174:177], v18
	s_waitcnt lgkmcnt(3)
	v_mfma_f32_16x16x32_bf16 v[88:91], v[154:157], v[178:181], v[88:91]
	v_mfma_f32_16x16x32_bf16 v[92:95], v[158:161], v[178:181], v[92:95]
	v_mfma_f32_16x16x32_bf16 v[96:99], v[162:165], v[178:181], v[96:99]
	v_mfma_f32_16x16x32_bf16 v[36:39], v[166:169], v[178:181], v[36:39]
	ds_read_b128 v[178:181], v19
	s_waitcnt lgkmcnt(3)
	v_mfma_f32_16x16x32_bf16 v[104:107], v[154:157], v[20:23], v[104:107]
	v_mfma_f32_16x16x32_bf16 v[108:111], v[158:161], v[20:23], v[108:111]
	v_mfma_f32_16x16x32_bf16 v[112:115], v[162:165], v[20:23], v[112:115]
	v_mfma_f32_16x16x32_bf16 v[52:55], v[166:169], v[20:23], v[52:55]
	s_waitcnt lgkmcnt(2)
	v_mfma_f32_16x16x32_bf16 v[116:119], v[154:157], v[28:31], v[116:119]
	v_mfma_f32_16x16x32_bf16 v[120:123], v[158:161], v[28:31], v[120:123]
	v_mfma_f32_16x16x32_bf16 v[124:127], v[162:165], v[28:31], v[124:127]
	v_mfma_f32_16x16x32_bf16 v[68:71], v[166:169], v[28:31], v[68:71]
	s_waitcnt lgkmcnt(1)
	v_mfma_f32_16x16x32_bf16 v[128:131], v[154:157], v[174:177], v[128:131]
	v_mfma_f32_16x16x32_bf16 v[132:135], v[158:161], v[174:177], v[132:135]
	v_mfma_f32_16x16x32_bf16 v[84:87], v[166:169], v[174:177], v[84:87]
	s_waitcnt lgkmcnt(0)
	v_mfma_f32_16x16x32_bf16 v[100:103], v[154:157], v[178:181], v[100:103]
	v_mfma_f32_16x16x32_bf16 v[150:153], v[162:165], v[178:181], v[150:153]
	v_mfma_f32_16x16x32_bf16 v[154:157], v[166:169], v[178:181], v[24:27]
	v_mfma_f32_16x16x32_bf16 v[136:139], v[162:165], v[174:177], v[136:139]
	v_mfma_f32_16x16x32_bf16 v[140:143], v[158:161], v[178:181], v[140:143]
	v_or_b32_e32 v20, 0x18400, v7
	v_or_b32_e32 v21, 0x18c00, v7
	v_or_b32_e32 v23, 0x19400, v7
	v_or_b32_e32 v22, 0x19c00, v7
	ds_read_b128 v[158:161], v20
	ds_read_b128 v[162:165], v21
	ds_read_b128 v[166:169], v23
	ds_read_b128 v[174:177], v22
	s_mov_b32 s45, 0x10400
	v_bitop3_b32 v145, v145, s45, v149 bitop3:0xde
	v_add_u32_e32 v24, v145, v182
	ds_read_b128 v[28:31], v24
	v_add_u32_e32 v25, v145, v183
	v_add_u32_e32 v26, v145, v189
	v_add_u32_e32 v27, v145, v199
	ds_read_b128 v[178:181], v25
	ds_read_b128 v[218:221], v26
	ds_read_b128 v[222:225], v27
	s_waitcnt lgkmcnt(3)
	v_mfma_f32_16x16x32_bf16 v[40:43], v[158:161], v[28:31], v[40:43]
	v_mfma_f32_16x16x32_bf16 v[44:47], v[162:165], v[28:31], v[44:47]
	v_mfma_f32_16x16x32_bf16 v[48:51], v[166:169], v[28:31], v[48:51]
	v_mfma_f32_16x16x32_bf16 v[214:217], v[174:177], v[28:31], v[214:217]
	v_add_u32_e32 v28, v145, v200
	v_add_u32_e32 v29, v145, v201
	v_add_u32_e32 v30, v145, v203
	v_add_u32_e32 v31, v145, v206
	ds_read_b128 v[226:229], v28
	s_waitcnt lgkmcnt(3)
	v_mfma_f32_16x16x32_bf16 v[56:59], v[158:161], v[178:181], v[56:59]
	v_mfma_f32_16x16x32_bf16 v[60:63], v[162:165], v[178:181], v[60:63]
	v_mfma_f32_16x16x32_bf16 v[64:67], v[166:169], v[178:181], v[64:67]
	v_mfma_f32_16x16x32_bf16 v[170:173], v[174:177], v[178:181], v[170:173]
	ds_read_b128 v[178:181], v29
	s_waitcnt lgkmcnt(3)
	v_mfma_f32_16x16x32_bf16 v[72:75], v[158:161], v[218:221], v[72:75]
	v_mfma_f32_16x16x32_bf16 v[76:79], v[162:165], v[218:221], v[76:79]
	v_mfma_f32_16x16x32_bf16 v[80:83], v[166:169], v[218:221], v[80:83]
	v_mfma_f32_16x16x32_bf16 v[32:35], v[174:177], v[218:221], v[32:35]
	ds_read_b128 v[218:221], v30
	s_waitcnt lgkmcnt(3)
	v_mfma_f32_16x16x32_bf16 v[88:91], v[158:161], v[222:225], v[88:91]
	v_mfma_f32_16x16x32_bf16 v[92:95], v[162:165], v[222:225], v[92:95]
	v_mfma_f32_16x16x32_bf16 v[96:99], v[166:169], v[222:225], v[96:99]
	v_mfma_f32_16x16x32_bf16 v[36:39], v[174:177], v[222:225], v[36:39]
	ds_read_b128 v[222:225], v31
	s_waitcnt lgkmcnt(3)
	v_mfma_f32_16x16x32_bf16 v[104:107], v[158:161], v[226:229], v[104:107]
	v_mfma_f32_16x16x32_bf16 v[108:111], v[162:165], v[226:229], v[108:111]
	v_mfma_f32_16x16x32_bf16 v[112:115], v[166:169], v[226:229], v[112:115]
	v_mfma_f32_16x16x32_bf16 v[52:55], v[174:177], v[226:229], v[52:55]
	s_waitcnt lgkmcnt(2)
	v_mfma_f32_16x16x32_bf16 v[116:119], v[158:161], v[178:181], v[116:119]
	v_mfma_f32_16x16x32_bf16 v[120:123], v[162:165], v[178:181], v[120:123]
	v_mfma_f32_16x16x32_bf16 v[124:127], v[166:169], v[178:181], v[124:127]
	v_mfma_f32_16x16x32_bf16 v[68:71], v[174:177], v[178:181], v[68:71]
	s_waitcnt lgkmcnt(1)
	v_mfma_f32_16x16x32_bf16 v[132:135], v[162:165], v[218:221], v[132:135]
	v_mfma_f32_16x16x32_bf16 v[84:87], v[174:177], v[218:221], v[84:87]
	s_waitcnt lgkmcnt(0)
	v_mfma_f32_16x16x32_bf16 v[100:103], v[158:161], v[222:225], v[100:103]
	v_mfma_f32_16x16x32_bf16 v[150:153], v[166:169], v[222:225], v[150:153]
	v_mfma_f32_16x16x32_bf16 v[154:157], v[174:177], v[222:225], v[154:157]
	v_mfma_f32_16x16x32_bf16 v[128:131], v[158:161], v[218:221], v[128:131]
	v_mfma_f32_16x16x32_bf16 v[136:139], v[166:169], v[218:221], v[136:139]
	v_mfma_f32_16x16x32_bf16 v[140:143], v[162:165], v[222:225], v[140:143]
	s_add_u32 s46, s0, 0x180
	s_addc_u32 s47, s1, 0
	s_add_u32 s48, s14, 0x180
	s_waitcnt vmcnt(0)
	s_barrier
	s_addc_u32 s49, s15, 0
	v_lshl_add_u64 v[158:159], s[46:47], 0, v[0:1]
	s_mov_b32 s45, m0
	s_mov_b32 m0, s38
	s_nop 0
	global_load_lds_dwordx4 v[158:159], off
	s_mov_b32 m0, s45
	v_lshl_add_u64 v[158:159], s[48:49], 0, v[0:1]
	s_mov_b32 s45, m0
	s_mov_b32 m0, s37
	s_nop 0
	global_load_lds_dwordx4 v[158:159], off
	s_mov_b32 m0, s45
	v_lshl_add_u64 v[158:159], s[46:47], 0, v[2:3]
	s_mov_b32 s45, m0
	s_mov_b32 m0, s39
	s_nop 0
	global_load_lds_dwordx4 v[158:159], off
	s_mov_b32 m0, s45
	v_lshl_add_u64 v[158:159], s[48:49], 0, v[2:3]
	s_mov_b32 s45, m0
	s_mov_b32 m0, s40
	s_nop 0
	global_load_lds_dwordx4 v[158:159], off
	s_mov_b32 m0, s45
	v_lshl_add_u64 v[158:159], s[46:47], 0, v[4:5]
	s_mov_b32 s45, m0
	s_mov_b32 m0, s41
	s_nop 0
	global_load_lds_dwordx4 v[158:159], off
	s_mov_b32 m0, s45
	v_lshl_add_u64 v[158:159], s[48:49], 0, v[4:5]
	s_mov_b32 s45, m0
	s_mov_b32 m0, s42
	s_nop 0
	global_load_lds_dwordx4 v[158:159], off
	s_mov_b32 m0, s45
	v_lshl_add_u64 v[158:159], s[46:47], 0, v[146:147]
	s_mov_b32 s45, m0
	s_mov_b32 m0, s43
	s_nop 0
	global_load_lds_dwordx4 v[158:159], off
	s_mov_b32 m0, s45
	v_lshl_add_u64 v[158:159], s[48:49], 0, v[146:147]
	s_mov_b32 s45, m0
	s_mov_b32 m0, s44
	s_nop 0
	global_load_lds_dwordx4 v[158:159], off
	s_mov_b32 m0, s45
	ds_read_b128 v[158:161], v7 offset:32768
	ds_read_b128 v[162:165], v7 offset:34816
	ds_read_b128 v[166:169], v7 offset:36864
	ds_read_b128 v[178:181], v7 offset:38912
	ds_read_b128 v[174:177], v6
	ds_read_b128 v[218:221], v6 offset:2048
	ds_read_b128 v[222:225], v6 offset:4096
	ds_read_b128 v[226:229], v6 offset:6144
	s_waitcnt lgkmcnt(3)
	v_mfma_f32_16x16x32_bf16 v[40:43], v[158:161], v[174:177], v[40:43]
	v_mfma_f32_16x16x32_bf16 v[44:47], v[162:165], v[174:177], v[44:47]
	v_mfma_f32_16x16x32_bf16 v[48:51], v[166:169], v[174:177], v[48:51]
	v_mfma_f32_16x16x32_bf16 v[174:177], v[178:181], v[174:177], v[214:217]
	s_nop 2
	ds_read_b128 v[214:217], v6 offset:8192
	s_waitcnt lgkmcnt(3)
	v_mfma_f32_16x16x32_bf16 v[56:59], v[158:161], v[218:221], v[56:59]
	v_mfma_f32_16x16x32_bf16 v[60:63], v[162:165], v[218:221], v[60:63]
	v_mfma_f32_16x16x32_bf16 v[64:67], v[166:169], v[218:221], v[64:67]
	v_mfma_f32_16x16x32_bf16 v[170:173], v[178:181], v[218:221], v[170:173]
	ds_read_b128 v[218:221], v6 offset:10240
	s_waitcnt lgkmcnt(3)
	v_mfma_f32_16x16x32_bf16 v[72:75], v[158:161], v[222:225], v[72:75]
	v_mfma_f32_16x16x32_bf16 v[76:79], v[162:165], v[222:225], v[76:79]
	v_mfma_f32_16x16x32_bf16 v[80:83], v[166:169], v[222:225], v[80:83]
	v_mfma_f32_16x16x32_bf16 v[32:35], v[178:181], v[222:225], v[32:35]
	ds_read_b128 v[222:225], v6 offset:12288
	s_waitcnt lgkmcnt(3)
	v_mfma_f32_16x16x32_bf16 v[88:91], v[158:161], v[226:229], v[88:91]
	v_mfma_f32_16x16x32_bf16 v[92:95], v[162:165], v[226:229], v[92:95]
	v_mfma_f32_16x16x32_bf16 v[96:99], v[166:169], v[226:229], v[96:99]
	v_mfma_f32_16x16x32_bf16 v[36:39], v[178:181], v[226:229], v[36:39]
	ds_read_b128 v[226:229], v6 offset:14336
	s_waitcnt lgkmcnt(3)
	v_mfma_f32_16x16x32_bf16 v[104:107], v[158:161], v[214:217], v[104:107]
	v_mfma_f32_16x16x32_bf16 v[108:111], v[162:165], v[214:217], v[108:111]
	v_mfma_f32_16x16x32_bf16 v[112:115], v[166:169], v[214:217], v[112:115]
	v_mfma_f32_16x16x32_bf16 v[52:55], v[178:181], v[214:217], v[52:55]
	s_waitcnt lgkmcnt(2)
	v_mfma_f32_16x16x32_bf16 v[116:119], v[158:161], v[218:221], v[116:119]
	v_mfma_f32_16x16x32_bf16 v[120:123], v[162:165], v[218:221], v[120:123]
	v_mfma_f32_16x16x32_bf16 v[124:127], v[166:169], v[218:221], v[124:127]
	v_mfma_f32_16x16x32_bf16 v[68:71], v[178:181], v[218:221], v[68:71]
	s_waitcnt lgkmcnt(1)
	v_mfma_f32_16x16x32_bf16 v[132:135], v[162:165], v[222:225], v[132:135]
	v_mfma_f32_16x16x32_bf16 v[84:87], v[178:181], v[222:225], v[84:87]
	s_waitcnt lgkmcnt(0)
	v_mfma_f32_16x16x32_bf16 v[100:103], v[158:161], v[226:229], v[100:103]
	v_mfma_f32_16x16x32_bf16 v[150:153], v[166:169], v[226:229], v[150:153]
	v_mfma_f32_16x16x32_bf16 v[154:157], v[178:181], v[226:229], v[154:157]
	v_mfma_f32_16x16x32_bf16 v[128:131], v[158:161], v[222:225], v[128:131]
	v_mfma_f32_16x16x32_bf16 v[136:139], v[166:169], v[222:225], v[136:139]
	v_mfma_f32_16x16x32_bf16 v[140:143], v[162:165], v[226:229], v[140:143]
	ds_read_b128 v[158:161], v7 offset:33792
	ds_read_b128 v[162:165], v7 offset:35840
	ds_read_b128 v[166:169], v7 offset:37888
	ds_read_b128 v[214:217], v7 offset:39936
	ds_read_b128 v[178:181], v6 offset:1024
	ds_read_b128 v[218:221], v6 offset:3072
	ds_read_b128 v[222:225], v6 offset:5120
	ds_read_b128 v[226:229], v6 offset:7168
	s_waitcnt lgkmcnt(3)
	v_mfma_f32_16x16x32_bf16 v[40:43], v[158:161], v[178:181], v[40:43]
	v_mfma_f32_16x16x32_bf16 v[44:47], v[162:165], v[178:181], v[44:47]
	v_mfma_f32_16x16x32_bf16 v[48:51], v[166:169], v[178:181], v[48:51]
	v_mfma_f32_16x16x32_bf16 v[174:177], v[214:217], v[178:181], v[174:177]
	ds_read_b128 v[178:181], v6 offset:9216
	s_waitcnt lgkmcnt(3)
	v_mfma_f32_16x16x32_bf16 v[56:59], v[158:161], v[218:221], v[56:59]
	v_mfma_f32_16x16x32_bf16 v[60:63], v[162:165], v[218:221], v[60:63]
	v_mfma_f32_16x16x32_bf16 v[64:67], v[166:169], v[218:221], v[64:67]
	v_mfma_f32_16x16x32_bf16 v[170:173], v[214:217], v[218:221], v[170:173]
	ds_read_b128 v[218:221], v6 offset:11264
	s_waitcnt lgkmcnt(3)
	v_mfma_f32_16x16x32_bf16 v[72:75], v[158:161], v[222:225], v[72:75]
	v_mfma_f32_16x16x32_bf16 v[76:79], v[162:165], v[222:225], v[76:79]
	v_mfma_f32_16x16x32_bf16 v[80:83], v[166:169], v[222:225], v[80:83]
	v_mfma_f32_16x16x32_bf16 v[32:35], v[214:217], v[222:225], v[32:35]
	ds_read_b128 v[222:225], v6 offset:13312
	s_waitcnt lgkmcnt(3)
	v_mfma_f32_16x16x32_bf16 v[88:91], v[158:161], v[226:229], v[88:91]
	v_mfma_f32_16x16x32_bf16 v[92:95], v[162:165], v[226:229], v[92:95]
	v_mfma_f32_16x16x32_bf16 v[96:99], v[166:169], v[226:229], v[96:99]
	v_mfma_f32_16x16x32_bf16 v[36:39], v[214:217], v[226:229], v[36:39]
	ds_read_b128 v[226:229], v6 offset:15360
	s_waitcnt lgkmcnt(3)
	v_mfma_f32_16x16x32_bf16 v[104:107], v[158:161], v[178:181], v[104:107]
	v_mfma_f32_16x16x32_bf16 v[108:111], v[162:165], v[178:181], v[108:111]
	v_mfma_f32_16x16x32_bf16 v[112:115], v[166:169], v[178:181], v[112:115]
	v_mfma_f32_16x16x32_bf16 v[52:55], v[214:217], v[178:181], v[52:55]
	s_waitcnt lgkmcnt(2)
	v_mfma_f32_16x16x32_bf16 v[116:119], v[158:161], v[218:221], v[116:119]
	v_mfma_f32_16x16x32_bf16 v[120:123], v[162:165], v[218:221], v[120:123]
	v_mfma_f32_16x16x32_bf16 v[124:127], v[166:169], v[218:221], v[124:127]
	v_mfma_f32_16x16x32_bf16 v[68:71], v[214:217], v[218:221], v[68:71]
	s_waitcnt lgkmcnt(1)
	v_mfma_f32_16x16x32_bf16 v[132:135], v[162:165], v[222:225], v[132:135]
	v_mfma_f32_16x16x32_bf16 v[84:87], v[214:217], v[222:225], v[84:87]
	s_waitcnt lgkmcnt(0)
	v_mfma_f32_16x16x32_bf16 v[100:103], v[158:161], v[226:229], v[100:103]
	v_mfma_f32_16x16x32_bf16 v[150:153], v[166:169], v[226:229], v[150:153]
	v_mfma_f32_16x16x32_bf16 v[154:157], v[214:217], v[226:229], v[154:157]
	v_mfma_f32_16x16x32_bf16 v[128:131], v[158:161], v[222:225], v[128:131]
	v_mfma_f32_16x16x32_bf16 v[136:139], v[166:169], v[222:225], v[136:139]
	v_mfma_f32_16x16x32_bf16 v[140:143], v[162:165], v[226:229], v[140:143]
	s_add_u32 s46, s0, 0x200
	s_addc_u32 s47, s1, 0
	s_add_u32 s48, s14, 0x200
	s_waitcnt vmcnt(0)
	s_barrier
	s_addc_u32 s49, s15, 0
	s_mov_b32 s45, 0x280
	ds_read_b128 v[158:161], v8
	ds_read_b128 v[162:165], v12
	s_mov_b32 m0, s27
	s_nop 0
	global_load_lds_dwordx4 v0, s[46:47]
	ds_read_b128 v[166:169], v9
	s_mov_b32 m0, s28
	s_nop 0
	global_load_lds_dwordx4 v0, s[48:49]
	ds_read_b128 v[178:181], v13
	ds_read_b128 v[214:217], v11
	s_mov_b32 m0, s29
	s_nop 0
	global_load_lds_dwordx4 v2, s[46:47]
	ds_read_b128 v[218:221], v10
	ds_read_b128 v[222:225], v14
	ds_read_b128 v[226:229], v15
	s_branch .Lmy_rot_r_r6b
.Lmy_rr_r6b:
	ds_read_b128 v[158:161], v8
	ds_read_b128 v[162:165], v12
	s_mov_b32 m0, s27
	v_mfma_f32_16x16x32_bf16 v[128:131], v[166:169], v[222:225], v[128:131]
	global_load_lds_dwordx4 v0, s[46:47]
	v_mfma_f32_16x16x32_bf16 v[100:103], v[166:169], v[226:229], v[100:103]
	ds_read_b128 v[166:169], v9
	v_mfma_f32_16x16x32_bf16 v[132:135], v[178:181], v[222:225], v[132:135]
	s_mov_b32 m0, s28
	v_mfma_f32_16x16x32_bf16 v[140:143], v[178:181], v[226:229], v[140:143]
	global_load_lds_dwordx4 v0, s[48:49]
	ds_read_b128 v[178:181], v13
	v_mfma_f32_16x16x32_bf16 v[136:139], v[214:217], v[222:225], v[136:139]
	v_mfma_f32_16x16x32_bf16 v[150:153], v[214:217], v[226:229], v[150:153]
	ds_read_b128 v[214:217], v11
	s_mov_b32 m0, s29
	v_mfma_f32_16x16x32_bf16 v[84:87], v[218:221], v[222:225], v[84:87]
	global_load_lds_dwordx4 v2, s[46:47]
	v_mfma_f32_16x16x32_bf16 v[154:157], v[218:221], v[226:229], v[154:157]
	ds_read_b128 v[218:221], v10
	ds_read_b128 v[222:225], v14
	ds_read_b128 v[226:229], v15
.Lmy_rot_r_r6b:
	s_waitcnt lgkmcnt(6)
	v_mfma_f32_16x16x32_bf16 v[40:43], v[158:161], v[162:165], v[40:43]
	s_waitcnt lgkmcnt(5)
	s_mov_b32 m0, s30
	v_mfma_f32_16x16x32_bf16 v[44:47], v[166:169], v[162:165], v[44:47]
	global_load_lds_dwordx4 v2, s[48:49]
	s_waitcnt lgkmcnt(4)
	v_mfma_f32_16x16x32_bf16 v[56:59], v[158:161], v[178:181], v[56:59]
	v_mfma_f32_16x16x32_bf16 v[60:63], v[166:169], v[178:181], v[60:63]
	s_waitcnt lgkmcnt(3)
	s_mov_b32 m0, s31
	v_mfma_f32_16x16x32_bf16 v[48:51], v[214:217], v[162:165], v[48:51]
	global_load_lds_dwordx4 v4, s[46:47]
	v_mfma_f32_16x16x32_bf16 v[64:67], v[214:217], v[178:181], v[64:67]
	s_waitcnt lgkmcnt(2)
	v_mfma_f32_16x16x32_bf16 v[174:177], v[218:221], v[162:165], v[174:177]
	ds_read_b128 v[162:165], v16
	s_mov_b32 m0, s34
	v_mfma_f32_16x16x32_bf16 v[170:173], v[218:221], v[178:181], v[170:173]
	global_load_lds_dwordx4 v4, s[48:49]
	ds_read_b128 v[178:181], v17
	s_waitcnt lgkmcnt(3)
	v_mfma_f32_16x16x32_bf16 v[72:75], v[158:161], v[222:225], v[72:75]
	v_mfma_f32_16x16x32_bf16 v[76:79], v[166:169], v[222:225], v[76:79]
	s_mov_b32 m0, s35
	v_mfma_f32_16x16x32_bf16 v[80:83], v[214:217], v[222:225], v[80:83]
	global_load_lds_dwordx4 v146, s[46:47]
	v_mfma_f32_16x16x32_bf16 v[32:35], v[218:221], v[222:225], v[32:35]
	ds_read_b128 v[222:225], v18
	s_waitcnt lgkmcnt(3)
	v_mfma_f32_16x16x32_bf16 v[88:91], v[158:161], v[226:229], v[88:91]
	s_mov_b32 m0, s36
	v_mfma_f32_16x16x32_bf16 v[92:95], v[166:169], v[226:229], v[92:95]
	global_load_lds_dwordx4 v146, s[48:49]
	v_mfma_f32_16x16x32_bf16 v[96:99], v[214:217], v[226:229], v[96:99]
	v_mfma_f32_16x16x32_bf16 v[36:39], v[218:221], v[226:229], v[36:39]
	ds_read_b128 v[226:229], v19
	s_waitcnt lgkmcnt(3)
	v_mfma_f32_16x16x32_bf16 v[108:111], v[166:169], v[162:165], v[108:111]
	s_waitcnt lgkmcnt(2)
	v_mfma_f32_16x16x32_bf16 v[120:123], v[166:169], v[178:181], v[120:123]
	s_waitcnt lgkmcnt(1)
	v_mfma_f32_16x16x32_bf16 v[132:135], v[166:169], v[222:225], v[132:135]
	s_waitcnt lgkmcnt(0)
	v_mfma_f32_16x16x32_bf16 v[140:143], v[166:169], v[226:229], v[140:143]
	ds_read_b128 v[166:169], v20
	v_mfma_f32_16x16x32_bf16 v[104:107], v[158:161], v[162:165], v[104:107]
	v_mfma_f32_16x16x32_bf16 v[116:119], v[158:161], v[178:181], v[116:119]
	v_mfma_f32_16x16x32_bf16 v[128:131], v[158:161], v[222:225], v[128:131]
	v_mfma_f32_16x16x32_bf16 v[100:103], v[158:161], v[226:229], v[100:103]
	ds_read_b128 v[158:161], v24
	v_mfma_f32_16x16x32_bf16 v[124:127], v[214:217], v[178:181], v[124:127]
	v_mfma_f32_16x16x32_bf16 v[68:71], v[218:221], v[178:181], v[68:71]
	ds_read_b128 v[178:181], v21
	v_mfma_f32_16x16x32_bf16 v[112:115], v[214:217], v[162:165], v[112:115]
	v_mfma_f32_16x16x32_bf16 v[52:55], v[218:221], v[162:165], v[52:55]
	ds_read_b128 v[162:165], v25
	v_mfma_f32_16x16x32_bf16 v[136:139], v[214:217], v[222:225], v[136:139]
	v_mfma_f32_16x16x32_bf16 v[84:87], v[218:221], v[222:225], v[84:87]
	ds_read_b128 v[222:225], v26
	v_mfma_f32_16x16x32_bf16 v[150:153], v[214:217], v[226:229], v[150:153]
	ds_read_b128 v[214:217], v23
	v_mfma_f32_16x16x32_bf16 v[154:157], v[218:221], v[226:229], v[154:157]
	ds_read_b128 v[218:221], v22
	ds_read_b128 v[226:229], v27
	s_waitcnt lgkmcnt(6)
	v_mfma_f32_16x16x32_bf16 v[40:43], v[166:169], v[158:161], v[40:43]
	s_waitcnt lgkmcnt(5)
	v_mfma_f32_16x16x32_bf16 v[44:47], v[178:181], v[158:161], v[44:47]
	s_waitcnt lgkmcnt(4)
	v_mfma_f32_16x16x32_bf16 v[56:59], v[166:169], v[162:165], v[56:59]
	v_mfma_f32_16x16x32_bf16 v[60:63], v[178:181], v[162:165], v[60:63]
	s_waitcnt lgkmcnt(3)
	v_mfma_f32_16x16x32_bf16 v[72:75], v[166:169], v[222:225], v[72:75]
	v_mfma_f32_16x16x32_bf16 v[76:79], v[178:181], v[222:225], v[76:79]
	s_waitcnt lgkmcnt(2)
	v_mfma_f32_16x16x32_bf16 v[48:51], v[214:217], v[158:161], v[48:51]
	s_waitcnt lgkmcnt(1)
	v_mfma_f32_16x16x32_bf16 v[174:177], v[218:221], v[158:161], v[174:177]
	ds_read_b128 v[158:161], v28
	v_mfma_f32_16x16x32_bf16 v[64:67], v[214:217], v[162:165], v[64:67]
	v_mfma_f32_16x16x32_bf16 v[170:173], v[218:221], v[162:165], v[170:173]
	ds_read_b128 v[162:165], v29
	v_mfma_f32_16x16x32_bf16 v[80:83], v[214:217], v[222:225], v[80:83]
	v_mfma_f32_16x16x32_bf16 v[32:35], v[218:221], v[222:225], v[32:35]
	ds_read_b128 v[222:225], v30
	s_waitcnt lgkmcnt(3)
	v_mfma_f32_16x16x32_bf16 v[88:91], v[166:169], v[226:229], v[88:91]
	v_mfma_f32_16x16x32_bf16 v[92:95], v[178:181], v[226:229], v[92:95]
	v_mfma_f32_16x16x32_bf16 v[96:99], v[214:217], v[226:229], v[96:99]
	v_mfma_f32_16x16x32_bf16 v[36:39], v[218:221], v[226:229], v[36:39]
	ds_read_b128 v[226:229], v31
	s_waitcnt lgkmcnt(3)
	v_mfma_f32_16x16x32_bf16 v[104:107], v[166:169], v[158:161], v[104:107]
	v_mfma_f32_16x16x32_bf16 v[108:111], v[178:181], v[158:161], v[108:111]
	v_mfma_f32_16x16x32_bf16 v[112:115], v[214:217], v[158:161], v[112:115]
	v_mfma_f32_16x16x32_bf16 v[52:55], v[218:221], v[158:161], v[52:55]
	s_waitcnt lgkmcnt(2)
	v_mfma_f32_16x16x32_bf16 v[116:119], v[166:169], v[162:165], v[116:119]
	v_mfma_f32_16x16x32_bf16 v[120:123], v[178:181], v[162:165], v[120:123]
	v_mfma_f32_16x16x32_bf16 v[124:127], v[214:217], v[162:165], v[124:127]
	v_mfma_f32_16x16x32_bf16 v[68:71], v[218:221], v[162:165], v[68:71]
	s_add_u32 s46, s0, s45
	s_addc_u32 s47, s1, 0
	s_add_u32 s48, s14, s45
	s_addc_u32 s49, s15, 0
	s_add_u32 s45, s45, 0x80
	s_waitcnt vmcnt(0)
	s_waitcnt lgkmcnt(0)
	s_barrier
	ds_read_b128 v[158:161], v7 offset:32768
	ds_read_b128 v[162:165], v6
	s_mov_b32 m0, s38
	v_mfma_f32_16x16x32_bf16 v[128:131], v[166:169], v[222:225], v[128:131]
	global_load_lds_dwordx4 v0, s[46:47]
	v_mfma_f32_16x16x32_bf16 v[100:103], v[166:169], v[226:229], v[100:103]
	ds_read_b128 v[166:169], v7 offset:34816
	v_mfma_f32_16x16x32_bf16 v[132:135], v[178:181], v[222:225], v[132:135]
	s_mov_b32 m0, s37
	v_mfma_f32_16x16x32_bf16 v[140:143], v[178:181], v[226:229], v[140:143]
	global_load_lds_dwordx4 v0, s[48:49]
	ds_read_b128 v[178:181], v6 offset:2048
	v_mfma_f32_16x16x32_bf16 v[136:139], v[214:217], v[222:225], v[136:139]
	v_mfma_f32_16x16x32_bf16 v[150:153], v[214:217], v[226:229], v[150:153]
	ds_read_b128 v[214:217], v7 offset:36864
	s_mov_b32 m0, s39
	v_mfma_f32_16x16x32_bf16 v[84:87], v[218:221], v[222:225], v[84:87]
	global_load_lds_dwordx4 v2, s[46:47]
	v_mfma_f32_16x16x32_bf16 v[154:157], v[218:221], v[226:229], v[154:157]
	ds_read_b128 v[218:221], v7 offset:38912
	ds_read_b128 v[222:225], v6 offset:4096
	ds_read_b128 v[226:229], v6 offset:6144
	s_waitcnt lgkmcnt(6)
	v_mfma_f32_16x16x32_bf16 v[40:43], v[158:161], v[162:165], v[40:43]
	s_waitcnt lgkmcnt(5)
	s_mov_b32 m0, s40
	v_mfma_f32_16x16x32_bf16 v[44:47], v[166:169], v[162:165], v[44:47]
	global_load_lds_dwordx4 v2, s[48:49]
	s_waitcnt lgkmcnt(4)
	v_mfma_f32_16x16x32_bf16 v[56:59], v[158:161], v[178:181], v[56:59]
	v_mfma_f32_16x16x32_bf16 v[60:63], v[166:169], v[178:181], v[60:63]
	s_waitcnt lgkmcnt(3)
	s_mov_b32 m0, s41
	v_mfma_f32_16x16x32_bf16 v[48:51], v[214:217], v[162:165], v[48:51]
	global_load_lds_dwordx4 v4, s[46:47]
	v_mfma_f32_16x16x32_bf16 v[64:67], v[214:217], v[178:181], v[64:67]
	s_waitcnt lgkmcnt(2)
	v_mfma_f32_16x16x32_bf16 v[174:177], v[218:221], v[162:165], v[174:177]
	ds_read_b128 v[162:165], v6 offset:8192
	s_mov_b32 m0, s42
	v_mfma_f32_16x16x32_bf16 v[170:173], v[218:221], v[178:181], v[170:173]
	global_load_lds_dwordx4 v4, s[48:49]
	ds_read_b128 v[178:181], v6 offset:10240
	s_waitcnt lgkmcnt(3)
	v_mfma_f32_16x16x32_bf16 v[72:75], v[158:161], v[222:225], v[72:75]
	v_mfma_f32_16x16x32_bf16 v[76:79], v[166:169], v[222:225], v[76:79]
	s_mov_b32 m0, s43
	v_mfma_f32_16x16x32_bf16 v[80:83], v[214:217], v[222:225], v[80:83]
	global_load_lds_dwordx4 v146, s[46:47]
	v_mfma_f32_16x16x32_bf16 v[32:35], v[218:221], v[222:225], v[32:35]
	ds_read_b128 v[222:225], v6 offset:12288
	s_waitcnt lgkmcnt(3)
	v_mfma_f32_16x16x32_bf16 v[88:91], v[158:161], v[226:229], v[88:91]
	s_mov_b32 m0, s44
	v_mfma_f32_16x16x32_bf16 v[92:95], v[166:169], v[226:229], v[92:95]
	global_load_lds_dwordx4 v146, s[48:49]
	v_mfma_f32_16x16x32_bf16 v[96:99], v[214:217], v[226:229], v[96:99]
	v_mfma_f32_16x16x32_bf16 v[36:39], v[218:221], v[226:229], v[36:39]
	ds_read_b128 v[226:229], v6 offset:14336
	s_waitcnt lgkmcnt(3)
	v_mfma_f32_16x16x32_bf16 v[108:111], v[166:169], v[162:165], v[108:111]
	s_waitcnt lgkmcnt(2)
	v_mfma_f32_16x16x32_bf16 v[120:123], v[166:169], v[178:181], v[120:123]
	s_waitcnt lgkmcnt(1)
	v_mfma_f32_16x16x32_bf16 v[132:135], v[166:169], v[222:225], v[132:135]
	s_waitcnt lgkmcnt(0)
	v_mfma_f32_16x16x32_bf16 v[140:143], v[166:169], v[226:229], v[140:143]
	ds_read_b128 v[166:169], v7 offset:33792
	v_mfma_f32_16x16x32_bf16 v[104:107], v[158:161], v[162:165], v[104:107]
	v_mfma_f32_16x16x32_bf16 v[116:119], v[158:161], v[178:181], v[116:119]
	v_mfma_f32_16x16x32_bf16 v[128:131], v[158:161], v[222:225], v[128:131]
	v_mfma_f32_16x16x32_bf16 v[100:103], v[158:161], v[226:229], v[100:103]
	ds_read_b128 v[158:161], v6 offset:1024
	v_mfma_f32_16x16x32_bf16 v[124:127], v[214:217], v[178:181], v[124:127]
	v_mfma_f32_16x16x32_bf16 v[68:71], v[218:221], v[178:181], v[68:71]
	ds_read_b128 v[178:181], v7 offset:35840
	v_mfma_f32_16x16x32_bf16 v[112:115], v[214:217], v[162:165], v[112:115]
	v_mfma_f32_16x16x32_bf16 v[52:55], v[218:221], v[162:165], v[52:55]
	ds_read_b128 v[162:165], v6 offset:3072
	v_mfma_f32_16x16x32_bf16 v[136:139], v[214:217], v[222:225], v[136:139]
	v_mfma_f32_16x16x32_bf16 v[84:87], v[218:221], v[222:225], v[84:87]
	ds_read_b128 v[222:225], v6 offset:5120
	v_mfma_f32_16x16x32_bf16 v[150:153], v[214:217], v[226:229], v[150:153]
	ds_read_b128 v[214:217], v7 offset:37888
	v_mfma_f32_16x16x32_bf16 v[154:157], v[218:221], v[226:229], v[154:157]
	ds_read_b128 v[218:221], v7 offset:39936
	ds_read_b128 v[226:229], v6 offset:7168
	s_waitcnt lgkmcnt(6)
	v_mfma_f32_16x16x32_bf16 v[40:43], v[166:169], v[158:161], v[40:43]
	s_waitcnt lgkmcnt(5)
	v_mfma_f32_16x16x32_bf16 v[44:47], v[178:181], v[158:161], v[44:47]
	s_waitcnt lgkmcnt(4)
	v_mfma_f32_16x16x32_bf16 v[56:59], v[166:169], v[162:165], v[56:59]
	v_mfma_f32_16x16x32_bf16 v[60:63], v[178:181], v[162:165], v[60:63]
	s_waitcnt lgkmcnt(3)
	v_mfma_f32_16x16x32_bf16 v[72:75], v[166:169], v[222:225], v[72:75]
	v_mfma_f32_16x16x32_bf16 v[76:79], v[178:181], v[222:225], v[76:79]
	s_waitcnt lgkmcnt(2)
	v_mfma_f32_16x16x32_bf16 v[48:51], v[214:217], v[158:161], v[48:51]
	s_waitcnt lgkmcnt(1)
	v_mfma_f32_16x16x32_bf16 v[174:177], v[218:221], v[158:161], v[174:177]
	ds_read_b128 v[158:161], v6 offset:9216
	v_mfma_f32_16x16x32_bf16 v[64:67], v[214:217], v[162:165], v[64:67]
	v_mfma_f32_16x16x32_bf16 v[170:173], v[218:221], v[162:165], v[170:173]
	ds_read_b128 v[162:165], v6 offset:11264
	v_mfma_f32_16x16x32_bf16 v[80:83], v[214:217], v[222:225], v[80:83]
	v_mfma_f32_16x16x32_bf16 v[32:35], v[218:221], v[222:225], v[32:35]
	ds_read_b128 v[222:225], v6 offset:13312
	s_waitcnt lgkmcnt(3)
	v_mfma_f32_16x16x32_bf16 v[88:91], v[166:169], v[226:229], v[88:91]
	v_mfma_f32_16x16x32_bf16 v[92:95], v[178:181], v[226:229], v[92:95]
	v_mfma_f32_16x16x32_bf16 v[96:99], v[214:217], v[226:229], v[96:99]
	v_mfma_f32_16x16x32_bf16 v[36:39], v[218:221], v[226:229], v[36:39]
	ds_read_b128 v[226:229], v6 offset:15360
	s_waitcnt lgkmcnt(3)
	v_mfma_f32_16x16x32_bf16 v[104:107], v[166:169], v[158:161], v[104:107]
	v_mfma_f32_16x16x32_bf16 v[108:111], v[178:181], v[158:161], v[108:111]
	v_mfma_f32_16x16x32_bf16 v[112:115], v[214:217], v[158:161], v[112:115]
	v_mfma_f32_16x16x32_bf16 v[52:55], v[218:221], v[158:161], v[52:55]
	s_waitcnt lgkmcnt(2)
	v_mfma_f32_16x16x32_bf16 v[116:119], v[166:169], v[162:165], v[116:119]
	v_mfma_f32_16x16x32_bf16 v[120:123], v[178:181], v[162:165], v[120:123]
	v_mfma_f32_16x16x32_bf16 v[124:127], v[214:217], v[162:165], v[124:127]
	v_mfma_f32_16x16x32_bf16 v[68:71], v[218:221], v[162:165], v[68:71]
	s_add_u32 s46, s0, s45
	s_addc_u32 s47, s1, 0
	s_add_u32 s48, s14, s45
	s_addc_u32 s49, s15, 0
	s_add_u32 s45, s45, 0x80
	s_cmp_lg_u32 s45, 0x2f80
	s_waitcnt vmcnt(0)
	s_waitcnt lgkmcnt(0)
	s_barrier
	s_cbranch_scc1 .Lmy_rr_r6b
	v_mfma_f32_16x16x32_bf16 v[128:131], v[166:169], v[222:225], v[128:131]
	v_mfma_f32_16x16x32_bf16 v[100:103], v[166:169], v[226:229], v[100:103]
	v_mfma_f32_16x16x32_bf16 v[132:135], v[178:181], v[222:225], v[132:135]
	v_mfma_f32_16x16x32_bf16 v[140:143], v[178:181], v[226:229], v[140:143]
	v_mfma_f32_16x16x32_bf16 v[136:139], v[214:217], v[222:225], v[136:139]
	v_mfma_f32_16x16x32_bf16 v[150:153], v[214:217], v[226:229], v[150:153]
	v_mfma_f32_16x16x32_bf16 v[84:87], v[218:221], v[222:225], v[84:87]
	v_mfma_f32_16x16x32_bf16 v[154:157], v[218:221], v[226:229], v[154:157]
	s_nop 15
	s_nop 15
	v_lshl_add_u64 v[158:159], s[46:47], 0, v[0:1]
	s_mov_b32 s45, m0
	s_mov_b32 m0, s27
	s_nop 0
	global_load_lds_dwordx4 v[158:159], off
	s_mov_b32 m0, s45
	v_lshl_add_u64 v[158:159], s[48:49], 0, v[0:1]
	s_mov_b32 s45, m0
	s_mov_b32 m0, s28
	s_nop 0
	global_load_lds_dwordx4 v[158:159], off
	s_mov_b32 m0, s45
	v_lshl_add_u64 v[158:159], s[46:47], 0, v[2:3]
	s_mov_b32 s45, m0
	s_mov_b32 m0, s29
	s_nop 0
	global_load_lds_dwordx4 v[158:159], off
	s_mov_b32 m0, s45
	v_lshl_add_u64 v[158:159], s[48:49], 0, v[2:3]
	s_mov_b32 s45, m0
	s_mov_b32 m0, s30
	s_nop 0
	global_load_lds_dwordx4 v[158:159], off
	s_mov_b32 m0, s45
	v_lshl_add_u64 v[158:159], s[46:47], 0, v[4:5]
	s_mov_b32 s45, m0
	s_mov_b32 m0, s31
	s_nop 0
	global_load_lds_dwordx4 v[158:159], off
	s_mov_b32 m0, s45
	v_lshl_add_u64 v[158:159], s[48:49], 0, v[4:5]
	s_mov_b32 s45, m0
	s_mov_b32 m0, s34
	s_nop 0
	global_load_lds_dwordx4 v[158:159], off
	s_mov_b32 m0, s45
	v_lshl_add_u64 v[158:159], s[46:47], 0, v[146:147]
	s_mov_b32 s45, m0
	s_mov_b32 m0, s35
	s_nop 0
	global_load_lds_dwordx4 v[158:159], off
	s_mov_b32 m0, s45
	v_lshl_add_u64 v[158:159], s[48:49], 0, v[146:147]
	s_mov_b32 s45, m0
	s_mov_b32 m0, s36
	s_nop 0
	global_load_lds_dwordx4 v[158:159], off
	s_mov_b32 m0, s45
	ds_read_b128 v[158:161], v8
	ds_read_b128 v[162:165], v9
	ds_read_b128 v[166:169], v11
	ds_read_b128 v[214:217], v10
	ds_read_b128 v[178:181], v12
	ds_read_b128 v[218:221], v13
	ds_read_b128 v[222:225], v14
	ds_read_b128 v[226:229], v15
	s_waitcnt lgkmcnt(3)
	v_mfma_f32_16x16x32_bf16 v[40:43], v[158:161], v[178:181], v[40:43]
	v_mfma_f32_16x16x32_bf16 v[44:47], v[162:165], v[178:181], v[44:47]
	v_mfma_f32_16x16x32_bf16 v[48:51], v[166:169], v[178:181], v[48:51]
	v_mfma_f32_16x16x32_bf16 v[174:177], v[214:217], v[178:181], v[174:177]
	ds_read_b128 v[178:181], v16
	s_waitcnt lgkmcnt(3)
	v_mfma_f32_16x16x32_bf16 v[56:59], v[158:161], v[218:221], v[56:59]
	v_mfma_f32_16x16x32_bf16 v[60:63], v[162:165], v[218:221], v[60:63]
	v_mfma_f32_16x16x32_bf16 v[64:67], v[166:169], v[218:221], v[64:67]
	v_mfma_f32_16x16x32_bf16 v[170:173], v[214:217], v[218:221], v[170:173]
	ds_read_b128 v[218:221], v17
	s_waitcnt lgkmcnt(3)
	v_mfma_f32_16x16x32_bf16 v[72:75], v[158:161], v[222:225], v[72:75]
	v_mfma_f32_16x16x32_bf16 v[76:79], v[162:165], v[222:225], v[76:79]
	v_mfma_f32_16x16x32_bf16 v[80:83], v[166:169], v[222:225], v[80:83]
	v_mfma_f32_16x16x32_bf16 v[32:35], v[214:217], v[222:225], v[32:35]
	ds_read_b128 v[222:225], v18
	s_waitcnt lgkmcnt(3)
	v_mfma_f32_16x16x32_bf16 v[88:91], v[158:161], v[226:229], v[88:91]
	v_mfma_f32_16x16x32_bf16 v[92:95], v[162:165], v[226:229], v[92:95]
	v_mfma_f32_16x16x32_bf16 v[96:99], v[166:169], v[226:229], v[96:99]
	v_mfma_f32_16x16x32_bf16 v[36:39], v[214:217], v[226:229], v[36:39]
	ds_read_b128 v[226:229], v19
	s_waitcnt lgkmcnt(3)
	v_mfma_f32_16x16x32_bf16 v[104:107], v[158:161], v[178:181], v[104:107]
	v_mfma_f32_16x16x32_bf16 v[108:111], v[162:165], v[178:181], v[108:111]
	v_mfma_f32_16x16x32_bf16 v[112:115], v[166:169], v[178:181], v[112:115]
	v_mfma_f32_16x16x32_bf16 v[52:55], v[214:217], v[178:181], v[52:55]
	s_waitcnt lgkmcnt(2)
	v_mfma_f32_16x16x32_bf16 v[116:119], v[158:161], v[218:221], v[116:119]
	v_mfma_f32_16x16x32_bf16 v[120:123], v[162:165], v[218:221], v[120:123]
	v_mfma_f32_16x16x32_bf16 v[124:127], v[166:169], v[218:221], v[124:127]
	v_mfma_f32_16x16x32_bf16 v[68:71], v[214:217], v[218:221], v[68:71]
	s_waitcnt lgkmcnt(1)
	v_mfma_f32_16x16x32_bf16 v[132:135], v[162:165], v[222:225], v[132:135]
	v_mfma_f32_16x16x32_bf16 v[84:87], v[214:217], v[222:225], v[84:87]
	s_waitcnt lgkmcnt(0)
	v_mfma_f32_16x16x32_bf16 v[100:103], v[158:161], v[226:229], v[100:103]
	v_mfma_f32_16x16x32_bf16 v[150:153], v[166:169], v[226:229], v[150:153]
	v_mfma_f32_16x16x32_bf16 v[154:157], v[214:217], v[226:229], v[154:157]
	v_mfma_f32_16x16x32_bf16 v[128:131], v[158:161], v[222:225], v[128:131]
	v_mfma_f32_16x16x32_bf16 v[136:139], v[166:169], v[222:225], v[136:139]
	v_mfma_f32_16x16x32_bf16 v[140:143], v[162:165], v[226:229], v[140:143]
	ds_read_b128 v[158:161], v20
	ds_read_b128 v[162:165], v21
	ds_read_b128 v[166:169], v23
	ds_read_b128 v[214:217], v22
	ds_read_b128 v[178:181], v24
	ds_read_b128 v[218:221], v25
	ds_read_b128 v[222:225], v26
	ds_read_b128 v[226:229], v27
	s_waitcnt lgkmcnt(3)
	v_mfma_f32_16x16x32_bf16 v[40:43], v[158:161], v[178:181], v[40:43]
	v_mfma_f32_16x16x32_bf16 v[44:47], v[162:165], v[178:181], v[44:47]
	v_mfma_f32_16x16x32_bf16 v[48:51], v[166:169], v[178:181], v[48:51]
	v_mfma_f32_16x16x32_bf16 v[174:177], v[214:217], v[178:181], v[174:177]
	ds_read_b128 v[178:181], v28
	s_waitcnt lgkmcnt(3)
	v_mfma_f32_16x16x32_bf16 v[56:59], v[158:161], v[218:221], v[56:59]
	v_mfma_f32_16x16x32_bf16 v[60:63], v[162:165], v[218:221], v[60:63]
	v_mfma_f32_16x16x32_bf16 v[64:67], v[166:169], v[218:221], v[64:67]
	v_mfma_f32_16x16x32_bf16 v[170:173], v[214:217], v[218:221], v[170:173]
	ds_read_b128 v[218:221], v29
	s_waitcnt lgkmcnt(3)
	v_mfma_f32_16x16x32_bf16 v[72:75], v[158:161], v[222:225], v[72:75]
	v_mfma_f32_16x16x32_bf16 v[76:79], v[162:165], v[222:225], v[76:79]
	v_mfma_f32_16x16x32_bf16 v[80:83], v[166:169], v[222:225], v[80:83]
	v_mfma_f32_16x16x32_bf16 v[32:35], v[214:217], v[222:225], v[32:35]
	ds_read_b128 v[222:225], v30
	s_waitcnt lgkmcnt(3)
	v_mfma_f32_16x16x32_bf16 v[88:91], v[158:161], v[226:229], v[88:91]
	v_mfma_f32_16x16x32_bf16 v[92:95], v[162:165], v[226:229], v[92:95]
	v_mfma_f32_16x16x32_bf16 v[96:99], v[166:169], v[226:229], v[96:99]
	v_mfma_f32_16x16x32_bf16 v[36:39], v[214:217], v[226:229], v[36:39]
	ds_read_b128 v[226:229], v31
	s_waitcnt lgkmcnt(3)
	v_mfma_f32_16x16x32_bf16 v[104:107], v[158:161], v[178:181], v[104:107]
	v_mfma_f32_16x16x32_bf16 v[108:111], v[162:165], v[178:181], v[108:111]
	v_mfma_f32_16x16x32_bf16 v[112:115], v[166:169], v[178:181], v[112:115]
	v_mfma_f32_16x16x32_bf16 v[52:55], v[214:217], v[178:181], v[52:55]
	s_waitcnt lgkmcnt(2)
	v_mfma_f32_16x16x32_bf16 v[116:119], v[158:161], v[218:221], v[116:119]
	v_mfma_f32_16x16x32_bf16 v[120:123], v[162:165], v[218:221], v[120:123]
	v_mfma_f32_16x16x32_bf16 v[124:127], v[166:169], v[218:221], v[124:127]
	v_mfma_f32_16x16x32_bf16 v[68:71], v[214:217], v[218:221], v[68:71]
	s_waitcnt lgkmcnt(1)
	v_mfma_f32_16x16x32_bf16 v[132:135], v[162:165], v[222:225], v[132:135]
	v_mfma_f32_16x16x32_bf16 v[84:87], v[214:217], v[222:225], v[84:87]
	s_waitcnt lgkmcnt(0)
	v_mfma_f32_16x16x32_bf16 v[100:103], v[158:161], v[226:229], v[100:103]
	v_mfma_f32_16x16x32_bf16 v[150:153], v[166:169], v[226:229], v[150:153]
	v_mfma_f32_16x16x32_bf16 v[154:157], v[214:217], v[226:229], v[154:157]
	v_mfma_f32_16x16x32_bf16 v[128:131], v[158:161], v[222:225], v[128:131]
	v_mfma_f32_16x16x32_bf16 v[136:139], v[166:169], v[222:225], v[136:139]
	v_mfma_f32_16x16x32_bf16 v[140:143], v[162:165], v[226:229], v[140:143]
	s_add_u32 s0, s0, 0x2f80
	s_addc_u32 s1, s1, 0
	s_add_u32 s14, s14, 0x2f80
	s_waitcnt vmcnt(0)
	s_barrier
	s_addc_u32 s15, s15, 0
	v_lshl_add_u64 v[158:159], s[0:1], 0, v[0:1]
	s_mov_b32 s45, m0
	s_mov_b32 m0, s38
	s_nop 0
	global_load_lds_dwordx4 v[158:159], off
	s_mov_b32 m0, s45
	v_lshl_add_u64 v[158:159], s[14:15], 0, v[0:1]
	s_mov_b32 s38, m0
	s_mov_b32 m0, s37
	s_nop 0
	global_load_lds_dwordx4 v[158:159], off
	s_mov_b32 m0, s38
	v_lshl_add_u64 v[158:159], s[0:1], 0, v[2:3]
	s_mov_b32 s37, m0
	s_mov_b32 m0, s39
	s_nop 0
	global_load_lds_dwordx4 v[158:159], off
	s_mov_b32 m0, s37
	v_lshl_add_u64 v[158:159], s[14:15], 0, v[2:3]
	s_mov_b32 s37, m0
	s_mov_b32 m0, s40
	s_nop 0
	global_load_lds_dwordx4 v[158:159], off
	s_mov_b32 m0, s37
	v_lshl_add_u64 v[158:159], s[0:1], 0, v[4:5]
	s_mov_b32 s37, m0
	s_mov_b32 m0, s41
	s_nop 0
	global_load_lds_dwordx4 v[158:159], off
	s_mov_b32 m0, s37
	v_lshl_add_u64 v[158:159], s[14:15], 0, v[4:5]
	s_mov_b32 s37, m0
	s_mov_b32 m0, s42
	s_nop 0
	global_load_lds_dwordx4 v[158:159], off
	s_mov_b32 m0, s37
	v_lshl_add_u64 v[158:159], s[0:1], 0, v[146:147]
	s_mov_b32 s0, m0
	s_mov_b32 m0, s43
	s_nop 0
	global_load_lds_dwordx4 v[158:159], off
	s_mov_b32 m0, s0
	v_lshl_add_u64 v[158:159], s[14:15], 0, v[146:147]
	s_mov_b32 s0, m0
	s_mov_b32 m0, s44
	s_nop 0
	global_load_lds_dwordx4 v[158:159], off
	s_mov_b32 m0, s0
	ds_read_b128 v[158:161], v7 offset:32768
	ds_read_b128 v[162:165], v7 offset:34816
	ds_read_b128 v[166:169], v7 offset:36864
	ds_read_b128 v[214:217], v7 offset:38912
	ds_read_b128 v[178:181], v6
	ds_read_b128 v[218:221], v6 offset:2048
	ds_read_b128 v[222:225], v6 offset:4096
	ds_read_b128 v[226:229], v6 offset:6144
	s_waitcnt lgkmcnt(3)
	v_mfma_f32_16x16x32_bf16 v[40:43], v[158:161], v[178:181], v[40:43]
	v_mfma_f32_16x16x32_bf16 v[44:47], v[162:165], v[178:181], v[44:47]
	v_mfma_f32_16x16x32_bf16 v[48:51], v[166:169], v[178:181], v[48:51]
	v_mfma_f32_16x16x32_bf16 v[174:177], v[214:217], v[178:181], v[174:177]
	ds_read_b128 v[178:181], v6 offset:8192
	s_waitcnt lgkmcnt(3)
	v_mfma_f32_16x16x32_bf16 v[56:59], v[158:161], v[218:221], v[56:59]
	v_mfma_f32_16x16x32_bf16 v[60:63], v[162:165], v[218:221], v[60:63]
	v_mfma_f32_16x16x32_bf16 v[64:67], v[166:169], v[218:221], v[64:67]
	v_mfma_f32_16x16x32_bf16 v[170:173], v[214:217], v[218:221], v[170:173]
	ds_read_b128 v[218:221], v6 offset:10240
	s_waitcnt lgkmcnt(3)
	v_mfma_f32_16x16x32_bf16 v[72:75], v[158:161], v[222:225], v[72:75]
	v_mfma_f32_16x16x32_bf16 v[76:79], v[162:165], v[222:225], v[76:79]
	v_mfma_f32_16x16x32_bf16 v[80:83], v[166:169], v[222:225], v[80:83]
	v_mfma_f32_16x16x32_bf16 v[32:35], v[214:217], v[222:225], v[32:35]
	ds_read_b128 v[222:225], v6 offset:12288
	s_waitcnt lgkmcnt(3)
	v_mfma_f32_16x16x32_bf16 v[88:91], v[158:161], v[226:229], v[88:91]
	v_mfma_f32_16x16x32_bf16 v[92:95], v[162:165], v[226:229], v[92:95]
	v_mfma_f32_16x16x32_bf16 v[96:99], v[166:169], v[226:229], v[96:99]
	v_mfma_f32_16x16x32_bf16 v[36:39], v[214:217], v[226:229], v[36:39]
	ds_read_b128 v[226:229], v6 offset:14336
	s_waitcnt lgkmcnt(3)
	v_mfma_f32_16x16x32_bf16 v[104:107], v[158:161], v[178:181], v[104:107]
	v_mfma_f32_16x16x32_bf16 v[108:111], v[162:165], v[178:181], v[108:111]
	v_mfma_f32_16x16x32_bf16 v[112:115], v[166:169], v[178:181], v[112:115]
	v_mfma_f32_16x16x32_bf16 v[52:55], v[214:217], v[178:181], v[52:55]
	s_waitcnt lgkmcnt(2)
	v_mfma_f32_16x16x32_bf16 v[116:119], v[158:161], v[218:221], v[116:119]
	v_mfma_f32_16x16x32_bf16 v[120:123], v[162:165], v[218:221], v[120:123]
	v_mfma_f32_16x16x32_bf16 v[124:127], v[166:169], v[218:221], v[124:127]
	v_mfma_f32_16x16x32_bf16 v[68:71], v[214:217], v[218:221], v[68:71]
	s_waitcnt lgkmcnt(1)
	v_mfma_f32_16x16x32_bf16 v[132:135], v[162:165], v[222:225], v[132:135]
	v_mfma_f32_16x16x32_bf16 v[84:87], v[214:217], v[222:225], v[84:87]
	s_waitcnt lgkmcnt(0)
	v_mfma_f32_16x16x32_bf16 v[100:103], v[158:161], v[226:229], v[100:103]
	v_mfma_f32_16x16x32_bf16 v[150:153], v[166:169], v[226:229], v[150:153]
	v_mfma_f32_16x16x32_bf16 v[154:157], v[214:217], v[226:229], v[154:157]
	v_mfma_f32_16x16x32_bf16 v[128:131], v[158:161], v[222:225], v[128:131]
	v_mfma_f32_16x16x32_bf16 v[136:139], v[166:169], v[222:225], v[136:139]
	v_mfma_f32_16x16x32_bf16 v[140:143], v[162:165], v[226:229], v[140:143]
	ds_read_b128 v[158:161], v7 offset:33792
	ds_read_b128 v[162:165], v7 offset:35840
	ds_read_b128 v[166:169], v7 offset:37888
	ds_read_b128 v[214:217], v7 offset:39936
	ds_read_b128 v[178:181], v6 offset:1024
	ds_read_b128 v[218:221], v6 offset:3072
	ds_read_b128 v[222:225], v6 offset:5120
	ds_read_b128 v[226:229], v6 offset:7168
	s_waitcnt lgkmcnt(3)
	v_mfma_f32_16x16x32_bf16 v[40:43], v[158:161], v[178:181], v[40:43]
	v_mfma_f32_16x16x32_bf16 v[44:47], v[162:165], v[178:181], v[44:47]
	v_mfma_f32_16x16x32_bf16 v[48:51], v[166:169], v[178:181], v[48:51]
	v_mfma_f32_16x16x32_bf16 v[174:177], v[214:217], v[178:181], v[174:177]
	ds_read_b128 v[178:181], v6 offset:9216
	s_waitcnt lgkmcnt(3)
	v_mfma_f32_16x16x32_bf16 v[56:59], v[158:161], v[218:221], v[56:59]
	v_mfma_f32_16x16x32_bf16 v[60:63], v[162:165], v[218:221], v[60:63]
	v_mfma_f32_16x16x32_bf16 v[64:67], v[166:169], v[218:221], v[64:67]
	v_mfma_f32_16x16x32_bf16 v[170:173], v[214:217], v[218:221], v[170:173]
	ds_read_b128 v[218:221], v6 offset:11264
	s_waitcnt lgkmcnt(3)
	v_mfma_f32_16x16x32_bf16 v[72:75], v[158:161], v[222:225], v[72:75]
	v_mfma_f32_16x16x32_bf16 v[76:79], v[162:165], v[222:225], v[76:79]
	v_mfma_f32_16x16x32_bf16 v[80:83], v[166:169], v[222:225], v[80:83]
	v_mfma_f32_16x16x32_bf16 v[32:35], v[214:217], v[222:225], v[32:35]
	ds_read_b128 v[222:225], v6 offset:13312
	s_waitcnt lgkmcnt(3)
	v_mfma_f32_16x16x32_bf16 v[88:91], v[158:161], v[226:229], v[88:91]
	v_mfma_f32_16x16x32_bf16 v[92:95], v[162:165], v[226:229], v[92:95]
	v_mfma_f32_16x16x32_bf16 v[96:99], v[166:169], v[226:229], v[96:99]
	v_mfma_f32_16x16x32_bf16 v[36:39], v[214:217], v[226:229], v[36:39]
	ds_read_b128 v[226:229], v6 offset:15360
	s_waitcnt lgkmcnt(3)
	v_mfma_f32_16x16x32_bf16 v[104:107], v[158:161], v[178:181], v[104:107]
	v_mfma_f32_16x16x32_bf16 v[108:111], v[162:165], v[178:181], v[108:111]
	v_mfma_f32_16x16x32_bf16 v[112:115], v[166:169], v[178:181], v[112:115]
	v_mfma_f32_16x16x32_bf16 v[52:55], v[214:217], v[178:181], v[52:55]
	s_waitcnt lgkmcnt(2)
	v_mfma_f32_16x16x32_bf16 v[116:119], v[158:161], v[218:221], v[116:119]
	v_mfma_f32_16x16x32_bf16 v[120:123], v[162:165], v[218:221], v[120:123]
	v_mfma_f32_16x16x32_bf16 v[124:127], v[166:169], v[218:221], v[124:127]
	v_mfma_f32_16x16x32_bf16 v[68:71], v[214:217], v[218:221], v[68:71]
	s_waitcnt lgkmcnt(1)
	v_mfma_f32_16x16x32_bf16 v[132:135], v[162:165], v[222:225], v[132:135]
	v_mfma_f32_16x16x32_bf16 v[84:87], v[214:217], v[222:225], v[84:87]
	s_waitcnt lgkmcnt(0)
	v_mfma_f32_16x16x32_bf16 v[100:103], v[158:161], v[226:229], v[100:103]
	v_mfma_f32_16x16x32_bf16 v[150:153], v[166:169], v[226:229], v[150:153]
	v_mfma_f32_16x16x32_bf16 v[154:157], v[214:217], v[226:229], v[154:157]
	v_mfma_f32_16x16x32_bf16 v[128:131], v[158:161], v[222:225], v[128:131]
	v_mfma_f32_16x16x32_bf16 v[136:139], v[166:169], v[222:225], v[136:139]
	v_mfma_f32_16x16x32_bf16 v[140:143], v[162:165], v[226:229], v[140:143]
	s_waitcnt vmcnt(0)
	s_barrier
	v_lshl_add_u64 v[6:7], s[16:17], 0, v[0:1]
	s_mov_b32 s0, m0
	s_mov_b32 m0, s27
	s_nop 0
	global_load_lds_dwordx4 v[6:7], off
	s_mov_b32 m0, s0
	v_lshl_add_u64 v[0:1], s[18:19], 0, v[0:1]
	s_mov_b32 s0, m0
	s_mov_b32 m0, s28
	s_nop 0
	global_load_lds_dwordx4 v[0:1], off
	s_mov_b32 m0, s0
	v_lshl_add_u64 v[0:1], s[16:17], 0, v[2:3]
	s_mov_b32 s0, m0
	s_mov_b32 m0, s29
	s_nop 0
	global_load_lds_dwordx4 v[0:1], off
	s_mov_b32 m0, s0
	v_lshl_add_u64 v[0:1], s[18:19], 0, v[2:3]
	s_mov_b32 s0, m0
	s_mov_b32 m0, s30
	s_nop 0
	global_load_lds_dwordx4 v[0:1], off
	s_mov_b32 m0, s0
	v_lshl_add_u64 v[0:1], s[16:17], 0, v[4:5]
	s_mov_b32 s0, m0
	s_mov_b32 m0, s31
	s_nop 0
	global_load_lds_dwordx4 v[0:1], off
	s_mov_b32 m0, s0
	v_lshl_add_u64 v[0:1], s[18:19], 0, v[4:5]
	s_mov_b32 s0, m0
	s_mov_b32 m0, s34
	s_nop 0
	global_load_lds_dwordx4 v[0:1], off
	s_mov_b32 m0, s0
	v_lshl_add_u64 v[0:1], s[16:17], 0, v[146:147]
	s_mov_b32 s0, m0
	s_mov_b32 m0, s35
	s_nop 0
	global_load_lds_dwordx4 v[0:1], off
	s_mov_b32 m0, s0
	v_lshl_add_u64 v[0:1], s[18:19], 0, v[146:147]
	s_mov_b32 s0, m0
	s_mov_b32 m0, s36
	s_nop 0
	global_load_lds_dwordx4 v[0:1], off
	s_mov_b32 m0, s0
	ds_read_b128 v[0:3], v8
	ds_read_b128 v[4:7], v9
	ds_read_b128 v[158:161], v11
	ds_read_b128 v[8:11], v10
	ds_read_b128 v[162:165], v12
	ds_read_b128 v[166:169], v13
	ds_read_b128 v[178:181], v14
	ds_read_b128 v[12:15], v15
	s_waitcnt lgkmcnt(3)
	v_mfma_f32_16x16x32_bf16 v[40:43], v[0:3], v[162:165], v[40:43]
	v_mfma_f32_16x16x32_bf16 v[44:47], v[4:7], v[162:165], v[44:47]
	v_mfma_f32_16x16x32_bf16 v[48:51], v[158:161], v[162:165], v[48:51]
	v_mfma_f32_16x16x32_bf16 v[162:165], v[8:11], v[162:165], v[174:177]
	s_nop 2
	ds_read_b128 v[174:177], v16
	s_waitcnt lgkmcnt(3)
	v_mfma_f32_16x16x32_bf16 v[56:59], v[0:3], v[166:169], v[56:59]
	v_mfma_f32_16x16x32_bf16 v[60:63], v[4:7], v[166:169], v[60:63]
	v_mfma_f32_16x16x32_bf16 v[64:67], v[158:161], v[166:169], v[64:67]
	v_mfma_f32_16x16x32_bf16 v[166:169], v[8:11], v[166:169], v[170:173]
	s_nop 2
	ds_read_b128 v[170:173], v17
	s_waitcnt lgkmcnt(3)
	v_mfma_f32_16x16x32_bf16 v[72:75], v[0:3], v[178:181], v[72:75]
	v_mfma_f32_16x16x32_bf16 v[76:79], v[4:7], v[178:181], v[76:79]
	v_mfma_f32_16x16x32_bf16 v[80:83], v[158:161], v[178:181], v[80:83]
	v_mfma_f32_16x16x32_bf16 v[32:35], v[8:11], v[178:181], v[32:35]
	ds_read_b128 v[178:181], v18
	s_waitcnt lgkmcnt(3)
	v_mfma_f32_16x16x32_bf16 v[214:217], v[0:3], v[12:15], v[88:91]
	v_mfma_f32_16x16x32_bf16 v[218:221], v[4:7], v[12:15], v[92:95]
	v_mfma_f32_16x16x32_bf16 v[222:225], v[158:161], v[12:15], v[96:99]
	v_mfma_f32_16x16x32_bf16 v[12:15], v[8:11], v[12:15], v[36:39]
	ds_read_b128 v[16:19], v19
	s_waitcnt lgkmcnt(3)
	v_mfma_f32_16x16x32_bf16 v[36:39], v[0:3], v[174:177], v[104:107]
	v_mfma_f32_16x16x32_bf16 v[226:229], v[4:7], v[174:177], v[108:111]
	v_mfma_f32_16x16x32_bf16 v[112:115], v[158:161], v[174:177], v[112:115]
	s_waitcnt lgkmcnt(2)
	v_mfma_f32_16x16x32_bf16 v[116:119], v[0:3], v[170:173], v[116:119]
	v_mfma_f32_16x16x32_bf16 v[120:123], v[4:7], v[170:173], v[120:123]
	v_mfma_f32_16x16x32_bf16 v[124:127], v[158:161], v[170:173], v[124:127]
	s_waitcnt lgkmcnt(1)
	v_mfma_f32_16x16x32_bf16 v[128:131], v[0:3], v[178:181], v[128:131]
	v_mfma_f32_16x16x32_bf16 v[132:135], v[4:7], v[178:181], v[132:135]
	s_waitcnt lgkmcnt(0)
	v_mfma_f32_16x16x32_bf16 v[0:3], v[0:3], v[16:19], v[100:103]
	v_mfma_f32_16x16x32_bf16 v[4:7], v[4:7], v[16:19], v[140:143]
	v_mfma_f32_16x16x32_bf16 v[140:143], v[158:161], v[16:19], v[150:153]
	v_mfma_f32_16x16x32_bf16 v[150:153], v[8:11], v[16:19], v[154:157]
	v_mfma_f32_16x16x32_bf16 v[174:177], v[8:11], v[174:177], v[52:55]
	v_mfma_f32_16x16x32_bf16 v[170:173], v[8:11], v[170:173], v[68:71]
	v_mfma_f32_16x16x32_bf16 v[136:139], v[158:161], v[178:181], v[136:139]
	v_mfma_f32_16x16x32_bf16 v[178:181], v[8:11], v[178:181], v[84:87]
	ds_read_b128 v[8:11], v20
	ds_read_b128 v[154:157], v21
	ds_read_b128 v[158:161], v23
	ds_read_b128 v[230:233], v22
	ds_read_b128 v[16:19], v24
	ds_read_b128 v[20:23], v25
	ds_read_b128 v[52:55], v26
	ds_read_b128 v[24:27], v27
	s_waitcnt lgkmcnt(3)
	v_mfma_f32_16x16x32_bf16 v[234:237], v[8:11], v[16:19], v[40:43]
	v_mfma_f32_16x16x32_bf16 v[238:241], v[154:157], v[16:19], v[44:47]
	v_mfma_f32_16x16x32_bf16 v[242:245], v[158:161], v[16:19], v[48:51]
	v_mfma_f32_16x16x32_bf16 v[162:165], v[230:233], v[16:19], v[162:165]
	ds_read_b128 v[16:19], v28
	s_waitcnt lgkmcnt(3)
	v_mfma_f32_16x16x32_bf16 v[108:111], v[8:11], v[20:23], v[56:59]
	v_mfma_f32_16x16x32_bf16 v[104:107], v[154:157], v[20:23], v[60:63]
	v_mfma_f32_16x16x32_bf16 v[100:103], v[158:161], v[20:23], v[64:67]
	v_mfma_f32_16x16x32_bf16 v[96:99], v[230:233], v[20:23], v[166:169]
	ds_read_b128 v[20:23], v29
	s_waitcnt lgkmcnt(3)
	v_mfma_f32_16x16x32_bf16 v[92:95], v[8:11], v[52:55], v[72:75]
	v_mfma_f32_16x16x32_bf16 v[88:91], v[154:157], v[52:55], v[76:79]
	v_mfma_f32_16x16x32_bf16 v[84:87], v[158:161], v[52:55], v[80:83]
	v_mfma_f32_16x16x32_bf16 v[80:83], v[230:233], v[52:55], v[32:35]
	ds_read_b128 v[166:169], v30
	s_waitcnt lgkmcnt(3)
	v_mfma_f32_16x16x32_bf16 v[76:79], v[8:11], v[24:27], v[214:217]
	v_mfma_f32_16x16x32_bf16 v[72:75], v[154:157], v[24:27], v[218:221]
	v_mfma_f32_16x16x32_bf16 v[68:71], v[158:161], v[24:27], v[222:225]
	v_mfma_f32_16x16x32_bf16 v[64:67], v[230:233], v[24:27], v[12:15]
	ds_read_b128 v[214:217], v31
	s_waitcnt lgkmcnt(3)
	v_mfma_f32_16x16x32_bf16 v[60:63], v[8:11], v[16:19], v[36:39]
	v_mfma_f32_16x16x32_bf16 v[56:59], v[154:157], v[16:19], v[226:229]
	v_mfma_f32_16x16x32_bf16 v[52:55], v[158:161], v[16:19], v[112:115]
	v_mfma_f32_16x16x32_bf16 v[48:51], v[230:233], v[16:19], v[174:177]
	s_waitcnt lgkmcnt(2)
	v_mfma_f32_16x16x32_bf16 v[44:47], v[8:11], v[20:23], v[116:119]
	v_mfma_f32_16x16x32_bf16 v[40:43], v[154:157], v[20:23], v[120:123]
	v_mfma_f32_16x16x32_bf16 v[36:39], v[158:161], v[20:23], v[124:127]
	v_mfma_f32_16x16x32_bf16 v[32:35], v[230:233], v[20:23], v[170:173]
	s_waitcnt lgkmcnt(1)
	v_mfma_f32_16x16x32_bf16 v[28:31], v[8:11], v[166:169], v[128:131]
	v_mfma_f32_16x16x32_bf16 v[24:27], v[154:157], v[166:169], v[132:135]
	v_mfma_f32_16x16x32_bf16 v[20:23], v[158:161], v[166:169], v[136:139]
	v_mfma_f32_16x16x32_bf16 v[16:19], v[230:233], v[166:169], v[178:181]
	s_waitcnt lgkmcnt(0)
	v_mfma_f32_16x16x32_bf16 v[12:15], v[8:11], v[214:217], v[0:3]
	v_mfma_f32_16x16x32_bf16 v[8:11], v[154:157], v[214:217], v[4:7]
	v_mfma_f32_16x16x32_bf16 v[4:7], v[158:161], v[214:217], v[140:143]
	v_mfma_f32_16x16x32_bf16 v[0:3], v[230:233], v[214:217], v[150:153]
	v_mov_b32_e32 v145, v184
	s_waitcnt vmcnt(0)
	s_barrier
	s_lshl_b32 s16, s13, 8
	s_lshl_b32 s14, s12, 8
	v_and_b32_e32 v151, 15, v145
	v_ashrrev_i32_e32 v112, 1, v145
	v_and_b32_e32 v153, 0xffffff80, v112
	v_or_b32_e32 v112, s16, v151
	v_add_u32_e32 v112, v112, v153
	v_ashrrev_i32_e32 v113, 31, v112
	v_lshlrev_b64 v[112:113], 13, v[112:113]
	v_bfe_u32 v150, v145, 6, 2
	v_lshl_add_u64 v[112:113], s[4:5], 0, v[112:113]
	s_ashr_i32 s15, s14, 31
	v_bfe_u32 v152, v145, 4, 2
	v_lshl_add_u64 v[112:113], s[14:15], 2, v[112:113]
	v_lshlrev_b32_e32 v146, 8, v150
	v_lshl_add_u64 v[112:113], v[112:113], 0, v[146:147]
	v_lshlrev_b32_e32 v146, 4, v152
	v_lshl_add_u64 v[154:155], v[112:113], 0, v[146:147]
	global_load_dwordx4 v[120:123], v[154:155], off offset:192
	global_load_dwordx4 v[128:131], v[154:155], off offset:128
	global_load_dwordx4 v[136:139], v[154:155], off offset:64
	global_load_dwordx4 v[140:143], v[154:155], off
	v_add_co_u32_e32 v112, vcc, s66, v154
	v_lshlrev_b32_e32 v158, 2, v152
	s_nop 0
	v_addc_co_u32_e32 v113, vcc, 0, v155, vcc
	global_load_dwordx4 v[132:135], v[112:113], off
	global_load_dwordx4 v[124:127], v[112:113], off offset:64
	global_load_dwordx4 v[116:119], v[112:113], off offset:128
	v_cmp_lt_i32_e32 vcc, v188, v186
	global_load_dwordx4 v[112:115], v[112:113], off offset:192
	v_cmp_eq_u32_e64 s[0:1], 0, v152
	v_cndmask_b32_e32 v146, v185, v188, vcc
	v_cmp_lt_i32_e32 vcc, v187, v186
	v_lshlrev_b32_e32 v149, 2, v146
	v_lshlrev_b32_e32 v157, 6, v150
	v_cndmask_b32_e32 v156, v185, v187, vcc
	v_lshlrev_b32_e32 v146, 2, v156
	v_or_b32_e32 v156, v153, v151
	v_add_u32_e32 v152, s16, v156
	v_ashrrev_i32_e32 v153, 31, v152
	v_lshl_or_b32 v182, v150, 10, v204
	v_or3_b32 v150, v157, s14, v158
	v_lshlrev_b64 v[158:159], 13, v[152:153]
	v_ashrrev_i32_e32 v151, 31, v150
	v_lshlrev_b64 v[160:161], 12, v[152:153]
	v_lshl_add_u64 v[158:159], s[4:5], 0, v[158:159]
	v_lshl_add_u64 v[160:161], s[6:7], 0, v[160:161]
	v_lshl_add_u64 v[166:167], v[150:151], 2, v[158:159]
	v_lshl_add_u64 v[168:169], v[150:151], 1, v[160:161]
	s_waitcnt vmcnt(7)
	v_pk_add_f32 v[158:159], v[162:163], v[120:121]
	s_waitcnt vmcnt(6)
	v_pk_add_f32 v[120:121], v[242:243], v[128:129]
	s_waitcnt vmcnt(5)
	v_pk_add_f32 v[128:129], v[238:239], v[136:137]
	s_waitcnt vmcnt(4)
	v_pk_add_f32 v[136:137], v[234:235], v[140:141]
	v_pk_add_f32 v[160:161], v[164:165], v[122:123]
	v_pk_add_f32 v[122:123], v[244:245], v[130:131]
	v_pk_add_f32 v[130:131], v[240:241], v[138:139]
	v_pk_add_f32 v[138:139], v[236:237], v[142:143]
	v_pk_mul_f32 v[172:173], v[128:129], v[128:129]
	v_pk_mul_f32 v[178:179], v[136:137], v[136:137]
	v_pk_mul_f32 v[162:163], v[120:121], v[120:121]
	v_pk_mul_f32 v[174:175], v[130:131], v[130:131]
	v_cvt_pk_bf16_f32 v176, v136, v137
	v_pk_mul_f32 v[180:181], v[138:139], v[138:139]
	global_store_dwordx4 v[166:167], v[136:139], off
	v_add_f32_e32 v153, v172, v173
	v_add_f32_e32 v157, v178, v179
	v_pk_mul_f32 v[136:137], v[158:159], v[158:159]
	v_pk_mul_f32 v[164:165], v[122:123], v[122:123]
	v_cvt_pk_bf16_f32 v177, v138, v139
	v_pk_mul_f32 v[138:139], v[160:161], v[160:161]
	v_add_f32_e32 v162, v162, v163
	v_add_f32_e32 v136, v136, v137
	v_add_f32_e32 v137, v174, v153
	v_add_f32_e32 v153, v180, v157
	v_add_f32_e32 v157, v164, v162
	v_add_f32_e32 v136, v138, v136
	v_add_f32_e32 v137, v175, v137
	v_add_f32_e32 v138, v181, v153
	v_add_f32_e32 v153, v165, v157
	v_add_f32_e32 v137, v138, v137
	v_add_f32_e32 v137, v137, v153
	v_add_f32_e32 v136, v139, v136
	v_add_f32_e32 v136, v137, v136
	ds_bpermute_b32 v137, v149, v136
	v_cvt_pk_bf16_f32 v170, v128, v129
	v_cvt_pk_bf16_f32 v171, v130, v131
	v_cvt_pk_bf16_f32 v142, v120, v121
	global_store_dwordx2 v[168:169], v[176:177], off
	global_store_dwordx4 v[166:167], v[128:131], off offset:64
	global_store_dwordx2 v[168:169], v[170:171], off offset:32
	global_store_dwordx4 v[166:167], v[120:123], off offset:128
	v_cvt_pk_bf16_f32 v140, v158, v159
	v_cvt_pk_bf16_f32 v141, v160, v161
	s_waitcnt lgkmcnt(0)
	v_add_f32_e32 v120, v136, v137
	ds_bpermute_b32 v121, v146, v120
	v_cvt_pk_bf16_f32 v143, v122, v123
	v_lshl_add_u32 v153, v156, 2, v182
	global_store_dwordx2 v[168:169], v[142:143], off offset:64
	global_store_dwordx4 v[166:167], v[158:161], off offset:192
	global_store_dwordx2 v[168:169], v[140:141], off offset:96
	s_and_saveexec_b64 s[14:15], s[0:1]
	s_cbranch_execz .LBB0_254
	s_waitcnt lgkmcnt(0)
	v_add_f32_e32 v120, v120, v121
	ds_write_b32 v153, v120

.LBB0_300:
	s_ashr_i32 s31, s30, 31
	s_lshl_b64 s[30:31], s[30:31], 20
	s_add_u32 s30, s38, s30
	s_addc_u32 s31, s39, s31
	s_ashr_i32 s5, s4, 31
	v_lshlrev_b32_e32 v3, 6, v1
	s_lshl_b64 s[4:5], s[4:5], 20
	v_and_b32_e32 v2, 48, v1
	v_and_b32_e32 v4, 0x3c0, v3
	v_lshlrev_b32_e32 v1, 2, v1
	s_add_u32 s34, s14, s4
	v_or_b32_e32 v5, v4, v2
	v_and_b32_e32 v1, 32, v1
	v_lshlrev_b32_e32 v0, 13, v0
	s_mov_b32 s4, 0x18000
	v_and_b32_e32 v135, 0x6000, v0
	v_bitop3_b32 v0, v5, s4, v1 bitop3:0xde
	s_mov_b32 s4, 0x10400
	s_addc_u32 s35, s15, s5
	v_bitop3_b32 v149, v5, s4, v1 bitop3:0xde
	s_lshl_b32 s4, s65, 2
	s_or_b32 s4, s4, s68
	s_lshl_b32 s5, s64, 2
	s_sub_i32 s4, s4, s5
	s_ashr_i32 s5, s4, 31
	s_waitcnt vmcnt(0)
	s_add_i32 s51, s1, 0x10000
	s_add_i32 s52, s1, 0x18000
	s_add_i32 s53, s1, 0x12000
	s_add_i32 s54, s1, 0x1a000
	s_add_i32 s55, s1, 0x14000
	s_add_i32 s58, s1, 0x1c000
	s_add_i32 s62, s1, 0x16000
	s_add_i32 s63, s1, 0x1e000
	s_lshl_b64 s[4:5], s[4:5], 20
	v_and_b32_e32 v136, 0xffffc000, v3
	s_add_u32 s64, s10, s4
	v_mov_b32_e32 v16, 0
	v_bitop3_b32 v134, v4, v1, v2 bitop3:0x36
	v_or_b32_e32 v137, 0x800, v136
	v_or_b32_e32 v138, 0x1000, v136
	v_or_b32_e32 v139, 0x1800, v136
	v_or_b32_e32 v140, 0x2000, v136
	v_or_b32_e32 v141, 0x2800, v136
	v_or_b32_e32 v142, 0x3000, v136
	v_or_b32_e32 v143, 0x3800, v136
	v_bitop3_b32 v145, v5, s33, v1 bitop3:0xde
	s_addc_u32 s65, s11, s5
	s_mov_b64 s[4:5], 0
	s_mov_b32 s68, 1
	v_add_u32_e32 v150, v0, v135
	v_mov_b32_e32 v17, v16
	v_mov_b32_e32 v18, v16
	v_mov_b32_e32 v19, v16
	v_mov_b32_e32 v20, v16
	v_mov_b32_e32 v21, v16
	v_mov_b32_e32 v22, v16
	v_mov_b32_e32 v23, v16
	v_mov_b32_e32 v24, v16
	v_mov_b32_e32 v25, v16
	v_mov_b32_e32 v26, v16
	v_mov_b32_e32 v27, v16
	v_mov_b32_e32 v28, v16
	v_mov_b32_e32 v29, v16
	v_mov_b32_e32 v30, v16
	v_mov_b32_e32 v31, v16
	v_mov_b32_e32 v32, v16
	v_mov_b32_e32 v33, v16
	v_mov_b32_e32 v34, v16
	v_mov_b32_e32 v35, v16
	v_mov_b32_e32 v36, v16
	v_mov_b32_e32 v37, v16
	v_mov_b32_e32 v38, v16
	v_mov_b32_e32 v39, v16
	v_mov_b32_e32 v40, v16
	v_mov_b32_e32 v41, v16
	v_mov_b32_e32 v42, v16
	v_mov_b32_e32 v43, v16
	v_mov_b32_e32 v44, v16
	v_mov_b32_e32 v45, v16
	v_mov_b32_e32 v46, v16
	v_mov_b32_e32 v47, v16
	v_mov_b32_e32 v48, v16
	v_mov_b32_e32 v49, v16
	v_mov_b32_e32 v50, v16
	v_mov_b32_e32 v51, v16
	v_mov_b32_e32 v52, v16
	v_mov_b32_e32 v53, v16
	v_mov_b32_e32 v54, v16
	v_mov_b32_e32 v55, v16
	v_mov_b32_e32 v56, v16
	v_mov_b32_e32 v57, v16
	v_mov_b32_e32 v58, v16
	v_mov_b32_e32 v59, v16
	v_mov_b32_e32 v60, v16
	v_mov_b32_e32 v61, v16
	v_mov_b32_e32 v62, v16
	v_mov_b32_e32 v63, v16
	v_mov_b32_e32 v64, v16
	v_mov_b32_e32 v65, v16
	v_mov_b32_e32 v66, v16
	v_mov_b32_e32 v67, v16
	v_mov_b32_e32 v68, v16
	v_mov_b32_e32 v69, v16
	v_mov_b32_e32 v70, v16
	v_mov_b32_e32 v71, v16
	v_mov_b32_e32 v72, v16
	v_mov_b32_e32 v73, v16
	v_mov_b32_e32 v74, v16
	v_mov_b32_e32 v75, v16
	v_mov_b32_e32 v76, v16
	v_mov_b32_e32 v77, v16
	v_mov_b32_e32 v78, v16
	v_mov_b32_e32 v79, v16
	v_mov_b32_e32 v80, v16
	v_mov_b32_e32 v81, v16
	v_mov_b32_e32 v82, v16
	v_mov_b32_e32 v83, v16
	v_mov_b32_e32 v84, v16
	v_mov_b32_e32 v85, v16
	v_mov_b32_e32 v86, v16
	v_mov_b32_e32 v87, v16
	v_mov_b32_e32 v88, v16
	v_mov_b32_e32 v89, v16
	v_mov_b32_e32 v90, v16
	v_mov_b32_e32 v91, v16
	v_mov_b32_e32 v92, v16
	v_mov_b32_e32 v93, v16
	v_mov_b32_e32 v94, v16
	v_mov_b32_e32 v95, v16
	v_mov_b32_e32 v96, v16
	v_mov_b32_e32 v97, v16
	v_mov_b32_e32 v98, v16
	v_mov_b32_e32 v99, v16
	v_mov_b32_e32 v100, v16
	v_mov_b32_e32 v101, v16
	v_mov_b32_e32 v102, v16
	v_mov_b32_e32 v103, v16
	v_mov_b32_e32 v104, v16
	v_mov_b32_e32 v105, v16
	v_mov_b32_e32 v106, v16
	v_mov_b32_e32 v107, v16
	v_mov_b32_e32 v108, v16
	v_mov_b32_e32 v109, v16
	v_mov_b32_e32 v110, v16
	v_mov_b32_e32 v111, v16
	v_mov_b32_e32 v112, v16
	v_mov_b32_e32 v113, v16
	v_mov_b32_e32 v114, v16
	v_mov_b32_e32 v115, v16
	v_mov_b32_e32 v116, v16
	v_mov_b32_e32 v117, v16
	v_mov_b32_e32 v118, v16
	v_mov_b32_e32 v119, v16
	v_mov_b32_e32 v120, v16
	v_mov_b32_e32 v121, v16
	v_mov_b32_e32 v122, v16
	v_mov_b32_e32 v123, v16
	v_mov_b32_e32 v124, v16
	v_mov_b32_e32 v125, v16
	v_mov_b32_e32 v126, v16
	v_mov_b32_e32 v127, v16
	v_mov_b32_e32 v12, v16
	v_mov_b32_e32 v13, v16
	v_mov_b32_e32 v14, v16
	v_mov_b32_e32 v15, v16
	v_mov_b32_e32 v8, v16
	v_mov_b32_e32 v9, v16
	v_mov_b32_e32 v10, v16
	v_mov_b32_e32 v11, v16
	v_mov_b32_e32 v4, v16
	v_mov_b32_e32 v5, v16
	v_mov_b32_e32 v6, v16
	v_mov_b32_e32 v7, v16
	v_mov_b32_e32 v0, v16
	v_mov_b32_e32 v1, v16
	v_mov_b32_e32 v2, v16
	v_mov_b32_e32 v3, v16
	s_waitcnt lgkmcnt(0)
	s_barrier
	s_add_u32 s69, s64, s4
	s_addc_u32 s74, s65, s5
	s_add_u32 s70, s69, 0x1b900080
	s_addc_u32 s71, s74, 0
	s_add_u32 s75, s2, s4
	s_addc_u32 s76, s3, s5
	s_add_u32 s72, s75, 0x80
	s_addc_u32 s73, s76, 0
	v_add_u32_e32 v151, v134, v135
	v_add_u32_e32 v189, v134, v136
	ds_read_b128 v[152:155], v151 offset:32768
	ds_read_b128 v[156:159], v189
	s_mov_b32 m0, s51
	s_nop 0
	global_load_lds_dwordx4 v128, s[70:71]
	ds_read_b128 v[160:163], v151 offset:34816
	s_mov_b32 m0, s52
	s_nop 0
	global_load_lds_dwordx4 v128, s[72:73]
	ds_read_b128 v[164:167], v189 offset:2048
	ds_read_b128 v[168:171], v151 offset:36864
	s_mov_b32 m0, s53
	s_nop 0
	global_load_lds_dwordx4 v130, s[70:71]
	ds_read_b128 v[172:175], v151 offset:38912
	ds_read_b128 v[176:179], v189 offset:4096
	ds_read_b128 v[180:183], v189 offset:6144
	s_branch .Lmy_rot_301
.LBB0_301:
	s_add_u32 s69, s64, s4
	s_addc_u32 s74, s65, s5
	s_add_u32 s70, s69, 0x1b900080
	s_addc_u32 s71, s74, 0
	s_add_u32 s75, s2, s4
	s_addc_u32 s76, s3, s5
	s_add_u32 s72, s75, 0x80
	s_addc_u32 s73, s76, 0
	v_add_u32_e32 v151, v134, v135
	v_add_u32_e32 v189, v134, v136
	ds_read_b128 v[152:155], v151 offset:32768
	ds_read_b128 v[156:159], v189
	s_mov_b32 m0, s51
	v_mfma_f32_16x16x32_bf16 v[28:31], v[160:163], v[176:179], v[28:31]
	global_load_lds_dwordx4 v128, s[70:71]
	v_mfma_f32_16x16x32_bf16 v[12:15], v[160:163], v[180:183], v[12:15]
	ds_read_b128 v[160:163], v151 offset:34816
	v_mfma_f32_16x16x32_bf16 v[24:27], v[164:167], v[176:179], v[24:27]
	s_mov_b32 m0, s52
	v_mfma_f32_16x16x32_bf16 v[8:11], v[164:167], v[180:183], v[8:11]
	global_load_lds_dwordx4 v128, s[72:73]
	ds_read_b128 v[164:167], v189 offset:2048
	v_mfma_f32_16x16x32_bf16 v[20:23], v[168:171], v[176:179], v[20:23]
	v_mfma_f32_16x16x32_bf16 v[4:7], v[168:171], v[180:183], v[4:7]
	ds_read_b128 v[168:171], v151 offset:36864
	s_mov_b32 m0, s53
	v_mfma_f32_16x16x32_bf16 v[16:19], v[172:175], v[176:179], v[16:19]
	global_load_lds_dwordx4 v130, s[70:71]
	v_mfma_f32_16x16x32_bf16 v[0:3], v[172:175], v[180:183], v[0:3]
	ds_read_b128 v[172:175], v151 offset:38912
	ds_read_b128 v[176:179], v189 offset:4096
	ds_read_b128 v[180:183], v189 offset:6144
.Lmy_rot_301:
	s_waitcnt lgkmcnt(6)
	v_mfma_f32_16x16x32_bf16 v[124:127], v[152:155], v[156:159], v[124:127]
	s_waitcnt lgkmcnt(5)
	s_mov_b32 m0, s54
	v_mfma_f32_16x16x32_bf16 v[120:123], v[160:163], v[156:159], v[120:123]
	global_load_lds_dwordx4 v130, s[72:73]
	s_waitcnt lgkmcnt(4)
	v_mfma_f32_16x16x32_bf16 v[108:111], v[152:155], v[164:167], v[108:111]
	v_mfma_f32_16x16x32_bf16 v[104:107], v[160:163], v[164:167], v[104:107]
	s_waitcnt lgkmcnt(3)
	s_mov_b32 m0, s55
	v_mfma_f32_16x16x32_bf16 v[116:119], v[168:171], v[156:159], v[116:119]
	global_load_lds_dwordx4 v132, s[70:71]
	v_mfma_f32_16x16x32_bf16 v[100:103], v[168:171], v[164:167], v[100:103]
	s_waitcnt lgkmcnt(2)
	v_mfma_f32_16x16x32_bf16 v[112:115], v[172:175], v[156:159], v[112:115]
	ds_read_b128 v[156:159], v189 offset:8192
	s_mov_b32 m0, s58
	v_mfma_f32_16x16x32_bf16 v[96:99], v[172:175], v[164:167], v[96:99]
	global_load_lds_dwordx4 v132, s[72:73]
	ds_read_b128 v[164:167], v189 offset:10240
	s_waitcnt lgkmcnt(3)
	v_mfma_f32_16x16x32_bf16 v[92:95], v[152:155], v[176:179], v[92:95]
	v_mfma_f32_16x16x32_bf16 v[88:91], v[160:163], v[176:179], v[88:91]
	s_mov_b32 m0, s62
	v_mfma_f32_16x16x32_bf16 v[84:87], v[168:171], v[176:179], v[84:87]
	global_load_lds_dwordx4 v146, s[70:71]
	v_mfma_f32_16x16x32_bf16 v[80:83], v[172:175], v[176:179], v[80:83]
	ds_read_b128 v[176:179], v189 offset:12288
	s_waitcnt lgkmcnt(3)
	v_mfma_f32_16x16x32_bf16 v[76:79], v[152:155], v[180:183], v[76:79]
	s_mov_b32 m0, s63
	v_mfma_f32_16x16x32_bf16 v[72:75], v[160:163], v[180:183], v[72:75]
	global_load_lds_dwordx4 v146, s[72:73]
	v_mfma_f32_16x16x32_bf16 v[68:71], v[168:171], v[180:183], v[68:71]
	v_mfma_f32_16x16x32_bf16 v[64:67], v[172:175], v[180:183], v[64:67]
	ds_read_b128 v[180:183], v189 offset:14336
	s_waitcnt lgkmcnt(3)
	v_mfma_f32_16x16x32_bf16 v[56:59], v[160:163], v[156:159], v[56:59]
	s_waitcnt lgkmcnt(2)
	v_mfma_f32_16x16x32_bf16 v[40:43], v[160:163], v[164:167], v[40:43]
	s_waitcnt lgkmcnt(1)
	v_mfma_f32_16x16x32_bf16 v[24:27], v[160:163], v[176:179], v[24:27]
	s_waitcnt lgkmcnt(0)
	v_mfma_f32_16x16x32_bf16 v[8:11], v[160:163], v[180:183], v[8:11]
	ds_read_b128 v[160:163], v151 offset:33792
	v_mfma_f32_16x16x32_bf16 v[60:63], v[152:155], v[156:159], v[60:63]
	v_mfma_f32_16x16x32_bf16 v[44:47], v[152:155], v[164:167], v[44:47]
	v_mfma_f32_16x16x32_bf16 v[28:31], v[152:155], v[176:179], v[28:31]
	v_mfma_f32_16x16x32_bf16 v[12:15], v[152:155], v[180:183], v[12:15]
	ds_read_b128 v[152:155], v189 offset:1024
	v_mfma_f32_16x16x32_bf16 v[36:39], v[168:171], v[164:167], v[36:39]
	v_mfma_f32_16x16x32_bf16 v[32:35], v[172:175], v[164:167], v[32:35]
	ds_read_b128 v[164:167], v151 offset:35840
	v_mfma_f32_16x16x32_bf16 v[52:55], v[168:171], v[156:159], v[52:55]
	v_mfma_f32_16x16x32_bf16 v[48:51], v[172:175], v[156:159], v[48:51]
	ds_read_b128 v[156:159], v189 offset:3072
	v_mfma_f32_16x16x32_bf16 v[20:23], v[168:171], v[176:179], v[20:23]
	v_mfma_f32_16x16x32_bf16 v[16:19], v[172:175], v[176:179], v[16:19]
	ds_read_b128 v[176:179], v189 offset:5120
	v_mfma_f32_16x16x32_bf16 v[4:7], v[168:171], v[180:183], v[4:7]
	ds_read_b128 v[168:171], v151 offset:37888
	v_mfma_f32_16x16x32_bf16 v[0:3], v[172:175], v[180:183], v[0:3]
	ds_read_b128 v[172:175], v151 offset:39936
	ds_read_b128 v[180:183], v189 offset:7168
	s_waitcnt lgkmcnt(6)
	v_mfma_f32_16x16x32_bf16 v[124:127], v[160:163], v[152:155], v[124:127]
	s_waitcnt lgkmcnt(5)
	v_mfma_f32_16x16x32_bf16 v[120:123], v[164:167], v[152:155], v[120:123]
	s_waitcnt lgkmcnt(4)
	v_mfma_f32_16x16x32_bf16 v[108:111], v[160:163], v[156:159], v[108:111]
	v_mfma_f32_16x16x32_bf16 v[104:107], v[164:167], v[156:159], v[104:107]
	s_waitcnt lgkmcnt(3)
	v_mfma_f32_16x16x32_bf16 v[92:95], v[160:163], v[176:179], v[92:95]
	v_mfma_f32_16x16x32_bf16 v[88:91], v[164:167], v[176:179], v[88:91]
	s_waitcnt lgkmcnt(2)
	v_mfma_f32_16x16x32_bf16 v[116:119], v[168:171], v[152:155], v[116:119]
	s_waitcnt lgkmcnt(1)
	v_mfma_f32_16x16x32_bf16 v[112:115], v[172:175], v[152:155], v[112:115]
	ds_read_b128 v[152:155], v189 offset:9216
	v_mfma_f32_16x16x32_bf16 v[100:103], v[168:171], v[156:159], v[100:103]
	v_mfma_f32_16x16x32_bf16 v[96:99], v[172:175], v[156:159], v[96:99]
	ds_read_b128 v[156:159], v189 offset:11264
	v_mfma_f32_16x16x32_bf16 v[84:87], v[168:171], v[176:179], v[84:87]
	v_mfma_f32_16x16x32_bf16 v[80:83], v[172:175], v[176:179], v[80:83]
	ds_read_b128 v[176:179], v189 offset:13312
	s_waitcnt lgkmcnt(3)
	v_mfma_f32_16x16x32_bf16 v[76:79], v[160:163], v[180:183], v[76:79]
	v_mfma_f32_16x16x32_bf16 v[72:75], v[164:167], v[180:183], v[72:75]
	v_mfma_f32_16x16x32_bf16 v[68:71], v[168:171], v[180:183], v[68:71]
	v_mfma_f32_16x16x32_bf16 v[64:67], v[172:175], v[180:183], v[64:67]
	ds_read_b128 v[180:183], v189 offset:15360
	s_waitcnt lgkmcnt(3)
	v_mfma_f32_16x16x32_bf16 v[60:63], v[160:163], v[152:155], v[60:63]
	v_mfma_f32_16x16x32_bf16 v[56:59], v[164:167], v[152:155], v[56:59]
	v_mfma_f32_16x16x32_bf16 v[52:55], v[168:171], v[152:155], v[52:55]
	v_mfma_f32_16x16x32_bf16 v[48:51], v[172:175], v[152:155], v[48:51]
	s_waitcnt lgkmcnt(2)
	v_mfma_f32_16x16x32_bf16 v[44:47], v[160:163], v[156:159], v[44:47]
	v_mfma_f32_16x16x32_bf16 v[40:43], v[164:167], v[156:159], v[40:43]
	v_mfma_f32_16x16x32_bf16 v[36:39], v[168:171], v[156:159], v[36:39]
	v_mfma_f32_16x16x32_bf16 v[32:35], v[172:175], v[156:159], v[32:35]
	s_add_u32 s69, s69, 0x1b900100
	s_addc_u32 s70, s74, 0
	s_add_u32 s72, s75, 0x100
	s_addc_u32 s73, s76, 0
	s_cmp_lt_u32 s68, 31
	s_cselect_b32 s71, s70, s31
	s_cselect_b32 s70, s69, s30
	s_waitcnt vmcnt(0)
	s_waitcnt lgkmcnt(0)
	s_barrier
	s_cselect_b32 s73, s73, s35
	s_cselect_b32 s72, s72, s34
	ds_read_b128 v[152:155], v150
	v_add_u32_e32 v151, v145, v136
	ds_read_b128 v[156:159], v151
	s_mov_b32 m0, s1
	v_mfma_f32_16x16x32_bf16 v[28:31], v[160:163], v[176:179], v[28:31]
	global_load_lds_dwordx4 v128, s[70:71]
	v_mfma_f32_16x16x32_bf16 v[12:15], v[160:163], v[180:183], v[12:15]
	ds_read_b128 v[160:163], v150 offset:2048
	v_mfma_f32_16x16x32_bf16 v[24:27], v[164:167], v[176:179], v[24:27]
	s_mov_b32 m0, s44
	v_mfma_f32_16x16x32_bf16 v[8:11], v[164:167], v[180:183], v[8:11]
	global_load_lds_dwordx4 v128, s[72:73]
	v_add_u32_e32 v151, v145, v137
	ds_read_b128 v[164:167], v151
	v_mfma_f32_16x16x32_bf16 v[20:23], v[168:171], v[176:179], v[20:23]
	v_mfma_f32_16x16x32_bf16 v[4:7], v[168:171], v[180:183], v[4:7]
	ds_read_b128 v[168:171], v150 offset:4096
	s_mov_b32 m0, s45
	v_mfma_f32_16x16x32_bf16 v[16:19], v[172:175], v[176:179], v[16:19]
	global_load_lds_dwordx4 v130, s[70:71]
	v_mfma_f32_16x16x32_bf16 v[0:3], v[172:175], v[180:183], v[0:3]
	ds_read_b128 v[172:175], v150 offset:6144
	v_add_u32_e32 v151, v145, v138
	ds_read_b128 v[176:179], v151
	v_add_u32_e32 v151, v145, v139
	ds_read_b128 v[180:183], v151
	s_waitcnt lgkmcnt(6)
	v_mfma_f32_16x16x32_bf16 v[124:127], v[152:155], v[156:159], v[124:127]
	s_waitcnt lgkmcnt(5)
	s_mov_b32 m0, s46
	v_mfma_f32_16x16x32_bf16 v[120:123], v[160:163], v[156:159], v[120:123]
	global_load_lds_dwordx4 v130, s[72:73]
	s_waitcnt lgkmcnt(4)
	v_mfma_f32_16x16x32_bf16 v[108:111], v[152:155], v[164:167], v[108:111]
	v_mfma_f32_16x16x32_bf16 v[104:107], v[160:163], v[164:167], v[104:107]
	s_waitcnt lgkmcnt(3)
	s_mov_b32 m0, s47
	v_mfma_f32_16x16x32_bf16 v[116:119], v[168:171], v[156:159], v[116:119]
	global_load_lds_dwordx4 v132, s[70:71]
	v_mfma_f32_16x16x32_bf16 v[100:103], v[168:171], v[164:167], v[100:103]
	s_waitcnt lgkmcnt(2)
	v_mfma_f32_16x16x32_bf16 v[112:115], v[172:175], v[156:159], v[112:115]
	v_add_u32_e32 v151, v145, v140
	ds_read_b128 v[156:159], v151
	s_mov_b32 m0, s48
	v_mfma_f32_16x16x32_bf16 v[96:99], v[172:175], v[164:167], v[96:99]
	global_load_lds_dwordx4 v132, s[72:73]
	v_add_u32_e32 v151, v145, v141
	ds_read_b128 v[164:167], v151
	s_waitcnt lgkmcnt(3)
	v_mfma_f32_16x16x32_bf16 v[92:95], v[152:155], v[176:179], v[92:95]
	v_mfma_f32_16x16x32_bf16 v[88:91], v[160:163], v[176:179], v[88:91]
	s_mov_b32 m0, s49
	v_mfma_f32_16x16x32_bf16 v[84:87], v[168:171], v[176:179], v[84:87]
	global_load_lds_dwordx4 v146, s[70:71]
	v_mfma_f32_16x16x32_bf16 v[80:83], v[172:175], v[176:179], v[80:83]
	v_add_u32_e32 v151, v145, v142
	ds_read_b128 v[176:179], v151
	s_waitcnt lgkmcnt(3)
	v_mfma_f32_16x16x32_bf16 v[76:79], v[152:155], v[180:183], v[76:79]
	s_mov_b32 m0, s50
	v_mfma_f32_16x16x32_bf16 v[72:75], v[160:163], v[180:183], v[72:75]
	global_load_lds_dwordx4 v146, s[72:73]
	v_mfma_f32_16x16x32_bf16 v[68:71], v[168:171], v[180:183], v[68:71]
	v_mfma_f32_16x16x32_bf16 v[64:67], v[172:175], v[180:183], v[64:67]
	v_add_u32_e32 v151, v145, v143
	ds_read_b128 v[180:183], v151
	s_waitcnt lgkmcnt(3)
	v_mfma_f32_16x16x32_bf16 v[56:59], v[160:163], v[156:159], v[56:59]
	s_waitcnt lgkmcnt(2)
	v_mfma_f32_16x16x32_bf16 v[40:43], v[160:163], v[164:167], v[40:43]
	s_waitcnt lgkmcnt(1)
	v_mfma_f32_16x16x32_bf16 v[24:27], v[160:163], v[176:179], v[24:27]
	s_waitcnt lgkmcnt(0)
	v_mfma_f32_16x16x32_bf16 v[8:11], v[160:163], v[180:183], v[8:11]
	ds_read_b128 v[160:163], v150 offset:1024
	v_mfma_f32_16x16x32_bf16 v[60:63], v[152:155], v[156:159], v[60:63]
	v_mfma_f32_16x16x32_bf16 v[44:47], v[152:155], v[164:167], v[44:47]
	v_mfma_f32_16x16x32_bf16 v[28:31], v[152:155], v[176:179], v[28:31]
	v_mfma_f32_16x16x32_bf16 v[12:15], v[152:155], v[180:183], v[12:15]
	v_add_u32_e32 v151, v149, v136
	ds_read_b128 v[152:155], v151
	v_mfma_f32_16x16x32_bf16 v[36:39], v[168:171], v[164:167], v[36:39]
	v_mfma_f32_16x16x32_bf16 v[32:35], v[172:175], v[164:167], v[32:35]
	ds_read_b128 v[164:167], v150 offset:3072
	v_mfma_f32_16x16x32_bf16 v[52:55], v[168:171], v[156:159], v[52:55]
	v_mfma_f32_16x16x32_bf16 v[48:51], v[172:175], v[156:159], v[48:51]
	v_add_u32_e32 v151, v149, v137
	ds_read_b128 v[156:159], v151
	v_mfma_f32_16x16x32_bf16 v[20:23], v[168:171], v[176:179], v[20:23]
	v_mfma_f32_16x16x32_bf16 v[16:19], v[172:175], v[176:179], v[16:19]
	v_add_u32_e32 v151, v149, v138
	ds_read_b128 v[176:179], v151
	v_mfma_f32_16x16x32_bf16 v[4:7], v[168:171], v[180:183], v[4:7]
	ds_read_b128 v[168:171], v150 offset:5120
	v_mfma_f32_16x16x32_bf16 v[0:3], v[172:175], v[180:183], v[0:3]
	ds_read_b128 v[172:175], v150 offset:7168
	v_add_u32_e32 v151, v149, v139
	ds_read_b128 v[180:183], v151
	s_waitcnt lgkmcnt(6)
	v_mfma_f32_16x16x32_bf16 v[124:127], v[160:163], v[152:155], v[124:127]
	s_waitcnt lgkmcnt(5)
	v_mfma_f32_16x16x32_bf16 v[120:123], v[164:167], v[152:155], v[120:123]
	s_waitcnt lgkmcnt(4)
	v_mfma_f32_16x16x32_bf16 v[108:111], v[160:163], v[156:159], v[108:111]
	v_mfma_f32_16x16x32_bf16 v[104:107], v[164:167], v[156:159], v[104:107]
	s_waitcnt lgkmcnt(3)
	v_mfma_f32_16x16x32_bf16 v[92:95], v[160:163], v[176:179], v[92:95]
	v_mfma_f32_16x16x32_bf16 v[88:91], v[164:167], v[176:179], v[88:91]
	s_waitcnt lgkmcnt(2)
	v_mfma_f32_16x16x32_bf16 v[116:119], v[168:171], v[152:155], v[116:119]
	s_waitcnt lgkmcnt(1)
	v_mfma_f32_16x16x32_bf16 v[112:115], v[172:175], v[152:155], v[112:115]
	v_add_u32_e32 v151, v149, v140
	ds_read_b128 v[152:155], v151
	v_mfma_f32_16x16x32_bf16 v[100:103], v[168:171], v[156:159], v[100:103]
	v_mfma_f32_16x16x32_bf16 v[96:99], v[172:175], v[156:159], v[96:99]
	v_add_u32_e32 v151, v149, v141
	ds_read_b128 v[156:159], v151
	v_mfma_f32_16x16x32_bf16 v[84:87], v[168:171], v[176:179], v[84:87]
	v_mfma_f32_16x16x32_bf16 v[80:83], v[172:175], v[176:179], v[80:83]
	v_add_u32_e32 v151, v149, v142
	ds_read_b128 v[176:179], v151
	s_waitcnt lgkmcnt(3)
	v_mfma_f32_16x16x32_bf16 v[76:79], v[160:163], v[180:183], v[76:79]
	v_mfma_f32_16x16x32_bf16 v[72:75], v[164:167], v[180:183], v[72:75]
	v_mfma_f32_16x16x32_bf16 v[68:71], v[168:171], v[180:183], v[68:71]
	v_mfma_f32_16x16x32_bf16 v[64:67], v[172:175], v[180:183], v[64:67]
	v_add_u32_e32 v151, v149, v143
	ds_read_b128 v[180:183], v151
	s_waitcnt lgkmcnt(3)
	v_mfma_f32_16x16x32_bf16 v[60:63], v[160:163], v[152:155], v[60:63]
	v_mfma_f32_16x16x32_bf16 v[56:59], v[164:167], v[152:155], v[56:59]
	v_mfma_f32_16x16x32_bf16 v[52:55], v[168:171], v[152:155], v[52:55]
	v_mfma_f32_16x16x32_bf16 v[48:51], v[172:175], v[152:155], v[48:51]
	s_waitcnt lgkmcnt(2)
	v_mfma_f32_16x16x32_bf16 v[44:47], v[160:163], v[156:159], v[44:47]
	v_mfma_f32_16x16x32_bf16 v[40:43], v[164:167], v[156:159], v[40:43]
	v_mfma_f32_16x16x32_bf16 v[36:39], v[168:171], v[156:159], v[36:39]
	v_mfma_f32_16x16x32_bf16 v[32:35], v[172:175], v[156:159], v[32:35]
	s_waitcnt vmcnt(0)
	s_add_u32 s4, s4, 0x100
	s_addc_u32 s5, s5, 0
	s_add_i32 s68, s68, 2
	s_cmpk_lg_i32 s4, 0x1000
	s_waitcnt lgkmcnt(0)
	s_barrier
	s_cbranch_scc1 .LBB0_301
	v_mfma_f32_16x16x32_bf16 v[28:31], v[160:163], v[176:179], v[28:31]
	v_mfma_f32_16x16x32_bf16 v[12:15], v[160:163], v[180:183], v[12:15]
	v_mfma_f32_16x16x32_bf16 v[24:27], v[164:167], v[176:179], v[24:27]
	v_mfma_f32_16x16x32_bf16 v[8:11], v[164:167], v[180:183], v[8:11]
	v_mfma_f32_16x16x32_bf16 v[20:23], v[168:171], v[176:179], v[20:23]
	v_mfma_f32_16x16x32_bf16 v[4:7], v[168:171], v[180:183], v[4:7]
	v_mfma_f32_16x16x32_bf16 v[16:19], v[172:175], v[176:179], v[16:19]
	v_mfma_f32_16x16x32_bf16 v[0:3], v[172:175], v[180:183], v[0:3]
	s_nop 15
	s_nop 15
	v_mov_b32_e32 v128, v184
	s_movk_i32 s1, 0xff80
	v_and_b32_e32 v129, 15, v128
	v_ashrrev_i32_e32 v130, 1, v128
	s_lshl_b32 s34, s0, 8
	v_and_or_b32 v163, v130, s1, v129
	s_cmp_lt_i32 s0, 8
	v_lshl_add_u32 v162, v163, 2, v202
	v_and_b32_e32 v164, 0xc0, v128
	s_cselect_b64 s[2:3], -1, 0
	s_cmp_lt_i32 s0, 10
	v_lshrrev_b32_e32 v128, 2, v128
	ds_read_b32 v150, v162
	s_cselect_b64 s[30:31], -1, 0
	s_add_i32 s1, s34, 0xfffff800
	v_and_b32_e32 v145, 12, v128
	v_or_b32_e32 v128, s34, v164
	v_ashrrev_i32_e32 v129, 31, v128
	v_or_b32_e32 v138, s1, v164
	v_add_u32_e32 v142, s43, v163
	s_cmp_gt_i32 s0, 9
	v_lshl_add_u64 v[140:141], v[128:129], 1, s[18:19]
	v_ashrrev_i32_e32 v128, 6, v138
	v_and_b32_e32 v165, 0xf8f, v142
	v_ashrrev_i32_e32 v168, 12, v142
	s_movk_i32 s0, 0xf7f
	v_ashrrev_i32_e32 v139, 31, v138
	v_add_u32_e32 v149, 0xffff8400, v128
	s_mov_b64 s[4:5], -1
	v_cmp_lt_u32_e64 s[0:1], s0, v165
	v_lshlrev_b32_e32 v166, 10, v168
	v_lshlrev_b32_e32 v167, 3, v165
	v_lshlrev_b32_e32 v136, 2, v145
	v_readlane_b32 s68, v253, 18
	s_cbranch_scc1 .LBB0_316
	v_lshlrev_b32_e32 v146, 7, v165
	v_lshl_add_u64 v[128:129], s[6:7], 0, v[146:147]
	v_mov_b32_e32 v137, v147
	v_lshl_add_u64 v[130:131], s[12:13], 0, v[146:147]
	v_lshl_add_u64 v[154:155], v[128:129], 0, v[136:137]
	v_lshl_add_u64 v[156:157], v[130:131], 0, v[136:137]
	global_load_dwordx4 v[128:131], v[154:155], off
	global_load_dwordx4 v[158:161], v[156:157], off
	v_ashrrev_i32_e32 v143, 31, v142
	v_lshlrev_b64 v[132:133], 12, v[142:143]
	s_waitcnt lgkmcnt(0)
	v_pk_mul_f32 v[170:171], v[116:117], v[150:151] op_sel_hi:[1,0]
	v_lshl_add_u64 v[152:153], v[140:141], 0, v[132:133]
	v_pk_mul_f32 v[134:135], v[124:125], v[150:151] op_sel_hi:[1,0]
	s_and_b64 vcc, exec, s[2:3]
	s_waitcnt vmcnt(0)
	v_pk_mul_f32 v[132:133], v[170:171], v[158:159]
	s_nop 0
	v_pk_fma_f32 v[132:133], v[134:135], v[128:129], v[132:133] neg_lo:[0,0,1] neg_hi:[0,0,1]
	v_pk_mul_f32 v[134:135], v[134:135], v[158:159]
	v_pk_mul_f32 v[158:159], v[126:127], v[150:151] op_sel_hi:[1,0]
	v_pk_fma_f32 v[128:129], v[170:171], v[128:129], v[134:135]
	v_pk_mul_f32 v[170:171], v[118:119], v[150:151] op_sel_hi:[1,0]
	s_nop 0
	v_pk_mul_f32 v[134:135], v[170:171], v[160:161]
	s_nop 0
	v_pk_fma_f32 v[134:135], v[158:159], v[130:131], v[134:135] neg_lo:[0,0,1] neg_hi:[0,0,1]
	v_pk_mul_f32 v[158:159], v[158:159], v[160:161]
	s_nop 0
	v_pk_fma_f32 v[130:131], v[170:171], v[130:131], v[158:159]
	s_cbranch_vccz .LBB0_305
	s_mov_b32 s4, 0x3e000000
	v_lshlrev_b32_e32 v146, 1, v145
	v_pk_mul_f32 v[160:161], v[132:133], s[4:5] op_sel_hi:[1,0]
	v_pk_mul_f32 v[170:171], v[134:135], s[4:5] op_sel_hi:[1,0]
	v_lshl_add_u64 v[158:159], v[152:153], 0, v[146:147]
	v_cvt_pk_bf16_f32 v160, v160, v161
	v_cvt_pk_bf16_f32 v161, v170, v171
	global_store_dwordx2 v[158:159], v[160:161], off
	v_pk_mul_f32 v[160:161], v[128:129], s[4:5] op_sel_hi:[1,0]
	v_pk_mul_f32 v[170:171], v[130:131], s[4:5] op_sel_hi:[1,0]
	v_cvt_pk_bf16_f32 v160, v160, v161
	v_cvt_pk_bf16_f32 v161, v170, v171
	s_mov_b64 s[4:5], 0
	global_store_dwordx2 v[158:159], v[160:161], off offset:64

.LBB0_565:
	s_mul_i32 s20, s23, 0x300000
	s_mul_hi_i32 s21, s23, 0x300000
	s_add_u32 s20, s26, s20
	s_addc_u32 s21, s27, s21
	s_mul_hi_i32 s23, s22, 0x300000
	s_mul_i32 s22, s22, 0x300000
	s_add_u32 s22, s38, s22
	s_addc_u32 s23, s39, s23
	s_add_u32 s62, s0, 0x80
	v_and_b32_e32 v8, 48, v7
	v_lshlrev_b32_e32 v9, 6, v7
	v_lshlrev_b32_e32 v7, 2, v7
	s_addc_u32 s63, s1, 0
	v_and_b32_e32 v10, 0x3c0, v9
	v_and_b32_e32 v149, 32, v7
	s_add_u32 s64, s14, 0x80
	v_or_b32_e32 v145, v10, v8
	v_bitop3_b32 v12, v10, v149, v8 bitop3:0x36
	s_waitcnt vmcnt(0)
	s_barrier
	v_lshlrev_b32_e32 v8, 13, v6
	s_addc_u32 s65, s15, 0
	s_add_i32 s52, s42, 0x10000
	v_lshl_add_u64 v[6:7], s[62:63], 0, v[0:1]
	s_mov_b32 s53, m0
	s_mov_b32 m0, s52
	s_nop 0
	global_load_lds_dwordx4 v[6:7], off
	s_mov_b32 m0, s53
	s_add_i32 s51, s42, 0x18000
	v_lshl_add_u64 v[6:7], s[64:65], 0, v[0:1]
	s_mov_b32 s53, m0
	s_mov_b32 m0, s51
	s_nop 0
	global_load_lds_dwordx4 v[6:7], off
	s_mov_b32 m0, s53
	v_lshl_add_u64 v[6:7], s[62:63], 0, v[2:3]
	s_add_i32 s53, s42, 0x12000
	s_mov_b32 s54, m0
	s_mov_b32 m0, s53
	s_nop 0
	global_load_lds_dwordx4 v[6:7], off
	s_mov_b32 m0, s54
	v_lshl_add_u64 v[6:7], s[64:65], 0, v[2:3]
	s_add_i32 s54, s42, 0x1a000
	s_mov_b32 s55, m0
	s_mov_b32 m0, s54
	s_nop 0
	global_load_lds_dwordx4 v[6:7], off
	s_mov_b32 m0, s55
	v_lshl_add_u64 v[6:7], s[62:63], 0, v[4:5]
	s_add_i32 s55, s42, 0x14000
	s_mov_b32 s58, m0
	s_mov_b32 m0, s55
	s_nop 0
	global_load_lds_dwordx4 v[6:7], off
	s_mov_b32 m0, s58
	v_lshl_add_u64 v[6:7], s[64:65], 0, v[4:5]
	s_add_i32 s58, s42, 0x1c000
	s_mov_b32 s68, m0
	s_mov_b32 m0, s58
	s_nop 0
	global_load_lds_dwordx4 v[6:7], off
	s_mov_b32 m0, s68
	v_lshl_add_u64 v[6:7], s[62:63], 0, v[146:147]
	s_add_i32 s62, s42, 0x16000
	s_mov_b32 s63, m0
	s_mov_b32 m0, s62
	s_nop 0
	global_load_lds_dwordx4 v[6:7], off
	s_mov_b32 m0, s63
	v_lshl_add_u64 v[6:7], s[64:65], 0, v[146:147]
	s_add_i32 s63, s42, 0x1e000
	s_mov_b32 s64, m0
	s_mov_b32 m0, s63
	s_nop 0
	global_load_lds_dwordx4 v[6:7], off
	s_mov_b32 m0, s64
	v_and_b32_e32 v182, 0xffffc000, v9
	v_or_b32_e32 v183, 0x800, v182
	v_or_b32_e32 v189, 0x1000, v182
	v_or_b32_e32 v199, 0x1800, v182
	v_or_b32_e32 v200, 0x2000, v182
	v_or_b32_e32 v201, 0x2800, v182
	v_or_b32_e32 v203, 0x3000, v182
	v_or_b32_e32 v206, 0x3800, v182
	s_movk_i32 s64, 0x6000
	v_and_or_b32 v7, v8, s64, v12
	ds_read_b128 v[8:11], v7 offset:32768
	v_or_b32_e32 v6, v12, v182
	ds_read_b128 v[12:15], v7 offset:34816
	ds_read_b128 v[16:19], v7 offset:36864
	ds_read_b128 v[24:27], v7 offset:38912
	ds_read_b128 v[20:23], v6
	ds_read_b128 v[28:31], v6 offset:2048
	ds_read_b128 v[32:35], v6 offset:4096
	ds_read_b128 v[36:39], v6 offset:6144
	s_waitcnt lgkmcnt(3)
	v_mfma_f32_16x16x32_bf16 v[40:43], v[8:11], v[20:23], 0
	v_mfma_f32_16x16x32_bf16 v[44:47], v[12:15], v[20:23], 0
	v_mfma_f32_16x16x32_bf16 v[48:51], v[16:19], v[20:23], 0
	v_mfma_f32_16x16x32_bf16 v[20:23], v[24:27], v[20:23], 0
	ds_read_b128 v[52:55], v6 offset:8192
	s_waitcnt lgkmcnt(3)
	v_mfma_f32_16x16x32_bf16 v[56:59], v[8:11], v[28:31], 0
	v_mfma_f32_16x16x32_bf16 v[60:63], v[12:15], v[28:31], 0
	v_mfma_f32_16x16x32_bf16 v[64:67], v[16:19], v[28:31], 0
	v_mfma_f32_16x16x32_bf16 v[28:31], v[24:27], v[28:31], 0
	ds_read_b128 v[68:71], v6 offset:10240
	s_waitcnt lgkmcnt(3)
	v_mfma_f32_16x16x32_bf16 v[72:75], v[8:11], v[32:35], 0
	v_mfma_f32_16x16x32_bf16 v[76:79], v[12:15], v[32:35], 0
	v_mfma_f32_16x16x32_bf16 v[80:83], v[16:19], v[32:35], 0
	v_mfma_f32_16x16x32_bf16 v[32:35], v[24:27], v[32:35], 0
	ds_read_b128 v[84:87], v6 offset:12288
	s_waitcnt lgkmcnt(3)
	v_mfma_f32_16x16x32_bf16 v[88:91], v[8:11], v[36:39], 0
	v_mfma_f32_16x16x32_bf16 v[92:95], v[12:15], v[36:39], 0
	v_mfma_f32_16x16x32_bf16 v[96:99], v[16:19], v[36:39], 0
	v_mfma_f32_16x16x32_bf16 v[36:39], v[24:27], v[36:39], 0
	ds_read_b128 v[100:103], v6 offset:14336
	s_waitcnt lgkmcnt(3)
	v_mfma_f32_16x16x32_bf16 v[104:107], v[8:11], v[52:55], 0
	v_mfma_f32_16x16x32_bf16 v[108:111], v[12:15], v[52:55], 0
	v_mfma_f32_16x16x32_bf16 v[112:115], v[16:19], v[52:55], 0
	v_mfma_f32_16x16x32_bf16 v[52:55], v[24:27], v[52:55], 0
	s_waitcnt lgkmcnt(2)
	v_mfma_f32_16x16x32_bf16 v[116:119], v[8:11], v[68:71], 0
	v_mfma_f32_16x16x32_bf16 v[120:123], v[12:15], v[68:71], 0
	v_mfma_f32_16x16x32_bf16 v[124:127], v[16:19], v[68:71], 0
	v_mfma_f32_16x16x32_bf16 v[68:71], v[24:27], v[68:71], 0
	s_waitcnt lgkmcnt(1)
	v_mfma_f32_16x16x32_bf16 v[128:131], v[8:11], v[84:87], 0
	v_mfma_f32_16x16x32_bf16 v[132:135], v[12:15], v[84:87], 0
	v_mfma_f32_16x16x32_bf16 v[136:139], v[16:19], v[84:87], 0
	v_mfma_f32_16x16x32_bf16 v[84:87], v[24:27], v[84:87], 0
	s_waitcnt lgkmcnt(0)
	v_mfma_f32_16x16x32_bf16 v[8:11], v[8:11], v[100:103], 0
	v_mfma_f32_16x16x32_bf16 v[12:15], v[12:15], v[100:103], 0
	v_mfma_f32_16x16x32_bf16 v[16:19], v[16:19], v[100:103], 0
	v_mfma_f32_16x16x32_bf16 v[24:27], v[24:27], v[100:103], 0
	ds_read_b128 v[100:103], v7 offset:33792
	ds_read_b128 v[140:143], v7 offset:35840
	ds_read_b128 v[150:153], v7 offset:37888
	ds_read_b128 v[158:161], v7 offset:39936
	ds_read_b128 v[154:157], v6 offset:1024
	ds_read_b128 v[162:165], v6 offset:3072
	ds_read_b128 v[166:169], v6 offset:5120
	ds_read_b128 v[170:173], v6 offset:7168
	s_waitcnt lgkmcnt(3)
	v_mfma_f32_16x16x32_bf16 v[40:43], v[100:103], v[154:157], v[40:43]
	v_mfma_f32_16x16x32_bf16 v[44:47], v[140:143], v[154:157], v[44:47]
	v_mfma_f32_16x16x32_bf16 v[48:51], v[150:153], v[154:157], v[48:51]
	v_mfma_f32_16x16x32_bf16 v[20:23], v[158:161], v[154:157], v[20:23]
	ds_read_b128 v[154:157], v6 offset:9216
	s_waitcnt lgkmcnt(3)
	v_mfma_f32_16x16x32_bf16 v[56:59], v[100:103], v[162:165], v[56:59]
	v_mfma_f32_16x16x32_bf16 v[60:63], v[140:143], v[162:165], v[60:63]
	v_mfma_f32_16x16x32_bf16 v[64:67], v[150:153], v[162:165], v[64:67]
	v_mfma_f32_16x16x32_bf16 v[28:31], v[158:161], v[162:165], v[28:31]
	ds_read_b128 v[162:165], v6 offset:11264
	s_waitcnt lgkmcnt(3)
	v_mfma_f32_16x16x32_bf16 v[72:75], v[100:103], v[166:169], v[72:75]
	v_mfma_f32_16x16x32_bf16 v[76:79], v[140:143], v[166:169], v[76:79]
	v_mfma_f32_16x16x32_bf16 v[80:83], v[150:153], v[166:169], v[80:83]
	v_mfma_f32_16x16x32_bf16 v[32:35], v[158:161], v[166:169], v[32:35]
	ds_read_b128 v[166:169], v6 offset:13312
	s_waitcnt lgkmcnt(3)
	v_mfma_f32_16x16x32_bf16 v[88:91], v[100:103], v[170:173], v[88:91]
	v_mfma_f32_16x16x32_bf16 v[92:95], v[140:143], v[170:173], v[92:95]
	v_mfma_f32_16x16x32_bf16 v[96:99], v[150:153], v[170:173], v[96:99]
	v_mfma_f32_16x16x32_bf16 v[36:39], v[158:161], v[170:173], v[36:39]
	ds_read_b128 v[170:173], v6 offset:15360
	s_waitcnt lgkmcnt(3)
	v_mfma_f32_16x16x32_bf16 v[104:107], v[100:103], v[154:157], v[104:107]
	v_mfma_f32_16x16x32_bf16 v[108:111], v[140:143], v[154:157], v[108:111]
	v_mfma_f32_16x16x32_bf16 v[112:115], v[150:153], v[154:157], v[112:115]
	v_mfma_f32_16x16x32_bf16 v[52:55], v[158:161], v[154:157], v[52:55]
	s_waitcnt lgkmcnt(2)
	v_mfma_f32_16x16x32_bf16 v[116:119], v[100:103], v[162:165], v[116:119]
	v_mfma_f32_16x16x32_bf16 v[120:123], v[140:143], v[162:165], v[120:123]
	v_mfma_f32_16x16x32_bf16 v[124:127], v[150:153], v[162:165], v[124:127]
	v_mfma_f32_16x16x32_bf16 v[68:71], v[158:161], v[162:165], v[68:71]
	s_waitcnt lgkmcnt(1)
	v_mfma_f32_16x16x32_bf16 v[128:131], v[100:103], v[166:169], v[128:131]
	v_mfma_f32_16x16x32_bf16 v[132:135], v[140:143], v[166:169], v[132:135]
	v_mfma_f32_16x16x32_bf16 v[136:139], v[150:153], v[166:169], v[136:139]
	v_mfma_f32_16x16x32_bf16 v[84:87], v[158:161], v[166:169], v[84:87]
	s_waitcnt lgkmcnt(0)
	v_mfma_f32_16x16x32_bf16 v[100:103], v[100:103], v[170:173], v[8:11]
	v_mfma_f32_16x16x32_bf16 v[150:153], v[150:153], v[170:173], v[16:19]
	v_mfma_f32_16x16x32_bf16 v[24:27], v[158:161], v[170:173], v[24:27]
	v_mfma_f32_16x16x32_bf16 v[140:143], v[140:143], v[170:173], v[12:15]
	s_add_u32 s64, s0, 0x100
	s_addc_u32 s65, s1, 0
	s_add_u32 s68, s14, 0x100
	s_waitcnt vmcnt(0)
	s_barrier
	s_addc_u32 s69, s15, 0
	v_lshl_add_u64 v[8:9], s[64:65], 0, v[0:1]
	s_mov_b32 s70, m0
	s_mov_b32 m0, s42
	s_nop 0
	global_load_lds_dwordx4 v[8:9], off
	s_mov_b32 m0, s70
	v_lshl_add_u64 v[8:9], s[68:69], 0, v[0:1]
	s_mov_b32 s70, m0
	s_mov_b32 m0, s43
	s_nop 0
	global_load_lds_dwordx4 v[8:9], off
	s_mov_b32 m0, s70
	v_lshl_add_u64 v[8:9], s[64:65], 0, v[2:3]
	s_mov_b32 s70, m0
	s_mov_b32 m0, s44
	s_nop 0
	global_load_lds_dwordx4 v[8:9], off
	s_mov_b32 m0, s70
	v_lshl_add_u64 v[8:9], s[68:69], 0, v[2:3]
	s_mov_b32 s70, m0
	s_mov_b32 m0, s45
	s_nop 0
	global_load_lds_dwordx4 v[8:9], off
	s_mov_b32 m0, s70
	v_lshl_add_u64 v[8:9], s[64:65], 0, v[4:5]
	s_mov_b32 s70, m0
	s_mov_b32 m0, s46
	s_nop 0
	global_load_lds_dwordx4 v[8:9], off
	s_mov_b32 m0, s70
	v_lshl_add_u64 v[8:9], s[68:69], 0, v[4:5]
	s_mov_b32 s70, m0
	s_mov_b32 m0, s47
	s_nop 0
	global_load_lds_dwordx4 v[8:9], off
	s_mov_b32 m0, s70
	v_lshl_add_u64 v[8:9], s[64:65], 0, v[146:147]
	s_mov_b32 s64, m0
	s_mov_b32 m0, s49
	s_nop 0
	global_load_lds_dwordx4 v[8:9], off
	s_mov_b32 m0, s64
	v_lshl_add_u64 v[8:9], s[68:69], 0, v[146:147]
	s_mov_b32 s64, m0
	s_mov_b32 m0, s50
	s_nop 0
	global_load_lds_dwordx4 v[8:9], off
	s_mov_b32 m0, s64
	v_or_b32_e32 v8, 0x18000, v7
	v_or_b32_e32 v9, 0x18800, v7
	v_or_b32_e32 v11, 0x19000, v7
	v_or_b32_e32 v10, 0x19800, v7
	ds_read_b128 v[154:157], v8
	ds_read_b128 v[158:161], v9
	ds_read_b128 v[162:165], v11
	ds_read_b128 v[166:169], v10
	v_bitop3_b32 v207, v145, s33, v149 bitop3:0xde
	v_add_u32_e32 v12, v207, v182
	ds_read_b128 v[16:19], v12
	v_add_u32_e32 v13, v207, v183
	v_add_u32_e32 v14, v207, v189
	v_add_u32_e32 v15, v207, v199
	ds_read_b128 v[170:173], v13
	ds_read_b128 v[174:177], v14
	ds_read_b128 v[178:181], v15
	s_waitcnt lgkmcnt(3)
	v_mfma_f32_16x16x32_bf16 v[40:43], v[154:157], v[16:19], v[40:43]
	v_mfma_f32_16x16x32_bf16 v[44:47], v[158:161], v[16:19], v[44:47]
	v_mfma_f32_16x16x32_bf16 v[48:51], v[162:165], v[16:19], v[48:51]
	v_mfma_f32_16x16x32_bf16 v[214:217], v[166:169], v[16:19], v[20:23]
	v_add_u32_e32 v16, v207, v200
	v_add_u32_e32 v17, v207, v201
	v_add_u32_e32 v18, v207, v203
	v_add_u32_e32 v19, v207, v206
	ds_read_b128 v[20:23], v16
	s_waitcnt lgkmcnt(3)
	v_mfma_f32_16x16x32_bf16 v[56:59], v[154:157], v[170:173], v[56:59]
	v_mfma_f32_16x16x32_bf16 v[60:63], v[158:161], v[170:173], v[60:63]
	v_mfma_f32_16x16x32_bf16 v[64:67], v[162:165], v[170:173], v[64:67]
	v_mfma_f32_16x16x32_bf16 v[170:173], v[166:169], v[170:173], v[28:31]
	s_nop 2
	ds_read_b128 v[28:31], v17
	s_waitcnt lgkmcnt(3)
	v_mfma_f32_16x16x32_bf16 v[72:75], v[154:157], v[174:177], v[72:75]
	v_mfma_f32_16x16x32_bf16 v[76:79], v[158:161], v[174:177], v[76:79]
	v_mfma_f32_16x16x32_bf16 v[80:83], v[162:165], v[174:177], v[80:83]
	v_mfma_f32_16x16x32_bf16 v[32:35], v[166:169], v[174:177], v[32:35]
	ds_read_b128 v[174:177], v18
	s_waitcnt lgkmcnt(3)
	v_mfma_f32_16x16x32_bf16 v[88:91], v[154:157], v[178:181], v[88:91]
	v_mfma_f32_16x16x32_bf16 v[92:95], v[158:161], v[178:181], v[92:95]
	v_mfma_f32_16x16x32_bf16 v[96:99], v[162:165], v[178:181], v[96:99]
	v_mfma_f32_16x16x32_bf16 v[36:39], v[166:169], v[178:181], v[36:39]
	ds_read_b128 v[178:181], v19
	s_waitcnt lgkmcnt(3)
	v_mfma_f32_16x16x32_bf16 v[104:107], v[154:157], v[20:23], v[104:107]
	v_mfma_f32_16x16x32_bf16 v[108:111], v[158:161], v[20:23], v[108:111]
	v_mfma_f32_16x16x32_bf16 v[112:115], v[162:165], v[20:23], v[112:115]
	v_mfma_f32_16x16x32_bf16 v[52:55], v[166:169], v[20:23], v[52:55]
	s_waitcnt lgkmcnt(2)
	v_mfma_f32_16x16x32_bf16 v[116:119], v[154:157], v[28:31], v[116:119]
	v_mfma_f32_16x16x32_bf16 v[120:123], v[158:161], v[28:31], v[120:123]
	v_mfma_f32_16x16x32_bf16 v[124:127], v[162:165], v[28:31], v[124:127]
	v_mfma_f32_16x16x32_bf16 v[68:71], v[166:169], v[28:31], v[68:71]
	s_waitcnt lgkmcnt(1)
	v_mfma_f32_16x16x32_bf16 v[128:131], v[154:157], v[174:177], v[128:131]
	v_mfma_f32_16x16x32_bf16 v[132:135], v[158:161], v[174:177], v[132:135]
	v_mfma_f32_16x16x32_bf16 v[84:87], v[166:169], v[174:177], v[84:87]
	s_waitcnt lgkmcnt(0)
	v_mfma_f32_16x16x32_bf16 v[100:103], v[154:157], v[178:181], v[100:103]
	v_mfma_f32_16x16x32_bf16 v[150:153], v[162:165], v[178:181], v[150:153]
	v_mfma_f32_16x16x32_bf16 v[154:157], v[166:169], v[178:181], v[24:27]
	v_mfma_f32_16x16x32_bf16 v[136:139], v[162:165], v[174:177], v[136:139]
	v_mfma_f32_16x16x32_bf16 v[140:143], v[158:161], v[178:181], v[140:143]
	v_or_b32_e32 v20, 0x18400, v7
	v_or_b32_e32 v21, 0x18c00, v7
	v_or_b32_e32 v23, 0x19400, v7
	v_or_b32_e32 v22, 0x19c00, v7
	ds_read_b128 v[158:161], v20
	ds_read_b128 v[162:165], v21
	ds_read_b128 v[166:169], v23
	ds_read_b128 v[174:177], v22
	s_mov_b32 s64, 0x10400
	v_bitop3_b32 v145, v145, s64, v149 bitop3:0xde
	v_add_u32_e32 v24, v145, v182
	ds_read_b128 v[28:31], v24
	v_add_u32_e32 v25, v145, v183
	v_add_u32_e32 v26, v145, v189
	v_add_u32_e32 v27, v145, v199
	ds_read_b128 v[178:181], v25
	ds_read_b128 v[218:221], v26
	ds_read_b128 v[222:225], v27
	s_waitcnt lgkmcnt(3)
	v_mfma_f32_16x16x32_bf16 v[40:43], v[158:161], v[28:31], v[40:43]
	v_mfma_f32_16x16x32_bf16 v[44:47], v[162:165], v[28:31], v[44:47]
	v_mfma_f32_16x16x32_bf16 v[48:51], v[166:169], v[28:31], v[48:51]
	v_mfma_f32_16x16x32_bf16 v[214:217], v[174:177], v[28:31], v[214:217]
	v_add_u32_e32 v28, v145, v200
	v_add_u32_e32 v29, v145, v201
	v_add_u32_e32 v30, v145, v203
	v_add_u32_e32 v31, v145, v206
	ds_read_b128 v[226:229], v28
	s_waitcnt lgkmcnt(3)
	v_mfma_f32_16x16x32_bf16 v[56:59], v[158:161], v[178:181], v[56:59]
	v_mfma_f32_16x16x32_bf16 v[60:63], v[162:165], v[178:181], v[60:63]
	v_mfma_f32_16x16x32_bf16 v[64:67], v[166:169], v[178:181], v[64:67]
	v_mfma_f32_16x16x32_bf16 v[170:173], v[174:177], v[178:181], v[170:173]
	ds_read_b128 v[178:181], v29
	s_waitcnt lgkmcnt(3)
	v_mfma_f32_16x16x32_bf16 v[72:75], v[158:161], v[218:221], v[72:75]
	v_mfma_f32_16x16x32_bf16 v[76:79], v[162:165], v[218:221], v[76:79]
	v_mfma_f32_16x16x32_bf16 v[80:83], v[166:169], v[218:221], v[80:83]
	v_mfma_f32_16x16x32_bf16 v[32:35], v[174:177], v[218:221], v[32:35]
	ds_read_b128 v[218:221], v30
	s_waitcnt lgkmcnt(3)
	v_mfma_f32_16x16x32_bf16 v[88:91], v[158:161], v[222:225], v[88:91]
	v_mfma_f32_16x16x32_bf16 v[92:95], v[162:165], v[222:225], v[92:95]
	v_mfma_f32_16x16x32_bf16 v[96:99], v[166:169], v[222:225], v[96:99]
	v_mfma_f32_16x16x32_bf16 v[36:39], v[174:177], v[222:225], v[36:39]
	ds_read_b128 v[222:225], v31
	s_waitcnt lgkmcnt(3)
	v_mfma_f32_16x16x32_bf16 v[104:107], v[158:161], v[226:229], v[104:107]
	v_mfma_f32_16x16x32_bf16 v[108:111], v[162:165], v[226:229], v[108:111]
	v_mfma_f32_16x16x32_bf16 v[112:115], v[166:169], v[226:229], v[112:115]
	v_mfma_f32_16x16x32_bf16 v[52:55], v[174:177], v[226:229], v[52:55]
	s_waitcnt lgkmcnt(2)
	v_mfma_f32_16x16x32_bf16 v[116:119], v[158:161], v[178:181], v[116:119]
	v_mfma_f32_16x16x32_bf16 v[120:123], v[162:165], v[178:181], v[120:123]
	v_mfma_f32_16x16x32_bf16 v[124:127], v[166:169], v[178:181], v[124:127]
	v_mfma_f32_16x16x32_bf16 v[68:71], v[174:177], v[178:181], v[68:71]
	s_waitcnt lgkmcnt(1)
	v_mfma_f32_16x16x32_bf16 v[132:135], v[162:165], v[218:221], v[132:135]
	v_mfma_f32_16x16x32_bf16 v[84:87], v[174:177], v[218:221], v[84:87]
	s_waitcnt lgkmcnt(0)
	v_mfma_f32_16x16x32_bf16 v[100:103], v[158:161], v[222:225], v[100:103]
	v_mfma_f32_16x16x32_bf16 v[150:153], v[166:169], v[222:225], v[150:153]
	v_mfma_f32_16x16x32_bf16 v[154:157], v[174:177], v[222:225], v[154:157]
	v_mfma_f32_16x16x32_bf16 v[128:131], v[158:161], v[218:221], v[128:131]
	v_mfma_f32_16x16x32_bf16 v[136:139], v[166:169], v[218:221], v[136:139]
	v_mfma_f32_16x16x32_bf16 v[140:143], v[162:165], v[222:225], v[140:143]
	s_add_u32 s64, s0, 0x180
	s_addc_u32 s65, s1, 0
	s_add_u32 s68, s14, 0x180
	s_waitcnt vmcnt(0)
	s_barrier
	s_addc_u32 s69, s15, 0
	v_lshl_add_u64 v[158:159], s[64:65], 0, v[0:1]
	s_mov_b32 s70, m0
	s_mov_b32 m0, s52
	s_nop 0
	global_load_lds_dwordx4 v[158:159], off
	s_mov_b32 m0, s70
	v_lshl_add_u64 v[158:159], s[68:69], 0, v[0:1]
	s_mov_b32 s70, m0
	s_mov_b32 m0, s51
	s_nop 0
	global_load_lds_dwordx4 v[158:159], off
	s_mov_b32 m0, s70
	v_lshl_add_u64 v[158:159], s[64:65], 0, v[2:3]
	s_mov_b32 s70, m0
	s_mov_b32 m0, s53
	s_nop 0
	global_load_lds_dwordx4 v[158:159], off
	s_mov_b32 m0, s70
	v_lshl_add_u64 v[158:159], s[68:69], 0, v[2:3]
	s_mov_b32 s70, m0
	s_mov_b32 m0, s54
	s_nop 0
	global_load_lds_dwordx4 v[158:159], off
	s_mov_b32 m0, s70
	v_lshl_add_u64 v[158:159], s[64:65], 0, v[4:5]
	s_mov_b32 s70, m0
	s_mov_b32 m0, s55
	s_nop 0
	global_load_lds_dwordx4 v[158:159], off
	s_mov_b32 m0, s70
	v_lshl_add_u64 v[158:159], s[68:69], 0, v[4:5]
	s_mov_b32 s70, m0
	s_mov_b32 m0, s58
	s_nop 0
	global_load_lds_dwordx4 v[158:159], off
	s_mov_b32 m0, s70
	v_lshl_add_u64 v[158:159], s[64:65], 0, v[146:147]
	s_mov_b32 s64, m0
	s_mov_b32 m0, s62
	s_nop 0
	global_load_lds_dwordx4 v[158:159], off
	s_mov_b32 m0, s64
	v_lshl_add_u64 v[158:159], s[68:69], 0, v[146:147]
	s_mov_b32 s64, m0
	s_mov_b32 m0, s63
	s_nop 0
	global_load_lds_dwordx4 v[158:159], off
	s_mov_b32 m0, s64
	ds_read_b128 v[158:161], v7 offset:32768
	ds_read_b128 v[162:165], v7 offset:34816
	ds_read_b128 v[166:169], v7 offset:36864
	ds_read_b128 v[178:181], v7 offset:38912
	ds_read_b128 v[174:177], v6
	ds_read_b128 v[218:221], v6 offset:2048
	ds_read_b128 v[222:225], v6 offset:4096
	ds_read_b128 v[226:229], v6 offset:6144
	s_waitcnt lgkmcnt(3)
	v_mfma_f32_16x16x32_bf16 v[40:43], v[158:161], v[174:177], v[40:43]
	v_mfma_f32_16x16x32_bf16 v[44:47], v[162:165], v[174:177], v[44:47]
	v_mfma_f32_16x16x32_bf16 v[48:51], v[166:169], v[174:177], v[48:51]
	v_mfma_f32_16x16x32_bf16 v[174:177], v[178:181], v[174:177], v[214:217]
	s_nop 2
	ds_read_b128 v[214:217], v6 offset:8192
	s_waitcnt lgkmcnt(3)
	v_mfma_f32_16x16x32_bf16 v[56:59], v[158:161], v[218:221], v[56:59]
	v_mfma_f32_16x16x32_bf16 v[60:63], v[162:165], v[218:221], v[60:63]
	v_mfma_f32_16x16x32_bf16 v[64:67], v[166:169], v[218:221], v[64:67]
	v_mfma_f32_16x16x32_bf16 v[170:173], v[178:181], v[218:221], v[170:173]
	ds_read_b128 v[218:221], v6 offset:10240
	s_waitcnt lgkmcnt(3)
	v_mfma_f32_16x16x32_bf16 v[72:75], v[158:161], v[222:225], v[72:75]
	v_mfma_f32_16x16x32_bf16 v[76:79], v[162:165], v[222:225], v[76:79]
	v_mfma_f32_16x16x32_bf16 v[80:83], v[166:169], v[222:225], v[80:83]
	v_mfma_f32_16x16x32_bf16 v[32:35], v[178:181], v[222:225], v[32:35]
	ds_read_b128 v[222:225], v6 offset:12288
	s_waitcnt lgkmcnt(3)
	v_mfma_f32_16x16x32_bf16 v[88:91], v[158:161], v[226:229], v[88:91]
	v_mfma_f32_16x16x32_bf16 v[92:95], v[162:165], v[226:229], v[92:95]
	v_mfma_f32_16x16x32_bf16 v[96:99], v[166:169], v[226:229], v[96:99]
	v_mfma_f32_16x16x32_bf16 v[36:39], v[178:181], v[226:229], v[36:39]
	ds_read_b128 v[226:229], v6 offset:14336
	s_waitcnt lgkmcnt(3)
	v_mfma_f32_16x16x32_bf16 v[104:107], v[158:161], v[214:217], v[104:107]
	v_mfma_f32_16x16x32_bf16 v[108:111], v[162:165], v[214:217], v[108:111]
	v_mfma_f32_16x16x32_bf16 v[112:115], v[166:169], v[214:217], v[112:115]
	v_mfma_f32_16x16x32_bf16 v[52:55], v[178:181], v[214:217], v[52:55]
	s_waitcnt lgkmcnt(2)
	v_mfma_f32_16x16x32_bf16 v[116:119], v[158:161], v[218:221], v[116:119]
	v_mfma_f32_16x16x32_bf16 v[120:123], v[162:165], v[218:221], v[120:123]
	v_mfma_f32_16x16x32_bf16 v[124:127], v[166:169], v[218:221], v[124:127]
	v_mfma_f32_16x16x32_bf16 v[68:71], v[178:181], v[218:221], v[68:71]
	s_waitcnt lgkmcnt(1)
	v_mfma_f32_16x16x32_bf16 v[132:135], v[162:165], v[222:225], v[132:135]
	v_mfma_f32_16x16x32_bf16 v[84:87], v[178:181], v[222:225], v[84:87]
	s_waitcnt lgkmcnt(0)
	v_mfma_f32_16x16x32_bf16 v[100:103], v[158:161], v[226:229], v[100:103]
	v_mfma_f32_16x16x32_bf16 v[150:153], v[166:169], v[226:229], v[150:153]
	v_mfma_f32_16x16x32_bf16 v[154:157], v[178:181], v[226:229], v[154:157]
	v_mfma_f32_16x16x32_bf16 v[128:131], v[158:161], v[222:225], v[128:131]
	v_mfma_f32_16x16x32_bf16 v[136:139], v[166:169], v[222:225], v[136:139]
	v_mfma_f32_16x16x32_bf16 v[140:143], v[162:165], v[226:229], v[140:143]
	ds_read_b128 v[158:161], v7 offset:33792
	ds_read_b128 v[162:165], v7 offset:35840
	ds_read_b128 v[166:169], v7 offset:37888
	ds_read_b128 v[214:217], v7 offset:39936
	ds_read_b128 v[178:181], v6 offset:1024
	ds_read_b128 v[218:221], v6 offset:3072
	ds_read_b128 v[222:225], v6 offset:5120
	ds_read_b128 v[226:229], v6 offset:7168
	s_waitcnt lgkmcnt(3)
	v_mfma_f32_16x16x32_bf16 v[40:43], v[158:161], v[178:181], v[40:43]
	v_mfma_f32_16x16x32_bf16 v[44:47], v[162:165], v[178:181], v[44:47]
	v_mfma_f32_16x16x32_bf16 v[48:51], v[166:169], v[178:181], v[48:51]
	v_mfma_f32_16x16x32_bf16 v[174:177], v[214:217], v[178:181], v[174:177]
	ds_read_b128 v[178:181], v6 offset:9216
	s_waitcnt lgkmcnt(3)
	v_mfma_f32_16x16x32_bf16 v[56:59], v[158:161], v[218:221], v[56:59]
	v_mfma_f32_16x16x32_bf16 v[60:63], v[162:165], v[218:221], v[60:63]
	v_mfma_f32_16x16x32_bf16 v[64:67], v[166:169], v[218:221], v[64:67]
	v_mfma_f32_16x16x32_bf16 v[170:173], v[214:217], v[218:221], v[170:173]
	ds_read_b128 v[218:221], v6 offset:11264
	s_waitcnt lgkmcnt(3)
	v_mfma_f32_16x16x32_bf16 v[72:75], v[158:161], v[222:225], v[72:75]
	v_mfma_f32_16x16x32_bf16 v[76:79], v[162:165], v[222:225], v[76:79]
	v_mfma_f32_16x16x32_bf16 v[80:83], v[166:169], v[222:225], v[80:83]
	v_mfma_f32_16x16x32_bf16 v[32:35], v[214:217], v[222:225], v[32:35]
	ds_read_b128 v[222:225], v6 offset:13312
	s_waitcnt lgkmcnt(3)
	v_mfma_f32_16x16x32_bf16 v[88:91], v[158:161], v[226:229], v[88:91]
	v_mfma_f32_16x16x32_bf16 v[92:95], v[162:165], v[226:229], v[92:95]
	v_mfma_f32_16x16x32_bf16 v[96:99], v[166:169], v[226:229], v[96:99]
	v_mfma_f32_16x16x32_bf16 v[36:39], v[214:217], v[226:229], v[36:39]
	ds_read_b128 v[226:229], v6 offset:15360
	s_waitcnt lgkmcnt(3)
	v_mfma_f32_16x16x32_bf16 v[104:107], v[158:161], v[178:181], v[104:107]
	v_mfma_f32_16x16x32_bf16 v[108:111], v[162:165], v[178:181], v[108:111]
	v_mfma_f32_16x16x32_bf16 v[112:115], v[166:169], v[178:181], v[112:115]
	v_mfma_f32_16x16x32_bf16 v[52:55], v[214:217], v[178:181], v[52:55]
	s_waitcnt lgkmcnt(2)
	v_mfma_f32_16x16x32_bf16 v[116:119], v[158:161], v[218:221], v[116:119]
	v_mfma_f32_16x16x32_bf16 v[120:123], v[162:165], v[218:221], v[120:123]
	v_mfma_f32_16x16x32_bf16 v[124:127], v[166:169], v[218:221], v[124:127]
	v_mfma_f32_16x16x32_bf16 v[68:71], v[214:217], v[218:221], v[68:71]
	s_waitcnt lgkmcnt(1)
	v_mfma_f32_16x16x32_bf16 v[132:135], v[162:165], v[222:225], v[132:135]
	v_mfma_f32_16x16x32_bf16 v[84:87], v[214:217], v[222:225], v[84:87]
	s_waitcnt lgkmcnt(0)
	v_mfma_f32_16x16x32_bf16 v[100:103], v[158:161], v[226:229], v[100:103]
	v_mfma_f32_16x16x32_bf16 v[150:153], v[166:169], v[226:229], v[150:153]
	v_mfma_f32_16x16x32_bf16 v[154:157], v[214:217], v[226:229], v[154:157]
	v_mfma_f32_16x16x32_bf16 v[128:131], v[158:161], v[222:225], v[128:131]
	v_mfma_f32_16x16x32_bf16 v[136:139], v[166:169], v[222:225], v[136:139]
	v_mfma_f32_16x16x32_bf16 v[140:143], v[162:165], v[226:229], v[140:143]
	s_add_u32 s64, s0, 0x200
	s_addc_u32 s65, s1, 0
	s_add_u32 s68, s14, 0x200
	s_waitcnt vmcnt(0)
	s_barrier
	s_addc_u32 s69, s15, 0
	s_mov_b32 s70, 0x280
	ds_read_b128 v[158:161], v8
	ds_read_b128 v[162:165], v12
	s_mov_b32 m0, s42
	s_nop 0
	global_load_lds_dwordx4 v0, s[64:65]
	ds_read_b128 v[166:169], v9
	s_mov_b32 m0, s43
	s_nop 0
	global_load_lds_dwordx4 v0, s[68:69]
	ds_read_b128 v[178:181], v13
	ds_read_b128 v[214:217], v11
	s_mov_b32 m0, s44
	s_nop 0
	global_load_lds_dwordx4 v2, s[64:65]
	ds_read_b128 v[218:221], v10
	ds_read_b128 v[222:225], v14
	ds_read_b128 v[226:229], v15
	s_branch .Lmy_rot_r_r6a
.Lmy_rr_r6a:
	ds_read_b128 v[158:161], v8
	ds_read_b128 v[162:165], v12
	s_mov_b32 m0, s42
	v_mfma_f32_16x16x32_bf16 v[128:131], v[166:169], v[222:225], v[128:131]
	global_load_lds_dwordx4 v0, s[64:65]
	v_mfma_f32_16x16x32_bf16 v[100:103], v[166:169], v[226:229], v[100:103]
	ds_read_b128 v[166:169], v9
	v_mfma_f32_16x16x32_bf16 v[132:135], v[178:181], v[222:225], v[132:135]
	s_mov_b32 m0, s43
	v_mfma_f32_16x16x32_bf16 v[140:143], v[178:181], v[226:229], v[140:143]
	global_load_lds_dwordx4 v0, s[68:69]
	ds_read_b128 v[178:181], v13
	v_mfma_f32_16x16x32_bf16 v[136:139], v[214:217], v[222:225], v[136:139]
	v_mfma_f32_16x16x32_bf16 v[150:153], v[214:217], v[226:229], v[150:153]
	ds_read_b128 v[214:217], v11
	s_mov_b32 m0, s44
	v_mfma_f32_16x16x32_bf16 v[84:87], v[218:221], v[222:225], v[84:87]
	global_load_lds_dwordx4 v2, s[64:65]
	v_mfma_f32_16x16x32_bf16 v[154:157], v[218:221], v[226:229], v[154:157]
	ds_read_b128 v[218:221], v10
	ds_read_b128 v[222:225], v14
	ds_read_b128 v[226:229], v15
.Lmy_rot_r_r6a:
	s_waitcnt lgkmcnt(6)
	v_mfma_f32_16x16x32_bf16 v[40:43], v[158:161], v[162:165], v[40:43]
	s_waitcnt lgkmcnt(5)
	s_mov_b32 m0, s45
	v_mfma_f32_16x16x32_bf16 v[44:47], v[166:169], v[162:165], v[44:47]
	global_load_lds_dwordx4 v2, s[68:69]
	s_waitcnt lgkmcnt(4)
	v_mfma_f32_16x16x32_bf16 v[56:59], v[158:161], v[178:181], v[56:59]
	v_mfma_f32_16x16x32_bf16 v[60:63], v[166:169], v[178:181], v[60:63]
	s_waitcnt lgkmcnt(3)
	s_mov_b32 m0, s46
	v_mfma_f32_16x16x32_bf16 v[48:51], v[214:217], v[162:165], v[48:51]
	global_load_lds_dwordx4 v4, s[64:65]
	v_mfma_f32_16x16x32_bf16 v[64:67], v[214:217], v[178:181], v[64:67]
	s_waitcnt lgkmcnt(2)
	v_mfma_f32_16x16x32_bf16 v[174:177], v[218:221], v[162:165], v[174:177]
	ds_read_b128 v[162:165], v16
	s_mov_b32 m0, s47
	v_mfma_f32_16x16x32_bf16 v[170:173], v[218:221], v[178:181], v[170:173]
	global_load_lds_dwordx4 v4, s[68:69]
	ds_read_b128 v[178:181], v17
	s_waitcnt lgkmcnt(3)
	v_mfma_f32_16x16x32_bf16 v[72:75], v[158:161], v[222:225], v[72:75]
	v_mfma_f32_16x16x32_bf16 v[76:79], v[166:169], v[222:225], v[76:79]
	s_mov_b32 m0, s49
	v_mfma_f32_16x16x32_bf16 v[80:83], v[214:217], v[222:225], v[80:83]
	global_load_lds_dwordx4 v146, s[64:65]
	v_mfma_f32_16x16x32_bf16 v[32:35], v[218:221], v[222:225], v[32:35]
	ds_read_b128 v[222:225], v18
	s_waitcnt lgkmcnt(3)
	v_mfma_f32_16x16x32_bf16 v[88:91], v[158:161], v[226:229], v[88:91]
	s_mov_b32 m0, s50
	v_mfma_f32_16x16x32_bf16 v[92:95], v[166:169], v[226:229], v[92:95]
	global_load_lds_dwordx4 v146, s[68:69]
	v_mfma_f32_16x16x32_bf16 v[96:99], v[214:217], v[226:229], v[96:99]
	v_mfma_f32_16x16x32_bf16 v[36:39], v[218:221], v[226:229], v[36:39]
	ds_read_b128 v[226:229], v19
	s_waitcnt lgkmcnt(3)
	v_mfma_f32_16x16x32_bf16 v[108:111], v[166:169], v[162:165], v[108:111]
	s_waitcnt lgkmcnt(2)
	v_mfma_f32_16x16x32_bf16 v[120:123], v[166:169], v[178:181], v[120:123]
	s_waitcnt lgkmcnt(1)
	v_mfma_f32_16x16x32_bf16 v[132:135], v[166:169], v[222:225], v[132:135]
	s_waitcnt lgkmcnt(0)
	v_mfma_f32_16x16x32_bf16 v[140:143], v[166:169], v[226:229], v[140:143]
	ds_read_b128 v[166:169], v20
	v_mfma_f32_16x16x32_bf16 v[104:107], v[158:161], v[162:165], v[104:107]
	v_mfma_f32_16x16x32_bf16 v[116:119], v[158:161], v[178:181], v[116:119]
	v_mfma_f32_16x16x32_bf16 v[128:131], v[158:161], v[222:225], v[128:131]
	v_mfma_f32_16x16x32_bf16 v[100:103], v[158:161], v[226:229], v[100:103]
	ds_read_b128 v[158:161], v24
	v_mfma_f32_16x16x32_bf16 v[124:127], v[214:217], v[178:181], v[124:127]
	v_mfma_f32_16x16x32_bf16 v[68:71], v[218:221], v[178:181], v[68:71]
	ds_read_b128 v[178:181], v21
	v_mfma_f32_16x16x32_bf16 v[112:115], v[214:217], v[162:165], v[112:115]
	v_mfma_f32_16x16x32_bf16 v[52:55], v[218:221], v[162:165], v[52:55]
	ds_read_b128 v[162:165], v25
	v_mfma_f32_16x16x32_bf16 v[136:139], v[214:217], v[222:225], v[136:139]
	v_mfma_f32_16x16x32_bf16 v[84:87], v[218:221], v[222:225], v[84:87]
	ds_read_b128 v[222:225], v26
	v_mfma_f32_16x16x32_bf16 v[150:153], v[214:217], v[226:229], v[150:153]
	ds_read_b128 v[214:217], v23
	v_mfma_f32_16x16x32_bf16 v[154:157], v[218:221], v[226:229], v[154:157]
	ds_read_b128 v[218:221], v22
	ds_read_b128 v[226:229], v27
	s_waitcnt lgkmcnt(6)
	v_mfma_f32_16x16x32_bf16 v[40:43], v[166:169], v[158:161], v[40:43]
	s_waitcnt lgkmcnt(5)
	v_mfma_f32_16x16x32_bf16 v[44:47], v[178:181], v[158:161], v[44:47]
	s_waitcnt lgkmcnt(4)
	v_mfma_f32_16x16x32_bf16 v[56:59], v[166:169], v[162:165], v[56:59]
	v_mfma_f32_16x16x32_bf16 v[60:63], v[178:181], v[162:165], v[60:63]
	s_waitcnt lgkmcnt(3)
	v_mfma_f32_16x16x32_bf16 v[72:75], v[166:169], v[222:225], v[72:75]
	v_mfma_f32_16x16x32_bf16 v[76:79], v[178:181], v[222:225], v[76:79]
	s_waitcnt lgkmcnt(2)
	v_mfma_f32_16x16x32_bf16 v[48:51], v[214:217], v[158:161], v[48:51]
	s_waitcnt lgkmcnt(1)
	v_mfma_f32_16x16x32_bf16 v[174:177], v[218:221], v[158:161], v[174:177]
	ds_read_b128 v[158:161], v28
	v_mfma_f32_16x16x32_bf16 v[64:67], v[214:217], v[162:165], v[64:67]
	v_mfma_f32_16x16x32_bf16 v[170:173], v[218:221], v[162:165], v[170:173]
	ds_read_b128 v[162:165], v29
	v_mfma_f32_16x16x32_bf16 v[80:83], v[214:217], v[222:225], v[80:83]
	v_mfma_f32_16x16x32_bf16 v[32:35], v[218:221], v[222:225], v[32:35]
	ds_read_b128 v[222:225], v30
	s_waitcnt lgkmcnt(3)
	v_mfma_f32_16x16x32_bf16 v[88:91], v[166:169], v[226:229], v[88:91]
	v_mfma_f32_16x16x32_bf16 v[92:95], v[178:181], v[226:229], v[92:95]
	v_mfma_f32_16x16x32_bf16 v[96:99], v[214:217], v[226:229], v[96:99]
	v_mfma_f32_16x16x32_bf16 v[36:39], v[218:221], v[226:229], v[36:39]
	ds_read_b128 v[226:229], v31
	s_waitcnt lgkmcnt(3)
	v_mfma_f32_16x16x32_bf16 v[104:107], v[166:169], v[158:161], v[104:107]
	v_mfma_f32_16x16x32_bf16 v[108:111], v[178:181], v[158:161], v[108:111]
	v_mfma_f32_16x16x32_bf16 v[112:115], v[214:217], v[158:161], v[112:115]
	v_mfma_f32_16x16x32_bf16 v[52:55], v[218:221], v[158:161], v[52:55]
	s_waitcnt lgkmcnt(2)
	v_mfma_f32_16x16x32_bf16 v[116:119], v[166:169], v[162:165], v[116:119]
	v_mfma_f32_16x16x32_bf16 v[120:123], v[178:181], v[162:165], v[120:123]
	v_mfma_f32_16x16x32_bf16 v[124:127], v[214:217], v[162:165], v[124:127]
	v_mfma_f32_16x16x32_bf16 v[68:71], v[218:221], v[162:165], v[68:71]
	s_add_u32 s64, s0, s70
	s_addc_u32 s65, s1, 0
	s_add_u32 s68, s14, s70
	s_addc_u32 s69, s15, 0
	s_add_u32 s70, s70, 0x80
	s_waitcnt vmcnt(0)
	s_waitcnt lgkmcnt(0)
	s_barrier
	ds_read_b128 v[158:161], v7 offset:32768
	ds_read_b128 v[162:165], v6
	s_mov_b32 m0, s52
	v_mfma_f32_16x16x32_bf16 v[128:131], v[166:169], v[222:225], v[128:131]
	global_load_lds_dwordx4 v0, s[64:65]
	v_mfma_f32_16x16x32_bf16 v[100:103], v[166:169], v[226:229], v[100:103]
	ds_read_b128 v[166:169], v7 offset:34816
	v_mfma_f32_16x16x32_bf16 v[132:135], v[178:181], v[222:225], v[132:135]
	s_mov_b32 m0, s51
	v_mfma_f32_16x16x32_bf16 v[140:143], v[178:181], v[226:229], v[140:143]
	global_load_lds_dwordx4 v0, s[68:69]
	ds_read_b128 v[178:181], v6 offset:2048
	v_mfma_f32_16x16x32_bf16 v[136:139], v[214:217], v[222:225], v[136:139]
	v_mfma_f32_16x16x32_bf16 v[150:153], v[214:217], v[226:229], v[150:153]
	ds_read_b128 v[214:217], v7 offset:36864
	s_mov_b32 m0, s53
	v_mfma_f32_16x16x32_bf16 v[84:87], v[218:221], v[222:225], v[84:87]
	global_load_lds_dwordx4 v2, s[64:65]
	v_mfma_f32_16x16x32_bf16 v[154:157], v[218:221], v[226:229], v[154:157]
	ds_read_b128 v[218:221], v7 offset:38912
	ds_read_b128 v[222:225], v6 offset:4096
	ds_read_b128 v[226:229], v6 offset:6144
	s_waitcnt lgkmcnt(6)
	v_mfma_f32_16x16x32_bf16 v[40:43], v[158:161], v[162:165], v[40:43]
	s_waitcnt lgkmcnt(5)
	s_mov_b32 m0, s54
	v_mfma_f32_16x16x32_bf16 v[44:47], v[166:169], v[162:165], v[44:47]
	global_load_lds_dwordx4 v2, s[68:69]
	s_waitcnt lgkmcnt(4)
	v_mfma_f32_16x16x32_bf16 v[56:59], v[158:161], v[178:181], v[56:59]
	v_mfma_f32_16x16x32_bf16 v[60:63], v[166:169], v[178:181], v[60:63]
	s_waitcnt lgkmcnt(3)
	s_mov_b32 m0, s55
	v_mfma_f32_16x16x32_bf16 v[48:51], v[214:217], v[162:165], v[48:51]
	global_load_lds_dwordx4 v4, s[64:65]
	v_mfma_f32_16x16x32_bf16 v[64:67], v[214:217], v[178:181], v[64:67]
	s_waitcnt lgkmcnt(2)
	v_mfma_f32_16x16x32_bf16 v[174:177], v[218:221], v[162:165], v[174:177]
	ds_read_b128 v[162:165], v6 offset:8192
	s_mov_b32 m0, s58
	v_mfma_f32_16x16x32_bf16 v[170:173], v[218:221], v[178:181], v[170:173]
	global_load_lds_dwordx4 v4, s[68:69]
	ds_read_b128 v[178:181], v6 offset:10240
	s_waitcnt lgkmcnt(3)
	v_mfma_f32_16x16x32_bf16 v[72:75], v[158:161], v[222:225], v[72:75]
	v_mfma_f32_16x16x32_bf16 v[76:79], v[166:169], v[222:225], v[76:79]
	s_mov_b32 m0, s62
	v_mfma_f32_16x16x32_bf16 v[80:83], v[214:217], v[222:225], v[80:83]
	global_load_lds_dwordx4 v146, s[64:65]
	v_mfma_f32_16x16x32_bf16 v[32:35], v[218:221], v[222:225], v[32:35]
	ds_read_b128 v[222:225], v6 offset:12288
	s_waitcnt lgkmcnt(3)
	v_mfma_f32_16x16x32_bf16 v[88:91], v[158:161], v[226:229], v[88:91]
	s_mov_b32 m0, s63
	v_mfma_f32_16x16x32_bf16 v[92:95], v[166:169], v[226:229], v[92:95]
	global_load_lds_dwordx4 v146, s[68:69]
	v_mfma_f32_16x16x32_bf16 v[96:99], v[214:217], v[226:229], v[96:99]
	v_mfma_f32_16x16x32_bf16 v[36:39], v[218:221], v[226:229], v[36:39]
	ds_read_b128 v[226:229], v6 offset:14336
	s_waitcnt lgkmcnt(3)
	v_mfma_f32_16x16x32_bf16 v[108:111], v[166:169], v[162:165], v[108:111]
	s_waitcnt lgkmcnt(2)
	v_mfma_f32_16x16x32_bf16 v[120:123], v[166:169], v[178:181], v[120:123]
	s_waitcnt lgkmcnt(1)
	v_mfma_f32_16x16x32_bf16 v[132:135], v[166:169], v[222:225], v[132:135]
	s_waitcnt lgkmcnt(0)
	v_mfma_f32_16x16x32_bf16 v[140:143], v[166:169], v[226:229], v[140:143]
	ds_read_b128 v[166:169], v7 offset:33792
	v_mfma_f32_16x16x32_bf16 v[104:107], v[158:161], v[162:165], v[104:107]
	v_mfma_f32_16x16x32_bf16 v[116:119], v[158:161], v[178:181], v[116:119]
	v_mfma_f32_16x16x32_bf16 v[128:131], v[158:161], v[222:225], v[128:131]
	v_mfma_f32_16x16x32_bf16 v[100:103], v[158:161], v[226:229], v[100:103]
	ds_read_b128 v[158:161], v6 offset:1024
	v_mfma_f32_16x16x32_bf16 v[124:127], v[214:217], v[178:181], v[124:127]
	v_mfma_f32_16x16x32_bf16 v[68:71], v[218:221], v[178:181], v[68:71]
	ds_read_b128 v[178:181], v7 offset:35840
	v_mfma_f32_16x16x32_bf16 v[112:115], v[214:217], v[162:165], v[112:115]
	v_mfma_f32_16x16x32_bf16 v[52:55], v[218:221], v[162:165], v[52:55]
	ds_read_b128 v[162:165], v6 offset:3072
	v_mfma_f32_16x16x32_bf16 v[136:139], v[214:217], v[222:225], v[136:139]
	v_mfma_f32_16x16x32_bf16 v[84:87], v[218:221], v[222:225], v[84:87]
	ds_read_b128 v[222:225], v6 offset:5120
	v_mfma_f32_16x16x32_bf16 v[150:153], v[214:217], v[226:229], v[150:153]
	ds_read_b128 v[214:217], v7 offset:37888
	v_mfma_f32_16x16x32_bf16 v[154:157], v[218:221], v[226:229], v[154:157]
	ds_read_b128 v[218:221], v7 offset:39936
	ds_read_b128 v[226:229], v6 offset:7168
	s_waitcnt lgkmcnt(6)
	v_mfma_f32_16x16x32_bf16 v[40:43], v[166:169], v[158:161], v[40:43]
	s_waitcnt lgkmcnt(5)
	v_mfma_f32_16x16x32_bf16 v[44:47], v[178:181], v[158:161], v[44:47]
	s_waitcnt lgkmcnt(4)
	v_mfma_f32_16x16x32_bf16 v[56:59], v[166:169], v[162:165], v[56:59]
	v_mfma_f32_16x16x32_bf16 v[60:63], v[178:181], v[162:165], v[60:63]
	s_waitcnt lgkmcnt(3)
	v_mfma_f32_16x16x32_bf16 v[72:75], v[166:169], v[222:225], v[72:75]
	v_mfma_f32_16x16x32_bf16 v[76:79], v[178:181], v[222:225], v[76:79]
	s_waitcnt lgkmcnt(2)
	v_mfma_f32_16x16x32_bf16 v[48:51], v[214:217], v[158:161], v[48:51]
	s_waitcnt lgkmcnt(1)
	v_mfma_f32_16x16x32_bf16 v[174:177], v[218:221], v[158:161], v[174:177]
	ds_read_b128 v[158:161], v6 offset:9216
	v_mfma_f32_16x16x32_bf16 v[64:67], v[214:217], v[162:165], v[64:67]
	v_mfma_f32_16x16x32_bf16 v[170:173], v[218:221], v[162:165], v[170:173]
	ds_read_b128 v[162:165], v6 offset:11264
	v_mfma_f32_16x16x32_bf16 v[80:83], v[214:217], v[222:225], v[80:83]
	v_mfma_f32_16x16x32_bf16 v[32:35], v[218:221], v[222:225], v[32:35]
	ds_read_b128 v[222:225], v6 offset:13312
	s_waitcnt lgkmcnt(3)
	v_mfma_f32_16x16x32_bf16 v[88:91], v[166:169], v[226:229], v[88:91]
	v_mfma_f32_16x16x32_bf16 v[92:95], v[178:181], v[226:229], v[92:95]
	v_mfma_f32_16x16x32_bf16 v[96:99], v[214:217], v[226:229], v[96:99]
	v_mfma_f32_16x16x32_bf16 v[36:39], v[218:221], v[226:229], v[36:39]
	ds_read_b128 v[226:229], v6 offset:15360
	s_waitcnt lgkmcnt(3)
	v_mfma_f32_16x16x32_bf16 v[104:107], v[166:169], v[158:161], v[104:107]
	v_mfma_f32_16x16x32_bf16 v[108:111], v[178:181], v[158:161], v[108:111]
	v_mfma_f32_16x16x32_bf16 v[112:115], v[214:217], v[158:161], v[112:115]
	v_mfma_f32_16x16x32_bf16 v[52:55], v[218:221], v[158:161], v[52:55]
	s_waitcnt lgkmcnt(2)
	v_mfma_f32_16x16x32_bf16 v[116:119], v[166:169], v[162:165], v[116:119]
	v_mfma_f32_16x16x32_bf16 v[120:123], v[178:181], v[162:165], v[120:123]
	v_mfma_f32_16x16x32_bf16 v[124:127], v[214:217], v[162:165], v[124:127]
	v_mfma_f32_16x16x32_bf16 v[68:71], v[218:221], v[162:165], v[68:71]
	s_add_u32 s64, s0, s70
	s_addc_u32 s65, s1, 0
	s_add_u32 s68, s14, s70
	s_addc_u32 s69, s15, 0
	s_add_u32 s70, s70, 0x80
	s_cmp_lg_u32 s70, 0x2f80
	s_waitcnt vmcnt(0)
	s_waitcnt lgkmcnt(0)
	s_barrier
	s_cbranch_scc1 .Lmy_rr_r6a
	v_mfma_f32_16x16x32_bf16 v[128:131], v[166:169], v[222:225], v[128:131]
	v_mfma_f32_16x16x32_bf16 v[100:103], v[166:169], v[226:229], v[100:103]
	v_mfma_f32_16x16x32_bf16 v[132:135], v[178:181], v[222:225], v[132:135]
	v_mfma_f32_16x16x32_bf16 v[140:143], v[178:181], v[226:229], v[140:143]
	v_mfma_f32_16x16x32_bf16 v[136:139], v[214:217], v[222:225], v[136:139]
	v_mfma_f32_16x16x32_bf16 v[150:153], v[214:217], v[226:229], v[150:153]
	v_mfma_f32_16x16x32_bf16 v[84:87], v[218:221], v[222:225], v[84:87]
	v_mfma_f32_16x16x32_bf16 v[154:157], v[218:221], v[226:229], v[154:157]
	s_nop 15
	s_nop 15
	v_lshl_add_u64 v[158:159], s[64:65], 0, v[0:1]
	s_mov_b32 s70, m0
	s_mov_b32 m0, s42
	s_nop 0
	global_load_lds_dwordx4 v[158:159], off
	s_mov_b32 m0, s70
	v_lshl_add_u64 v[158:159], s[68:69], 0, v[0:1]
	s_mov_b32 s70, m0
	s_mov_b32 m0, s43
	s_nop 0
	global_load_lds_dwordx4 v[158:159], off
	s_mov_b32 m0, s70
	v_lshl_add_u64 v[158:159], s[64:65], 0, v[2:3]
	s_mov_b32 s70, m0
	s_mov_b32 m0, s44
	s_nop 0
	global_load_lds_dwordx4 v[158:159], off
	s_mov_b32 m0, s70
	v_lshl_add_u64 v[158:159], s[68:69], 0, v[2:3]
	s_mov_b32 s70, m0
	s_mov_b32 m0, s45
	s_nop 0
	global_load_lds_dwordx4 v[158:159], off
	s_mov_b32 m0, s70
	v_lshl_add_u64 v[158:159], s[64:65], 0, v[4:5]
	s_mov_b32 s70, m0
	s_mov_b32 m0, s46
	s_nop 0
	global_load_lds_dwordx4 v[158:159], off
	s_mov_b32 m0, s70
	v_lshl_add_u64 v[158:159], s[68:69], 0, v[4:5]
	s_mov_b32 s70, m0
	s_mov_b32 m0, s47
	s_nop 0
	global_load_lds_dwordx4 v[158:159], off
	s_mov_b32 m0, s70
	v_lshl_add_u64 v[158:159], s[64:65], 0, v[146:147]
	s_mov_b32 s64, m0
	s_mov_b32 m0, s49
	s_nop 0
	global_load_lds_dwordx4 v[158:159], off
	s_mov_b32 m0, s64
	v_lshl_add_u64 v[158:159], s[68:69], 0, v[146:147]
	s_mov_b32 s64, m0
	s_mov_b32 m0, s50
	s_nop 0
	global_load_lds_dwordx4 v[158:159], off
	s_mov_b32 m0, s64
	ds_read_b128 v[158:161], v8
	ds_read_b128 v[162:165], v9
	ds_read_b128 v[166:169], v11
	ds_read_b128 v[214:217], v10
	ds_read_b128 v[178:181], v12
	ds_read_b128 v[218:221], v13
	ds_read_b128 v[222:225], v14
	ds_read_b128 v[226:229], v15
	s_waitcnt lgkmcnt(3)
	v_mfma_f32_16x16x32_bf16 v[40:43], v[158:161], v[178:181], v[40:43]
	v_mfma_f32_16x16x32_bf16 v[44:47], v[162:165], v[178:181], v[44:47]
	v_mfma_f32_16x16x32_bf16 v[48:51], v[166:169], v[178:181], v[48:51]
	v_mfma_f32_16x16x32_bf16 v[174:177], v[214:217], v[178:181], v[174:177]
	ds_read_b128 v[178:181], v16
	s_waitcnt lgkmcnt(3)
	v_mfma_f32_16x16x32_bf16 v[56:59], v[158:161], v[218:221], v[56:59]
	v_mfma_f32_16x16x32_bf16 v[60:63], v[162:165], v[218:221], v[60:63]
	v_mfma_f32_16x16x32_bf16 v[64:67], v[166:169], v[218:221], v[64:67]
	v_mfma_f32_16x16x32_bf16 v[170:173], v[214:217], v[218:221], v[170:173]
	ds_read_b128 v[218:221], v17
	s_waitcnt lgkmcnt(3)
	v_mfma_f32_16x16x32_bf16 v[72:75], v[158:161], v[222:225], v[72:75]
	v_mfma_f32_16x16x32_bf16 v[76:79], v[162:165], v[222:225], v[76:79]
	v_mfma_f32_16x16x32_bf16 v[80:83], v[166:169], v[222:225], v[80:83]
	v_mfma_f32_16x16x32_bf16 v[32:35], v[214:217], v[222:225], v[32:35]
	ds_read_b128 v[222:225], v18
	s_waitcnt lgkmcnt(3)
	v_mfma_f32_16x16x32_bf16 v[88:91], v[158:161], v[226:229], v[88:91]
	v_mfma_f32_16x16x32_bf16 v[92:95], v[162:165], v[226:229], v[92:95]
	v_mfma_f32_16x16x32_bf16 v[96:99], v[166:169], v[226:229], v[96:99]
	v_mfma_f32_16x16x32_bf16 v[36:39], v[214:217], v[226:229], v[36:39]
	ds_read_b128 v[226:229], v19
	s_waitcnt lgkmcnt(3)
	v_mfma_f32_16x16x32_bf16 v[104:107], v[158:161], v[178:181], v[104:107]
	v_mfma_f32_16x16x32_bf16 v[108:111], v[162:165], v[178:181], v[108:111]
	v_mfma_f32_16x16x32_bf16 v[112:115], v[166:169], v[178:181], v[112:115]
	v_mfma_f32_16x16x32_bf16 v[52:55], v[214:217], v[178:181], v[52:55]
	s_waitcnt lgkmcnt(2)
	v_mfma_f32_16x16x32_bf16 v[116:119], v[158:161], v[218:221], v[116:119]
	v_mfma_f32_16x16x32_bf16 v[120:123], v[162:165], v[218:221], v[120:123]
	v_mfma_f32_16x16x32_bf16 v[124:127], v[166:169], v[218:221], v[124:127]
	v_mfma_f32_16x16x32_bf16 v[68:71], v[214:217], v[218:221], v[68:71]
	s_waitcnt lgkmcnt(1)
	v_mfma_f32_16x16x32_bf16 v[132:135], v[162:165], v[222:225], v[132:135]
	v_mfma_f32_16x16x32_bf16 v[84:87], v[214:217], v[222:225], v[84:87]
	s_waitcnt lgkmcnt(0)
	v_mfma_f32_16x16x32_bf16 v[100:103], v[158:161], v[226:229], v[100:103]
	v_mfma_f32_16x16x32_bf16 v[150:153], v[166:169], v[226:229], v[150:153]
	v_mfma_f32_16x16x32_bf16 v[154:157], v[214:217], v[226:229], v[154:157]
	v_mfma_f32_16x16x32_bf16 v[128:131], v[158:161], v[222:225], v[128:131]
	v_mfma_f32_16x16x32_bf16 v[136:139], v[166:169], v[222:225], v[136:139]
	v_mfma_f32_16x16x32_bf16 v[140:143], v[162:165], v[226:229], v[140:143]
	ds_read_b128 v[158:161], v20
	ds_read_b128 v[162:165], v21
	ds_read_b128 v[166:169], v23
	ds_read_b128 v[214:217], v22
	ds_read_b128 v[178:181], v24
	ds_read_b128 v[218:221], v25
	ds_read_b128 v[222:225], v26
	ds_read_b128 v[226:229], v27
	s_waitcnt lgkmcnt(3)
	v_mfma_f32_16x16x32_bf16 v[40:43], v[158:161], v[178:181], v[40:43]
	v_mfma_f32_16x16x32_bf16 v[44:47], v[162:165], v[178:181], v[44:47]
	v_mfma_f32_16x16x32_bf16 v[48:51], v[166:169], v[178:181], v[48:51]
	v_mfma_f32_16x16x32_bf16 v[174:177], v[214:217], v[178:181], v[174:177]
	ds_read_b128 v[178:181], v28
	s_waitcnt lgkmcnt(3)
	v_mfma_f32_16x16x32_bf16 v[56:59], v[158:161], v[218:221], v[56:59]
	v_mfma_f32_16x16x32_bf16 v[60:63], v[162:165], v[218:221], v[60:63]
	v_mfma_f32_16x16x32_bf16 v[64:67], v[166:169], v[218:221], v[64:67]
	v_mfma_f32_16x16x32_bf16 v[170:173], v[214:217], v[218:221], v[170:173]
	ds_read_b128 v[218:221], v29
	s_waitcnt lgkmcnt(3)
	v_mfma_f32_16x16x32_bf16 v[72:75], v[158:161], v[222:225], v[72:75]
	v_mfma_f32_16x16x32_bf16 v[76:79], v[162:165], v[222:225], v[76:79]
	v_mfma_f32_16x16x32_bf16 v[80:83], v[166:169], v[222:225], v[80:83]
	v_mfma_f32_16x16x32_bf16 v[32:35], v[214:217], v[222:225], v[32:35]
	ds_read_b128 v[222:225], v30
	s_waitcnt lgkmcnt(3)
	v_mfma_f32_16x16x32_bf16 v[88:91], v[158:161], v[226:229], v[88:91]
	v_mfma_f32_16x16x32_bf16 v[92:95], v[162:165], v[226:229], v[92:95]
	v_mfma_f32_16x16x32_bf16 v[96:99], v[166:169], v[226:229], v[96:99]
	v_mfma_f32_16x16x32_bf16 v[36:39], v[214:217], v[226:229], v[36:39]
	ds_read_b128 v[226:229], v31
	s_waitcnt lgkmcnt(3)
	v_mfma_f32_16x16x32_bf16 v[104:107], v[158:161], v[178:181], v[104:107]
	v_mfma_f32_16x16x32_bf16 v[108:111], v[162:165], v[178:181], v[108:111]
	v_mfma_f32_16x16x32_bf16 v[112:115], v[166:169], v[178:181], v[112:115]
	v_mfma_f32_16x16x32_bf16 v[52:55], v[214:217], v[178:181], v[52:55]
	s_waitcnt lgkmcnt(2)
	v_mfma_f32_16x16x32_bf16 v[116:119], v[158:161], v[218:221], v[116:119]
	v_mfma_f32_16x16x32_bf16 v[120:123], v[162:165], v[218:221], v[120:123]
	v_mfma_f32_16x16x32_bf16 v[124:127], v[166:169], v[218:221], v[124:127]
	v_mfma_f32_16x16x32_bf16 v[68:71], v[214:217], v[218:221], v[68:71]
	s_waitcnt lgkmcnt(1)
	v_mfma_f32_16x16x32_bf16 v[132:135], v[162:165], v[222:225], v[132:135]
	v_mfma_f32_16x16x32_bf16 v[84:87], v[214:217], v[222:225], v[84:87]
	s_waitcnt lgkmcnt(0)
	v_mfma_f32_16x16x32_bf16 v[100:103], v[158:161], v[226:229], v[100:103]
	v_mfma_f32_16x16x32_bf16 v[150:153], v[166:169], v[226:229], v[150:153]
	v_mfma_f32_16x16x32_bf16 v[154:157], v[214:217], v[226:229], v[154:157]
	v_mfma_f32_16x16x32_bf16 v[128:131], v[158:161], v[222:225], v[128:131]
	v_mfma_f32_16x16x32_bf16 v[136:139], v[166:169], v[222:225], v[136:139]
	v_mfma_f32_16x16x32_bf16 v[140:143], v[162:165], v[226:229], v[140:143]
	s_add_u32 s0, s0, 0x2f80
	s_addc_u32 s1, s1, 0
	s_add_u32 s14, s14, 0x2f80
	s_waitcnt vmcnt(0)
	s_barrier
	s_addc_u32 s15, s15, 0
	v_lshl_add_u64 v[158:159], s[0:1], 0, v[0:1]
	s_mov_b32 s64, m0
	s_mov_b32 m0, s52
	s_nop 0
	global_load_lds_dwordx4 v[158:159], off
	s_mov_b32 m0, s64
	v_lshl_add_u64 v[158:159], s[14:15], 0, v[0:1]
	s_mov_b32 s52, m0
	s_mov_b32 m0, s51
	s_nop 0
	global_load_lds_dwordx4 v[158:159], off
	s_mov_b32 m0, s52
	v_lshl_add_u64 v[158:159], s[0:1], 0, v[2:3]
	s_mov_b32 s51, m0
	s_mov_b32 m0, s53
	s_nop 0
	global_load_lds_dwordx4 v[158:159], off
	s_mov_b32 m0, s51
	v_lshl_add_u64 v[158:159], s[14:15], 0, v[2:3]
	s_mov_b32 s51, m0
	s_mov_b32 m0, s54
	s_nop 0
	global_load_lds_dwordx4 v[158:159], off
	s_mov_b32 m0, s51
	v_lshl_add_u64 v[158:159], s[0:1], 0, v[4:5]
	s_mov_b32 s51, m0
	s_mov_b32 m0, s55
	s_nop 0
	global_load_lds_dwordx4 v[158:159], off
	s_mov_b32 m0, s51
	v_lshl_add_u64 v[158:159], s[14:15], 0, v[4:5]
	s_mov_b32 s51, m0
	s_mov_b32 m0, s58
	s_nop 0
	global_load_lds_dwordx4 v[158:159], off
	s_mov_b32 m0, s51
	v_lshl_add_u64 v[158:159], s[0:1], 0, v[146:147]
	s_mov_b32 s0, m0
	s_mov_b32 m0, s62
	s_nop 0
	global_load_lds_dwordx4 v[158:159], off
	s_mov_b32 m0, s0
	v_lshl_add_u64 v[158:159], s[14:15], 0, v[146:147]
	s_mov_b32 s0, m0
	s_mov_b32 m0, s63
	s_nop 0
	global_load_lds_dwordx4 v[158:159], off
	s_mov_b32 m0, s0
	ds_read_b128 v[158:161], v7 offset:32768
	ds_read_b128 v[162:165], v7 offset:34816
	ds_read_b128 v[166:169], v7 offset:36864
	ds_read_b128 v[214:217], v7 offset:38912
	ds_read_b128 v[178:181], v6
	ds_read_b128 v[218:221], v6 offset:2048
	ds_read_b128 v[222:225], v6 offset:4096
	ds_read_b128 v[226:229], v6 offset:6144
	s_waitcnt lgkmcnt(3)
	v_mfma_f32_16x16x32_bf16 v[40:43], v[158:161], v[178:181], v[40:43]
	v_mfma_f32_16x16x32_bf16 v[44:47], v[162:165], v[178:181], v[44:47]
	v_mfma_f32_16x16x32_bf16 v[48:51], v[166:169], v[178:181], v[48:51]
	v_mfma_f32_16x16x32_bf16 v[174:177], v[214:217], v[178:181], v[174:177]
	ds_read_b128 v[178:181], v6 offset:8192
	s_waitcnt lgkmcnt(3)
	v_mfma_f32_16x16x32_bf16 v[56:59], v[158:161], v[218:221], v[56:59]
	v_mfma_f32_16x16x32_bf16 v[60:63], v[162:165], v[218:221], v[60:63]
	v_mfma_f32_16x16x32_bf16 v[64:67], v[166:169], v[218:221], v[64:67]
	v_mfma_f32_16x16x32_bf16 v[170:173], v[214:217], v[218:221], v[170:173]
	ds_read_b128 v[218:221], v6 offset:10240
	s_waitcnt lgkmcnt(3)
	v_mfma_f32_16x16x32_bf16 v[72:75], v[158:161], v[222:225], v[72:75]
	v_mfma_f32_16x16x32_bf16 v[76:79], v[162:165], v[222:225], v[76:79]
	v_mfma_f32_16x16x32_bf16 v[80:83], v[166:169], v[222:225], v[80:83]
	v_mfma_f32_16x16x32_bf16 v[32:35], v[214:217], v[222:225], v[32:35]
	ds_read_b128 v[222:225], v6 offset:12288
	s_waitcnt lgkmcnt(3)
	v_mfma_f32_16x16x32_bf16 v[88:91], v[158:161], v[226:229], v[88:91]
	v_mfma_f32_16x16x32_bf16 v[92:95], v[162:165], v[226:229], v[92:95]
	v_mfma_f32_16x16x32_bf16 v[96:99], v[166:169], v[226:229], v[96:99]
	v_mfma_f32_16x16x32_bf16 v[36:39], v[214:217], v[226:229], v[36:39]
	ds_read_b128 v[226:229], v6 offset:14336
	s_waitcnt lgkmcnt(3)
	v_mfma_f32_16x16x32_bf16 v[104:107], v[158:161], v[178:181], v[104:107]
	v_mfma_f32_16x16x32_bf16 v[108:111], v[162:165], v[178:181], v[108:111]
	v_mfma_f32_16x16x32_bf16 v[112:115], v[166:169], v[178:181], v[112:115]
	v_mfma_f32_16x16x32_bf16 v[52:55], v[214:217], v[178:181], v[52:55]
	s_waitcnt lgkmcnt(2)
	v_mfma_f32_16x16x32_bf16 v[116:119], v[158:161], v[218:221], v[116:119]
	v_mfma_f32_16x16x32_bf16 v[120:123], v[162:165], v[218:221], v[120:123]
	v_mfma_f32_16x16x32_bf16 v[124:127], v[166:169], v[218:221], v[124:127]
	v_mfma_f32_16x16x32_bf16 v[68:71], v[214:217], v[218:221], v[68:71]
	s_waitcnt lgkmcnt(1)
	v_mfma_f32_16x16x32_bf16 v[132:135], v[162:165], v[222:225], v[132:135]
	v_mfma_f32_16x16x32_bf16 v[84:87], v[214:217], v[222:225], v[84:87]
	s_waitcnt lgkmcnt(0)
	v_mfma_f32_16x16x32_bf16 v[100:103], v[158:161], v[226:229], v[100:103]
	v_mfma_f32_16x16x32_bf16 v[150:153], v[166:169], v[226:229], v[150:153]
	v_mfma_f32_16x16x32_bf16 v[154:157], v[214:217], v[226:229], v[154:157]
	v_mfma_f32_16x16x32_bf16 v[128:131], v[158:161], v[222:225], v[128:131]
	v_mfma_f32_16x16x32_bf16 v[136:139], v[166:169], v[222:225], v[136:139]
	v_mfma_f32_16x16x32_bf16 v[140:143], v[162:165], v[226:229], v[140:143]
	ds_read_b128 v[158:161], v7 offset:33792
	ds_read_b128 v[162:165], v7 offset:35840
	ds_read_b128 v[166:169], v7 offset:37888
	ds_read_b128 v[214:217], v7 offset:39936
	ds_read_b128 v[178:181], v6 offset:1024
	ds_read_b128 v[218:221], v6 offset:3072
	ds_read_b128 v[222:225], v6 offset:5120
	ds_read_b128 v[226:229], v6 offset:7168
	s_waitcnt lgkmcnt(3)
	v_mfma_f32_16x16x32_bf16 v[40:43], v[158:161], v[178:181], v[40:43]
	v_mfma_f32_16x16x32_bf16 v[44:47], v[162:165], v[178:181], v[44:47]
	v_mfma_f32_16x16x32_bf16 v[48:51], v[166:169], v[178:181], v[48:51]
	v_mfma_f32_16x16x32_bf16 v[174:177], v[214:217], v[178:181], v[174:177]
	ds_read_b128 v[178:181], v6 offset:9216
	s_waitcnt lgkmcnt(3)
	v_mfma_f32_16x16x32_bf16 v[56:59], v[158:161], v[218:221], v[56:59]
	v_mfma_f32_16x16x32_bf16 v[60:63], v[162:165], v[218:221], v[60:63]
	v_mfma_f32_16x16x32_bf16 v[64:67], v[166:169], v[218:221], v[64:67]
	v_mfma_f32_16x16x32_bf16 v[170:173], v[214:217], v[218:221], v[170:173]
	ds_read_b128 v[218:221], v6 offset:11264
	s_waitcnt lgkmcnt(3)
	v_mfma_f32_16x16x32_bf16 v[72:75], v[158:161], v[222:225], v[72:75]
	v_mfma_f32_16x16x32_bf16 v[76:79], v[162:165], v[222:225], v[76:79]
	v_mfma_f32_16x16x32_bf16 v[80:83], v[166:169], v[222:225], v[80:83]
	v_mfma_f32_16x16x32_bf16 v[32:35], v[214:217], v[222:225], v[32:35]
	ds_read_b128 v[222:225], v6 offset:13312
	s_waitcnt lgkmcnt(3)
	v_mfma_f32_16x16x32_bf16 v[88:91], v[158:161], v[226:229], v[88:91]
	v_mfma_f32_16x16x32_bf16 v[92:95], v[162:165], v[226:229], v[92:95]
	v_mfma_f32_16x16x32_bf16 v[96:99], v[166:169], v[226:229], v[96:99]
	v_mfma_f32_16x16x32_bf16 v[36:39], v[214:217], v[226:229], v[36:39]
	ds_read_b128 v[226:229], v6 offset:15360
	s_waitcnt lgkmcnt(3)
	v_mfma_f32_16x16x32_bf16 v[104:107], v[158:161], v[178:181], v[104:107]
	v_mfma_f32_16x16x32_bf16 v[108:111], v[162:165], v[178:181], v[108:111]
	v_mfma_f32_16x16x32_bf16 v[112:115], v[166:169], v[178:181], v[112:115]
	v_mfma_f32_16x16x32_bf16 v[52:55], v[214:217], v[178:181], v[52:55]
	s_waitcnt lgkmcnt(2)
	v_mfma_f32_16x16x32_bf16 v[116:119], v[158:161], v[218:221], v[116:119]
	v_mfma_f32_16x16x32_bf16 v[120:123], v[162:165], v[218:221], v[120:123]
	v_mfma_f32_16x16x32_bf16 v[124:127], v[166:169], v[218:221], v[124:127]
	v_mfma_f32_16x16x32_bf16 v[68:71], v[214:217], v[218:221], v[68:71]
	s_waitcnt lgkmcnt(1)
	v_mfma_f32_16x16x32_bf16 v[132:135], v[162:165], v[222:225], v[132:135]
	v_mfma_f32_16x16x32_bf16 v[84:87], v[214:217], v[222:225], v[84:87]
	s_waitcnt lgkmcnt(0)
	v_mfma_f32_16x16x32_bf16 v[100:103], v[158:161], v[226:229], v[100:103]
	v_mfma_f32_16x16x32_bf16 v[150:153], v[166:169], v[226:229], v[150:153]
	v_mfma_f32_16x16x32_bf16 v[154:157], v[214:217], v[226:229], v[154:157]
	v_mfma_f32_16x16x32_bf16 v[128:131], v[158:161], v[222:225], v[128:131]
	v_mfma_f32_16x16x32_bf16 v[136:139], v[166:169], v[222:225], v[136:139]
	v_mfma_f32_16x16x32_bf16 v[140:143], v[162:165], v[226:229], v[140:143]
	s_waitcnt vmcnt(0)
	s_barrier
	v_lshl_add_u64 v[6:7], s[20:21], 0, v[0:1]
	s_mov_b32 s0, m0
	s_mov_b32 m0, s42
	s_nop 0
	global_load_lds_dwordx4 v[6:7], off
	s_mov_b32 m0, s0
	v_lshl_add_u64 v[0:1], s[22:23], 0, v[0:1]
	s_mov_b32 s0, m0
	s_mov_b32 m0, s43
	s_nop 0
	global_load_lds_dwordx4 v[0:1], off
	s_mov_b32 m0, s0
	v_lshl_add_u64 v[0:1], s[20:21], 0, v[2:3]
	s_mov_b32 s0, m0
	s_mov_b32 m0, s44
	s_nop 0
	global_load_lds_dwordx4 v[0:1], off
	s_mov_b32 m0, s0
	v_lshl_add_u64 v[0:1], s[22:23], 0, v[2:3]
	s_mov_b32 s0, m0
	s_mov_b32 m0, s45
	s_nop 0
	global_load_lds_dwordx4 v[0:1], off
	s_mov_b32 m0, s0
	v_lshl_add_u64 v[0:1], s[20:21], 0, v[4:5]
	s_mov_b32 s0, m0
	s_mov_b32 m0, s46
	s_nop 0
	global_load_lds_dwordx4 v[0:1], off
	s_mov_b32 m0, s0
	v_lshl_add_u64 v[0:1], s[22:23], 0, v[4:5]
	s_mov_b32 s0, m0
	s_mov_b32 m0, s47
	s_nop 0
	global_load_lds_dwordx4 v[0:1], off
	s_mov_b32 m0, s0
	v_lshl_add_u64 v[0:1], s[20:21], 0, v[146:147]
	s_mov_b32 s0, m0
	s_mov_b32 m0, s49
	s_nop 0
	global_load_lds_dwordx4 v[0:1], off
	s_mov_b32 m0, s0
	v_lshl_add_u64 v[0:1], s[22:23], 0, v[146:147]
	s_mov_b32 s0, m0
	s_mov_b32 m0, s50
	s_nop 0
	global_load_lds_dwordx4 v[0:1], off
	s_mov_b32 m0, s0
	ds_read_b128 v[0:3], v8
	ds_read_b128 v[4:7], v9
	ds_read_b128 v[158:161], v11
	ds_read_b128 v[8:11], v10
	ds_read_b128 v[162:165], v12
	ds_read_b128 v[166:169], v13
	ds_read_b128 v[178:181], v14
	ds_read_b128 v[12:15], v15
	s_waitcnt lgkmcnt(3)
	v_mfma_f32_16x16x32_bf16 v[40:43], v[0:3], v[162:165], v[40:43]
	v_mfma_f32_16x16x32_bf16 v[44:47], v[4:7], v[162:165], v[44:47]
	v_mfma_f32_16x16x32_bf16 v[48:51], v[158:161], v[162:165], v[48:51]
	v_mfma_f32_16x16x32_bf16 v[162:165], v[8:11], v[162:165], v[174:177]
	s_nop 2
	ds_read_b128 v[174:177], v16
	s_waitcnt lgkmcnt(3)
	v_mfma_f32_16x16x32_bf16 v[56:59], v[0:3], v[166:169], v[56:59]
	v_mfma_f32_16x16x32_bf16 v[60:63], v[4:7], v[166:169], v[60:63]
	v_mfma_f32_16x16x32_bf16 v[64:67], v[158:161], v[166:169], v[64:67]
	v_mfma_f32_16x16x32_bf16 v[166:169], v[8:11], v[166:169], v[170:173]
	s_nop 2
	ds_read_b128 v[170:173], v17
	s_waitcnt lgkmcnt(3)
	v_mfma_f32_16x16x32_bf16 v[72:75], v[0:3], v[178:181], v[72:75]
	v_mfma_f32_16x16x32_bf16 v[76:79], v[4:7], v[178:181], v[76:79]
	v_mfma_f32_16x16x32_bf16 v[80:83], v[158:161], v[178:181], v[80:83]
	v_mfma_f32_16x16x32_bf16 v[32:35], v[8:11], v[178:181], v[32:35]
	ds_read_b128 v[178:181], v18
	s_waitcnt lgkmcnt(3)
	v_mfma_f32_16x16x32_bf16 v[214:217], v[0:3], v[12:15], v[88:91]
	v_mfma_f32_16x16x32_bf16 v[218:221], v[4:7], v[12:15], v[92:95]
	v_mfma_f32_16x16x32_bf16 v[222:225], v[158:161], v[12:15], v[96:99]
	v_mfma_f32_16x16x32_bf16 v[12:15], v[8:11], v[12:15], v[36:39]
	ds_read_b128 v[16:19], v19
	s_waitcnt lgkmcnt(3)
	v_mfma_f32_16x16x32_bf16 v[36:39], v[0:3], v[174:177], v[104:107]
	v_mfma_f32_16x16x32_bf16 v[226:229], v[4:7], v[174:177], v[108:111]
	v_mfma_f32_16x16x32_bf16 v[112:115], v[158:161], v[174:177], v[112:115]
	s_waitcnt lgkmcnt(2)
	v_mfma_f32_16x16x32_bf16 v[116:119], v[0:3], v[170:173], v[116:119]
	v_mfma_f32_16x16x32_bf16 v[120:123], v[4:7], v[170:173], v[120:123]
	v_mfma_f32_16x16x32_bf16 v[124:127], v[158:161], v[170:173], v[124:127]
	s_waitcnt lgkmcnt(1)
	v_mfma_f32_16x16x32_bf16 v[128:131], v[0:3], v[178:181], v[128:131]
	v_mfma_f32_16x16x32_bf16 v[132:135], v[4:7], v[178:181], v[132:135]
	s_waitcnt lgkmcnt(0)
	v_mfma_f32_16x16x32_bf16 v[0:3], v[0:3], v[16:19], v[100:103]
	v_mfma_f32_16x16x32_bf16 v[4:7], v[4:7], v[16:19], v[140:143]
	v_mfma_f32_16x16x32_bf16 v[140:143], v[158:161], v[16:19], v[150:153]
	v_mfma_f32_16x16x32_bf16 v[150:153], v[8:11], v[16:19], v[154:157]
	v_mfma_f32_16x16x32_bf16 v[174:177], v[8:11], v[174:177], v[52:55]
	v_mfma_f32_16x16x32_bf16 v[170:173], v[8:11], v[170:173], v[68:71]
	v_mfma_f32_16x16x32_bf16 v[136:139], v[158:161], v[178:181], v[136:139]
	v_mfma_f32_16x16x32_bf16 v[178:181], v[8:11], v[178:181], v[84:87]
	ds_read_b128 v[8:11], v20
	ds_read_b128 v[154:157], v21
	ds_read_b128 v[158:161], v23
	ds_read_b128 v[230:233], v22
	ds_read_b128 v[16:19], v24
	ds_read_b128 v[20:23], v25
	ds_read_b128 v[52:55], v26
	ds_read_b128 v[24:27], v27
	s_waitcnt lgkmcnt(3)
	v_mfma_f32_16x16x32_bf16 v[234:237], v[8:11], v[16:19], v[40:43]
	v_mfma_f32_16x16x32_bf16 v[238:241], v[154:157], v[16:19], v[44:47]
	v_mfma_f32_16x16x32_bf16 v[242:245], v[158:161], v[16:19], v[48:51]
	v_mfma_f32_16x16x32_bf16 v[162:165], v[230:233], v[16:19], v[162:165]
	ds_read_b128 v[16:19], v28
	s_waitcnt lgkmcnt(3)
	v_mfma_f32_16x16x32_bf16 v[108:111], v[8:11], v[20:23], v[56:59]
	v_mfma_f32_16x16x32_bf16 v[104:107], v[154:157], v[20:23], v[60:63]
	v_mfma_f32_16x16x32_bf16 v[100:103], v[158:161], v[20:23], v[64:67]
	v_mfma_f32_16x16x32_bf16 v[96:99], v[230:233], v[20:23], v[166:169]
	ds_read_b128 v[20:23], v29
	s_waitcnt lgkmcnt(3)
	v_mfma_f32_16x16x32_bf16 v[92:95], v[8:11], v[52:55], v[72:75]
	v_mfma_f32_16x16x32_bf16 v[88:91], v[154:157], v[52:55], v[76:79]
	v_mfma_f32_16x16x32_bf16 v[84:87], v[158:161], v[52:55], v[80:83]
	v_mfma_f32_16x16x32_bf16 v[80:83], v[230:233], v[52:55], v[32:35]
	ds_read_b128 v[166:169], v30
	s_waitcnt lgkmcnt(3)
	v_mfma_f32_16x16x32_bf16 v[76:79], v[8:11], v[24:27], v[214:217]
	v_mfma_f32_16x16x32_bf16 v[72:75], v[154:157], v[24:27], v[218:221]
	v_mfma_f32_16x16x32_bf16 v[68:71], v[158:161], v[24:27], v[222:225]
	v_mfma_f32_16x16x32_bf16 v[64:67], v[230:233], v[24:27], v[12:15]
	ds_read_b128 v[214:217], v31
	s_waitcnt lgkmcnt(3)
	v_mfma_f32_16x16x32_bf16 v[60:63], v[8:11], v[16:19], v[36:39]
	v_mfma_f32_16x16x32_bf16 v[56:59], v[154:157], v[16:19], v[226:229]
	v_mfma_f32_16x16x32_bf16 v[52:55], v[158:161], v[16:19], v[112:115]
	v_mfma_f32_16x16x32_bf16 v[48:51], v[230:233], v[16:19], v[174:177]
	s_waitcnt lgkmcnt(2)
	v_mfma_f32_16x16x32_bf16 v[44:47], v[8:11], v[20:23], v[116:119]
	v_mfma_f32_16x16x32_bf16 v[40:43], v[154:157], v[20:23], v[120:123]
	v_mfma_f32_16x16x32_bf16 v[36:39], v[158:161], v[20:23], v[124:127]
	v_mfma_f32_16x16x32_bf16 v[32:35], v[230:233], v[20:23], v[170:173]
	s_waitcnt lgkmcnt(1)
	v_mfma_f32_16x16x32_bf16 v[28:31], v[8:11], v[166:169], v[128:131]
	v_mfma_f32_16x16x32_bf16 v[24:27], v[154:157], v[166:169], v[132:135]
	v_mfma_f32_16x16x32_bf16 v[20:23], v[158:161], v[166:169], v[136:139]
	v_mfma_f32_16x16x32_bf16 v[16:19], v[230:233], v[166:169], v[178:181]
	s_waitcnt lgkmcnt(0)
	v_mfma_f32_16x16x32_bf16 v[12:15], v[8:11], v[214:217], v[0:3]
	v_mfma_f32_16x16x32_bf16 v[8:11], v[154:157], v[214:217], v[4:7]
	v_mfma_f32_16x16x32_bf16 v[4:7], v[158:161], v[214:217], v[140:143]
	v_mfma_f32_16x16x32_bf16 v[0:3], v[230:233], v[214:217], v[150:153]
	v_mov_b32_e32 v145, v184
	s_waitcnt vmcnt(0)
	s_barrier
	s_lshl_b32 s20, s13, 8
	s_lshl_b32 s14, s12, 8
	v_and_b32_e32 v151, 15, v145
	v_ashrrev_i32_e32 v112, 1, v145
	v_and_b32_e32 v153, 0xffffff80, v112
	v_or_b32_e32 v112, s20, v151
	v_add_u32_e32 v112, v112, v153
	v_ashrrev_i32_e32 v113, 31, v112
	v_lshlrev_b64 v[112:113], 13, v[112:113]
	v_bfe_u32 v150, v145, 6, 2
	v_lshl_add_u64 v[112:113], s[4:5], 0, v[112:113]
	s_ashr_i32 s15, s14, 31
	v_bfe_u32 v152, v145, 4, 2
	v_lshl_add_u64 v[112:113], s[14:15], 2, v[112:113]
	v_lshlrev_b32_e32 v146, 8, v150
	v_lshl_add_u64 v[112:113], v[112:113], 0, v[146:147]
	v_lshlrev_b32_e32 v146, 4, v152
	v_lshl_add_u64 v[154:155], v[112:113], 0, v[146:147]
	global_load_dwordx4 v[120:123], v[154:155], off offset:192
	global_load_dwordx4 v[128:131], v[154:155], off offset:128
	global_load_dwordx4 v[136:139], v[154:155], off offset:64
	global_load_dwordx4 v[140:143], v[154:155], off
	v_add_co_u32_e32 v112, vcc, s66, v154
	v_lshlrev_b32_e32 v158, 2, v152
	s_nop 0
	v_addc_co_u32_e32 v113, vcc, 0, v155, vcc
	global_load_dwordx4 v[132:135], v[112:113], off
	global_load_dwordx4 v[124:127], v[112:113], off offset:64
	global_load_dwordx4 v[116:119], v[112:113], off offset:128
	v_cmp_lt_i32_e32 vcc, v188, v186
	global_load_dwordx4 v[112:115], v[112:113], off offset:192
	v_cmp_eq_u32_e64 s[0:1], 0, v152
	v_cndmask_b32_e32 v146, v185, v188, vcc
	v_cmp_lt_i32_e32 vcc, v187, v186
	v_lshlrev_b32_e32 v149, 2, v146
	v_lshlrev_b32_e32 v157, 6, v150
	v_cndmask_b32_e32 v156, v185, v187, vcc
	v_lshlrev_b32_e32 v146, 2, v156
	v_or_b32_e32 v156, v153, v151
	v_add_u32_e32 v152, s20, v156
	v_ashrrev_i32_e32 v153, 31, v152
	v_lshl_or_b32 v182, v150, 10, v204
	v_or3_b32 v150, v157, s14, v158
	v_lshlrev_b64 v[158:159], 13, v[152:153]
	v_ashrrev_i32_e32 v151, 31, v150
	v_lshlrev_b64 v[160:161], 12, v[152:153]
	v_lshl_add_u64 v[158:159], s[4:5], 0, v[158:159]
	v_lshl_add_u64 v[160:161], s[6:7], 0, v[160:161]
	v_lshl_add_u64 v[166:167], v[150:151], 2, v[158:159]
	v_lshl_add_u64 v[168:169], v[150:151], 1, v[160:161]
	s_waitcnt vmcnt(7)
	v_pk_add_f32 v[158:159], v[162:163], v[120:121]
	s_waitcnt vmcnt(6)
	v_pk_add_f32 v[120:121], v[242:243], v[128:129]
	s_waitcnt vmcnt(5)
	v_pk_add_f32 v[128:129], v[238:239], v[136:137]
	s_waitcnt vmcnt(4)
	v_pk_add_f32 v[136:137], v[234:235], v[140:141]
	v_pk_add_f32 v[160:161], v[164:165], v[122:123]
	v_pk_add_f32 v[122:123], v[244:245], v[130:131]
	v_pk_add_f32 v[130:131], v[240:241], v[138:139]
	v_pk_add_f32 v[138:139], v[236:237], v[142:143]
	v_pk_mul_f32 v[172:173], v[128:129], v[128:129]
	v_pk_mul_f32 v[178:179], v[136:137], v[136:137]
	v_pk_mul_f32 v[162:163], v[120:121], v[120:121]
	v_pk_mul_f32 v[174:175], v[130:131], v[130:131]
	v_cvt_pk_bf16_f32 v176, v136, v137
	v_pk_mul_f32 v[180:181], v[138:139], v[138:139]
	global_store_dwordx4 v[166:167], v[136:139], off
	v_add_f32_e32 v153, v172, v173
	v_add_f32_e32 v157, v178, v179
	v_pk_mul_f32 v[136:137], v[158:159], v[158:159]
	v_pk_mul_f32 v[164:165], v[122:123], v[122:123]
	v_cvt_pk_bf16_f32 v177, v138, v139
	v_pk_mul_f32 v[138:139], v[160:161], v[160:161]
	v_add_f32_e32 v162, v162, v163
	v_add_f32_e32 v136, v136, v137
	v_add_f32_e32 v137, v174, v153
	v_add_f32_e32 v153, v180, v157
	v_add_f32_e32 v157, v164, v162
	v_add_f32_e32 v136, v138, v136
	v_add_f32_e32 v137, v175, v137
	v_add_f32_e32 v138, v181, v153
	v_add_f32_e32 v153, v165, v157
	v_add_f32_e32 v137, v138, v137
	v_add_f32_e32 v137, v137, v153
	v_add_f32_e32 v136, v139, v136
	v_add_f32_e32 v136, v137, v136
	ds_bpermute_b32 v137, v149, v136
	v_cvt_pk_bf16_f32 v170, v128, v129
	v_cvt_pk_bf16_f32 v171, v130, v131
	v_cvt_pk_bf16_f32 v142, v120, v121
	global_store_dwordx2 v[168:169], v[176:177], off
	global_store_dwordx4 v[166:167], v[128:131], off offset:64
	global_store_dwordx2 v[168:169], v[170:171], off offset:32
	global_store_dwordx4 v[166:167], v[120:123], off offset:128
	v_cvt_pk_bf16_f32 v140, v158, v159
	v_cvt_pk_bf16_f32 v141, v160, v161
	s_waitcnt lgkmcnt(0)
	v_add_f32_e32 v120, v136, v137
	ds_bpermute_b32 v121, v146, v120
	v_cvt_pk_bf16_f32 v143, v122, v123
	v_lshl_add_u32 v153, v156, 2, v182
	global_store_dwordx2 v[168:169], v[142:143], off offset:64
	global_store_dwordx4 v[166:167], v[158:161], off offset:192
	global_store_dwordx2 v[168:169], v[140:141], off offset:96
	s_and_saveexec_b64 s[14:15], s[0:1]
	s_cbranch_execz .LBB0_567
	s_waitcnt lgkmcnt(0)
	v_add_f32_e32 v120, v120, v121
	ds_write_b32 v153, v120

.LBB0_626:
	s_ashr_i32 s43, s42, 31
	s_lshl_b64 s[42:43], s[42:43], 20
	s_add_u32 s42, s58, s42
	s_addc_u32 s43, s62, s43
	s_ashr_i32 s5, s4, 31
	v_lshlrev_b32_e32 v3, 6, v1
	s_lshl_b64 s[4:5], s[4:5], 20
	v_and_b32_e32 v2, 48, v1
	v_and_b32_e32 v4, 0x3c0, v3
	v_lshlrev_b32_e32 v1, 2, v1
	s_add_u32 s4, s54, s4
	v_or_b32_e32 v5, v4, v2
	v_and_b32_e32 v1, 32, v1
	v_lshlrev_b32_e32 v0, 13, v0
	s_mov_b32 s80, 0x18000
	s_addc_u32 s5, s55, s5
	v_and_b32_e32 v111, 0x6000, v0
	s_add_i32 s46, s1, 0x10000
	s_add_i32 s47, s1, 0x18000
	s_add_i32 s74, s1, 0x12000
	s_add_i32 s75, s1, 0x1a000
	s_add_i32 s76, s1, 0x14000
	s_add_i32 s77, s1, 0x1c000
	s_add_i32 s78, s1, 0x16000
	s_add_i32 s79, s1, 0x1e000
	v_bitop3_b32 v0, v5, s80, v1 bitop3:0xde
	s_mov_b32 s80, 0x10400
	v_bitop3_b32 v149, v5, s80, v1 bitop3:0xde
	s_add_u32 s80, s52, s2
	s_addc_u32 s81, s53, s3
	s_add_i32 s2, s82, s83
	s_ashr_i32 s3, s2, 31
	s_waitcnt vmcnt(0)
	s_lshl_b64 s[2:3], s[2:3], 20
	v_bitop3_b32 v110, v4, v1, v2 bitop3:0x36
	v_and_b32_e32 v112, 0xffffc000, v3
	s_add_u32 s82, s10, s2
	v_mov_b32_e32 v4, 0
	v_or_b32_e32 v113, 0x800, v112
	v_or_b32_e32 v114, 0x1000, v112
	v_or_b32_e32 v115, 0x1800, v112
	v_or_b32_e32 v116, 0x2000, v112
	v_or_b32_e32 v117, 0x2800, v112
	v_or_b32_e32 v118, 0x3000, v112
	v_or_b32_e32 v119, 0x3800, v112
	v_bitop3_b32 v145, v5, s33, v1 bitop3:0xde
	s_addc_u32 s83, s11, s3
	s_mov_b64 s[2:3], 0
	s_mov_b32 s84, 1
	v_add_u32_e32 v150, v0, v111
	v_mov_b32_e32 v5, v4
	v_mov_b32_e32 v6, v4
	v_mov_b32_e32 v7, v4
	v_mov_b32_e32 v72, v4
	v_mov_b32_e32 v73, v4
	v_mov_b32_e32 v74, v4
	v_mov_b32_e32 v75, v4
	v_mov_b32_e32 v12, v4
	v_mov_b32_e32 v13, v4
	v_mov_b32_e32 v14, v4
	v_mov_b32_e32 v15, v4
	v_mov_b32_e32 v76, v4
	v_mov_b32_e32 v77, v4
	v_mov_b32_e32 v78, v4
	v_mov_b32_e32 v79, v4
	v_mov_b32_e32 v16, v4
	v_mov_b32_e32 v17, v4
	v_mov_b32_e32 v18, v4
	v_mov_b32_e32 v19, v4
	v_mov_b32_e32 v80, v4
	v_mov_b32_e32 v81, v4
	v_mov_b32_e32 v82, v4
	v_mov_b32_e32 v83, v4
	v_mov_b32_e32 v20, v4
	v_mov_b32_e32 v21, v4
	v_mov_b32_e32 v22, v4
	v_mov_b32_e32 v23, v4
	v_mov_b32_e32 v84, v4
	v_mov_b32_e32 v85, v4
	v_mov_b32_e32 v86, v4
	v_mov_b32_e32 v87, v4
	v_mov_b32_e32 v24, v4
	v_mov_b32_e32 v25, v4
	v_mov_b32_e32 v26, v4
	v_mov_b32_e32 v27, v4
	v_mov_b32_e32 v88, v4
	v_mov_b32_e32 v89, v4
	v_mov_b32_e32 v90, v4
	v_mov_b32_e32 v91, v4
	v_mov_b32_e32 v28, v4
	v_mov_b32_e32 v29, v4
	v_mov_b32_e32 v30, v4
	v_mov_b32_e32 v31, v4
	v_mov_b32_e32 v92, v4
	v_mov_b32_e32 v93, v4
	v_mov_b32_e32 v94, v4
	v_mov_b32_e32 v95, v4
	v_mov_b32_e32 v32, v4
	v_mov_b32_e32 v33, v4
	v_mov_b32_e32 v34, v4
	v_mov_b32_e32 v35, v4
	v_mov_b32_e32 v96, v4
	v_mov_b32_e32 v97, v4
	v_mov_b32_e32 v98, v4
	v_mov_b32_e32 v99, v4
	v_mov_b32_e32 v36, v4
	v_mov_b32_e32 v37, v4
	v_mov_b32_e32 v38, v4
	v_mov_b32_e32 v39, v4
	v_mov_b32_e32 v100, v4
	v_mov_b32_e32 v101, v4
	v_mov_b32_e32 v102, v4
	v_mov_b32_e32 v103, v4
	v_mov_b32_e32 v40, v4
	v_mov_b32_e32 v41, v4
	v_mov_b32_e32 v42, v4
	v_mov_b32_e32 v43, v4
	v_mov_b32_e32 v120, v4
	v_mov_b32_e32 v121, v4
	v_mov_b32_e32 v122, v4
	v_mov_b32_e32 v123, v4
	v_mov_b32_e32 v44, v4
	v_mov_b32_e32 v45, v4
	v_mov_b32_e32 v46, v4
	v_mov_b32_e32 v47, v4
	v_mov_b32_e32 v124, v4
	v_mov_b32_e32 v125, v4
	v_mov_b32_e32 v126, v4
	v_mov_b32_e32 v127, v4
	v_mov_b32_e32 v48, v4
	v_mov_b32_e32 v49, v4
	v_mov_b32_e32 v50, v4
	v_mov_b32_e32 v51, v4
	v_mov_b32_e32 v128, v4
	v_mov_b32_e32 v129, v4
	v_mov_b32_e32 v130, v4
	v_mov_b32_e32 v131, v4
	v_mov_b32_e32 v52, v4
	v_mov_b32_e32 v53, v4
	v_mov_b32_e32 v54, v4
	v_mov_b32_e32 v55, v4
	v_mov_b32_e32 v132, v4
	v_mov_b32_e32 v133, v4
	v_mov_b32_e32 v134, v4
	v_mov_b32_e32 v135, v4
	v_mov_b32_e32 v56, v4
	v_mov_b32_e32 v57, v4
	v_mov_b32_e32 v58, v4
	v_mov_b32_e32 v59, v4
	v_mov_b32_e32 v136, v4
	v_mov_b32_e32 v137, v4
	v_mov_b32_e32 v138, v4
	v_mov_b32_e32 v139, v4
	v_mov_b32_e32 v60, v4
	v_mov_b32_e32 v61, v4
	v_mov_b32_e32 v62, v4
	v_mov_b32_e32 v63, v4
	v_mov_b32_e32 v140, v4
	v_mov_b32_e32 v141, v4
	v_mov_b32_e32 v142, v4
	v_mov_b32_e32 v143, v4
	v_mov_b32_e32 v64, v4
	v_mov_b32_e32 v65, v4
	v_mov_b32_e32 v66, v4
	v_mov_b32_e32 v67, v4
	v_mov_b32_e32 v0, v4
	v_mov_b32_e32 v1, v4
	v_mov_b32_e32 v2, v4
	v_mov_b32_e32 v3, v4
	v_mov_b32_e32 v68, v4
	v_mov_b32_e32 v69, v4
	v_mov_b32_e32 v70, v4
	v_mov_b32_e32 v71, v4
	v_mov_b32_e32 v8, v4
	v_mov_b32_e32 v9, v4
	v_mov_b32_e32 v10, v4
	v_mov_b32_e32 v11, v4
	s_waitcnt lgkmcnt(0)
	s_barrier
	s_add_u32 s85, s82, s2
	s_addc_u32 s90, s83, s3
	s_add_u32 s86, s85, 0x1b900080
	s_addc_u32 s87, s90, 0
	s_add_u32 s91, s80, s2
	s_addc_u32 s92, s81, s3
	s_add_u32 s88, s91, 0x3400080
	s_addc_u32 s89, s92, 0
	v_add_u32_e32 v151, v110, v111
	v_add_u32_e32 v189, v110, v112
	ds_read_b128 v[152:155], v151 offset:32768
	ds_read_b128 v[156:159], v189
	s_mov_b32 m0, s46
	s_nop 0
	global_load_lds_dwordx4 v104, s[86:87]
	ds_read_b128 v[160:163], v151 offset:34816
	s_mov_b32 m0, s47
	s_nop 0
	global_load_lds_dwordx4 v104, s[88:89]
	ds_read_b128 v[164:167], v189 offset:2048
	ds_read_b128 v[168:171], v151 offset:36864
	s_mov_b32 m0, s74
	s_nop 0
	global_load_lds_dwordx4 v106, s[86:87]
	ds_read_b128 v[172:175], v151 offset:38912
	ds_read_b128 v[176:179], v189 offset:4096
	ds_read_b128 v[180:183], v189 offset:6144
	s_branch .Lmy_rot_627
.LBB0_627:
	s_add_u32 s85, s82, s2
	s_addc_u32 s90, s83, s3
	s_add_u32 s86, s85, 0x1b900080
	s_addc_u32 s87, s90, 0
	s_add_u32 s91, s80, s2
	s_addc_u32 s92, s81, s3
	s_add_u32 s88, s91, 0x3400080
	s_addc_u32 s89, s92, 0
	v_add_u32_e32 v151, v110, v111
	v_add_u32_e32 v189, v110, v112
	ds_read_b128 v[152:155], v151 offset:32768
	ds_read_b128 v[156:159], v189
	s_mov_b32 m0, s46
	v_mfma_f32_16x16x32_bf16 v[76:79], v[160:163], v[176:179], v[76:79]
	global_load_lds_dwordx4 v104, s[86:87]
	v_mfma_f32_16x16x32_bf16 v[64:67], v[160:163], v[180:183], v[64:67]
	ds_read_b128 v[160:163], v151 offset:34816
	v_mfma_f32_16x16x32_bf16 v[12:15], v[164:167], v[176:179], v[12:15]
	s_mov_b32 m0, s47
	v_mfma_f32_16x16x32_bf16 v[0:3], v[164:167], v[180:183], v[0:3]
	global_load_lds_dwordx4 v104, s[88:89]
	ds_read_b128 v[164:167], v189 offset:2048
	v_mfma_f32_16x16x32_bf16 v[72:75], v[168:171], v[176:179], v[72:75]
	v_mfma_f32_16x16x32_bf16 v[68:71], v[168:171], v[180:183], v[68:71]
	ds_read_b128 v[168:171], v151 offset:36864
	s_mov_b32 m0, s74
	v_mfma_f32_16x16x32_bf16 v[4:7], v[172:175], v[176:179], v[4:7]
	global_load_lds_dwordx4 v106, s[86:87]
	v_mfma_f32_16x16x32_bf16 v[8:11], v[172:175], v[180:183], v[8:11]
	ds_read_b128 v[172:175], v151 offset:38912
	ds_read_b128 v[176:179], v189 offset:4096
	ds_read_b128 v[180:183], v189 offset:6144
.Lmy_rot_627:
	s_waitcnt lgkmcnt(6)
	v_mfma_f32_16x16x32_bf16 v[140:143], v[152:155], v[156:159], v[140:143]
	s_waitcnt lgkmcnt(5)
	s_mov_b32 m0, s75
	v_mfma_f32_16x16x32_bf16 v[60:63], v[160:163], v[156:159], v[60:63]
	global_load_lds_dwordx4 v106, s[88:89]
	s_waitcnt lgkmcnt(4)
	v_mfma_f32_16x16x32_bf16 v[132:135], v[152:155], v[164:167], v[132:135]
	v_mfma_f32_16x16x32_bf16 v[52:55], v[160:163], v[164:167], v[52:55]
	s_waitcnt lgkmcnt(3)
	s_mov_b32 m0, s76
	v_mfma_f32_16x16x32_bf16 v[136:139], v[168:171], v[156:159], v[136:139]
	global_load_lds_dwordx4 v108, s[86:87]
	v_mfma_f32_16x16x32_bf16 v[128:131], v[168:171], v[164:167], v[128:131]
	s_waitcnt lgkmcnt(2)
	v_mfma_f32_16x16x32_bf16 v[56:59], v[172:175], v[156:159], v[56:59]
	ds_read_b128 v[156:159], v189 offset:8192
	s_mov_b32 m0, s77
	v_mfma_f32_16x16x32_bf16 v[48:51], v[172:175], v[164:167], v[48:51]
	global_load_lds_dwordx4 v108, s[88:89]
	ds_read_b128 v[164:167], v189 offset:10240
	s_waitcnt lgkmcnt(3)
	v_mfma_f32_16x16x32_bf16 v[124:127], v[152:155], v[176:179], v[124:127]
	v_mfma_f32_16x16x32_bf16 v[44:47], v[160:163], v[176:179], v[44:47]
	s_mov_b32 m0, s78
	v_mfma_f32_16x16x32_bf16 v[120:123], v[168:171], v[176:179], v[120:123]
	global_load_lds_dwordx4 v146, s[86:87]
	v_mfma_f32_16x16x32_bf16 v[40:43], v[172:175], v[176:179], v[40:43]
	ds_read_b128 v[176:179], v189 offset:12288
	s_waitcnt lgkmcnt(3)
	v_mfma_f32_16x16x32_bf16 v[100:103], v[152:155], v[180:183], v[100:103]
	s_mov_b32 m0, s79
	v_mfma_f32_16x16x32_bf16 v[36:39], v[160:163], v[180:183], v[36:39]
	global_load_lds_dwordx4 v146, s[88:89]
	v_mfma_f32_16x16x32_bf16 v[96:99], v[168:171], v[180:183], v[96:99]
	v_mfma_f32_16x16x32_bf16 v[32:35], v[172:175], v[180:183], v[32:35]
	ds_read_b128 v[180:183], v189 offset:14336
	s_waitcnt lgkmcnt(3)
	v_mfma_f32_16x16x32_bf16 v[28:31], v[160:163], v[156:159], v[28:31]
	s_waitcnt lgkmcnt(2)
	v_mfma_f32_16x16x32_bf16 v[20:23], v[160:163], v[164:167], v[20:23]
	s_waitcnt lgkmcnt(1)
	v_mfma_f32_16x16x32_bf16 v[12:15], v[160:163], v[176:179], v[12:15]
	s_waitcnt lgkmcnt(0)
	v_mfma_f32_16x16x32_bf16 v[0:3], v[160:163], v[180:183], v[0:3]
	ds_read_b128 v[160:163], v151 offset:33792
	v_mfma_f32_16x16x32_bf16 v[92:95], v[152:155], v[156:159], v[92:95]
	v_mfma_f32_16x16x32_bf16 v[84:87], v[152:155], v[164:167], v[84:87]
	v_mfma_f32_16x16x32_bf16 v[76:79], v[152:155], v[176:179], v[76:79]
	v_mfma_f32_16x16x32_bf16 v[64:67], v[152:155], v[180:183], v[64:67]
	ds_read_b128 v[152:155], v189 offset:1024
	v_mfma_f32_16x16x32_bf16 v[80:83], v[168:171], v[164:167], v[80:83]
	v_mfma_f32_16x16x32_bf16 v[16:19], v[172:175], v[164:167], v[16:19]
	ds_read_b128 v[164:167], v151 offset:35840
	v_mfma_f32_16x16x32_bf16 v[88:91], v[168:171], v[156:159], v[88:91]
	v_mfma_f32_16x16x32_bf16 v[24:27], v[172:175], v[156:159], v[24:27]
	ds_read_b128 v[156:159], v189 offset:3072
	v_mfma_f32_16x16x32_bf16 v[72:75], v[168:171], v[176:179], v[72:75]
	v_mfma_f32_16x16x32_bf16 v[4:7], v[172:175], v[176:179], v[4:7]
	ds_read_b128 v[176:179], v189 offset:5120
	v_mfma_f32_16x16x32_bf16 v[68:71], v[168:171], v[180:183], v[68:71]
	ds_read_b128 v[168:171], v151 offset:37888
	v_mfma_f32_16x16x32_bf16 v[8:11], v[172:175], v[180:183], v[8:11]
	ds_read_b128 v[172:175], v151 offset:39936
	ds_read_b128 v[180:183], v189 offset:7168
	s_waitcnt lgkmcnt(6)
	v_mfma_f32_16x16x32_bf16 v[140:143], v[160:163], v[152:155], v[140:143]
	s_waitcnt lgkmcnt(5)
	v_mfma_f32_16x16x32_bf16 v[60:63], v[164:167], v[152:155], v[60:63]
	s_waitcnt lgkmcnt(4)
	v_mfma_f32_16x16x32_bf16 v[132:135], v[160:163], v[156:159], v[132:135]
	v_mfma_f32_16x16x32_bf16 v[52:55], v[164:167], v[156:159], v[52:55]
	s_waitcnt lgkmcnt(3)
	v_mfma_f32_16x16x32_bf16 v[124:127], v[160:163], v[176:179], v[124:127]
	v_mfma_f32_16x16x32_bf16 v[44:47], v[164:167], v[176:179], v[44:47]
	s_waitcnt lgkmcnt(2)
	v_mfma_f32_16x16x32_bf16 v[136:139], v[168:171], v[152:155], v[136:139]
	s_waitcnt lgkmcnt(1)
	v_mfma_f32_16x16x32_bf16 v[56:59], v[172:175], v[152:155], v[56:59]
	ds_read_b128 v[152:155], v189 offset:9216
	v_mfma_f32_16x16x32_bf16 v[128:131], v[168:171], v[156:159], v[128:131]
	v_mfma_f32_16x16x32_bf16 v[48:51], v[172:175], v[156:159], v[48:51]
	ds_read_b128 v[156:159], v189 offset:11264
	v_mfma_f32_16x16x32_bf16 v[120:123], v[168:171], v[176:179], v[120:123]
	v_mfma_f32_16x16x32_bf16 v[40:43], v[172:175], v[176:179], v[40:43]
	ds_read_b128 v[176:179], v189 offset:13312
	s_waitcnt lgkmcnt(3)
	v_mfma_f32_16x16x32_bf16 v[100:103], v[160:163], v[180:183], v[100:103]
	v_mfma_f32_16x16x32_bf16 v[36:39], v[164:167], v[180:183], v[36:39]
	v_mfma_f32_16x16x32_bf16 v[96:99], v[168:171], v[180:183], v[96:99]
	v_mfma_f32_16x16x32_bf16 v[32:35], v[172:175], v[180:183], v[32:35]
	ds_read_b128 v[180:183], v189 offset:15360
	s_waitcnt lgkmcnt(3)
	v_mfma_f32_16x16x32_bf16 v[92:95], v[160:163], v[152:155], v[92:95]
	v_mfma_f32_16x16x32_bf16 v[28:31], v[164:167], v[152:155], v[28:31]
	v_mfma_f32_16x16x32_bf16 v[88:91], v[168:171], v[152:155], v[88:91]
	v_mfma_f32_16x16x32_bf16 v[24:27], v[172:175], v[152:155], v[24:27]
	s_waitcnt lgkmcnt(2)
	v_mfma_f32_16x16x32_bf16 v[84:87], v[160:163], v[156:159], v[84:87]
	v_mfma_f32_16x16x32_bf16 v[20:23], v[164:167], v[156:159], v[20:23]
	v_mfma_f32_16x16x32_bf16 v[80:83], v[168:171], v[156:159], v[80:83]
	v_mfma_f32_16x16x32_bf16 v[16:19], v[172:175], v[156:159], v[16:19]
	s_add_u32 s85, s85, 0x1b900100
	s_addc_u32 s86, s90, 0
	s_add_u32 s88, s91, 0x3400100
	s_addc_u32 s89, s92, 0
	s_cmp_lt_u32 s84, 31
	s_cselect_b32 s87, s86, s43
	s_cselect_b32 s86, s85, s42
	s_waitcnt vmcnt(0)
	s_waitcnt lgkmcnt(0)
	s_barrier
	s_cselect_b32 s89, s89, s5
	s_cselect_b32 s88, s88, s4
	ds_read_b128 v[152:155], v150
	v_add_u32_e32 v151, v145, v112
	ds_read_b128 v[156:159], v151
	s_mov_b32 m0, s1
	v_mfma_f32_16x16x32_bf16 v[76:79], v[160:163], v[176:179], v[76:79]
	global_load_lds_dwordx4 v104, s[86:87]
	v_mfma_f32_16x16x32_bf16 v[64:67], v[160:163], v[180:183], v[64:67]
	ds_read_b128 v[160:163], v150 offset:2048
	v_mfma_f32_16x16x32_bf16 v[12:15], v[164:167], v[176:179], v[12:15]
	s_mov_b32 m0, s45
	v_mfma_f32_16x16x32_bf16 v[0:3], v[164:167], v[180:183], v[0:3]
	global_load_lds_dwordx4 v104, s[88:89]
	v_add_u32_e32 v151, v145, v113
	ds_read_b128 v[164:167], v151
	v_mfma_f32_16x16x32_bf16 v[72:75], v[168:171], v[176:179], v[72:75]
	v_mfma_f32_16x16x32_bf16 v[68:71], v[168:171], v[180:183], v[68:71]
	ds_read_b128 v[168:171], v150 offset:4096
	s_mov_b32 m0, s68
	v_mfma_f32_16x16x32_bf16 v[4:7], v[172:175], v[176:179], v[4:7]
	global_load_lds_dwordx4 v106, s[86:87]
	v_mfma_f32_16x16x32_bf16 v[8:11], v[172:175], v[180:183], v[8:11]
	ds_read_b128 v[172:175], v150 offset:6144
	v_add_u32_e32 v151, v145, v114
	ds_read_b128 v[176:179], v151
	v_add_u32_e32 v151, v145, v115
	ds_read_b128 v[180:183], v151
	s_waitcnt lgkmcnt(6)
	v_mfma_f32_16x16x32_bf16 v[140:143], v[152:155], v[156:159], v[140:143]
	s_waitcnt lgkmcnt(5)
	s_mov_b32 m0, s69
	v_mfma_f32_16x16x32_bf16 v[60:63], v[160:163], v[156:159], v[60:63]
	global_load_lds_dwordx4 v106, s[88:89]
	s_waitcnt lgkmcnt(4)
	v_mfma_f32_16x16x32_bf16 v[132:135], v[152:155], v[164:167], v[132:135]
	v_mfma_f32_16x16x32_bf16 v[52:55], v[160:163], v[164:167], v[52:55]
	s_waitcnt lgkmcnt(3)
	s_mov_b32 m0, s70
	v_mfma_f32_16x16x32_bf16 v[136:139], v[168:171], v[156:159], v[136:139]
	global_load_lds_dwordx4 v108, s[86:87]
	v_mfma_f32_16x16x32_bf16 v[128:131], v[168:171], v[164:167], v[128:131]
	s_waitcnt lgkmcnt(2)
	v_mfma_f32_16x16x32_bf16 v[56:59], v[172:175], v[156:159], v[56:59]
	v_add_u32_e32 v151, v145, v116
	ds_read_b128 v[156:159], v151
	s_mov_b32 m0, s71
	v_mfma_f32_16x16x32_bf16 v[48:51], v[172:175], v[164:167], v[48:51]
	global_load_lds_dwordx4 v108, s[88:89]
	v_add_u32_e32 v151, v145, v117
	ds_read_b128 v[164:167], v151
	s_waitcnt lgkmcnt(3)
	v_mfma_f32_16x16x32_bf16 v[124:127], v[152:155], v[176:179], v[124:127]
	v_mfma_f32_16x16x32_bf16 v[44:47], v[160:163], v[176:179], v[44:47]
	s_mov_b32 m0, s72
	v_mfma_f32_16x16x32_bf16 v[120:123], v[168:171], v[176:179], v[120:123]
	global_load_lds_dwordx4 v146, s[86:87]
	v_mfma_f32_16x16x32_bf16 v[40:43], v[172:175], v[176:179], v[40:43]
	v_add_u32_e32 v151, v145, v118
	ds_read_b128 v[176:179], v151
	s_waitcnt lgkmcnt(3)
	v_mfma_f32_16x16x32_bf16 v[100:103], v[152:155], v[180:183], v[100:103]
	s_mov_b32 m0, s73
	v_mfma_f32_16x16x32_bf16 v[36:39], v[160:163], v[180:183], v[36:39]
	global_load_lds_dwordx4 v146, s[88:89]
	v_mfma_f32_16x16x32_bf16 v[96:99], v[168:171], v[180:183], v[96:99]
	v_mfma_f32_16x16x32_bf16 v[32:35], v[172:175], v[180:183], v[32:35]
	v_add_u32_e32 v151, v145, v119
	ds_read_b128 v[180:183], v151
	s_waitcnt lgkmcnt(3)
	v_mfma_f32_16x16x32_bf16 v[28:31], v[160:163], v[156:159], v[28:31]
	s_waitcnt lgkmcnt(2)
	v_mfma_f32_16x16x32_bf16 v[20:23], v[160:163], v[164:167], v[20:23]
	s_waitcnt lgkmcnt(1)
	v_mfma_f32_16x16x32_bf16 v[12:15], v[160:163], v[176:179], v[12:15]
	s_waitcnt lgkmcnt(0)
	v_mfma_f32_16x16x32_bf16 v[0:3], v[160:163], v[180:183], v[0:3]
	ds_read_b128 v[160:163], v150 offset:1024
	v_mfma_f32_16x16x32_bf16 v[92:95], v[152:155], v[156:159], v[92:95]
	v_mfma_f32_16x16x32_bf16 v[84:87], v[152:155], v[164:167], v[84:87]
	v_mfma_f32_16x16x32_bf16 v[76:79], v[152:155], v[176:179], v[76:79]
	v_mfma_f32_16x16x32_bf16 v[64:67], v[152:155], v[180:183], v[64:67]
	v_add_u32_e32 v151, v149, v112
	ds_read_b128 v[152:155], v151
	v_mfma_f32_16x16x32_bf16 v[80:83], v[168:171], v[164:167], v[80:83]
	v_mfma_f32_16x16x32_bf16 v[16:19], v[172:175], v[164:167], v[16:19]
	ds_read_b128 v[164:167], v150 offset:3072
	v_mfma_f32_16x16x32_bf16 v[88:91], v[168:171], v[156:159], v[88:91]
	v_mfma_f32_16x16x32_bf16 v[24:27], v[172:175], v[156:159], v[24:27]
	v_add_u32_e32 v151, v149, v113
	ds_read_b128 v[156:159], v151
	v_mfma_f32_16x16x32_bf16 v[72:75], v[168:171], v[176:179], v[72:75]
	v_mfma_f32_16x16x32_bf16 v[4:7], v[172:175], v[176:179], v[4:7]
	v_add_u32_e32 v151, v149, v114
	ds_read_b128 v[176:179], v151
	v_mfma_f32_16x16x32_bf16 v[68:71], v[168:171], v[180:183], v[68:71]
	ds_read_b128 v[168:171], v150 offset:5120
	v_mfma_f32_16x16x32_bf16 v[8:11], v[172:175], v[180:183], v[8:11]
	ds_read_b128 v[172:175], v150 offset:7168
	v_add_u32_e32 v151, v149, v115
	ds_read_b128 v[180:183], v151
	s_waitcnt lgkmcnt(6)
	v_mfma_f32_16x16x32_bf16 v[140:143], v[160:163], v[152:155], v[140:143]
	s_waitcnt lgkmcnt(5)
	v_mfma_f32_16x16x32_bf16 v[60:63], v[164:167], v[152:155], v[60:63]
	s_waitcnt lgkmcnt(4)
	v_mfma_f32_16x16x32_bf16 v[132:135], v[160:163], v[156:159], v[132:135]
	v_mfma_f32_16x16x32_bf16 v[52:55], v[164:167], v[156:159], v[52:55]
	s_waitcnt lgkmcnt(3)
	v_mfma_f32_16x16x32_bf16 v[124:127], v[160:163], v[176:179], v[124:127]
	v_mfma_f32_16x16x32_bf16 v[44:47], v[164:167], v[176:179], v[44:47]
	s_waitcnt lgkmcnt(2)
	v_mfma_f32_16x16x32_bf16 v[136:139], v[168:171], v[152:155], v[136:139]
	s_waitcnt lgkmcnt(1)
	v_mfma_f32_16x16x32_bf16 v[56:59], v[172:175], v[152:155], v[56:59]
	v_add_u32_e32 v151, v149, v116
	ds_read_b128 v[152:155], v151
	v_mfma_f32_16x16x32_bf16 v[128:131], v[168:171], v[156:159], v[128:131]
	v_mfma_f32_16x16x32_bf16 v[48:51], v[172:175], v[156:159], v[48:51]
	v_add_u32_e32 v151, v149, v117
	ds_read_b128 v[156:159], v151
	v_mfma_f32_16x16x32_bf16 v[120:123], v[168:171], v[176:179], v[120:123]
	v_mfma_f32_16x16x32_bf16 v[40:43], v[172:175], v[176:179], v[40:43]
	v_add_u32_e32 v151, v149, v118
	ds_read_b128 v[176:179], v151
	s_waitcnt lgkmcnt(3)
	v_mfma_f32_16x16x32_bf16 v[100:103], v[160:163], v[180:183], v[100:103]
	v_mfma_f32_16x16x32_bf16 v[36:39], v[164:167], v[180:183], v[36:39]
	v_mfma_f32_16x16x32_bf16 v[96:99], v[168:171], v[180:183], v[96:99]
	v_mfma_f32_16x16x32_bf16 v[32:35], v[172:175], v[180:183], v[32:35]
	v_add_u32_e32 v151, v149, v119
	ds_read_b128 v[180:183], v151
	s_waitcnt lgkmcnt(3)
	v_mfma_f32_16x16x32_bf16 v[92:95], v[160:163], v[152:155], v[92:95]
	v_mfma_f32_16x16x32_bf16 v[28:31], v[164:167], v[152:155], v[28:31]
	v_mfma_f32_16x16x32_bf16 v[88:91], v[168:171], v[152:155], v[88:91]
	v_mfma_f32_16x16x32_bf16 v[24:27], v[172:175], v[152:155], v[24:27]
	s_waitcnt lgkmcnt(2)
	v_mfma_f32_16x16x32_bf16 v[84:87], v[160:163], v[156:159], v[84:87]
	v_mfma_f32_16x16x32_bf16 v[20:23], v[164:167], v[156:159], v[20:23]
	v_mfma_f32_16x16x32_bf16 v[80:83], v[168:171], v[156:159], v[80:83]
	v_mfma_f32_16x16x32_bf16 v[16:19], v[172:175], v[156:159], v[16:19]
	s_waitcnt vmcnt(0)
	s_add_u32 s2, s2, 0x100
	s_addc_u32 s3, s3, 0
	s_add_i32 s84, s84, 2
	s_cmpk_lg_i32 s2, 0x1000
	s_waitcnt lgkmcnt(0)
	s_barrier
	s_cbranch_scc1 .LBB0_627
	v_mfma_f32_16x16x32_bf16 v[76:79], v[160:163], v[176:179], v[76:79]
	v_mfma_f32_16x16x32_bf16 v[64:67], v[160:163], v[180:183], v[64:67]
	v_mfma_f32_16x16x32_bf16 v[12:15], v[164:167], v[176:179], v[12:15]
	v_mfma_f32_16x16x32_bf16 v[0:3], v[164:167], v[180:183], v[0:3]
	v_mfma_f32_16x16x32_bf16 v[72:75], v[168:171], v[176:179], v[72:75]
	v_mfma_f32_16x16x32_bf16 v[68:71], v[168:171], v[180:183], v[68:71]
	v_mfma_f32_16x16x32_bf16 v[4:7], v[172:175], v[176:179], v[4:7]
	v_mfma_f32_16x16x32_bf16 v[8:11], v[172:175], v[180:183], v[8:11]
	s_nop 15
	s_nop 15
	v_mov_b32_e32 v145, v184
	s_movk_i32 s1, 0x100
	v_and_b32_e32 v167, 15, v145
	v_cmp_gt_u32_e64 s[2:3], s1, v145
	v_cmp_lt_u32_e32 vcc, 13, v167
	s_and_b64 s[4:5], s[2:3], vcc
	s_xor_b64 s[4:5], s[4:5], -1
	v_lshlrev_b32_e32 v149, 6, v167
	s_and_saveexec_b64 s[42:43], s[4:5]
	s_xor_b64 s[4:5], exec, s[42:43]
	v_lshlrev_b32_e32 v149, 6, v167
	s_or_saveexec_b64 s[4:5], s[4:5]
	v_bfe_u32 v152, v145, 4, 2
	v_readlane_b32 s68, v253, 18
	v_readlane_b32 s75, v253, 20
	s_xor_b64 exec, exec, s[4:5]
	s_cbranch_execz .LBB0_632
	v_mov_b32_e32 v104, 0x211c0
	v_lshl_or_b32 v104, v167, 2, v104
	ds_read_b32 v108, v104
	v_and_b32_e32 v104, 0xc0, v145
	v_lshl_add_u32 v104, v104, 2, v149
	v_lshl_or_b32 v109, v152, 4, v104
	v_add_u32_e32 v110, 0x1fc80, v109
	s_waitcnt lgkmcnt(0)
	v_pk_mul_f32 v[104:105], v[64:65], v[108:109] op_sel_hi:[1,0]
	v_pk_mul_f32 v[106:107], v[66:67], v[108:109] op_sel_hi:[1,0]
	v_add_u32_e32 v109, 0x1fd00, v109
	ds_write_b128 v110, v[104:107]
	v_pk_mul_f32 v[104:105], v[0:1], v[108:109] op_sel_hi:[1,0]
	v_pk_mul_f32 v[106:107], v[2:3], v[108:109] op_sel_hi:[1,0]
	ds_write_b128 v109, v[104:107]

.LBB0_696:
	s_ashr_i32 s23, s22, 31
	s_lshl_b64 s[22:23], s[22:23], 20
	s_add_u32 s22, s28, s22
	s_addc_u32 s23, s29, s23
	s_ashr_i32 s25, s24, 31
	s_lshl_b64 s[24:25], s[24:25], 20
	s_add_u32 s24, s6, s24
	s_addc_u32 s25, s7, s25
	s_add_u32 s46, s14, 0x80
	v_and_b32_e32 v8, 48, v7
	v_lshlrev_b32_e32 v9, 6, v7
	v_lshlrev_b32_e32 v7, 2, v7
	s_addc_u32 s47, s15, 0
	v_and_b32_e32 v10, 0x3c0, v9
	v_and_b32_e32 v149, 32, v7
	s_add_u32 s50, s20, 0x80
	v_or_b32_e32 v145, v10, v8
	v_bitop3_b32 v12, v10, v149, v8 bitop3:0x36
	s_waitcnt vmcnt(0)
	s_barrier
	v_lshlrev_b32_e32 v8, 13, v6
	s_addc_u32 s51, s21, 0
	s_add_i32 s27, s1, 0x10000
	v_lshl_add_u64 v[6:7], s[46:47], 0, v[0:1]
	s_mov_b32 s41, m0
	s_mov_b32 m0, s27
	s_nop 0
	global_load_lds_dwordx4 v[6:7], off
	s_mov_b32 m0, s41
	s_add_i32 s26, s1, 0x18000
	v_lshl_add_u64 v[6:7], s[50:51], 0, v[0:1]
	s_mov_b32 s41, m0
	s_mov_b32 m0, s26
	s_nop 0
	global_load_lds_dwordx4 v[6:7], off
	s_mov_b32 m0, s41
	v_lshl_add_u64 v[6:7], s[46:47], 0, v[2:3]
	s_add_i32 s41, s1, 0x12000
	s_mov_b32 s42, m0
	s_mov_b32 m0, s41
	s_nop 0
	global_load_lds_dwordx4 v[6:7], off
	s_mov_b32 m0, s42
	v_lshl_add_u64 v[6:7], s[50:51], 0, v[2:3]
	s_add_i32 s42, s1, 0x1a000
	s_mov_b32 s43, m0
	s_mov_b32 m0, s42
	s_nop 0
	global_load_lds_dwordx4 v[6:7], off
	s_mov_b32 m0, s43
	v_lshl_add_u64 v[6:7], s[46:47], 0, v[4:5]
	s_add_i32 s43, s1, 0x14000
	s_mov_b32 s44, m0
	s_mov_b32 m0, s43
	s_nop 0
	global_load_lds_dwordx4 v[6:7], off
	s_mov_b32 m0, s44
	v_lshl_add_u64 v[6:7], s[50:51], 0, v[4:5]
	s_add_i32 s44, s1, 0x1c000
	s_mov_b32 s45, m0
	s_mov_b32 m0, s44
	s_nop 0
	global_load_lds_dwordx4 v[6:7], off
	s_mov_b32 m0, s45
	v_lshl_add_u64 v[6:7], s[46:47], 0, v[146:147]
	s_add_i32 s45, s1, 0x16000
	s_mov_b32 s46, m0
	s_mov_b32 m0, s45
	s_nop 0
	global_load_lds_dwordx4 v[6:7], off
	s_mov_b32 m0, s46
	v_lshl_add_u64 v[6:7], s[50:51], 0, v[146:147]
	s_add_i32 s46, s1, 0x1e000
	s_mov_b32 s47, m0
	s_mov_b32 m0, s46
	s_nop 0
	global_load_lds_dwordx4 v[6:7], off
	s_mov_b32 m0, s47
	v_and_b32_e32 v182, 0xffffc000, v9
	v_or_b32_e32 v183, 0x800, v182
	v_or_b32_e32 v189, 0x1000, v182
	v_or_b32_e32 v199, 0x1800, v182
	v_or_b32_e32 v200, 0x2000, v182
	v_or_b32_e32 v201, 0x2800, v182
	v_or_b32_e32 v203, 0x3000, v182
	v_or_b32_e32 v206, 0x3800, v182
	s_movk_i32 s47, 0x6000
	v_and_or_b32 v7, v8, s47, v12
	ds_read_b128 v[8:11], v7 offset:32768
	v_or_b32_e32 v6, v12, v182
	ds_read_b128 v[12:15], v7 offset:34816
	ds_read_b128 v[16:19], v7 offset:36864
	ds_read_b128 v[24:27], v7 offset:38912
	ds_read_b128 v[20:23], v6
	ds_read_b128 v[28:31], v6 offset:2048
	ds_read_b128 v[32:35], v6 offset:4096
	ds_read_b128 v[36:39], v6 offset:6144
	s_waitcnt lgkmcnt(3)
	v_mfma_f32_16x16x32_bf16 v[40:43], v[8:11], v[20:23], 0
	v_mfma_f32_16x16x32_bf16 v[44:47], v[12:15], v[20:23], 0
	v_mfma_f32_16x16x32_bf16 v[48:51], v[16:19], v[20:23], 0
	v_mfma_f32_16x16x32_bf16 v[20:23], v[24:27], v[20:23], 0
	ds_read_b128 v[52:55], v6 offset:8192
	s_waitcnt lgkmcnt(3)
	v_mfma_f32_16x16x32_bf16 v[56:59], v[8:11], v[28:31], 0
	v_mfma_f32_16x16x32_bf16 v[60:63], v[12:15], v[28:31], 0
	v_mfma_f32_16x16x32_bf16 v[64:67], v[16:19], v[28:31], 0
	v_mfma_f32_16x16x32_bf16 v[28:31], v[24:27], v[28:31], 0
	ds_read_b128 v[68:71], v6 offset:10240
	s_waitcnt lgkmcnt(3)
	v_mfma_f32_16x16x32_bf16 v[72:75], v[8:11], v[32:35], 0
	v_mfma_f32_16x16x32_bf16 v[76:79], v[12:15], v[32:35], 0
	v_mfma_f32_16x16x32_bf16 v[80:83], v[16:19], v[32:35], 0
	v_mfma_f32_16x16x32_bf16 v[32:35], v[24:27], v[32:35], 0
	ds_read_b128 v[84:87], v6 offset:12288
	s_waitcnt lgkmcnt(3)
	v_mfma_f32_16x16x32_bf16 v[88:91], v[8:11], v[36:39], 0
	v_mfma_f32_16x16x32_bf16 v[92:95], v[12:15], v[36:39], 0
	v_mfma_f32_16x16x32_bf16 v[96:99], v[16:19], v[36:39], 0
	v_mfma_f32_16x16x32_bf16 v[36:39], v[24:27], v[36:39], 0
	ds_read_b128 v[100:103], v6 offset:14336
	s_waitcnt lgkmcnt(3)
	v_mfma_f32_16x16x32_bf16 v[104:107], v[8:11], v[52:55], 0
	v_mfma_f32_16x16x32_bf16 v[108:111], v[12:15], v[52:55], 0
	v_mfma_f32_16x16x32_bf16 v[112:115], v[16:19], v[52:55], 0
	v_mfma_f32_16x16x32_bf16 v[52:55], v[24:27], v[52:55], 0
	s_waitcnt lgkmcnt(2)
	v_mfma_f32_16x16x32_bf16 v[116:119], v[8:11], v[68:71], 0
	v_mfma_f32_16x16x32_bf16 v[120:123], v[12:15], v[68:71], 0
	v_mfma_f32_16x16x32_bf16 v[124:127], v[16:19], v[68:71], 0
	v_mfma_f32_16x16x32_bf16 v[68:71], v[24:27], v[68:71], 0
	s_waitcnt lgkmcnt(1)
	v_mfma_f32_16x16x32_bf16 v[128:131], v[8:11], v[84:87], 0
	v_mfma_f32_16x16x32_bf16 v[132:135], v[12:15], v[84:87], 0
	v_mfma_f32_16x16x32_bf16 v[136:139], v[16:19], v[84:87], 0
	v_mfma_f32_16x16x32_bf16 v[84:87], v[24:27], v[84:87], 0
	s_waitcnt lgkmcnt(0)
	v_mfma_f32_16x16x32_bf16 v[8:11], v[8:11], v[100:103], 0
	v_mfma_f32_16x16x32_bf16 v[12:15], v[12:15], v[100:103], 0
	v_mfma_f32_16x16x32_bf16 v[16:19], v[16:19], v[100:103], 0
	v_mfma_f32_16x16x32_bf16 v[24:27], v[24:27], v[100:103], 0
	ds_read_b128 v[100:103], v7 offset:33792
	ds_read_b128 v[140:143], v7 offset:35840
	ds_read_b128 v[150:153], v7 offset:37888
	ds_read_b128 v[158:161], v7 offset:39936
	ds_read_b128 v[154:157], v6 offset:1024
	ds_read_b128 v[162:165], v6 offset:3072
	ds_read_b128 v[166:169], v6 offset:5120
	ds_read_b128 v[170:173], v6 offset:7168
	s_waitcnt lgkmcnt(3)
	v_mfma_f32_16x16x32_bf16 v[40:43], v[100:103], v[154:157], v[40:43]
	v_mfma_f32_16x16x32_bf16 v[44:47], v[140:143], v[154:157], v[44:47]
	v_mfma_f32_16x16x32_bf16 v[48:51], v[150:153], v[154:157], v[48:51]
	v_mfma_f32_16x16x32_bf16 v[20:23], v[158:161], v[154:157], v[20:23]
	ds_read_b128 v[154:157], v6 offset:9216
	s_waitcnt lgkmcnt(3)
	v_mfma_f32_16x16x32_bf16 v[56:59], v[100:103], v[162:165], v[56:59]
	v_mfma_f32_16x16x32_bf16 v[60:63], v[140:143], v[162:165], v[60:63]
	v_mfma_f32_16x16x32_bf16 v[64:67], v[150:153], v[162:165], v[64:67]
	v_mfma_f32_16x16x32_bf16 v[28:31], v[158:161], v[162:165], v[28:31]
	ds_read_b128 v[162:165], v6 offset:11264
	s_waitcnt lgkmcnt(3)
	v_mfma_f32_16x16x32_bf16 v[72:75], v[100:103], v[166:169], v[72:75]
	v_mfma_f32_16x16x32_bf16 v[76:79], v[140:143], v[166:169], v[76:79]
	v_mfma_f32_16x16x32_bf16 v[80:83], v[150:153], v[166:169], v[80:83]
	v_mfma_f32_16x16x32_bf16 v[32:35], v[158:161], v[166:169], v[32:35]
	ds_read_b128 v[166:169], v6 offset:13312
	s_waitcnt lgkmcnt(3)
	v_mfma_f32_16x16x32_bf16 v[88:91], v[100:103], v[170:173], v[88:91]
	v_mfma_f32_16x16x32_bf16 v[92:95], v[140:143], v[170:173], v[92:95]
	v_mfma_f32_16x16x32_bf16 v[96:99], v[150:153], v[170:173], v[96:99]
	v_mfma_f32_16x16x32_bf16 v[36:39], v[158:161], v[170:173], v[36:39]
	ds_read_b128 v[170:173], v6 offset:15360
	s_waitcnt lgkmcnt(3)
	v_mfma_f32_16x16x32_bf16 v[104:107], v[100:103], v[154:157], v[104:107]
	v_mfma_f32_16x16x32_bf16 v[108:111], v[140:143], v[154:157], v[108:111]
	v_mfma_f32_16x16x32_bf16 v[112:115], v[150:153], v[154:157], v[112:115]
	v_mfma_f32_16x16x32_bf16 v[52:55], v[158:161], v[154:157], v[52:55]
	s_waitcnt lgkmcnt(2)
	v_mfma_f32_16x16x32_bf16 v[116:119], v[100:103], v[162:165], v[116:119]
	v_mfma_f32_16x16x32_bf16 v[120:123], v[140:143], v[162:165], v[120:123]
	v_mfma_f32_16x16x32_bf16 v[124:127], v[150:153], v[162:165], v[124:127]
	v_mfma_f32_16x16x32_bf16 v[68:71], v[158:161], v[162:165], v[68:71]
	s_waitcnt lgkmcnt(1)
	v_mfma_f32_16x16x32_bf16 v[128:131], v[100:103], v[166:169], v[128:131]
	v_mfma_f32_16x16x32_bf16 v[132:135], v[140:143], v[166:169], v[132:135]
	v_mfma_f32_16x16x32_bf16 v[136:139], v[150:153], v[166:169], v[136:139]
	v_mfma_f32_16x16x32_bf16 v[84:87], v[158:161], v[166:169], v[84:87]
	s_waitcnt lgkmcnt(0)
	v_mfma_f32_16x16x32_bf16 v[100:103], v[100:103], v[170:173], v[8:11]
	v_mfma_f32_16x16x32_bf16 v[150:153], v[150:153], v[170:173], v[16:19]
	v_mfma_f32_16x16x32_bf16 v[24:27], v[158:161], v[170:173], v[24:27]
	v_mfma_f32_16x16x32_bf16 v[140:143], v[140:143], v[170:173], v[12:15]
	s_add_u32 s50, s14, 0x100
	s_addc_u32 s51, s15, 0
	s_add_u32 s52, s20, 0x100
	s_waitcnt vmcnt(0)
	s_barrier
	s_addc_u32 s53, s21, 0
	v_lshl_add_u64 v[8:9], s[50:51], 0, v[0:1]
	s_mov_b32 s47, m0
	s_mov_b32 m0, s1
	s_nop 0
	global_load_lds_dwordx4 v[8:9], off
	s_mov_b32 m0, s47
	v_lshl_add_u64 v[8:9], s[52:53], 0, v[0:1]
	s_mov_b32 s47, m0
	s_mov_b32 m0, s34
	s_nop 0
	global_load_lds_dwordx4 v[8:9], off
	s_mov_b32 m0, s47
	v_lshl_add_u64 v[8:9], s[50:51], 0, v[2:3]
	s_mov_b32 s47, m0
	s_mov_b32 m0, s35
	s_nop 0
	global_load_lds_dwordx4 v[8:9], off
	s_mov_b32 m0, s47
	v_lshl_add_u64 v[8:9], s[52:53], 0, v[2:3]
	s_mov_b32 s47, m0
	s_mov_b32 m0, s36
	s_nop 0
	global_load_lds_dwordx4 v[8:9], off
	s_mov_b32 m0, s47
	v_lshl_add_u64 v[8:9], s[50:51], 0, v[4:5]
	s_mov_b32 s47, m0
	s_mov_b32 m0, s37
	s_nop 0
	global_load_lds_dwordx4 v[8:9], off
	s_mov_b32 m0, s47
	v_lshl_add_u64 v[8:9], s[52:53], 0, v[4:5]
	s_mov_b32 s47, m0
	s_mov_b32 m0, s38
	s_nop 0
	global_load_lds_dwordx4 v[8:9], off
	s_mov_b32 m0, s47
	v_lshl_add_u64 v[8:9], s[50:51], 0, v[146:147]
	s_mov_b32 s47, m0
	s_mov_b32 m0, s39
	s_nop 0
	global_load_lds_dwordx4 v[8:9], off
	s_mov_b32 m0, s47
	v_lshl_add_u64 v[8:9], s[52:53], 0, v[146:147]
	s_mov_b32 s47, m0
	s_mov_b32 m0, s40
	s_nop 0
	global_load_lds_dwordx4 v[8:9], off
	s_mov_b32 m0, s47
	v_or_b32_e32 v8, 0x18000, v7
	v_or_b32_e32 v9, 0x18800, v7
	v_or_b32_e32 v11, 0x19000, v7
	v_or_b32_e32 v10, 0x19800, v7
	ds_read_b128 v[154:157], v8
	ds_read_b128 v[158:161], v9
	ds_read_b128 v[162:165], v11
	ds_read_b128 v[166:169], v10
	v_bitop3_b32 v207, v145, s33, v149 bitop3:0xde
	v_add_u32_e32 v12, v207, v182
	ds_read_b128 v[16:19], v12
	v_add_u32_e32 v13, v207, v183
	v_add_u32_e32 v14, v207, v189
	v_add_u32_e32 v15, v207, v199
	ds_read_b128 v[170:173], v13
	ds_read_b128 v[174:177], v14
	ds_read_b128 v[178:181], v15
	s_waitcnt lgkmcnt(3)
	v_mfma_f32_16x16x32_bf16 v[40:43], v[154:157], v[16:19], v[40:43]
	v_mfma_f32_16x16x32_bf16 v[44:47], v[158:161], v[16:19], v[44:47]
	v_mfma_f32_16x16x32_bf16 v[48:51], v[162:165], v[16:19], v[48:51]
	v_mfma_f32_16x16x32_bf16 v[214:217], v[166:169], v[16:19], v[20:23]
	v_add_u32_e32 v16, v207, v200
	v_add_u32_e32 v17, v207, v201
	v_add_u32_e32 v18, v207, v203
	v_add_u32_e32 v19, v207, v206
	ds_read_b128 v[20:23], v16
	s_waitcnt lgkmcnt(3)
	v_mfma_f32_16x16x32_bf16 v[56:59], v[154:157], v[170:173], v[56:59]
	v_mfma_f32_16x16x32_bf16 v[60:63], v[158:161], v[170:173], v[60:63]
	v_mfma_f32_16x16x32_bf16 v[64:67], v[162:165], v[170:173], v[64:67]
	v_mfma_f32_16x16x32_bf16 v[170:173], v[166:169], v[170:173], v[28:31]
	s_nop 2
	ds_read_b128 v[28:31], v17
	s_waitcnt lgkmcnt(3)
	v_mfma_f32_16x16x32_bf16 v[72:75], v[154:157], v[174:177], v[72:75]
	v_mfma_f32_16x16x32_bf16 v[76:79], v[158:161], v[174:177], v[76:79]
	v_mfma_f32_16x16x32_bf16 v[80:83], v[162:165], v[174:177], v[80:83]
	v_mfma_f32_16x16x32_bf16 v[32:35], v[166:169], v[174:177], v[32:35]
	ds_read_b128 v[174:177], v18
	s_waitcnt lgkmcnt(3)
	v_mfma_f32_16x16x32_bf16 v[88:91], v[154:157], v[178:181], v[88:91]
	v_mfma_f32_16x16x32_bf16 v[92:95], v[158:161], v[178:181], v[92:95]
	v_mfma_f32_16x16x32_bf16 v[96:99], v[162:165], v[178:181], v[96:99]
	v_mfma_f32_16x16x32_bf16 v[36:39], v[166:169], v[178:181], v[36:39]
	ds_read_b128 v[178:181], v19
	s_waitcnt lgkmcnt(3)
	v_mfma_f32_16x16x32_bf16 v[104:107], v[154:157], v[20:23], v[104:107]
	v_mfma_f32_16x16x32_bf16 v[108:111], v[158:161], v[20:23], v[108:111]
	v_mfma_f32_16x16x32_bf16 v[112:115], v[162:165], v[20:23], v[112:115]
	v_mfma_f32_16x16x32_bf16 v[52:55], v[166:169], v[20:23], v[52:55]
	s_waitcnt lgkmcnt(2)
	v_mfma_f32_16x16x32_bf16 v[116:119], v[154:157], v[28:31], v[116:119]
	v_mfma_f32_16x16x32_bf16 v[120:123], v[158:161], v[28:31], v[120:123]
	v_mfma_f32_16x16x32_bf16 v[124:127], v[162:165], v[28:31], v[124:127]
	v_mfma_f32_16x16x32_bf16 v[68:71], v[166:169], v[28:31], v[68:71]
	s_waitcnt lgkmcnt(1)
	v_mfma_f32_16x16x32_bf16 v[128:131], v[154:157], v[174:177], v[128:131]
	v_mfma_f32_16x16x32_bf16 v[132:135], v[158:161], v[174:177], v[132:135]
	v_mfma_f32_16x16x32_bf16 v[84:87], v[166:169], v[174:177], v[84:87]
	s_waitcnt lgkmcnt(0)
	v_mfma_f32_16x16x32_bf16 v[100:103], v[154:157], v[178:181], v[100:103]
	v_mfma_f32_16x16x32_bf16 v[150:153], v[162:165], v[178:181], v[150:153]
	v_mfma_f32_16x16x32_bf16 v[154:157], v[166:169], v[178:181], v[24:27]
	v_mfma_f32_16x16x32_bf16 v[136:139], v[162:165], v[174:177], v[136:139]
	v_mfma_f32_16x16x32_bf16 v[140:143], v[158:161], v[178:181], v[140:143]
	v_or_b32_e32 v20, 0x18400, v7
	v_or_b32_e32 v21, 0x18c00, v7
	v_or_b32_e32 v23, 0x19400, v7
	v_or_b32_e32 v22, 0x19c00, v7
	ds_read_b128 v[158:161], v20
	ds_read_b128 v[162:165], v21
	ds_read_b128 v[166:169], v23
	ds_read_b128 v[174:177], v22
	s_mov_b32 s47, 0x10400
	v_bitop3_b32 v145, v145, s47, v149 bitop3:0xde
	v_add_u32_e32 v24, v145, v182
	ds_read_b128 v[28:31], v24
	v_add_u32_e32 v25, v145, v183
	v_add_u32_e32 v26, v145, v189
	v_add_u32_e32 v27, v145, v199
	ds_read_b128 v[178:181], v25
	ds_read_b128 v[218:221], v26
	ds_read_b128 v[222:225], v27
	s_waitcnt lgkmcnt(3)
	v_mfma_f32_16x16x32_bf16 v[40:43], v[158:161], v[28:31], v[40:43]
	v_mfma_f32_16x16x32_bf16 v[44:47], v[162:165], v[28:31], v[44:47]
	v_mfma_f32_16x16x32_bf16 v[48:51], v[166:169], v[28:31], v[48:51]
	v_mfma_f32_16x16x32_bf16 v[214:217], v[174:177], v[28:31], v[214:217]
	v_add_u32_e32 v28, v145, v200
	v_add_u32_e32 v29, v145, v201
	v_add_u32_e32 v30, v145, v203
	v_add_u32_e32 v31, v145, v206
	ds_read_b128 v[226:229], v28
	s_waitcnt lgkmcnt(3)
	v_mfma_f32_16x16x32_bf16 v[56:59], v[158:161], v[178:181], v[56:59]
	v_mfma_f32_16x16x32_bf16 v[60:63], v[162:165], v[178:181], v[60:63]
	v_mfma_f32_16x16x32_bf16 v[64:67], v[166:169], v[178:181], v[64:67]
	v_mfma_f32_16x16x32_bf16 v[170:173], v[174:177], v[178:181], v[170:173]
	ds_read_b128 v[178:181], v29
	s_waitcnt lgkmcnt(3)
	v_mfma_f32_16x16x32_bf16 v[72:75], v[158:161], v[218:221], v[72:75]
	v_mfma_f32_16x16x32_bf16 v[76:79], v[162:165], v[218:221], v[76:79]
	v_mfma_f32_16x16x32_bf16 v[80:83], v[166:169], v[218:221], v[80:83]
	v_mfma_f32_16x16x32_bf16 v[32:35], v[174:177], v[218:221], v[32:35]
	ds_read_b128 v[218:221], v30
	s_waitcnt lgkmcnt(3)
	v_mfma_f32_16x16x32_bf16 v[88:91], v[158:161], v[222:225], v[88:91]
	v_mfma_f32_16x16x32_bf16 v[92:95], v[162:165], v[222:225], v[92:95]
	v_mfma_f32_16x16x32_bf16 v[96:99], v[166:169], v[222:225], v[96:99]
	v_mfma_f32_16x16x32_bf16 v[36:39], v[174:177], v[222:225], v[36:39]
	ds_read_b128 v[222:225], v31
	s_waitcnt lgkmcnt(3)
	v_mfma_f32_16x16x32_bf16 v[104:107], v[158:161], v[226:229], v[104:107]
	v_mfma_f32_16x16x32_bf16 v[108:111], v[162:165], v[226:229], v[108:111]
	v_mfma_f32_16x16x32_bf16 v[112:115], v[166:169], v[226:229], v[112:115]
	v_mfma_f32_16x16x32_bf16 v[52:55], v[174:177], v[226:229], v[52:55]
	s_waitcnt lgkmcnt(2)
	v_mfma_f32_16x16x32_bf16 v[116:119], v[158:161], v[178:181], v[116:119]
	v_mfma_f32_16x16x32_bf16 v[120:123], v[162:165], v[178:181], v[120:123]
	v_mfma_f32_16x16x32_bf16 v[124:127], v[166:169], v[178:181], v[124:127]
	v_mfma_f32_16x16x32_bf16 v[68:71], v[174:177], v[178:181], v[68:71]
	s_waitcnt lgkmcnt(1)
	v_mfma_f32_16x16x32_bf16 v[132:135], v[162:165], v[218:221], v[132:135]
	v_mfma_f32_16x16x32_bf16 v[84:87], v[174:177], v[218:221], v[84:87]
	s_waitcnt lgkmcnt(0)
	v_mfma_f32_16x16x32_bf16 v[100:103], v[158:161], v[222:225], v[100:103]
	v_mfma_f32_16x16x32_bf16 v[150:153], v[166:169], v[222:225], v[150:153]
	v_mfma_f32_16x16x32_bf16 v[154:157], v[174:177], v[222:225], v[154:157]
	v_mfma_f32_16x16x32_bf16 v[128:131], v[158:161], v[218:221], v[128:131]
	v_mfma_f32_16x16x32_bf16 v[136:139], v[166:169], v[218:221], v[136:139]
	v_mfma_f32_16x16x32_bf16 v[140:143], v[162:165], v[222:225], v[140:143]
	s_add_u32 s50, s14, 0x180
	s_addc_u32 s51, s15, 0
	s_add_u32 s52, s20, 0x180
	s_waitcnt vmcnt(0)
	s_barrier
	s_addc_u32 s53, s21, 0
	v_lshl_add_u64 v[158:159], s[50:51], 0, v[0:1]
	s_mov_b32 s47, m0
	s_mov_b32 m0, s27
	s_nop 0
	global_load_lds_dwordx4 v[158:159], off
	s_mov_b32 m0, s47
	v_lshl_add_u64 v[158:159], s[52:53], 0, v[0:1]
	s_mov_b32 s47, m0
	s_mov_b32 m0, s26
	s_nop 0
	global_load_lds_dwordx4 v[158:159], off
	s_mov_b32 m0, s47
	v_lshl_add_u64 v[158:159], s[50:51], 0, v[2:3]
	s_mov_b32 s47, m0
	s_mov_b32 m0, s41
	s_nop 0
	global_load_lds_dwordx4 v[158:159], off
	s_mov_b32 m0, s47
	v_lshl_add_u64 v[158:159], s[52:53], 0, v[2:3]
	s_mov_b32 s47, m0
	s_mov_b32 m0, s42
	s_nop 0
	global_load_lds_dwordx4 v[158:159], off
	s_mov_b32 m0, s47
	v_lshl_add_u64 v[158:159], s[50:51], 0, v[4:5]
	s_mov_b32 s47, m0
	s_mov_b32 m0, s43
	s_nop 0
	global_load_lds_dwordx4 v[158:159], off
	s_mov_b32 m0, s47
	v_lshl_add_u64 v[158:159], s[52:53], 0, v[4:5]
	s_mov_b32 s47, m0
	s_mov_b32 m0, s44
	s_nop 0
	global_load_lds_dwordx4 v[158:159], off
	s_mov_b32 m0, s47
	v_lshl_add_u64 v[158:159], s[50:51], 0, v[146:147]
	s_mov_b32 s47, m0
	s_mov_b32 m0, s45
	s_nop 0
	global_load_lds_dwordx4 v[158:159], off
	s_mov_b32 m0, s47
	v_lshl_add_u64 v[158:159], s[52:53], 0, v[146:147]
	s_mov_b32 s47, m0
	s_mov_b32 m0, s46
	s_nop 0
	global_load_lds_dwordx4 v[158:159], off
	s_mov_b32 m0, s47
	ds_read_b128 v[158:161], v7 offset:32768
	ds_read_b128 v[162:165], v7 offset:34816
	ds_read_b128 v[166:169], v7 offset:36864
	ds_read_b128 v[178:181], v7 offset:38912
	ds_read_b128 v[174:177], v6
	ds_read_b128 v[218:221], v6 offset:2048
	ds_read_b128 v[222:225], v6 offset:4096
	ds_read_b128 v[226:229], v6 offset:6144
	s_waitcnt lgkmcnt(3)
	v_mfma_f32_16x16x32_bf16 v[40:43], v[158:161], v[174:177], v[40:43]
	v_mfma_f32_16x16x32_bf16 v[44:47], v[162:165], v[174:177], v[44:47]
	v_mfma_f32_16x16x32_bf16 v[48:51], v[166:169], v[174:177], v[48:51]
	v_mfma_f32_16x16x32_bf16 v[174:177], v[178:181], v[174:177], v[214:217]
	s_nop 2
	ds_read_b128 v[214:217], v6 offset:8192
	s_waitcnt lgkmcnt(3)
	v_mfma_f32_16x16x32_bf16 v[56:59], v[158:161], v[218:221], v[56:59]
	v_mfma_f32_16x16x32_bf16 v[60:63], v[162:165], v[218:221], v[60:63]
	v_mfma_f32_16x16x32_bf16 v[64:67], v[166:169], v[218:221], v[64:67]
	v_mfma_f32_16x16x32_bf16 v[170:173], v[178:181], v[218:221], v[170:173]
	ds_read_b128 v[218:221], v6 offset:10240
	s_waitcnt lgkmcnt(3)
	v_mfma_f32_16x16x32_bf16 v[72:75], v[158:161], v[222:225], v[72:75]
	v_mfma_f32_16x16x32_bf16 v[76:79], v[162:165], v[222:225], v[76:79]
	v_mfma_f32_16x16x32_bf16 v[80:83], v[166:169], v[222:225], v[80:83]
	v_mfma_f32_16x16x32_bf16 v[32:35], v[178:181], v[222:225], v[32:35]
	ds_read_b128 v[222:225], v6 offset:12288
	s_waitcnt lgkmcnt(3)
	v_mfma_f32_16x16x32_bf16 v[88:91], v[158:161], v[226:229], v[88:91]
	v_mfma_f32_16x16x32_bf16 v[92:95], v[162:165], v[226:229], v[92:95]
	v_mfma_f32_16x16x32_bf16 v[96:99], v[166:169], v[226:229], v[96:99]
	v_mfma_f32_16x16x32_bf16 v[36:39], v[178:181], v[226:229], v[36:39]
	ds_read_b128 v[226:229], v6 offset:14336
	s_waitcnt lgkmcnt(3)
	v_mfma_f32_16x16x32_bf16 v[104:107], v[158:161], v[214:217], v[104:107]
	v_mfma_f32_16x16x32_bf16 v[108:111], v[162:165], v[214:217], v[108:111]
	v_mfma_f32_16x16x32_bf16 v[112:115], v[166:169], v[214:217], v[112:115]
	v_mfma_f32_16x16x32_bf16 v[52:55], v[178:181], v[214:217], v[52:55]
	s_waitcnt lgkmcnt(2)
	v_mfma_f32_16x16x32_bf16 v[116:119], v[158:161], v[218:221], v[116:119]
	v_mfma_f32_16x16x32_bf16 v[120:123], v[162:165], v[218:221], v[120:123]
	v_mfma_f32_16x16x32_bf16 v[124:127], v[166:169], v[218:221], v[124:127]
	v_mfma_f32_16x16x32_bf16 v[68:71], v[178:181], v[218:221], v[68:71]
	s_waitcnt lgkmcnt(1)
	v_mfma_f32_16x16x32_bf16 v[132:135], v[162:165], v[222:225], v[132:135]
	v_mfma_f32_16x16x32_bf16 v[84:87], v[178:181], v[222:225], v[84:87]
	s_waitcnt lgkmcnt(0)
	v_mfma_f32_16x16x32_bf16 v[100:103], v[158:161], v[226:229], v[100:103]
	v_mfma_f32_16x16x32_bf16 v[150:153], v[166:169], v[226:229], v[150:153]
	v_mfma_f32_16x16x32_bf16 v[154:157], v[178:181], v[226:229], v[154:157]
	v_mfma_f32_16x16x32_bf16 v[128:131], v[158:161], v[222:225], v[128:131]
	v_mfma_f32_16x16x32_bf16 v[136:139], v[166:169], v[222:225], v[136:139]
	v_mfma_f32_16x16x32_bf16 v[140:143], v[162:165], v[226:229], v[140:143]
	ds_read_b128 v[158:161], v7 offset:33792
	ds_read_b128 v[162:165], v7 offset:35840
	ds_read_b128 v[166:169], v7 offset:37888
	ds_read_b128 v[214:217], v7 offset:39936
	ds_read_b128 v[178:181], v6 offset:1024
	ds_read_b128 v[218:221], v6 offset:3072
	ds_read_b128 v[222:225], v6 offset:5120
	ds_read_b128 v[226:229], v6 offset:7168
	s_waitcnt lgkmcnt(3)
	v_mfma_f32_16x16x32_bf16 v[40:43], v[158:161], v[178:181], v[40:43]
	v_mfma_f32_16x16x32_bf16 v[44:47], v[162:165], v[178:181], v[44:47]
	v_mfma_f32_16x16x32_bf16 v[48:51], v[166:169], v[178:181], v[48:51]
	v_mfma_f32_16x16x32_bf16 v[174:177], v[214:217], v[178:181], v[174:177]
	ds_read_b128 v[178:181], v6 offset:9216
	s_waitcnt lgkmcnt(3)
	v_mfma_f32_16x16x32_bf16 v[56:59], v[158:161], v[218:221], v[56:59]
	v_mfma_f32_16x16x32_bf16 v[60:63], v[162:165], v[218:221], v[60:63]
	v_mfma_f32_16x16x32_bf16 v[64:67], v[166:169], v[218:221], v[64:67]
	v_mfma_f32_16x16x32_bf16 v[170:173], v[214:217], v[218:221], v[170:173]
	ds_read_b128 v[218:221], v6 offset:11264
	s_waitcnt lgkmcnt(3)
	v_mfma_f32_16x16x32_bf16 v[72:75], v[158:161], v[222:225], v[72:75]
	v_mfma_f32_16x16x32_bf16 v[76:79], v[162:165], v[222:225], v[76:79]
	v_mfma_f32_16x16x32_bf16 v[80:83], v[166:169], v[222:225], v[80:83]
	v_mfma_f32_16x16x32_bf16 v[32:35], v[214:217], v[222:225], v[32:35]
	ds_read_b128 v[222:225], v6 offset:13312
	s_waitcnt lgkmcnt(3)
	v_mfma_f32_16x16x32_bf16 v[88:91], v[158:161], v[226:229], v[88:91]
	v_mfma_f32_16x16x32_bf16 v[92:95], v[162:165], v[226:229], v[92:95]
	v_mfma_f32_16x16x32_bf16 v[96:99], v[166:169], v[226:229], v[96:99]
	v_mfma_f32_16x16x32_bf16 v[36:39], v[214:217], v[226:229], v[36:39]
	ds_read_b128 v[226:229], v6 offset:15360
	s_waitcnt lgkmcnt(3)
	v_mfma_f32_16x16x32_bf16 v[104:107], v[158:161], v[178:181], v[104:107]
	v_mfma_f32_16x16x32_bf16 v[108:111], v[162:165], v[178:181], v[108:111]
	v_mfma_f32_16x16x32_bf16 v[112:115], v[166:169], v[178:181], v[112:115]
	v_mfma_f32_16x16x32_bf16 v[52:55], v[214:217], v[178:181], v[52:55]
	s_waitcnt lgkmcnt(2)
	v_mfma_f32_16x16x32_bf16 v[116:119], v[158:161], v[218:221], v[116:119]
	v_mfma_f32_16x16x32_bf16 v[120:123], v[162:165], v[218:221], v[120:123]
	v_mfma_f32_16x16x32_bf16 v[124:127], v[166:169], v[218:221], v[124:127]
	v_mfma_f32_16x16x32_bf16 v[68:71], v[214:217], v[218:221], v[68:71]
	s_waitcnt lgkmcnt(1)
	v_mfma_f32_16x16x32_bf16 v[132:135], v[162:165], v[222:225], v[132:135]
	v_mfma_f32_16x16x32_bf16 v[84:87], v[214:217], v[222:225], v[84:87]
	s_waitcnt lgkmcnt(0)
	v_mfma_f32_16x16x32_bf16 v[100:103], v[158:161], v[226:229], v[100:103]
	v_mfma_f32_16x16x32_bf16 v[150:153], v[166:169], v[226:229], v[150:153]
	v_mfma_f32_16x16x32_bf16 v[154:157], v[214:217], v[226:229], v[154:157]
	v_mfma_f32_16x16x32_bf16 v[128:131], v[158:161], v[222:225], v[128:131]
	v_mfma_f32_16x16x32_bf16 v[136:139], v[166:169], v[222:225], v[136:139]
	v_mfma_f32_16x16x32_bf16 v[140:143], v[162:165], v[226:229], v[140:143]
	s_add_u32 s50, s14, 0x200
	s_addc_u32 s51, s15, 0
	s_add_u32 s52, s20, 0x200
	s_waitcnt vmcnt(0)
	s_barrier
	s_addc_u32 s53, s21, 0
	s_mov_b32 s47, 0x280
	ds_read_b128 v[158:161], v8
	ds_read_b128 v[162:165], v12
	s_mov_b32 m0, s1
	s_nop 0
	global_load_lds_dwordx4 v0, s[50:51]
	ds_read_b128 v[166:169], v9
	s_mov_b32 m0, s34
	s_nop 0
	global_load_lds_dwordx4 v0, s[52:53]
	ds_read_b128 v[178:181], v13
	ds_read_b128 v[214:217], v11
	s_mov_b32 m0, s35
	s_nop 0
	global_load_lds_dwordx4 v2, s[50:51]
	ds_read_b128 v[218:221], v10
	ds_read_b128 v[222:225], v14
	ds_read_b128 v[226:229], v15
	s_branch .Lmy_rot_r_r2a
.Lmy_rr_r2a:
	ds_read_b128 v[158:161], v8
	ds_read_b128 v[162:165], v12
	s_mov_b32 m0, s1
	v_mfma_f32_16x16x32_bf16 v[128:131], v[166:169], v[222:225], v[128:131]
	global_load_lds_dwordx4 v0, s[50:51]
	v_mfma_f32_16x16x32_bf16 v[100:103], v[166:169], v[226:229], v[100:103]
	ds_read_b128 v[166:169], v9
	v_mfma_f32_16x16x32_bf16 v[132:135], v[178:181], v[222:225], v[132:135]
	s_mov_b32 m0, s34
	v_mfma_f32_16x16x32_bf16 v[140:143], v[178:181], v[226:229], v[140:143]
	global_load_lds_dwordx4 v0, s[52:53]
	ds_read_b128 v[178:181], v13
	v_mfma_f32_16x16x32_bf16 v[136:139], v[214:217], v[222:225], v[136:139]
	v_mfma_f32_16x16x32_bf16 v[150:153], v[214:217], v[226:229], v[150:153]
	ds_read_b128 v[214:217], v11
	s_mov_b32 m0, s35
	v_mfma_f32_16x16x32_bf16 v[84:87], v[218:221], v[222:225], v[84:87]
	global_load_lds_dwordx4 v2, s[50:51]
	v_mfma_f32_16x16x32_bf16 v[154:157], v[218:221], v[226:229], v[154:157]
	ds_read_b128 v[218:221], v10
	ds_read_b128 v[222:225], v14
	ds_read_b128 v[226:229], v15
.Lmy_rot_r_r2a:
	s_waitcnt lgkmcnt(6)
	v_mfma_f32_16x16x32_bf16 v[40:43], v[158:161], v[162:165], v[40:43]
	s_waitcnt lgkmcnt(5)
	s_mov_b32 m0, s36
	v_mfma_f32_16x16x32_bf16 v[44:47], v[166:169], v[162:165], v[44:47]
	global_load_lds_dwordx4 v2, s[52:53]
	s_waitcnt lgkmcnt(4)
	v_mfma_f32_16x16x32_bf16 v[56:59], v[158:161], v[178:181], v[56:59]
	v_mfma_f32_16x16x32_bf16 v[60:63], v[166:169], v[178:181], v[60:63]
	s_waitcnt lgkmcnt(3)
	s_mov_b32 m0, s37
	v_mfma_f32_16x16x32_bf16 v[48:51], v[214:217], v[162:165], v[48:51]
	global_load_lds_dwordx4 v4, s[50:51]
	v_mfma_f32_16x16x32_bf16 v[64:67], v[214:217], v[178:181], v[64:67]
	s_waitcnt lgkmcnt(2)
	v_mfma_f32_16x16x32_bf16 v[174:177], v[218:221], v[162:165], v[174:177]
	ds_read_b128 v[162:165], v16
	s_mov_b32 m0, s38
	v_mfma_f32_16x16x32_bf16 v[170:173], v[218:221], v[178:181], v[170:173]
	global_load_lds_dwordx4 v4, s[52:53]
	ds_read_b128 v[178:181], v17
	s_waitcnt lgkmcnt(3)
	v_mfma_f32_16x16x32_bf16 v[72:75], v[158:161], v[222:225], v[72:75]
	v_mfma_f32_16x16x32_bf16 v[76:79], v[166:169], v[222:225], v[76:79]
	s_mov_b32 m0, s39
	v_mfma_f32_16x16x32_bf16 v[80:83], v[214:217], v[222:225], v[80:83]
	global_load_lds_dwordx4 v146, s[50:51]
	v_mfma_f32_16x16x32_bf16 v[32:35], v[218:221], v[222:225], v[32:35]
	ds_read_b128 v[222:225], v18
	s_waitcnt lgkmcnt(3)
	v_mfma_f32_16x16x32_bf16 v[88:91], v[158:161], v[226:229], v[88:91]
	s_mov_b32 m0, s40
	v_mfma_f32_16x16x32_bf16 v[92:95], v[166:169], v[226:229], v[92:95]
	global_load_lds_dwordx4 v146, s[52:53]
	v_mfma_f32_16x16x32_bf16 v[96:99], v[214:217], v[226:229], v[96:99]
	v_mfma_f32_16x16x32_bf16 v[36:39], v[218:221], v[226:229], v[36:39]
	ds_read_b128 v[226:229], v19
	s_waitcnt lgkmcnt(3)
	v_mfma_f32_16x16x32_bf16 v[108:111], v[166:169], v[162:165], v[108:111]
	s_waitcnt lgkmcnt(2)
	v_mfma_f32_16x16x32_bf16 v[120:123], v[166:169], v[178:181], v[120:123]
	s_waitcnt lgkmcnt(1)
	v_mfma_f32_16x16x32_bf16 v[132:135], v[166:169], v[222:225], v[132:135]
	s_waitcnt lgkmcnt(0)
	v_mfma_f32_16x16x32_bf16 v[140:143], v[166:169], v[226:229], v[140:143]
	ds_read_b128 v[166:169], v20
	v_mfma_f32_16x16x32_bf16 v[104:107], v[158:161], v[162:165], v[104:107]
	v_mfma_f32_16x16x32_bf16 v[116:119], v[158:161], v[178:181], v[116:119]
	v_mfma_f32_16x16x32_bf16 v[128:131], v[158:161], v[222:225], v[128:131]
	v_mfma_f32_16x16x32_bf16 v[100:103], v[158:161], v[226:229], v[100:103]
	ds_read_b128 v[158:161], v24
	v_mfma_f32_16x16x32_bf16 v[124:127], v[214:217], v[178:181], v[124:127]
	v_mfma_f32_16x16x32_bf16 v[68:71], v[218:221], v[178:181], v[68:71]
	ds_read_b128 v[178:181], v21
	v_mfma_f32_16x16x32_bf16 v[112:115], v[214:217], v[162:165], v[112:115]
	v_mfma_f32_16x16x32_bf16 v[52:55], v[218:221], v[162:165], v[52:55]
	ds_read_b128 v[162:165], v25
	v_mfma_f32_16x16x32_bf16 v[136:139], v[214:217], v[222:225], v[136:139]
	v_mfma_f32_16x16x32_bf16 v[84:87], v[218:221], v[222:225], v[84:87]
	ds_read_b128 v[222:225], v26
	v_mfma_f32_16x16x32_bf16 v[150:153], v[214:217], v[226:229], v[150:153]
	ds_read_b128 v[214:217], v23
	v_mfma_f32_16x16x32_bf16 v[154:157], v[218:221], v[226:229], v[154:157]
	ds_read_b128 v[218:221], v22
	ds_read_b128 v[226:229], v27
	s_waitcnt lgkmcnt(6)
	v_mfma_f32_16x16x32_bf16 v[40:43], v[166:169], v[158:161], v[40:43]
	s_waitcnt lgkmcnt(5)
	v_mfma_f32_16x16x32_bf16 v[44:47], v[178:181], v[158:161], v[44:47]
	s_waitcnt lgkmcnt(4)
	v_mfma_f32_16x16x32_bf16 v[56:59], v[166:169], v[162:165], v[56:59]
	v_mfma_f32_16x16x32_bf16 v[60:63], v[178:181], v[162:165], v[60:63]
	s_waitcnt lgkmcnt(3)
	v_mfma_f32_16x16x32_bf16 v[72:75], v[166:169], v[222:225], v[72:75]
	v_mfma_f32_16x16x32_bf16 v[76:79], v[178:181], v[222:225], v[76:79]
	s_waitcnt lgkmcnt(2)
	v_mfma_f32_16x16x32_bf16 v[48:51], v[214:217], v[158:161], v[48:51]
	s_waitcnt lgkmcnt(1)
	v_mfma_f32_16x16x32_bf16 v[174:177], v[218:221], v[158:161], v[174:177]
	ds_read_b128 v[158:161], v28
	v_mfma_f32_16x16x32_bf16 v[64:67], v[214:217], v[162:165], v[64:67]
	v_mfma_f32_16x16x32_bf16 v[170:173], v[218:221], v[162:165], v[170:173]
	ds_read_b128 v[162:165], v29
	v_mfma_f32_16x16x32_bf16 v[80:83], v[214:217], v[222:225], v[80:83]
	v_mfma_f32_16x16x32_bf16 v[32:35], v[218:221], v[222:225], v[32:35]
	ds_read_b128 v[222:225], v30
	s_waitcnt lgkmcnt(3)
	v_mfma_f32_16x16x32_bf16 v[88:91], v[166:169], v[226:229], v[88:91]
	v_mfma_f32_16x16x32_bf16 v[92:95], v[178:181], v[226:229], v[92:95]
	v_mfma_f32_16x16x32_bf16 v[96:99], v[214:217], v[226:229], v[96:99]
	v_mfma_f32_16x16x32_bf16 v[36:39], v[218:221], v[226:229], v[36:39]
	ds_read_b128 v[226:229], v31
	s_waitcnt lgkmcnt(3)
	v_mfma_f32_16x16x32_bf16 v[104:107], v[166:169], v[158:161], v[104:107]
	v_mfma_f32_16x16x32_bf16 v[108:111], v[178:181], v[158:161], v[108:111]
	v_mfma_f32_16x16x32_bf16 v[112:115], v[214:217], v[158:161], v[112:115]
	v_mfma_f32_16x16x32_bf16 v[52:55], v[218:221], v[158:161], v[52:55]
	s_waitcnt lgkmcnt(2)
	v_mfma_f32_16x16x32_bf16 v[116:119], v[166:169], v[162:165], v[116:119]
	v_mfma_f32_16x16x32_bf16 v[120:123], v[178:181], v[162:165], v[120:123]
	v_mfma_f32_16x16x32_bf16 v[124:127], v[214:217], v[162:165], v[124:127]
	v_mfma_f32_16x16x32_bf16 v[68:71], v[218:221], v[162:165], v[68:71]
	s_add_u32 s50, s14, s47
	s_addc_u32 s51, s15, 0
	s_add_u32 s52, s20, s47
	s_addc_u32 s53, s21, 0
	s_add_u32 s47, s47, 0x80
	s_waitcnt vmcnt(0)
	s_waitcnt lgkmcnt(0)
	s_barrier
	ds_read_b128 v[158:161], v7 offset:32768
	ds_read_b128 v[162:165], v6
	s_mov_b32 m0, s27
	v_mfma_f32_16x16x32_bf16 v[128:131], v[166:169], v[222:225], v[128:131]
	global_load_lds_dwordx4 v0, s[50:51]
	v_mfma_f32_16x16x32_bf16 v[100:103], v[166:169], v[226:229], v[100:103]
	ds_read_b128 v[166:169], v7 offset:34816
	v_mfma_f32_16x16x32_bf16 v[132:135], v[178:181], v[222:225], v[132:135]
	s_mov_b32 m0, s26
	v_mfma_f32_16x16x32_bf16 v[140:143], v[178:181], v[226:229], v[140:143]
	global_load_lds_dwordx4 v0, s[52:53]
	ds_read_b128 v[178:181], v6 offset:2048
	v_mfma_f32_16x16x32_bf16 v[136:139], v[214:217], v[222:225], v[136:139]
	v_mfma_f32_16x16x32_bf16 v[150:153], v[214:217], v[226:229], v[150:153]
	ds_read_b128 v[214:217], v7 offset:36864
	s_mov_b32 m0, s41
	v_mfma_f32_16x16x32_bf16 v[84:87], v[218:221], v[222:225], v[84:87]
	global_load_lds_dwordx4 v2, s[50:51]
	v_mfma_f32_16x16x32_bf16 v[154:157], v[218:221], v[226:229], v[154:157]
	ds_read_b128 v[218:221], v7 offset:38912
	ds_read_b128 v[222:225], v6 offset:4096
	ds_read_b128 v[226:229], v6 offset:6144
	s_waitcnt lgkmcnt(6)
	v_mfma_f32_16x16x32_bf16 v[40:43], v[158:161], v[162:165], v[40:43]
	s_waitcnt lgkmcnt(5)
	s_mov_b32 m0, s42
	v_mfma_f32_16x16x32_bf16 v[44:47], v[166:169], v[162:165], v[44:47]
	global_load_lds_dwordx4 v2, s[52:53]
	s_waitcnt lgkmcnt(4)
	v_mfma_f32_16x16x32_bf16 v[56:59], v[158:161], v[178:181], v[56:59]
	v_mfma_f32_16x16x32_bf16 v[60:63], v[166:169], v[178:181], v[60:63]
	s_waitcnt lgkmcnt(3)
	s_mov_b32 m0, s43
	v_mfma_f32_16x16x32_bf16 v[48:51], v[214:217], v[162:165], v[48:51]
	global_load_lds_dwordx4 v4, s[50:51]
	v_mfma_f32_16x16x32_bf16 v[64:67], v[214:217], v[178:181], v[64:67]
	s_waitcnt lgkmcnt(2)
	v_mfma_f32_16x16x32_bf16 v[174:177], v[218:221], v[162:165], v[174:177]
	ds_read_b128 v[162:165], v6 offset:8192
	s_mov_b32 m0, s44
	v_mfma_f32_16x16x32_bf16 v[170:173], v[218:221], v[178:181], v[170:173]
	global_load_lds_dwordx4 v4, s[52:53]
	ds_read_b128 v[178:181], v6 offset:10240
	s_waitcnt lgkmcnt(3)
	v_mfma_f32_16x16x32_bf16 v[72:75], v[158:161], v[222:225], v[72:75]
	v_mfma_f32_16x16x32_bf16 v[76:79], v[166:169], v[222:225], v[76:79]
	s_mov_b32 m0, s45
	v_mfma_f32_16x16x32_bf16 v[80:83], v[214:217], v[222:225], v[80:83]
	global_load_lds_dwordx4 v146, s[50:51]
	v_mfma_f32_16x16x32_bf16 v[32:35], v[218:221], v[222:225], v[32:35]
	ds_read_b128 v[222:225], v6 offset:12288
	s_waitcnt lgkmcnt(3)
	v_mfma_f32_16x16x32_bf16 v[88:91], v[158:161], v[226:229], v[88:91]
	s_mov_b32 m0, s46
	v_mfma_f32_16x16x32_bf16 v[92:95], v[166:169], v[226:229], v[92:95]
	global_load_lds_dwordx4 v146, s[52:53]
	v_mfma_f32_16x16x32_bf16 v[96:99], v[214:217], v[226:229], v[96:99]
	v_mfma_f32_16x16x32_bf16 v[36:39], v[218:221], v[226:229], v[36:39]
	ds_read_b128 v[226:229], v6 offset:14336
	s_waitcnt lgkmcnt(3)
	v_mfma_f32_16x16x32_bf16 v[108:111], v[166:169], v[162:165], v[108:111]
	s_waitcnt lgkmcnt(2)
	v_mfma_f32_16x16x32_bf16 v[120:123], v[166:169], v[178:181], v[120:123]
	s_waitcnt lgkmcnt(1)
	v_mfma_f32_16x16x32_bf16 v[132:135], v[166:169], v[222:225], v[132:135]
	s_waitcnt lgkmcnt(0)
	v_mfma_f32_16x16x32_bf16 v[140:143], v[166:169], v[226:229], v[140:143]
	ds_read_b128 v[166:169], v7 offset:33792
	v_mfma_f32_16x16x32_bf16 v[104:107], v[158:161], v[162:165], v[104:107]
	v_mfma_f32_16x16x32_bf16 v[116:119], v[158:161], v[178:181], v[116:119]
	v_mfma_f32_16x16x32_bf16 v[128:131], v[158:161], v[222:225], v[128:131]
	v_mfma_f32_16x16x32_bf16 v[100:103], v[158:161], v[226:229], v[100:103]
	ds_read_b128 v[158:161], v6 offset:1024
	v_mfma_f32_16x16x32_bf16 v[124:127], v[214:217], v[178:181], v[124:127]
	v_mfma_f32_16x16x32_bf16 v[68:71], v[218:221], v[178:181], v[68:71]
	ds_read_b128 v[178:181], v7 offset:35840
	v_mfma_f32_16x16x32_bf16 v[112:115], v[214:217], v[162:165], v[112:115]
	v_mfma_f32_16x16x32_bf16 v[52:55], v[218:221], v[162:165], v[52:55]
	ds_read_b128 v[162:165], v6 offset:3072
	v_mfma_f32_16x16x32_bf16 v[136:139], v[214:217], v[222:225], v[136:139]
	v_mfma_f32_16x16x32_bf16 v[84:87], v[218:221], v[222:225], v[84:87]
	ds_read_b128 v[222:225], v6 offset:5120
	v_mfma_f32_16x16x32_bf16 v[150:153], v[214:217], v[226:229], v[150:153]
	ds_read_b128 v[214:217], v7 offset:37888
	v_mfma_f32_16x16x32_bf16 v[154:157], v[218:221], v[226:229], v[154:157]
	ds_read_b128 v[218:221], v7 offset:39936
	ds_read_b128 v[226:229], v6 offset:7168
	s_waitcnt lgkmcnt(6)
	v_mfma_f32_16x16x32_bf16 v[40:43], v[166:169], v[158:161], v[40:43]
	s_waitcnt lgkmcnt(5)
	v_mfma_f32_16x16x32_bf16 v[44:47], v[178:181], v[158:161], v[44:47]
	s_waitcnt lgkmcnt(4)
	v_mfma_f32_16x16x32_bf16 v[56:59], v[166:169], v[162:165], v[56:59]
	v_mfma_f32_16x16x32_bf16 v[60:63], v[178:181], v[162:165], v[60:63]
	s_waitcnt lgkmcnt(3)
	v_mfma_f32_16x16x32_bf16 v[72:75], v[166:169], v[222:225], v[72:75]
	v_mfma_f32_16x16x32_bf16 v[76:79], v[178:181], v[222:225], v[76:79]
	s_waitcnt lgkmcnt(2)
	v_mfma_f32_16x16x32_bf16 v[48:51], v[214:217], v[158:161], v[48:51]
	s_waitcnt lgkmcnt(1)
	v_mfma_f32_16x16x32_bf16 v[174:177], v[218:221], v[158:161], v[174:177]
	ds_read_b128 v[158:161], v6 offset:9216
	v_mfma_f32_16x16x32_bf16 v[64:67], v[214:217], v[162:165], v[64:67]
	v_mfma_f32_16x16x32_bf16 v[170:173], v[218:221], v[162:165], v[170:173]
	ds_read_b128 v[162:165], v6 offset:11264
	v_mfma_f32_16x16x32_bf16 v[80:83], v[214:217], v[222:225], v[80:83]
	v_mfma_f32_16x16x32_bf16 v[32:35], v[218:221], v[222:225], v[32:35]
	ds_read_b128 v[222:225], v6 offset:13312
	s_waitcnt lgkmcnt(3)
	v_mfma_f32_16x16x32_bf16 v[88:91], v[166:169], v[226:229], v[88:91]
	v_mfma_f32_16x16x32_bf16 v[92:95], v[178:181], v[226:229], v[92:95]
	v_mfma_f32_16x16x32_bf16 v[96:99], v[214:217], v[226:229], v[96:99]
	v_mfma_f32_16x16x32_bf16 v[36:39], v[218:221], v[226:229], v[36:39]
	ds_read_b128 v[226:229], v6 offset:15360
	s_waitcnt lgkmcnt(3)
	v_mfma_f32_16x16x32_bf16 v[104:107], v[166:169], v[158:161], v[104:107]
	v_mfma_f32_16x16x32_bf16 v[108:111], v[178:181], v[158:161], v[108:111]
	v_mfma_f32_16x16x32_bf16 v[112:115], v[214:217], v[158:161], v[112:115]
	v_mfma_f32_16x16x32_bf16 v[52:55], v[218:221], v[158:161], v[52:55]
	s_waitcnt lgkmcnt(2)
	v_mfma_f32_16x16x32_bf16 v[116:119], v[166:169], v[162:165], v[116:119]
	v_mfma_f32_16x16x32_bf16 v[120:123], v[178:181], v[162:165], v[120:123]
	v_mfma_f32_16x16x32_bf16 v[124:127], v[214:217], v[162:165], v[124:127]
	v_mfma_f32_16x16x32_bf16 v[68:71], v[218:221], v[162:165], v[68:71]
	s_add_u32 s50, s14, s47
	s_addc_u32 s51, s15, 0
	s_add_u32 s52, s20, s47
	s_addc_u32 s53, s21, 0
	s_add_u32 s47, s47, 0x80
	s_cmp_lg_u32 s47, 0xf80
	s_waitcnt vmcnt(0)
	s_waitcnt lgkmcnt(0)
	s_barrier
	s_cbranch_scc1 .Lmy_rr_r2a
	v_mfma_f32_16x16x32_bf16 v[128:131], v[166:169], v[222:225], v[128:131]
	v_mfma_f32_16x16x32_bf16 v[100:103], v[166:169], v[226:229], v[100:103]
	v_mfma_f32_16x16x32_bf16 v[132:135], v[178:181], v[222:225], v[132:135]
	v_mfma_f32_16x16x32_bf16 v[140:143], v[178:181], v[226:229], v[140:143]
	v_mfma_f32_16x16x32_bf16 v[136:139], v[214:217], v[222:225], v[136:139]
	v_mfma_f32_16x16x32_bf16 v[150:153], v[214:217], v[226:229], v[150:153]
	v_mfma_f32_16x16x32_bf16 v[84:87], v[218:221], v[222:225], v[84:87]
	v_mfma_f32_16x16x32_bf16 v[154:157], v[218:221], v[226:229], v[154:157]
	s_nop 15
	s_nop 15
	v_lshl_add_u64 v[158:159], s[50:51], 0, v[0:1]
	s_mov_b32 s47, m0
	s_mov_b32 m0, s1
	s_nop 0
	global_load_lds_dwordx4 v[158:159], off
	s_mov_b32 m0, s47
	v_lshl_add_u64 v[158:159], s[52:53], 0, v[0:1]
	s_mov_b32 s47, m0
	s_mov_b32 m0, s34
	s_nop 0
	global_load_lds_dwordx4 v[158:159], off
	s_mov_b32 m0, s47
	v_lshl_add_u64 v[158:159], s[50:51], 0, v[2:3]
	s_mov_b32 s47, m0
	s_mov_b32 m0, s35
	s_nop 0
	global_load_lds_dwordx4 v[158:159], off
	s_mov_b32 m0, s47
	v_lshl_add_u64 v[158:159], s[52:53], 0, v[2:3]
	s_mov_b32 s47, m0
	s_mov_b32 m0, s36
	s_nop 0
	global_load_lds_dwordx4 v[158:159], off
	s_mov_b32 m0, s47
	v_lshl_add_u64 v[158:159], s[50:51], 0, v[4:5]
	s_mov_b32 s47, m0
	s_mov_b32 m0, s37
	s_nop 0
	global_load_lds_dwordx4 v[158:159], off
	s_mov_b32 m0, s47
	v_lshl_add_u64 v[158:159], s[52:53], 0, v[4:5]
	s_mov_b32 s47, m0
	s_mov_b32 m0, s38
	s_nop 0
	global_load_lds_dwordx4 v[158:159], off
	s_mov_b32 m0, s47
	v_lshl_add_u64 v[158:159], s[50:51], 0, v[146:147]
	s_mov_b32 s47, m0
	s_mov_b32 m0, s39
	s_nop 0
	global_load_lds_dwordx4 v[158:159], off
	s_mov_b32 m0, s47
	v_lshl_add_u64 v[158:159], s[52:53], 0, v[146:147]
	s_mov_b32 s47, m0
	s_mov_b32 m0, s40
	s_nop 0
	global_load_lds_dwordx4 v[158:159], off
	s_mov_b32 m0, s47
	ds_read_b128 v[158:161], v8
	ds_read_b128 v[162:165], v9
	ds_read_b128 v[166:169], v11
	ds_read_b128 v[214:217], v10
	ds_read_b128 v[178:181], v12
	ds_read_b128 v[218:221], v13
	ds_read_b128 v[222:225], v14
	ds_read_b128 v[226:229], v15
	s_waitcnt lgkmcnt(3)
	v_mfma_f32_16x16x32_bf16 v[40:43], v[158:161], v[178:181], v[40:43]
	v_mfma_f32_16x16x32_bf16 v[44:47], v[162:165], v[178:181], v[44:47]
	v_mfma_f32_16x16x32_bf16 v[48:51], v[166:169], v[178:181], v[48:51]
	v_mfma_f32_16x16x32_bf16 v[174:177], v[214:217], v[178:181], v[174:177]
	ds_read_b128 v[178:181], v16
	s_waitcnt lgkmcnt(3)
	v_mfma_f32_16x16x32_bf16 v[56:59], v[158:161], v[218:221], v[56:59]
	v_mfma_f32_16x16x32_bf16 v[60:63], v[162:165], v[218:221], v[60:63]
	v_mfma_f32_16x16x32_bf16 v[64:67], v[166:169], v[218:221], v[64:67]
	v_mfma_f32_16x16x32_bf16 v[170:173], v[214:217], v[218:221], v[170:173]
	ds_read_b128 v[218:221], v17
	s_waitcnt lgkmcnt(3)
	v_mfma_f32_16x16x32_bf16 v[72:75], v[158:161], v[222:225], v[72:75]
	v_mfma_f32_16x16x32_bf16 v[76:79], v[162:165], v[222:225], v[76:79]
	v_mfma_f32_16x16x32_bf16 v[80:83], v[166:169], v[222:225], v[80:83]
	v_mfma_f32_16x16x32_bf16 v[32:35], v[214:217], v[222:225], v[32:35]
	ds_read_b128 v[222:225], v18
	s_waitcnt lgkmcnt(3)
	v_mfma_f32_16x16x32_bf16 v[88:91], v[158:161], v[226:229], v[88:91]
	v_mfma_f32_16x16x32_bf16 v[92:95], v[162:165], v[226:229], v[92:95]
	v_mfma_f32_16x16x32_bf16 v[96:99], v[166:169], v[226:229], v[96:99]
	v_mfma_f32_16x16x32_bf16 v[36:39], v[214:217], v[226:229], v[36:39]
	ds_read_b128 v[226:229], v19
	s_waitcnt lgkmcnt(3)
	v_mfma_f32_16x16x32_bf16 v[104:107], v[158:161], v[178:181], v[104:107]
	v_mfma_f32_16x16x32_bf16 v[108:111], v[162:165], v[178:181], v[108:111]
	v_mfma_f32_16x16x32_bf16 v[112:115], v[166:169], v[178:181], v[112:115]
	v_mfma_f32_16x16x32_bf16 v[52:55], v[214:217], v[178:181], v[52:55]
	s_waitcnt lgkmcnt(2)
	v_mfma_f32_16x16x32_bf16 v[116:119], v[158:161], v[218:221], v[116:119]
	v_mfma_f32_16x16x32_bf16 v[120:123], v[162:165], v[218:221], v[120:123]
	v_mfma_f32_16x16x32_bf16 v[124:127], v[166:169], v[218:221], v[124:127]
	v_mfma_f32_16x16x32_bf16 v[68:71], v[214:217], v[218:221], v[68:71]
	s_waitcnt lgkmcnt(1)
	v_mfma_f32_16x16x32_bf16 v[132:135], v[162:165], v[222:225], v[132:135]
	v_mfma_f32_16x16x32_bf16 v[84:87], v[214:217], v[222:225], v[84:87]
	s_waitcnt lgkmcnt(0)
	v_mfma_f32_16x16x32_bf16 v[100:103], v[158:161], v[226:229], v[100:103]
	v_mfma_f32_16x16x32_bf16 v[150:153], v[166:169], v[226:229], v[150:153]
	v_mfma_f32_16x16x32_bf16 v[154:157], v[214:217], v[226:229], v[154:157]
	v_mfma_f32_16x16x32_bf16 v[128:131], v[158:161], v[222:225], v[128:131]
	v_mfma_f32_16x16x32_bf16 v[136:139], v[166:169], v[222:225], v[136:139]
	v_mfma_f32_16x16x32_bf16 v[140:143], v[162:165], v[226:229], v[140:143]
	ds_read_b128 v[158:161], v20
	ds_read_b128 v[162:165], v21
	ds_read_b128 v[166:169], v23
	ds_read_b128 v[214:217], v22
	ds_read_b128 v[178:181], v24
	ds_read_b128 v[218:221], v25
	ds_read_b128 v[222:225], v26
	ds_read_b128 v[226:229], v27
	s_waitcnt lgkmcnt(3)
	v_mfma_f32_16x16x32_bf16 v[40:43], v[158:161], v[178:181], v[40:43]
	v_mfma_f32_16x16x32_bf16 v[44:47], v[162:165], v[178:181], v[44:47]
	v_mfma_f32_16x16x32_bf16 v[48:51], v[166:169], v[178:181], v[48:51]
	v_mfma_f32_16x16x32_bf16 v[174:177], v[214:217], v[178:181], v[174:177]
	ds_read_b128 v[178:181], v28
	s_waitcnt lgkmcnt(3)
	v_mfma_f32_16x16x32_bf16 v[56:59], v[158:161], v[218:221], v[56:59]
	v_mfma_f32_16x16x32_bf16 v[60:63], v[162:165], v[218:221], v[60:63]
	v_mfma_f32_16x16x32_bf16 v[64:67], v[166:169], v[218:221], v[64:67]
	v_mfma_f32_16x16x32_bf16 v[170:173], v[214:217], v[218:221], v[170:173]
	ds_read_b128 v[218:221], v29
	s_waitcnt lgkmcnt(3)
	v_mfma_f32_16x16x32_bf16 v[72:75], v[158:161], v[222:225], v[72:75]
	v_mfma_f32_16x16x32_bf16 v[76:79], v[162:165], v[222:225], v[76:79]
	v_mfma_f32_16x16x32_bf16 v[80:83], v[166:169], v[222:225], v[80:83]
	v_mfma_f32_16x16x32_bf16 v[32:35], v[214:217], v[222:225], v[32:35]
	ds_read_b128 v[222:225], v30
	s_waitcnt lgkmcnt(3)
	v_mfma_f32_16x16x32_bf16 v[88:91], v[158:161], v[226:229], v[88:91]
	v_mfma_f32_16x16x32_bf16 v[92:95], v[162:165], v[226:229], v[92:95]
	v_mfma_f32_16x16x32_bf16 v[96:99], v[166:169], v[226:229], v[96:99]
	v_mfma_f32_16x16x32_bf16 v[36:39], v[214:217], v[226:229], v[36:39]
	ds_read_b128 v[226:229], v31
	s_waitcnt lgkmcnt(3)
	v_mfma_f32_16x16x32_bf16 v[104:107], v[158:161], v[178:181], v[104:107]
	v_mfma_f32_16x16x32_bf16 v[108:111], v[162:165], v[178:181], v[108:111]
	v_mfma_f32_16x16x32_bf16 v[112:115], v[166:169], v[178:181], v[112:115]
	v_mfma_f32_16x16x32_bf16 v[52:55], v[214:217], v[178:181], v[52:55]
	s_waitcnt lgkmcnt(2)
	v_mfma_f32_16x16x32_bf16 v[116:119], v[158:161], v[218:221], v[116:119]
	v_mfma_f32_16x16x32_bf16 v[120:123], v[162:165], v[218:221], v[120:123]
	v_mfma_f32_16x16x32_bf16 v[124:127], v[166:169], v[218:221], v[124:127]
	v_mfma_f32_16x16x32_bf16 v[68:71], v[214:217], v[218:221], v[68:71]
	s_waitcnt lgkmcnt(1)
	v_mfma_f32_16x16x32_bf16 v[132:135], v[162:165], v[222:225], v[132:135]
	v_mfma_f32_16x16x32_bf16 v[84:87], v[214:217], v[222:225], v[84:87]
	s_waitcnt lgkmcnt(0)
	v_mfma_f32_16x16x32_bf16 v[100:103], v[158:161], v[226:229], v[100:103]
	v_mfma_f32_16x16x32_bf16 v[150:153], v[166:169], v[226:229], v[150:153]
	v_mfma_f32_16x16x32_bf16 v[154:157], v[214:217], v[226:229], v[154:157]
	v_mfma_f32_16x16x32_bf16 v[128:131], v[158:161], v[222:225], v[128:131]
	v_mfma_f32_16x16x32_bf16 v[136:139], v[166:169], v[222:225], v[136:139]
	v_mfma_f32_16x16x32_bf16 v[140:143], v[162:165], v[226:229], v[140:143]
	s_add_u32 s14, s14, 0xf80
	s_addc_u32 s15, s15, 0
	s_add_u32 s20, s20, 0xf80
	s_waitcnt vmcnt(0)
	s_barrier
	s_addc_u32 s21, s21, 0
	v_lshl_add_u64 v[158:159], s[14:15], 0, v[0:1]
	s_mov_b32 s47, m0
	s_mov_b32 m0, s27
	s_nop 0
	global_load_lds_dwordx4 v[158:159], off
	s_mov_b32 m0, s47
	v_lshl_add_u64 v[158:159], s[20:21], 0, v[0:1]
	s_mov_b32 s27, m0
	s_mov_b32 m0, s26
	s_nop 0
	global_load_lds_dwordx4 v[158:159], off
	s_mov_b32 m0, s27
	v_lshl_add_u64 v[158:159], s[14:15], 0, v[2:3]
	s_mov_b32 s26, m0
	s_mov_b32 m0, s41
	s_nop 0
	global_load_lds_dwordx4 v[158:159], off
	s_mov_b32 m0, s26
	v_lshl_add_u64 v[158:159], s[20:21], 0, v[2:3]
	s_mov_b32 s26, m0
	s_mov_b32 m0, s42
	s_nop 0
	global_load_lds_dwordx4 v[158:159], off
	s_mov_b32 m0, s26
	v_lshl_add_u64 v[158:159], s[14:15], 0, v[4:5]
	s_mov_b32 s26, m0
	s_mov_b32 m0, s43
	s_nop 0
	global_load_lds_dwordx4 v[158:159], off
	s_mov_b32 m0, s26
	v_lshl_add_u64 v[158:159], s[20:21], 0, v[4:5]
	s_mov_b32 s26, m0
	s_mov_b32 m0, s44
	s_nop 0
	global_load_lds_dwordx4 v[158:159], off
	s_mov_b32 m0, s26
	v_lshl_add_u64 v[158:159], s[14:15], 0, v[146:147]
	s_mov_b32 s14, m0
	s_mov_b32 m0, s45
	s_nop 0
	global_load_lds_dwordx4 v[158:159], off
	s_mov_b32 m0, s14
	v_lshl_add_u64 v[158:159], s[20:21], 0, v[146:147]
	s_mov_b32 s14, m0
	s_mov_b32 m0, s46
	s_nop 0
	global_load_lds_dwordx4 v[158:159], off
	s_mov_b32 m0, s14
	ds_read_b128 v[158:161], v7 offset:32768
	ds_read_b128 v[162:165], v7 offset:34816
	ds_read_b128 v[166:169], v7 offset:36864
	ds_read_b128 v[214:217], v7 offset:38912
	ds_read_b128 v[178:181], v6
	ds_read_b128 v[218:221], v6 offset:2048
	ds_read_b128 v[222:225], v6 offset:4096
	ds_read_b128 v[226:229], v6 offset:6144
	s_waitcnt lgkmcnt(3)
	v_mfma_f32_16x16x32_bf16 v[40:43], v[158:161], v[178:181], v[40:43]
	v_mfma_f32_16x16x32_bf16 v[44:47], v[162:165], v[178:181], v[44:47]
	v_mfma_f32_16x16x32_bf16 v[48:51], v[166:169], v[178:181], v[48:51]
	v_mfma_f32_16x16x32_bf16 v[174:177], v[214:217], v[178:181], v[174:177]
	ds_read_b128 v[178:181], v6 offset:8192
	s_waitcnt lgkmcnt(3)
	v_mfma_f32_16x16x32_bf16 v[56:59], v[158:161], v[218:221], v[56:59]
	v_mfma_f32_16x16x32_bf16 v[60:63], v[162:165], v[218:221], v[60:63]
	v_mfma_f32_16x16x32_bf16 v[64:67], v[166:169], v[218:221], v[64:67]
	v_mfma_f32_16x16x32_bf16 v[170:173], v[214:217], v[218:221], v[170:173]
	ds_read_b128 v[218:221], v6 offset:10240
	s_waitcnt lgkmcnt(3)
	v_mfma_f32_16x16x32_bf16 v[72:75], v[158:161], v[222:225], v[72:75]
	v_mfma_f32_16x16x32_bf16 v[76:79], v[162:165], v[222:225], v[76:79]
	v_mfma_f32_16x16x32_bf16 v[80:83], v[166:169], v[222:225], v[80:83]
	v_mfma_f32_16x16x32_bf16 v[32:35], v[214:217], v[222:225], v[32:35]
	ds_read_b128 v[222:225], v6 offset:12288
	s_waitcnt lgkmcnt(3)
	v_mfma_f32_16x16x32_bf16 v[88:91], v[158:161], v[226:229], v[88:91]
	v_mfma_f32_16x16x32_bf16 v[92:95], v[162:165], v[226:229], v[92:95]
	v_mfma_f32_16x16x32_bf16 v[96:99], v[166:169], v[226:229], v[96:99]
	v_mfma_f32_16x16x32_bf16 v[36:39], v[214:217], v[226:229], v[36:39]
	ds_read_b128 v[226:229], v6 offset:14336
	s_waitcnt lgkmcnt(3)
	v_mfma_f32_16x16x32_bf16 v[104:107], v[158:161], v[178:181], v[104:107]
	v_mfma_f32_16x16x32_bf16 v[108:111], v[162:165], v[178:181], v[108:111]
	v_mfma_f32_16x16x32_bf16 v[112:115], v[166:169], v[178:181], v[112:115]
	v_mfma_f32_16x16x32_bf16 v[52:55], v[214:217], v[178:181], v[52:55]
	s_waitcnt lgkmcnt(2)
	v_mfma_f32_16x16x32_bf16 v[116:119], v[158:161], v[218:221], v[116:119]
	v_mfma_f32_16x16x32_bf16 v[120:123], v[162:165], v[218:221], v[120:123]
	v_mfma_f32_16x16x32_bf16 v[124:127], v[166:169], v[218:221], v[124:127]
	v_mfma_f32_16x16x32_bf16 v[68:71], v[214:217], v[218:221], v[68:71]
	s_waitcnt lgkmcnt(1)
	v_mfma_f32_16x16x32_bf16 v[132:135], v[162:165], v[222:225], v[132:135]
	v_mfma_f32_16x16x32_bf16 v[84:87], v[214:217], v[222:225], v[84:87]
	s_waitcnt lgkmcnt(0)
	v_mfma_f32_16x16x32_bf16 v[100:103], v[158:161], v[226:229], v[100:103]
	v_mfma_f32_16x16x32_bf16 v[150:153], v[166:169], v[226:229], v[150:153]
	v_mfma_f32_16x16x32_bf16 v[154:157], v[214:217], v[226:229], v[154:157]
	v_mfma_f32_16x16x32_bf16 v[128:131], v[158:161], v[222:225], v[128:131]
	v_mfma_f32_16x16x32_bf16 v[136:139], v[166:169], v[222:225], v[136:139]
	v_mfma_f32_16x16x32_bf16 v[140:143], v[162:165], v[226:229], v[140:143]
	ds_read_b128 v[158:161], v7 offset:33792
	ds_read_b128 v[162:165], v7 offset:35840
	ds_read_b128 v[166:169], v7 offset:37888
	ds_read_b128 v[214:217], v7 offset:39936
	ds_read_b128 v[178:181], v6 offset:1024
	ds_read_b128 v[218:221], v6 offset:3072
	ds_read_b128 v[222:225], v6 offset:5120
	ds_read_b128 v[226:229], v6 offset:7168
	s_waitcnt lgkmcnt(3)
	v_mfma_f32_16x16x32_bf16 v[40:43], v[158:161], v[178:181], v[40:43]
	v_mfma_f32_16x16x32_bf16 v[44:47], v[162:165], v[178:181], v[44:47]
	v_mfma_f32_16x16x32_bf16 v[48:51], v[166:169], v[178:181], v[48:51]
	v_mfma_f32_16x16x32_bf16 v[174:177], v[214:217], v[178:181], v[174:177]
	ds_read_b128 v[178:181], v6 offset:9216
	s_waitcnt lgkmcnt(3)
	v_mfma_f32_16x16x32_bf16 v[56:59], v[158:161], v[218:221], v[56:59]
	v_mfma_f32_16x16x32_bf16 v[60:63], v[162:165], v[218:221], v[60:63]
	v_mfma_f32_16x16x32_bf16 v[64:67], v[166:169], v[218:221], v[64:67]
	v_mfma_f32_16x16x32_bf16 v[170:173], v[214:217], v[218:221], v[170:173]
	ds_read_b128 v[218:221], v6 offset:11264
	s_waitcnt lgkmcnt(3)
	v_mfma_f32_16x16x32_bf16 v[72:75], v[158:161], v[222:225], v[72:75]
	v_mfma_f32_16x16x32_bf16 v[76:79], v[162:165], v[222:225], v[76:79]
	v_mfma_f32_16x16x32_bf16 v[80:83], v[166:169], v[222:225], v[80:83]
	v_mfma_f32_16x16x32_bf16 v[32:35], v[214:217], v[222:225], v[32:35]
	ds_read_b128 v[222:225], v6 offset:13312
	s_waitcnt lgkmcnt(3)
	v_mfma_f32_16x16x32_bf16 v[88:91], v[158:161], v[226:229], v[88:91]
	v_mfma_f32_16x16x32_bf16 v[92:95], v[162:165], v[226:229], v[92:95]
	v_mfma_f32_16x16x32_bf16 v[96:99], v[166:169], v[226:229], v[96:99]
	v_mfma_f32_16x16x32_bf16 v[36:39], v[214:217], v[226:229], v[36:39]
	ds_read_b128 v[226:229], v6 offset:15360
	s_waitcnt lgkmcnt(3)
	v_mfma_f32_16x16x32_bf16 v[104:107], v[158:161], v[178:181], v[104:107]
	v_mfma_f32_16x16x32_bf16 v[108:111], v[162:165], v[178:181], v[108:111]
	v_mfma_f32_16x16x32_bf16 v[112:115], v[166:169], v[178:181], v[112:115]
	v_mfma_f32_16x16x32_bf16 v[52:55], v[214:217], v[178:181], v[52:55]
	s_waitcnt lgkmcnt(2)
	v_mfma_f32_16x16x32_bf16 v[116:119], v[158:161], v[218:221], v[116:119]
	v_mfma_f32_16x16x32_bf16 v[120:123], v[162:165], v[218:221], v[120:123]
	v_mfma_f32_16x16x32_bf16 v[124:127], v[166:169], v[218:221], v[124:127]
	v_mfma_f32_16x16x32_bf16 v[68:71], v[214:217], v[218:221], v[68:71]
	s_waitcnt lgkmcnt(1)
	v_mfma_f32_16x16x32_bf16 v[132:135], v[162:165], v[222:225], v[132:135]
	v_mfma_f32_16x16x32_bf16 v[84:87], v[214:217], v[222:225], v[84:87]
	s_waitcnt lgkmcnt(0)
	v_mfma_f32_16x16x32_bf16 v[100:103], v[158:161], v[226:229], v[100:103]
	v_mfma_f32_16x16x32_bf16 v[150:153], v[166:169], v[226:229], v[150:153]
	v_mfma_f32_16x16x32_bf16 v[154:157], v[214:217], v[226:229], v[154:157]
	v_mfma_f32_16x16x32_bf16 v[128:131], v[158:161], v[222:225], v[128:131]
	v_mfma_f32_16x16x32_bf16 v[136:139], v[166:169], v[222:225], v[136:139]
	v_mfma_f32_16x16x32_bf16 v[140:143], v[162:165], v[226:229], v[140:143]
	s_waitcnt vmcnt(0)
	s_barrier
	v_lshl_add_u64 v[6:7], s[22:23], 0, v[0:1]
	s_mov_b32 s14, m0
	s_mov_b32 m0, s1
	s_nop 0
	global_load_lds_dwordx4 v[6:7], off
	s_mov_b32 m0, s14
	v_lshl_add_u64 v[0:1], s[24:25], 0, v[0:1]
	s_mov_b32 s1, m0
	s_mov_b32 m0, s34
	s_nop 0
	global_load_lds_dwordx4 v[0:1], off
	s_mov_b32 m0, s1
	v_lshl_add_u64 v[0:1], s[22:23], 0, v[2:3]
	s_mov_b32 s1, m0
	s_mov_b32 m0, s35
	s_nop 0
	global_load_lds_dwordx4 v[0:1], off
	s_mov_b32 m0, s1
	v_lshl_add_u64 v[0:1], s[24:25], 0, v[2:3]
	s_mov_b32 s1, m0
	s_mov_b32 m0, s36
	s_nop 0
	global_load_lds_dwordx4 v[0:1], off
	s_mov_b32 m0, s1
	v_lshl_add_u64 v[0:1], s[22:23], 0, v[4:5]
	s_mov_b32 s1, m0
	s_mov_b32 m0, s37
	s_nop 0
	global_load_lds_dwordx4 v[0:1], off
	s_mov_b32 m0, s1
	v_lshl_add_u64 v[0:1], s[24:25], 0, v[4:5]
	s_mov_b32 s1, m0
	s_mov_b32 m0, s38
	s_nop 0
	global_load_lds_dwordx4 v[0:1], off
	s_mov_b32 m0, s1
	v_lshl_add_u64 v[0:1], s[22:23], 0, v[146:147]
	s_mov_b32 s1, m0
	s_mov_b32 m0, s39
	s_nop 0
	global_load_lds_dwordx4 v[0:1], off
	s_mov_b32 m0, s1
	v_lshl_add_u64 v[0:1], s[24:25], 0, v[146:147]
	s_mov_b32 s1, m0
	s_mov_b32 m0, s40
	s_nop 0
	global_load_lds_dwordx4 v[0:1], off
	s_mov_b32 m0, s1
	ds_read_b128 v[0:3], v8
	ds_read_b128 v[4:7], v9
	ds_read_b128 v[158:161], v11
	ds_read_b128 v[8:11], v10
	ds_read_b128 v[162:165], v12
	ds_read_b128 v[166:169], v13
	ds_read_b128 v[178:181], v14
	ds_read_b128 v[12:15], v15
	s_waitcnt lgkmcnt(3)
	v_mfma_f32_16x16x32_bf16 v[40:43], v[0:3], v[162:165], v[40:43]
	v_mfma_f32_16x16x32_bf16 v[44:47], v[4:7], v[162:165], v[44:47]
	v_mfma_f32_16x16x32_bf16 v[48:51], v[158:161], v[162:165], v[48:51]
	v_mfma_f32_16x16x32_bf16 v[162:165], v[8:11], v[162:165], v[174:177]
	s_nop 2
	ds_read_b128 v[174:177], v16
	s_waitcnt lgkmcnt(3)
	v_mfma_f32_16x16x32_bf16 v[56:59], v[0:3], v[166:169], v[56:59]
	v_mfma_f32_16x16x32_bf16 v[60:63], v[4:7], v[166:169], v[60:63]
	v_mfma_f32_16x16x32_bf16 v[64:67], v[158:161], v[166:169], v[64:67]
	v_mfma_f32_16x16x32_bf16 v[166:169], v[8:11], v[166:169], v[170:173]
	s_nop 2
	ds_read_b128 v[170:173], v17
	s_waitcnt lgkmcnt(3)
	v_mfma_f32_16x16x32_bf16 v[72:75], v[0:3], v[178:181], v[72:75]
	v_mfma_f32_16x16x32_bf16 v[76:79], v[4:7], v[178:181], v[76:79]
	v_mfma_f32_16x16x32_bf16 v[80:83], v[158:161], v[178:181], v[80:83]
	v_mfma_f32_16x16x32_bf16 v[32:35], v[8:11], v[178:181], v[32:35]
	ds_read_b128 v[178:181], v18
	s_waitcnt lgkmcnt(3)
	v_mfma_f32_16x16x32_bf16 v[214:217], v[0:3], v[12:15], v[88:91]
	v_mfma_f32_16x16x32_bf16 v[218:221], v[4:7], v[12:15], v[92:95]
	v_mfma_f32_16x16x32_bf16 v[222:225], v[158:161], v[12:15], v[96:99]
	v_mfma_f32_16x16x32_bf16 v[12:15], v[8:11], v[12:15], v[36:39]
	ds_read_b128 v[16:19], v19
	s_waitcnt lgkmcnt(3)
	v_mfma_f32_16x16x32_bf16 v[36:39], v[0:3], v[174:177], v[104:107]
	v_mfma_f32_16x16x32_bf16 v[226:229], v[4:7], v[174:177], v[108:111]
	v_mfma_f32_16x16x32_bf16 v[112:115], v[158:161], v[174:177], v[112:115]
	s_waitcnt lgkmcnt(2)
	v_mfma_f32_16x16x32_bf16 v[116:119], v[0:3], v[170:173], v[116:119]
	v_mfma_f32_16x16x32_bf16 v[120:123], v[4:7], v[170:173], v[120:123]
	v_mfma_f32_16x16x32_bf16 v[124:127], v[158:161], v[170:173], v[124:127]
	s_waitcnt lgkmcnt(1)
	v_mfma_f32_16x16x32_bf16 v[128:131], v[0:3], v[178:181], v[128:131]
	v_mfma_f32_16x16x32_bf16 v[132:135], v[4:7], v[178:181], v[132:135]
	s_waitcnt lgkmcnt(0)
	v_mfma_f32_16x16x32_bf16 v[0:3], v[0:3], v[16:19], v[100:103]
	v_mfma_f32_16x16x32_bf16 v[4:7], v[4:7], v[16:19], v[140:143]
	v_mfma_f32_16x16x32_bf16 v[140:143], v[158:161], v[16:19], v[150:153]
	v_mfma_f32_16x16x32_bf16 v[150:153], v[8:11], v[16:19], v[154:157]
	v_mfma_f32_16x16x32_bf16 v[174:177], v[8:11], v[174:177], v[52:55]
	v_mfma_f32_16x16x32_bf16 v[170:173], v[8:11], v[170:173], v[68:71]
	v_mfma_f32_16x16x32_bf16 v[136:139], v[158:161], v[178:181], v[136:139]
	v_mfma_f32_16x16x32_bf16 v[178:181], v[8:11], v[178:181], v[84:87]
	ds_read_b128 v[8:11], v20
	ds_read_b128 v[154:157], v21
	ds_read_b128 v[158:161], v23
	ds_read_b128 v[230:233], v22
	ds_read_b128 v[16:19], v24
	ds_read_b128 v[20:23], v25
	ds_read_b128 v[52:55], v26
	ds_read_b128 v[24:27], v27
	s_waitcnt lgkmcnt(3)
	v_mfma_f32_16x16x32_bf16 v[234:237], v[8:11], v[16:19], v[40:43]
	v_mfma_f32_16x16x32_bf16 v[238:241], v[154:157], v[16:19], v[44:47]
	v_mfma_f32_16x16x32_bf16 v[242:245], v[158:161], v[16:19], v[48:51]
	v_mfma_f32_16x16x32_bf16 v[162:165], v[230:233], v[16:19], v[162:165]
	ds_read_b128 v[16:19], v28
	s_waitcnt lgkmcnt(3)
	v_mfma_f32_16x16x32_bf16 v[108:111], v[8:11], v[20:23], v[56:59]
	v_mfma_f32_16x16x32_bf16 v[104:107], v[154:157], v[20:23], v[60:63]
	v_mfma_f32_16x16x32_bf16 v[100:103], v[158:161], v[20:23], v[64:67]
	v_mfma_f32_16x16x32_bf16 v[96:99], v[230:233], v[20:23], v[166:169]
	ds_read_b128 v[20:23], v29
	s_waitcnt lgkmcnt(3)
	v_mfma_f32_16x16x32_bf16 v[92:95], v[8:11], v[52:55], v[72:75]
	v_mfma_f32_16x16x32_bf16 v[88:91], v[154:157], v[52:55], v[76:79]
	v_mfma_f32_16x16x32_bf16 v[84:87], v[158:161], v[52:55], v[80:83]
	v_mfma_f32_16x16x32_bf16 v[80:83], v[230:233], v[52:55], v[32:35]
	ds_read_b128 v[166:169], v30
	s_waitcnt lgkmcnt(3)
	v_mfma_f32_16x16x32_bf16 v[76:79], v[8:11], v[24:27], v[214:217]
	v_mfma_f32_16x16x32_bf16 v[72:75], v[154:157], v[24:27], v[218:221]
	v_mfma_f32_16x16x32_bf16 v[68:71], v[158:161], v[24:27], v[222:225]
	v_mfma_f32_16x16x32_bf16 v[64:67], v[230:233], v[24:27], v[12:15]
	ds_read_b128 v[214:217], v31
	s_waitcnt lgkmcnt(3)
	v_mfma_f32_16x16x32_bf16 v[60:63], v[8:11], v[16:19], v[36:39]
	v_mfma_f32_16x16x32_bf16 v[56:59], v[154:157], v[16:19], v[226:229]
	v_mfma_f32_16x16x32_bf16 v[52:55], v[158:161], v[16:19], v[112:115]
	v_mfma_f32_16x16x32_bf16 v[48:51], v[230:233], v[16:19], v[174:177]
	s_waitcnt lgkmcnt(2)
	v_mfma_f32_16x16x32_bf16 v[44:47], v[8:11], v[20:23], v[116:119]
	v_mfma_f32_16x16x32_bf16 v[40:43], v[154:157], v[20:23], v[120:123]
	v_mfma_f32_16x16x32_bf16 v[36:39], v[158:161], v[20:23], v[124:127]
	v_mfma_f32_16x16x32_bf16 v[32:35], v[230:233], v[20:23], v[170:173]
	s_waitcnt lgkmcnt(1)
	v_mfma_f32_16x16x32_bf16 v[28:31], v[8:11], v[166:169], v[128:131]
	v_mfma_f32_16x16x32_bf16 v[24:27], v[154:157], v[166:169], v[132:135]
	v_mfma_f32_16x16x32_bf16 v[20:23], v[158:161], v[166:169], v[136:139]
	v_mfma_f32_16x16x32_bf16 v[16:19], v[230:233], v[166:169], v[178:181]
	s_waitcnt lgkmcnt(0)
	v_mfma_f32_16x16x32_bf16 v[12:15], v[8:11], v[214:217], v[0:3]
	v_mfma_f32_16x16x32_bf16 v[8:11], v[154:157], v[214:217], v[4:7]
	v_mfma_f32_16x16x32_bf16 v[4:7], v[158:161], v[214:217], v[140:143]
	v_mfma_f32_16x16x32_bf16 v[0:3], v[230:233], v[214:217], v[150:153]
	v_mov_b32_e32 v145, v184
	s_waitcnt vmcnt(0)
	s_barrier
	s_lshl_b32 s20, s0, 8
	s_lshl_b32 s14, s12, 8
	v_and_b32_e32 v151, 15, v145
	v_ashrrev_i32_e32 v112, 1, v145
	v_and_b32_e32 v153, 0xffffff80, v112
	v_or_b32_e32 v112, s20, v151
	v_add_u32_e32 v112, v112, v153
	v_ashrrev_i32_e32 v113, 31, v112
	v_lshlrev_b64 v[112:113], 13, v[112:113]
	v_bfe_u32 v150, v145, 6, 2
	v_lshl_add_u64 v[112:113], s[2:3], 0, v[112:113]
	s_ashr_i32 s15, s14, 31
	v_bfe_u32 v152, v145, 4, 2
	v_lshl_add_u64 v[112:113], s[14:15], 2, v[112:113]
	v_lshlrev_b32_e32 v146, 8, v150
	v_lshl_add_u64 v[112:113], v[112:113], 0, v[146:147]
	v_lshlrev_b32_e32 v146, 4, v152
	v_lshl_add_u64 v[154:155], v[112:113], 0, v[146:147]
	global_load_dwordx4 v[120:123], v[154:155], off offset:192
	global_load_dwordx4 v[128:131], v[154:155], off offset:128
	global_load_dwordx4 v[136:139], v[154:155], off offset:64
	global_load_dwordx4 v[140:143], v[154:155], off
	v_add_co_u32_e32 v112, vcc, s66, v154
	v_lshlrev_b32_e32 v158, 2, v152
	s_nop 0
	v_addc_co_u32_e32 v113, vcc, 0, v155, vcc
	global_load_dwordx4 v[132:135], v[112:113], off
	global_load_dwordx4 v[124:127], v[112:113], off offset:64
	global_load_dwordx4 v[116:119], v[112:113], off offset:128
	v_cmp_lt_i32_e32 vcc, v188, v186
	global_load_dwordx4 v[112:115], v[112:113], off offset:192
	v_cmp_eq_u32_e64 s[0:1], 0, v152
	v_cndmask_b32_e32 v146, v185, v188, vcc
	v_cmp_lt_i32_e32 vcc, v187, v186
	v_lshlrev_b32_e32 v149, 2, v146
	v_lshlrev_b32_e32 v157, 6, v150
	v_cndmask_b32_e32 v156, v185, v187, vcc
	v_lshlrev_b32_e32 v146, 2, v156
	v_or_b32_e32 v156, v153, v151
	v_add_u32_e32 v152, s20, v156
	v_ashrrev_i32_e32 v153, 31, v152
	v_lshl_or_b32 v182, v150, 10, v204
	v_or3_b32 v150, v157, s14, v158
	v_lshlrev_b64 v[158:159], 13, v[152:153]
	v_ashrrev_i32_e32 v151, 31, v150
	v_lshlrev_b64 v[160:161], 12, v[152:153]
	v_lshl_add_u64 v[158:159], s[2:3], 0, v[158:159]
	v_lshl_add_u64 v[160:161], s[4:5], 0, v[160:161]
	v_lshl_add_u64 v[166:167], v[150:151], 2, v[158:159]
	v_lshl_add_u64 v[168:169], v[150:151], 1, v[160:161]
	s_waitcnt vmcnt(7)
	v_pk_add_f32 v[158:159], v[162:163], v[120:121]
	s_waitcnt vmcnt(6)
	v_pk_add_f32 v[120:121], v[242:243], v[128:129]
	s_waitcnt vmcnt(5)
	v_pk_add_f32 v[128:129], v[238:239], v[136:137]
	s_waitcnt vmcnt(4)
	v_pk_add_f32 v[136:137], v[234:235], v[140:141]
	v_pk_add_f32 v[160:161], v[164:165], v[122:123]
	v_pk_add_f32 v[122:123], v[244:245], v[130:131]
	v_pk_add_f32 v[130:131], v[240:241], v[138:139]
	v_pk_add_f32 v[138:139], v[236:237], v[142:143]
	v_pk_mul_f32 v[172:173], v[128:129], v[128:129]
	v_pk_mul_f32 v[178:179], v[136:137], v[136:137]
	v_pk_mul_f32 v[162:163], v[120:121], v[120:121]
	v_pk_mul_f32 v[174:175], v[130:131], v[130:131]
	v_cvt_pk_bf16_f32 v176, v136, v137
	v_pk_mul_f32 v[180:181], v[138:139], v[138:139]
	global_store_dwordx4 v[166:167], v[136:139], off
	v_add_f32_e32 v153, v172, v173
	v_add_f32_e32 v157, v178, v179
	v_pk_mul_f32 v[136:137], v[158:159], v[158:159]
	v_pk_mul_f32 v[164:165], v[122:123], v[122:123]
	v_cvt_pk_bf16_f32 v177, v138, v139
	v_pk_mul_f32 v[138:139], v[160:161], v[160:161]
	v_add_f32_e32 v162, v162, v163
	v_add_f32_e32 v136, v136, v137
	v_add_f32_e32 v137, v174, v153
	v_add_f32_e32 v153, v180, v157
	v_add_f32_e32 v157, v164, v162
	v_add_f32_e32 v136, v138, v136
	v_add_f32_e32 v137, v175, v137
	v_add_f32_e32 v138, v181, v153
	v_add_f32_e32 v153, v165, v157
	v_add_f32_e32 v137, v138, v137
	v_add_f32_e32 v137, v137, v153
	v_add_f32_e32 v136, v139, v136
	v_add_f32_e32 v136, v137, v136
	ds_bpermute_b32 v137, v149, v136
	v_cvt_pk_bf16_f32 v170, v128, v129
	v_cvt_pk_bf16_f32 v171, v130, v131
	v_cvt_pk_bf16_f32 v142, v120, v121
	global_store_dwordx2 v[168:169], v[176:177], off
	global_store_dwordx4 v[166:167], v[128:131], off offset:64
	global_store_dwordx2 v[168:169], v[170:171], off offset:32
	global_store_dwordx4 v[166:167], v[120:123], off offset:128
	v_cvt_pk_bf16_f32 v140, v158, v159
	v_cvt_pk_bf16_f32 v141, v160, v161
	s_waitcnt lgkmcnt(0)
	v_add_f32_e32 v120, v136, v137
	ds_bpermute_b32 v121, v146, v120
	v_cvt_pk_bf16_f32 v143, v122, v123
	v_lshl_add_u32 v153, v156, 2, v182
	global_store_dwordx2 v[168:169], v[142:143], off offset:64
	global_store_dwordx4 v[166:167], v[158:161], off offset:192
	global_store_dwordx2 v[168:169], v[140:141], off offset:96
	s_and_saveexec_b64 s[14:15], s[0:1]
	s_cbranch_execz .LBB0_698
	s_waitcnt lgkmcnt(0)
	v_add_f32_e32 v120, v120, v121
	ds_write_b32 v153, v120

.LBB0_757:
	s_ashr_i32 s25, s24, 31
	s_lshl_b64 s[24:25], s[24:25], 20
	s_add_u32 s27, s2, s24
	s_addc_u32 s45, s3, s25
	s_ashr_i32 s47, s46, 1
	s_lshl_b32 s24, s47, 8
	s_ashr_i32 s25, s24, 31
	s_lshl_b64 s[24:25], s[24:25], 1
	s_add_u32 s27, s27, s24
	s_addc_u32 s45, s45, s25
	s_add_i32 s24, s47, s28
	s_ashr_i32 s25, s24, 31
	s_lshl_b64 s[24:25], s[24:25], 18
	s_add_u32 s24, s29, s24
	s_addc_u32 s25, s30, s25
	s_lshl_b32 s46, s46, 17
	v_lshlrev_b32_e32 v3, 6, v1
	s_and_b32 s46, s46, 0x20000
	v_and_b32_e32 v2, 48, v1
	v_and_b32_e32 v4, 0x3c0, v3
	v_lshlrev_b32_e32 v1, 2, v1
	s_add_u32 s46, s24, s46
	v_or_b32_e32 v5, v4, v2
	v_and_b32_e32 v1, 32, v1
	v_lshlrev_b32_e32 v0, 13, v0
	s_mov_b32 s24, 0x18000
	v_and_b32_e32 v143, 0x6000, v0
	v_bitop3_b32 v0, v5, s24, v1 bitop3:0xde
	s_mov_b32 s24, 0x10400
	s_addc_u32 s47, s25, 0
	v_bitop3_b32 v157, v5, s24, v1 bitop3:0xde
	s_add_i32 s24, s31, s63
	s_ashr_i32 s25, s24, 31
	s_lshl_b32 s62, s62, 15
	s_lshl_b64 s[24:25], s[24:25], 18
	s_and_b32 s62, s62, 0x20000
	s_add_i32 s49, s38, 0x10000
	s_add_i32 s50, s38, 0x18000
	s_add_i32 s51, s38, 0x12000
	s_add_i32 s52, s38, 0x1a000
	s_add_i32 s53, s38, 0x14000
	s_add_i32 s54, s38, 0x1c000
	s_add_i32 s55, s38, 0x16000
	s_add_i32 s58, s38, 0x1e000
	s_or_b32 s24, s24, s62
	s_add_u32 s62, s10, s24
	s_addc_u32 s63, s11, s25
	s_add_i32 s24, s64, s65
	s_ashr_i32 s25, s24, 31
	s_lshl_b64 s[24:25], s[24:25], 20
	s_lshl_b64 s[64:65], s[22:23], 1
	s_add_u32 s23, s24, s64
	s_waitcnt vmcnt(0)
	s_addc_u32 s24, s25, s65
	v_and_b32_e32 v145, 0xffffc000, v3
	s_add_u32 s23, s10, s23
	v_mov_b32_e32 v8, 0
	s_mov_b32 s26, 1
	v_bitop3_b32 v142, v4, v1, v2 bitop3:0x36
	v_or_b32_e32 v149, 0x800, v145
	v_or_b32_e32 v150, 0x1000, v145
	v_or_b32_e32 v151, 0x1800, v145
	v_or_b32_e32 v152, 0x2000, v145
	v_or_b32_e32 v153, 0x2800, v145
	v_or_b32_e32 v154, 0x3000, v145
	v_or_b32_e32 v155, 0x3800, v145
	v_bitop3_b32 v156, v5, s33, v1 bitop3:0xde
	s_addc_u32 s64, s11, s24
	s_mov_b64 s[24:25], 0
	v_add_u32_e32 v158, v0, v143
	v_mov_b32_e32 v9, v8
	v_mov_b32_e32 v10, v8
	v_mov_b32_e32 v11, v8
	v_mov_b32_e32 v72, v8
	v_mov_b32_e32 v73, v8
	v_mov_b32_e32 v74, v8
	v_mov_b32_e32 v75, v8
	v_mov_b32_e32 v12, v8
	v_mov_b32_e32 v13, v8
	v_mov_b32_e32 v14, v8
	v_mov_b32_e32 v15, v8
	v_mov_b32_e32 v76, v8
	v_mov_b32_e32 v77, v8
	v_mov_b32_e32 v78, v8
	v_mov_b32_e32 v79, v8
	v_mov_b32_e32 v16, v8
	v_mov_b32_e32 v17, v8
	v_mov_b32_e32 v18, v8
	v_mov_b32_e32 v19, v8
	v_mov_b32_e32 v80, v8
	v_mov_b32_e32 v81, v8
	v_mov_b32_e32 v82, v8
	v_mov_b32_e32 v83, v8
	v_mov_b32_e32 v20, v8
	v_mov_b32_e32 v21, v8
	v_mov_b32_e32 v22, v8
	v_mov_b32_e32 v23, v8
	v_mov_b32_e32 v84, v8
	v_mov_b32_e32 v85, v8
	v_mov_b32_e32 v86, v8
	v_mov_b32_e32 v87, v8
	v_mov_b32_e32 v24, v8
	v_mov_b32_e32 v25, v8
	v_mov_b32_e32 v26, v8
	v_mov_b32_e32 v27, v8
	v_mov_b32_e32 v96, v8
	v_mov_b32_e32 v97, v8
	v_mov_b32_e32 v98, v8
	v_mov_b32_e32 v99, v8
	v_mov_b32_e32 v28, v8
	v_mov_b32_e32 v29, v8
	v_mov_b32_e32 v30, v8
	v_mov_b32_e32 v31, v8
	v_mov_b32_e32 v100, v8
	v_mov_b32_e32 v101, v8
	v_mov_b32_e32 v102, v8
	v_mov_b32_e32 v103, v8
	v_mov_b32_e32 v32, v8
	v_mov_b32_e32 v33, v8
	v_mov_b32_e32 v34, v8
	v_mov_b32_e32 v35, v8
	v_mov_b32_e32 v104, v8
	v_mov_b32_e32 v105, v8
	v_mov_b32_e32 v106, v8
	v_mov_b32_e32 v107, v8
	v_mov_b32_e32 v36, v8
	v_mov_b32_e32 v37, v8
	v_mov_b32_e32 v38, v8
	v_mov_b32_e32 v39, v8
	v_mov_b32_e32 v108, v8
	v_mov_b32_e32 v109, v8
	v_mov_b32_e32 v110, v8
	v_mov_b32_e32 v111, v8
	v_mov_b32_e32 v40, v8
	v_mov_b32_e32 v41, v8
	v_mov_b32_e32 v42, v8
	v_mov_b32_e32 v43, v8
	v_mov_b32_e32 v112, v8
	v_mov_b32_e32 v113, v8
	v_mov_b32_e32 v114, v8
	v_mov_b32_e32 v115, v8
	v_mov_b32_e32 v44, v8
	v_mov_b32_e32 v45, v8
	v_mov_b32_e32 v46, v8
	v_mov_b32_e32 v47, v8
	v_mov_b32_e32 v116, v8
	v_mov_b32_e32 v117, v8
	v_mov_b32_e32 v118, v8
	v_mov_b32_e32 v119, v8
	v_mov_b32_e32 v48, v8
	v_mov_b32_e32 v49, v8
	v_mov_b32_e32 v50, v8
	v_mov_b32_e32 v51, v8
	v_mov_b32_e32 v120, v8
	v_mov_b32_e32 v121, v8
	v_mov_b32_e32 v122, v8
	v_mov_b32_e32 v123, v8
	v_mov_b32_e32 v52, v8
	v_mov_b32_e32 v53, v8
	v_mov_b32_e32 v54, v8
	v_mov_b32_e32 v55, v8
	v_mov_b32_e32 v124, v8
	v_mov_b32_e32 v125, v8
	v_mov_b32_e32 v126, v8
	v_mov_b32_e32 v127, v8
	v_mov_b32_e32 v56, v8
	v_mov_b32_e32 v57, v8
	v_mov_b32_e32 v58, v8
	v_mov_b32_e32 v59, v8
	v_mov_b32_e32 v128, v8
	v_mov_b32_e32 v129, v8
	v_mov_b32_e32 v130, v8
	v_mov_b32_e32 v131, v8
	v_mov_b32_e32 v60, v8
	v_mov_b32_e32 v61, v8
	v_mov_b32_e32 v62, v8
	v_mov_b32_e32 v63, v8
	v_mov_b32_e32 v132, v8
	v_mov_b32_e32 v133, v8
	v_mov_b32_e32 v134, v8
	v_mov_b32_e32 v135, v8
	v_mov_b32_e32 v64, v8
	v_mov_b32_e32 v65, v8
	v_mov_b32_e32 v66, v8
	v_mov_b32_e32 v67, v8
	v_mov_b32_e32 v0, v8
	v_mov_b32_e32 v1, v8
	v_mov_b32_e32 v2, v8
	v_mov_b32_e32 v3, v8
	v_mov_b32_e32 v68, v8
	v_mov_b32_e32 v69, v8
	v_mov_b32_e32 v70, v8
	v_mov_b32_e32 v71, v8
	v_mov_b32_e32 v4, v8
	v_mov_b32_e32 v5, v8
	v_mov_b32_e32 v6, v8
	v_mov_b32_e32 v7, v8
	s_barrier
	s_add_u32 s65, s23, s24
	s_addc_u32 s72, s64, s25
	s_add_u32 s68, s65, 0x21ac0080
	s_addc_u32 s69, s72, 0
	s_add_u32 s73, s62, s24
	s_addc_u32 s74, s63, s25
	s_add_u32 s70, s73, 0x2000080
	s_addc_u32 s71, s74, 0
	v_add_u32_e32 v159, v142, v143
	v_add_u32_e32 v189, v142, v145
	ds_read_b128 v[160:163], v159 offset:32768
	ds_read_b128 v[164:167], v189
	s_mov_b32 m0, s49
	s_nop 0
	global_load_lds_dwordx4 v88, s[68:69]
	ds_read_b128 v[168:171], v159 offset:34816
	s_mov_b32 m0, s50
	s_nop 0
	global_load_lds_dwordx4 v90, s[70:71]
	ds_read_b128 v[172:175], v189 offset:2048
	ds_read_b128 v[176:179], v159 offset:36864
	s_mov_b32 m0, s51
	s_nop 0
	global_load_lds_dwordx4 v92, s[68:69]
	ds_read_b128 v[180:183], v159 offset:38912
	ds_read_b128 v[214:217], v189 offset:4096
	ds_read_b128 v[218:221], v189 offset:6144
	s_branch .Lmy_rot_758
.LBB0_758:
	s_add_u32 s65, s23, s24
	s_addc_u32 s72, s64, s25
	s_add_u32 s68, s65, 0x21ac0080
	s_addc_u32 s69, s72, 0
	s_add_u32 s73, s62, s24
	s_addc_u32 s74, s63, s25
	s_add_u32 s70, s73, 0x2000080
	s_addc_u32 s71, s74, 0
	v_add_u32_e32 v159, v142, v143
	v_add_u32_e32 v189, v142, v145
	ds_read_b128 v[160:163], v159 offset:32768
	ds_read_b128 v[164:167], v189
	s_mov_b32 m0, s49
	v_mfma_f32_16x16x32_bf16 v[76:79], v[168:171], v[214:217], v[76:79]
	global_load_lds_dwordx4 v88, s[68:69]
	v_mfma_f32_16x16x32_bf16 v[64:67], v[168:171], v[218:221], v[64:67]
	ds_read_b128 v[168:171], v159 offset:34816
	v_mfma_f32_16x16x32_bf16 v[12:15], v[172:175], v[214:217], v[12:15]
	s_mov_b32 m0, s50
	v_mfma_f32_16x16x32_bf16 v[0:3], v[172:175], v[218:221], v[0:3]
	global_load_lds_dwordx4 v90, s[70:71]
	ds_read_b128 v[172:175], v189 offset:2048
	v_mfma_f32_16x16x32_bf16 v[72:75], v[176:179], v[214:217], v[72:75]
	v_mfma_f32_16x16x32_bf16 v[68:71], v[176:179], v[218:221], v[68:71]
	ds_read_b128 v[176:179], v159 offset:36864
	s_mov_b32 m0, s51
	v_mfma_f32_16x16x32_bf16 v[8:11], v[180:183], v[214:217], v[8:11]
	global_load_lds_dwordx4 v92, s[68:69]
	v_mfma_f32_16x16x32_bf16 v[4:7], v[180:183], v[218:221], v[4:7]
	ds_read_b128 v[180:183], v159 offset:38912
	ds_read_b128 v[214:217], v189 offset:4096
	ds_read_b128 v[218:221], v189 offset:6144
.Lmy_rot_758:
	s_waitcnt lgkmcnt(6)
	v_mfma_f32_16x16x32_bf16 v[132:135], v[160:163], v[164:167], v[132:135]
	s_waitcnt lgkmcnt(5)
	s_mov_b32 m0, s52
	v_mfma_f32_16x16x32_bf16 v[60:63], v[168:171], v[164:167], v[60:63]
	global_load_lds_dwordx4 v94, s[70:71]
	s_waitcnt lgkmcnt(4)
	v_mfma_f32_16x16x32_bf16 v[124:127], v[160:163], v[172:175], v[124:127]
	v_mfma_f32_16x16x32_bf16 v[52:55], v[168:171], v[172:175], v[52:55]
	s_waitcnt lgkmcnt(3)
	s_mov_b32 m0, s53
	v_mfma_f32_16x16x32_bf16 v[128:131], v[176:179], v[164:167], v[128:131]
	global_load_lds_dwordx4 v136, s[68:69]
	v_mfma_f32_16x16x32_bf16 v[120:123], v[176:179], v[172:175], v[120:123]
	s_waitcnt lgkmcnt(2)
	v_mfma_f32_16x16x32_bf16 v[56:59], v[180:183], v[164:167], v[56:59]
	ds_read_b128 v[164:167], v189 offset:8192
	s_mov_b32 m0, s54
	v_mfma_f32_16x16x32_bf16 v[48:51], v[180:183], v[172:175], v[48:51]
	global_load_lds_dwordx4 v138, s[70:71]
	ds_read_b128 v[172:175], v189 offset:10240
	s_waitcnt lgkmcnt(3)
	v_mfma_f32_16x16x32_bf16 v[116:119], v[160:163], v[214:217], v[116:119]
	v_mfma_f32_16x16x32_bf16 v[44:47], v[168:171], v[214:217], v[44:47]
	s_mov_b32 m0, s55
	v_mfma_f32_16x16x32_bf16 v[112:115], v[176:179], v[214:217], v[112:115]
	global_load_lds_dwordx4 v140, s[68:69]
	v_mfma_f32_16x16x32_bf16 v[40:43], v[180:183], v[214:217], v[40:43]
	ds_read_b128 v[214:217], v189 offset:12288
	s_waitcnt lgkmcnt(3)
	v_mfma_f32_16x16x32_bf16 v[108:111], v[160:163], v[218:221], v[108:111]
	s_mov_b32 m0, s58
	v_mfma_f32_16x16x32_bf16 v[36:39], v[168:171], v[218:221], v[36:39]
	global_load_lds_dwordx4 v146, s[70:71]
	v_mfma_f32_16x16x32_bf16 v[104:107], v[176:179], v[218:221], v[104:107]
	v_mfma_f32_16x16x32_bf16 v[32:35], v[180:183], v[218:221], v[32:35]
	ds_read_b128 v[218:221], v189 offset:14336
	s_waitcnt lgkmcnt(3)
	v_mfma_f32_16x16x32_bf16 v[28:31], v[168:171], v[164:167], v[28:31]
	s_waitcnt lgkmcnt(2)
	v_mfma_f32_16x16x32_bf16 v[20:23], v[168:171], v[172:175], v[20:23]
	s_waitcnt lgkmcnt(1)
	v_mfma_f32_16x16x32_bf16 v[12:15], v[168:171], v[214:217], v[12:15]
	s_waitcnt lgkmcnt(0)
	v_mfma_f32_16x16x32_bf16 v[0:3], v[168:171], v[218:221], v[0:3]
	ds_read_b128 v[168:171], v159 offset:33792
	v_mfma_f32_16x16x32_bf16 v[100:103], v[160:163], v[164:167], v[100:103]
	v_mfma_f32_16x16x32_bf16 v[84:87], v[160:163], v[172:175], v[84:87]
	v_mfma_f32_16x16x32_bf16 v[76:79], v[160:163], v[214:217], v[76:79]
	v_mfma_f32_16x16x32_bf16 v[64:67], v[160:163], v[218:221], v[64:67]
	ds_read_b128 v[160:163], v189 offset:1024
	v_mfma_f32_16x16x32_bf16 v[80:83], v[176:179], v[172:175], v[80:83]
	v_mfma_f32_16x16x32_bf16 v[16:19], v[180:183], v[172:175], v[16:19]
	ds_read_b128 v[172:175], v159 offset:35840
	v_mfma_f32_16x16x32_bf16 v[96:99], v[176:179], v[164:167], v[96:99]
	v_mfma_f32_16x16x32_bf16 v[24:27], v[180:183], v[164:167], v[24:27]
	ds_read_b128 v[164:167], v189 offset:3072
	v_mfma_f32_16x16x32_bf16 v[72:75], v[176:179], v[214:217], v[72:75]
	v_mfma_f32_16x16x32_bf16 v[8:11], v[180:183], v[214:217], v[8:11]
	ds_read_b128 v[214:217], v189 offset:5120
	v_mfma_f32_16x16x32_bf16 v[68:71], v[176:179], v[218:221], v[68:71]
	ds_read_b128 v[176:179], v159 offset:37888
	v_mfma_f32_16x16x32_bf16 v[4:7], v[180:183], v[218:221], v[4:7]
	ds_read_b128 v[180:183], v159 offset:39936
	ds_read_b128 v[218:221], v189 offset:7168
	s_waitcnt lgkmcnt(6)
	v_mfma_f32_16x16x32_bf16 v[132:135], v[168:171], v[160:163], v[132:135]
	s_waitcnt lgkmcnt(5)
	v_mfma_f32_16x16x32_bf16 v[60:63], v[172:175], v[160:163], v[60:63]
	s_waitcnt lgkmcnt(4)
	v_mfma_f32_16x16x32_bf16 v[124:127], v[168:171], v[164:167], v[124:127]
	v_mfma_f32_16x16x32_bf16 v[52:55], v[172:175], v[164:167], v[52:55]
	s_waitcnt lgkmcnt(3)
	v_mfma_f32_16x16x32_bf16 v[116:119], v[168:171], v[214:217], v[116:119]
	v_mfma_f32_16x16x32_bf16 v[44:47], v[172:175], v[214:217], v[44:47]
	s_waitcnt lgkmcnt(2)
	v_mfma_f32_16x16x32_bf16 v[128:131], v[176:179], v[160:163], v[128:131]
	s_waitcnt lgkmcnt(1)
	v_mfma_f32_16x16x32_bf16 v[56:59], v[180:183], v[160:163], v[56:59]
	ds_read_b128 v[160:163], v189 offset:9216
	v_mfma_f32_16x16x32_bf16 v[120:123], v[176:179], v[164:167], v[120:123]
	v_mfma_f32_16x16x32_bf16 v[48:51], v[180:183], v[164:167], v[48:51]
	ds_read_b128 v[164:167], v189 offset:11264
	v_mfma_f32_16x16x32_bf16 v[112:115], v[176:179], v[214:217], v[112:115]
	v_mfma_f32_16x16x32_bf16 v[40:43], v[180:183], v[214:217], v[40:43]
	ds_read_b128 v[214:217], v189 offset:13312
	s_waitcnt lgkmcnt(3)
	v_mfma_f32_16x16x32_bf16 v[108:111], v[168:171], v[218:221], v[108:111]
	v_mfma_f32_16x16x32_bf16 v[36:39], v[172:175], v[218:221], v[36:39]
	v_mfma_f32_16x16x32_bf16 v[104:107], v[176:179], v[218:221], v[104:107]
	v_mfma_f32_16x16x32_bf16 v[32:35], v[180:183], v[218:221], v[32:35]
	ds_read_b128 v[218:221], v189 offset:15360
	s_waitcnt lgkmcnt(3)
	v_mfma_f32_16x16x32_bf16 v[100:103], v[168:171], v[160:163], v[100:103]
	v_mfma_f32_16x16x32_bf16 v[28:31], v[172:175], v[160:163], v[28:31]
	v_mfma_f32_16x16x32_bf16 v[96:99], v[176:179], v[160:163], v[96:99]
	v_mfma_f32_16x16x32_bf16 v[24:27], v[180:183], v[160:163], v[24:27]
	s_waitcnt lgkmcnt(2)
	v_mfma_f32_16x16x32_bf16 v[84:87], v[168:171], v[164:167], v[84:87]
	v_mfma_f32_16x16x32_bf16 v[20:23], v[172:175], v[164:167], v[20:23]
	v_mfma_f32_16x16x32_bf16 v[80:83], v[176:179], v[164:167], v[80:83]
	v_mfma_f32_16x16x32_bf16 v[16:19], v[180:183], v[164:167], v[16:19]
	s_add_u32 s65, s65, 0x21ac0100
	s_addc_u32 s68, s72, 0
	s_add_u32 s70, s73, 0x2000100
	s_addc_u32 s71, s74, 0
	s_cmp_lt_u32 s26, 3
	s_cselect_b32 s69, s68, s45
	s_cselect_b32 s68, s65, s27
	s_waitcnt vmcnt(0)
	s_waitcnt lgkmcnt(0)
	s_barrier
	s_cselect_b32 s71, s71, s47
	s_cselect_b32 s70, s70, s46
	ds_read_b128 v[160:163], v158
	v_add_u32_e32 v159, v156, v145
	ds_read_b128 v[164:167], v159
	s_mov_b32 m0, s38
	v_mfma_f32_16x16x32_bf16 v[76:79], v[168:171], v[214:217], v[76:79]
	global_load_lds_dwordx4 v88, s[68:69]
	v_mfma_f32_16x16x32_bf16 v[64:67], v[168:171], v[218:221], v[64:67]
	ds_read_b128 v[168:171], v158 offset:2048
	v_mfma_f32_16x16x32_bf16 v[12:15], v[172:175], v[214:217], v[12:15]
	s_mov_b32 m0, s1
	v_mfma_f32_16x16x32_bf16 v[0:3], v[172:175], v[218:221], v[0:3]
	global_load_lds_dwordx4 v90, s[70:71]
	v_add_u32_e32 v159, v156, v149
	ds_read_b128 v[172:175], v159
	v_mfma_f32_16x16x32_bf16 v[72:75], v[176:179], v[214:217], v[72:75]
	v_mfma_f32_16x16x32_bf16 v[68:71], v[176:179], v[218:221], v[68:71]
	ds_read_b128 v[176:179], v158 offset:4096
	s_mov_b32 m0, s39
	v_mfma_f32_16x16x32_bf16 v[8:11], v[180:183], v[214:217], v[8:11]
	global_load_lds_dwordx4 v92, s[68:69]
	v_mfma_f32_16x16x32_bf16 v[4:7], v[180:183], v[218:221], v[4:7]
	ds_read_b128 v[180:183], v158 offset:6144
	v_add_u32_e32 v159, v156, v150
	ds_read_b128 v[214:217], v159
	v_add_u32_e32 v159, v156, v151
	ds_read_b128 v[218:221], v159
	s_waitcnt lgkmcnt(6)
	v_mfma_f32_16x16x32_bf16 v[132:135], v[160:163], v[164:167], v[132:135]
	s_waitcnt lgkmcnt(5)
	s_mov_b32 m0, s40
	v_mfma_f32_16x16x32_bf16 v[60:63], v[168:171], v[164:167], v[60:63]
	global_load_lds_dwordx4 v94, s[70:71]
	s_waitcnt lgkmcnt(4)
	v_mfma_f32_16x16x32_bf16 v[124:127], v[160:163], v[172:175], v[124:127]
	v_mfma_f32_16x16x32_bf16 v[52:55], v[168:171], v[172:175], v[52:55]
	s_waitcnt lgkmcnt(3)
	s_mov_b32 m0, s41
	v_mfma_f32_16x16x32_bf16 v[128:131], v[176:179], v[164:167], v[128:131]
	global_load_lds_dwordx4 v136, s[68:69]
	v_mfma_f32_16x16x32_bf16 v[120:123], v[176:179], v[172:175], v[120:123]
	s_waitcnt lgkmcnt(2)
	v_mfma_f32_16x16x32_bf16 v[56:59], v[180:183], v[164:167], v[56:59]
	v_add_u32_e32 v159, v156, v152
	ds_read_b128 v[164:167], v159
	s_mov_b32 m0, s42
	v_mfma_f32_16x16x32_bf16 v[48:51], v[180:183], v[172:175], v[48:51]
	global_load_lds_dwordx4 v138, s[70:71]
	v_add_u32_e32 v159, v156, v153
	ds_read_b128 v[172:175], v159
	s_waitcnt lgkmcnt(3)
	v_mfma_f32_16x16x32_bf16 v[116:119], v[160:163], v[214:217], v[116:119]
	v_mfma_f32_16x16x32_bf16 v[44:47], v[168:171], v[214:217], v[44:47]
	s_mov_b32 m0, s43
	v_mfma_f32_16x16x32_bf16 v[112:115], v[176:179], v[214:217], v[112:115]
	global_load_lds_dwordx4 v140, s[68:69]
	v_mfma_f32_16x16x32_bf16 v[40:43], v[180:183], v[214:217], v[40:43]
	v_add_u32_e32 v159, v156, v154
	ds_read_b128 v[214:217], v159
	s_waitcnt lgkmcnt(3)
	v_mfma_f32_16x16x32_bf16 v[108:111], v[160:163], v[218:221], v[108:111]
	s_mov_b32 m0, s44
	v_mfma_f32_16x16x32_bf16 v[36:39], v[168:171], v[218:221], v[36:39]
	global_load_lds_dwordx4 v146, s[70:71]
	v_mfma_f32_16x16x32_bf16 v[104:107], v[176:179], v[218:221], v[104:107]
	v_mfma_f32_16x16x32_bf16 v[32:35], v[180:183], v[218:221], v[32:35]
	v_add_u32_e32 v159, v156, v155
	ds_read_b128 v[218:221], v159
	s_waitcnt lgkmcnt(3)
	v_mfma_f32_16x16x32_bf16 v[28:31], v[168:171], v[164:167], v[28:31]
	s_waitcnt lgkmcnt(2)
	v_mfma_f32_16x16x32_bf16 v[20:23], v[168:171], v[172:175], v[20:23]
	s_waitcnt lgkmcnt(1)
	v_mfma_f32_16x16x32_bf16 v[12:15], v[168:171], v[214:217], v[12:15]
	s_waitcnt lgkmcnt(0)
	v_mfma_f32_16x16x32_bf16 v[0:3], v[168:171], v[218:221], v[0:3]
	ds_read_b128 v[168:171], v158 offset:1024
	v_mfma_f32_16x16x32_bf16 v[100:103], v[160:163], v[164:167], v[100:103]
	v_mfma_f32_16x16x32_bf16 v[84:87], v[160:163], v[172:175], v[84:87]
	v_mfma_f32_16x16x32_bf16 v[76:79], v[160:163], v[214:217], v[76:79]
	v_mfma_f32_16x16x32_bf16 v[64:67], v[160:163], v[218:221], v[64:67]
	v_add_u32_e32 v159, v157, v145
	ds_read_b128 v[160:163], v159
	v_mfma_f32_16x16x32_bf16 v[80:83], v[176:179], v[172:175], v[80:83]
	v_mfma_f32_16x16x32_bf16 v[16:19], v[180:183], v[172:175], v[16:19]
	ds_read_b128 v[172:175], v158 offset:3072
	v_mfma_f32_16x16x32_bf16 v[96:99], v[176:179], v[164:167], v[96:99]
	v_mfma_f32_16x16x32_bf16 v[24:27], v[180:183], v[164:167], v[24:27]
	v_add_u32_e32 v159, v157, v149
	ds_read_b128 v[164:167], v159
	v_mfma_f32_16x16x32_bf16 v[72:75], v[176:179], v[214:217], v[72:75]
	v_mfma_f32_16x16x32_bf16 v[8:11], v[180:183], v[214:217], v[8:11]
	v_add_u32_e32 v159, v157, v150
	ds_read_b128 v[214:217], v159
	v_mfma_f32_16x16x32_bf16 v[68:71], v[176:179], v[218:221], v[68:71]
	ds_read_b128 v[176:179], v158 offset:5120
	v_mfma_f32_16x16x32_bf16 v[4:7], v[180:183], v[218:221], v[4:7]
	ds_read_b128 v[180:183], v158 offset:7168
	v_add_u32_e32 v159, v157, v151
	ds_read_b128 v[218:221], v159
	s_waitcnt lgkmcnt(6)
	v_mfma_f32_16x16x32_bf16 v[132:135], v[168:171], v[160:163], v[132:135]
	s_waitcnt lgkmcnt(5)
	v_mfma_f32_16x16x32_bf16 v[60:63], v[172:175], v[160:163], v[60:63]
	s_waitcnt lgkmcnt(4)
	v_mfma_f32_16x16x32_bf16 v[124:127], v[168:171], v[164:167], v[124:127]
	v_mfma_f32_16x16x32_bf16 v[52:55], v[172:175], v[164:167], v[52:55]
	s_waitcnt lgkmcnt(3)
	v_mfma_f32_16x16x32_bf16 v[116:119], v[168:171], v[214:217], v[116:119]
	v_mfma_f32_16x16x32_bf16 v[44:47], v[172:175], v[214:217], v[44:47]
	s_waitcnt lgkmcnt(2)
	v_mfma_f32_16x16x32_bf16 v[128:131], v[176:179], v[160:163], v[128:131]
	s_waitcnt lgkmcnt(1)
	v_mfma_f32_16x16x32_bf16 v[56:59], v[180:183], v[160:163], v[56:59]
	v_add_u32_e32 v159, v157, v152
	ds_read_b128 v[160:163], v159
	v_mfma_f32_16x16x32_bf16 v[120:123], v[176:179], v[164:167], v[120:123]
	v_mfma_f32_16x16x32_bf16 v[48:51], v[180:183], v[164:167], v[48:51]
	v_add_u32_e32 v159, v157, v153
	ds_read_b128 v[164:167], v159
	v_mfma_f32_16x16x32_bf16 v[112:115], v[176:179], v[214:217], v[112:115]
	v_mfma_f32_16x16x32_bf16 v[40:43], v[180:183], v[214:217], v[40:43]
	v_add_u32_e32 v159, v157, v154
	ds_read_b128 v[214:217], v159
	s_waitcnt lgkmcnt(3)
	v_mfma_f32_16x16x32_bf16 v[108:111], v[168:171], v[218:221], v[108:111]
	v_mfma_f32_16x16x32_bf16 v[36:39], v[172:175], v[218:221], v[36:39]
	v_mfma_f32_16x16x32_bf16 v[104:107], v[176:179], v[218:221], v[104:107]
	v_mfma_f32_16x16x32_bf16 v[32:35], v[180:183], v[218:221], v[32:35]
	v_add_u32_e32 v159, v157, v155
	ds_read_b128 v[218:221], v159
	s_waitcnt lgkmcnt(3)
	v_mfma_f32_16x16x32_bf16 v[100:103], v[168:171], v[160:163], v[100:103]
	v_mfma_f32_16x16x32_bf16 v[28:31], v[172:175], v[160:163], v[28:31]
	v_mfma_f32_16x16x32_bf16 v[96:99], v[176:179], v[160:163], v[96:99]
	v_mfma_f32_16x16x32_bf16 v[24:27], v[180:183], v[160:163], v[24:27]
	s_waitcnt lgkmcnt(2)
	v_mfma_f32_16x16x32_bf16 v[84:87], v[168:171], v[164:167], v[84:87]
	v_mfma_f32_16x16x32_bf16 v[20:23], v[172:175], v[164:167], v[20:23]
	v_mfma_f32_16x16x32_bf16 v[80:83], v[176:179], v[164:167], v[80:83]
	v_mfma_f32_16x16x32_bf16 v[16:19], v[180:183], v[164:167], v[16:19]
	s_waitcnt vmcnt(0)
	s_add_u32 s24, s24, 0x100
	s_addc_u32 s25, s25, 0
	s_add_i32 s26, s26, 2
	s_cmpk_lg_i32 s24, 0x200
	s_waitcnt lgkmcnt(0)
	s_barrier
	s_cbranch_scc1 .LBB0_758
	v_mfma_f32_16x16x32_bf16 v[76:79], v[168:171], v[214:217], v[76:79]
	v_mfma_f32_16x16x32_bf16 v[64:67], v[168:171], v[218:221], v[64:67]
	v_mfma_f32_16x16x32_bf16 v[12:15], v[172:175], v[214:217], v[12:15]
	v_mfma_f32_16x16x32_bf16 v[0:3], v[172:175], v[218:221], v[0:3]
	v_mfma_f32_16x16x32_bf16 v[72:75], v[176:179], v[214:217], v[72:75]
	v_mfma_f32_16x16x32_bf16 v[68:71], v[176:179], v[218:221], v[68:71]
	v_mfma_f32_16x16x32_bf16 v[8:11], v[180:183], v[214:217], v[8:11]
	v_mfma_f32_16x16x32_bf16 v[4:7], v[180:183], v[218:221], v[4:7]
	s_nop 15
	s_nop 15
	v_mov_b32_e32 v88, v184
	s_lshl_b32 s0, s0, 8
	v_lshrrev_b32_e32 v89, 1, v88
	v_and_b32_e32 v89, 0x60, v89
	v_lshl_or_b32 v89, s37, 7, v89
	v_or_b32_e32 v142, s22, v89
	v_lshrrev_b32_e32 v89, 2, v88
	v_and_b32_e32 v146, 12, v89
	v_ashrrev_i32_e32 v89, 1, v88
	v_and_b32_e32 v89, 0xffffff80, v89
	v_and_or_b32 v88, v88, 15, s0
	v_add_u32_e32 v172, v88, v89
	v_or_b32_e32 v182, v142, v146
	v_ashrrev_i32_e32 v173, 31, v172
	v_ashrrev_i32_e32 v183, 31, v182
	v_lshlrev_b64 v[88:89], 12, v[172:173]
	v_lshlrev_b64 v[92:93], 2, v[182:183]
	v_lshl_add_u64 v[140:141], s[2:3], 0, v[88:89]
	v_lshl_add_u64 v[88:89], s[4:5], 0, v[92:93]
	global_load_dwordx4 v[136:139], v[88:89], off
	s_mov_b32 s24, 0xbfb8aa3b
	s_mov_b32 s25, 0x42ce8ed0
	s_mov_b32 s26, 0xc2b17218
	s_mov_b32 s37, 0x3f2aaaab
	s_mov_b32 s38, 0x3f317218
	v_lshl_add_u64 v[88:89], s[6:7], 0, v[92:93]
	v_lshl_add_u64 v[92:93], s[8:9], 0, v[92:93]
	global_load_dwordx4 v[92:95], v[92:93], off
	s_mov_b32 s27, 0x7f800000
	global_load_dwordx4 v[88:91], v[88:89], off
	s_mov_b32 s39, 0x33800000
	s_mov_b32 s40, 0xbd4ccccd
	s_mov_b32 s44, 0xc1000000
	s_waitcnt vmcnt(2)
	v_mul_f32_e32 v143, 0xbfb8aa3b, v136
	v_fma_f32 v145, v136, s24, -v143
	v_rndne_f32_e32 v149, v143
	v_fmac_f32_e32 v145, 0xb2a5705f, v136
	v_sub_f32_e32 v143, v143, v149
	v_add_f32_e32 v143, v143, v145
	v_exp_f32_e32 v143, v143
	v_cvt_i32_f32_e32 v145, v149
	v_cmp_nlt_f32_e32 vcc, s25, v136
	s_waitcnt vmcnt(1)
	v_add_f32_e32 v128, v128, v92
	v_mul_f32_e32 v128, 0xbfb8aa3b, v128
	v_ldexp_f32 v143, v143, v145
	v_cndmask_b32_e32 v143, 0, v143, vcc
	v_cmp_ngt_f32_e32 vcc, s26, v136
	v_exp_f32_e32 v128, v128
	v_add_f32_e32 v112, v112, v92
	v_cndmask_b32_e32 v143, v209, v143, vcc
	v_add_f32_e32 v136, 1.0, v143
	v_add_f32_e32 v145, -1.0, v136
	v_sub_f32_e32 v149, v145, v136
	v_add_f32_e32 v149, 1.0, v149
	v_sub_f32_e32 v145, v143, v145
	v_add_f32_e32 v145, v145, v149
	v_frexp_mant_f32_e32 v149, v136
	v_cvt_f64_f32_e32 v[150:151], v136
	v_cmp_gt_f32_e32 vcc, s37, v149
	v_frexp_exp_i32_f64_e32 v149, v[150:151]
	v_add_f32_e32 v128, 1.0, v128
	v_subbrev_co_u32_e32 v158, vcc, 0, v149, vcc
	v_sub_u32_e32 v149, 0, v158
	v_ldexp_f32 v136, v136, v149
	v_ldexp_f32 v145, v145, v149
	v_add_f32_e32 v149, -1.0, v136
	v_add_f32_e32 v150, 1.0, v149
	v_sub_f32_e32 v150, v136, v150
	v_add_f32_e32 v150, v145, v150
	v_add_f32_e32 v151, v149, v150
	v_sub_f32_e32 v149, v149, v151
	v_add_f32_e32 v149, v150, v149
	v_add_f32_e32 v150, 1.0, v136
	v_add_f32_e32 v152, -1.0, v150
	v_sub_f32_e32 v136, v136, v152
	v_add_f32_e32 v136, v145, v136
	v_add_f32_e32 v145, v150, v136
	v_rcp_f32_e32 v159, v145
	v_sub_f32_e32 v150, v150, v145
	v_add_f32_e32 v136, v136, v150
	v_cmp_nlt_f32_e32 vcc, s25, v137
	v_mul_f32_e32 v160, v151, v159
	v_mul_f32_e32 v152, v145, v160
	v_fma_f32 v154, v160, v145, -v152
	v_fmac_f32_e32 v154, v160, v136
	v_add_f32_e32 v150, v152, v154
	v_sub_f32_e32 v153, v151, v150
	v_pk_add_f32 v[156:157], v[150:151], v[152:153] neg_lo:[0,1] neg_hi:[0,1]
	v_mov_b32_e32 v155, v150
	v_pk_add_f32 v[150:151], v[156:157], v[154:155] neg_lo:[0,1] neg_hi:[0,1]
	v_mul_f32_e32 v112, 0xbfb8aa3b, v112
	v_add_f32_e32 v149, v149, v151
	v_add_f32_e32 v149, v150, v149
	v_add_f32_e32 v151, v153, v149
	v_mul_f32_e32 v161, v159, v151
	v_mul_f32_e32 v152, v145, v161
	v_fma_f32 v154, v161, v145, -v152
	v_fmac_f32_e32 v154, v161, v136
	v_add_f32_e32 v150, v152, v154
	v_sub_f32_e32 v136, v153, v151
	v_sub_f32_e32 v153, v151, v150
	v_pk_add_f32 v[156:157], v[150:151], v[152:153] neg_lo:[0,1] neg_hi:[0,1]
	v_mov_b32_e32 v155, v150
	v_add_f32_e32 v136, v149, v136
	v_pk_add_f32 v[150:151], v[156:157], v[154:155] neg_lo:[0,1] neg_hi:[0,1]
	v_add_f32_e32 v145, v160, v161
	v_add_f32_e32 v136, v136, v151
	v_add_f32_e32 v136, v150, v136
	v_add_f32_e32 v136, v153, v136
	v_sub_f32_e32 v149, v145, v160
	v_mul_f32_e32 v136, v159, v136
	v_sub_f32_e32 v149, v161, v149
	v_add_f32_e32 v136, v149, v136
	v_add_f32_e32 v151, v145, v136
	v_cvt_f32_i32_e32 v150, v158
	v_mul_f32_e32 v152, v151, v151
	v_fmamk_f32 v149, v152, 0x3e9b6dac, v195
	v_fmaak_f32 v149, v152, v149, 0x3f2aaada
	v_sub_f32_e32 v145, v151, v145
	v_ldexp_f32 v153, v151, 1
	v_mul_f32_e32 v151, v151, v152
	v_pk_mul_f32 v[154:155], v[150:151], v[148:149]
	v_sub_f32_e32 v136, v136, v145
	v_fma_f32 v152, v150, s38, -v154
	v_fmac_f32_e32 v152, 0xb102e308, v150
	v_pk_add_f32 v[156:157], v[154:155], v[152:153]
	v_ldexp_f32 v136, v136, 1
	v_sub_f32_e32 v145, v157, v153
	v_sub_f32_e32 v145, v155, v145
	v_add_f32_e32 v159, v136, v145
	v_mul_f32_e32 v136, 0xbfb8aa3b, v137
	v_fma_f32 v145, v137, s24, -v136
	v_rndne_f32_e32 v149, v136
	v_fmac_f32_e32 v145, 0xb2a5705f, v137
	v_sub_f32_e32 v136, v136, v149
	v_add_f32_e32 v136, v136, v145
	v_exp_f32_e32 v136, v136
	v_cvt_i32_f32_e32 v145, v149
	v_mov_b32_e32 v158, v154
	v_pk_add_f32 v[154:155], v[156:157], v[154:155] neg_lo:[0,1] neg_hi:[0,1]
	v_pk_add_f32 v[160:161], v[156:157], v[158:159]
	v_ldexp_f32 v136, v136, v145
	v_cndmask_b32_e32 v136, 0, v136, vcc
	v_cmp_ngt_f32_e32 vcc, s26, v137
	v_mov_b32_e32 v155, v161
	v_mov_b32_e32 v153, v156
	v_cndmask_b32_e32 v173, v209, v136, vcc
	v_add_f32_e32 v145, 1.0, v173
	v_add_f32_e32 v136, -1.0, v145
	v_sub_f32_e32 v137, v136, v145
	v_add_f32_e32 v137, 1.0, v137
	v_sub_f32_e32 v136, v173, v136
	v_pk_add_f32 v[150:151], v[152:153], v[154:155] neg_lo:[0,1] neg_hi:[0,1]
	v_pk_add_f32 v[152:153], v[152:153], v[154:155]
	v_add_f32_e32 v149, v136, v137
	v_frexp_mant_f32_e32 v136, v145
	v_pk_add_f32 v[154:155], v[152:153], v[156:157] op_sel:[1,0] op_sel_hi:[0,1] neg_lo:[0,1] neg_hi:[0,1]
	v_cmp_gt_f32_e32 vcc, s37, v136
	v_cvt_f64_f32_e32 v[136:137], v145
	v_pk_add_f32 v[162:163], v[160:161], v[154:155] op_sel_hi:[1,0] neg_lo:[0,1] neg_hi:[0,1]
	v_mov_b32_e32 v152, v161
	v_pk_mov_b32 v[154:155], v[156:157], v[154:155] op_sel:[1,0]
	v_frexp_exp_i32_f64_e32 v136, v[136:137]
	v_pk_add_f32 v[154:155], v[152:153], v[154:155] neg_lo:[0,1] neg_hi:[0,1]
	v_subbrev_co_u32_e32 v152, vcc, 0, v136, vcc
	v_sub_u32_e32 v136, 0, v152
	v_ldexp_f32 v145, v145, v136
	v_ldexp_f32 v136, v149, v136
	v_add_f32_e32 v149, -1.0, v145
	v_mov_b32_e32 v158, v159
	v_mov_b32_e32 v159, v156
	v_add_f32_e32 v137, 1.0, v149
	v_pk_add_f32 v[154:155], v[158:159], v[154:155] neg_lo:[0,1] neg_hi:[0,1]
	v_mov_b32_e32 v162, v150
	v_sub_f32_e32 v137, v145, v137
	v_pk_add_f32 v[156:157], v[162:163], v[154:155]
	v_add_f32_e32 v155, v136, v137
	v_add_f32_e32 v137, v149, v155
	v_sub_f32_e32 v149, v149, v137
	v_add_f32_e32 v149, v155, v149
	v_add_f32_e32 v155, 1.0, v145
	v_add_f32_e32 v158, -1.0, v155
	v_sub_f32_e32 v145, v145, v158
	v_add_f32_e32 v136, v136, v145
	v_add_f32_e32 v145, v155, v136
	v_rcp_f32_e32 v164, v145
	v_sub_f32_e32 v155, v155, v145
	v_add_f32_e32 v155, v136, v155
	v_cmp_nlt_f32_e32 vcc, s25, v138
	v_mul_f32_e32 v165, v137, v164
	v_mul_f32_e32 v158, v145, v165
	v_fma_f32 v160, v165, v145, -v158
	v_fmac_f32_e32 v160, v165, v155
	v_add_f32_e32 v136, v158, v160
	v_sub_f32_e32 v159, v137, v136
	v_pk_add_f32 v[162:163], v[136:137], v[158:159] neg_lo:[0,1] neg_hi:[0,1]
	v_mov_b32_e32 v161, v136
	v_pk_add_f32 v[136:137], v[162:163], v[160:161] neg_lo:[0,1] neg_hi:[0,1]
	v_exp_f32_e32 v112, v112
	v_add_f32_e32 v137, v149, v137
	v_add_f32_e32 v136, v136, v137
	v_add_f32_e32 v137, v159, v136
	v_mul_f32_e32 v149, v164, v137
	v_mul_f32_e32 v158, v145, v149
	v_fma_f32 v160, v149, v145, -v158
	v_fmac_f32_e32 v160, v149, v155
	v_sub_f32_e32 v145, v159, v137
	v_add_f32_e32 v145, v136, v145
	v_add_f32_e32 v136, v158, v160
	v_sub_f32_e32 v159, v137, v136
	v_pk_add_f32 v[162:163], v[136:137], v[158:159] neg_lo:[0,1] neg_hi:[0,1]
	v_mov_b32_e32 v161, v136
	v_pk_add_f32 v[136:137], v[162:163], v[160:161] neg_lo:[0,1] neg_hi:[0,1]
	v_add_f32_e32 v72, v72, v92
	v_add_f32_e32 v137, v145, v137
	v_add_f32_e32 v136, v136, v137
	v_add_f32_e32 v137, v165, v149
	v_add_f32_e32 v136, v159, v136
	v_sub_f32_e32 v145, v137, v165
	v_mul_f32_e32 v136, v164, v136
	v_sub_f32_e32 v145, v149, v145
	v_add_f32_e32 v145, v145, v136
	v_add_f32_e32 v155, v137, v145
	v_mul_f32_e32 v158, v155, v155
	v_fmamk_f32 v136, v158, 0x3e9b6dac, v195
	v_fmaak_f32 v149, v158, v136, 0x3f2aaada
	v_cvt_f32_i32_e32 v136, v152
	v_sub_f32_e32 v137, v155, v137
	v_sub_f32_e32 v137, v145, v137
	v_ldexp_f32 v145, v137, 1
	v_mul_f32_e32 v137, v155, v158
	v_pk_mul_f32 v[160:161], v[136:137], v[148:149]
	v_ldexp_f32 v159, v155, 1
	v_fma_f32 v158, v136, s38, -v160
	v_fmac_f32_e32 v158, 0xb102e308, v136
	v_pk_add_f32 v[136:137], v[160:161], v[158:159]
	v_mov_b32_e32 v162, v160
	v_sub_f32_e32 v149, v137, v159
	v_sub_f32_e32 v149, v161, v149
	v_add_f32_e32 v163, v145, v149
	v_pk_add_f32 v[160:161], v[136:137], v[160:161] neg_lo:[0,1] neg_hi:[0,1]
	v_pk_add_f32 v[164:165], v[136:137], v[162:163]
	v_mov_b32_e32 v159, v136
	v_mov_b32_e32 v161, v165
	v_pk_add_f32 v[178:179], v[158:159], v[160:161]
	v_pk_add_f32 v[174:175], v[158:159], v[160:161] neg_lo:[0,1] neg_hi:[0,1]
	v_pk_add_f32 v[158:159], v[178:179], v[136:137] op_sel:[1,0] op_sel_hi:[0,1] neg_lo:[0,1] neg_hi:[0,1]
	v_pk_add_f32 v[160:161], v[164:165], v[158:159] op_sel_hi:[1,0] neg_lo:[0,1] neg_hi:[0,1]
	v_pk_mov_b32 v[158:159], v[136:137], v[158:159] op_sel:[1,0]
	v_mov_b32_e32 v162, v163
	v_mov_b32_e32 v163, v136
	v_mul_f32_e32 v136, 0xbfb8aa3b, v138
	v_fma_f32 v137, v138, s24, -v136
	v_rndne_f32_e32 v145, v136
	v_fmac_f32_e32 v137, 0xb2a5705f, v138
	v_sub_f32_e32 v136, v136, v145
	v_add_f32_e32 v136, v136, v137
	v_exp_f32_e32 v136, v136
	v_cvt_i32_f32_e32 v137, v145
	v_mov_b32_e32 v178, v165
	v_pk_add_f32 v[158:159], v[178:179], v[158:159] neg_lo:[0,1] neg_hi:[0,1]
	v_mov_b32_e32 v160, v174
	v_ldexp_f32 v136, v136, v137
	v_cndmask_b32_e32 v136, 0, v136, vcc
	v_cmp_ngt_f32_e32 vcc, s26, v138
	v_pk_add_f32 v[176:177], v[162:163], v[158:159] neg_lo:[0,1] neg_hi:[0,1]
	v_mul_f32_e32 v72, 0xbfb8aa3b, v72
	v_cndmask_b32_e32 v145, v209, v136, vcc
	v_add_f32_e32 v138, 1.0, v145
	v_add_f32_e32 v136, -1.0, v138
	v_sub_f32_e32 v137, v136, v138
	v_add_f32_e32 v137, 1.0, v137
	v_sub_f32_e32 v136, v145, v136
	v_add_f32_e32 v149, v136, v137
	v_frexp_mant_f32_e32 v136, v138
	v_cmp_gt_f32_e32 vcc, s37, v136
	v_cvt_f64_f32_e32 v[136:137], v138
	v_frexp_exp_i32_f64_e32 v136, v[136:137]
	v_subbrev_co_u32_e32 v152, vcc, 0, v136, vcc
	v_sub_u32_e32 v136, 0, v152
	v_ldexp_f32 v138, v138, v136
	v_ldexp_f32 v136, v149, v136
	v_add_f32_e32 v149, -1.0, v138
	v_add_f32_e32 v137, 1.0, v149
	v_sub_f32_e32 v137, v138, v137
	v_add_f32_e32 v155, v136, v137
	v_add_f32_e32 v137, v149, v155
	v_sub_f32_e32 v149, v149, v137
	v_add_f32_e32 v149, v155, v149
	v_add_f32_e32 v155, 1.0, v138
	v_add_f32_e32 v158, -1.0, v155
	v_sub_f32_e32 v138, v138, v158
	v_add_f32_e32 v136, v136, v138
	v_add_f32_e32 v138, v155, v136
	v_rcp_f32_e32 v164, v138
	v_sub_f32_e32 v155, v155, v138
	v_pk_add_f32 v[180:181], v[160:161], v[176:177]
	v_add_f32_e32 v155, v136, v155
	v_mul_f32_e32 v165, v137, v164
	v_mul_f32_e32 v158, v138, v165
	v_fma_f32 v160, v165, v138, -v158
	v_fmac_f32_e32 v160, v165, v155
	v_add_f32_e32 v136, v158, v160
	v_sub_f32_e32 v159, v137, v136
	v_pk_add_f32 v[162:163], v[136:137], v[158:159] neg_lo:[0,1] neg_hi:[0,1]
	v_mov_b32_e32 v161, v136
	v_pk_add_f32 v[136:137], v[162:163], v[160:161] neg_lo:[0,1] neg_hi:[0,1]
	v_cmp_nlt_f32_e32 vcc, s25, v139
	v_add_f32_e32 v137, v149, v137
	v_add_f32_e32 v136, v136, v137
	v_add_f32_e32 v137, v159, v136
	v_mul_f32_e32 v149, v164, v137
	v_mul_f32_e32 v158, v138, v149
	v_fma_f32 v160, v149, v138, -v158
	v_fmac_f32_e32 v160, v149, v155
	v_sub_f32_e32 v138, v159, v137
	v_add_f32_e32 v138, v136, v138
	v_add_f32_e32 v136, v158, v160
	v_sub_f32_e32 v159, v137, v136
	v_pk_add_f32 v[162:163], v[136:137], v[158:159] neg_lo:[0,1] neg_hi:[0,1]
	v_mov_b32_e32 v161, v136
	v_pk_add_f32 v[136:137], v[162:163], v[160:161] neg_lo:[0,1] neg_hi:[0,1]
	v_exp_f32_e32 v72, v72
	v_add_f32_e32 v137, v138, v137
	v_add_f32_e32 v136, v136, v137
	v_add_f32_e32 v137, v165, v149
	v_add_f32_e32 v136, v159, v136
	v_sub_f32_e32 v138, v137, v165
	v_mul_f32_e32 v136, v164, v136
	v_sub_f32_e32 v138, v149, v138
	v_add_f32_e32 v138, v138, v136
	v_add_f32_e32 v155, v137, v138
	v_mul_f32_e32 v158, v155, v155
	v_fmamk_f32 v136, v158, 0x3e9b6dac, v195
	v_fmaak_f32 v149, v158, v136, 0x3f2aaada
	v_cvt_f32_i32_e32 v136, v152
	v_sub_f32_e32 v137, v155, v137
	v_sub_f32_e32 v137, v138, v137
	v_ldexp_f32 v138, v137, 1
	v_mul_f32_e32 v137, v155, v158
	v_pk_mul_f32 v[158:159], v[136:137], v[148:149]
	v_ldexp_f32 v161, v155, 1
	v_fma_f32 v160, v136, s38, -v158
	v_fmac_f32_e32 v160, 0xb102e308, v136
	v_pk_add_f32 v[136:137], v[158:159], v[160:161]
	v_mov_b32_e32 v162, v158
	v_sub_f32_e32 v149, v137, v161
	v_sub_f32_e32 v149, v159, v149
	v_add_f32_e32 v163, v138, v149
	v_pk_add_f32 v[164:165], v[136:137], v[158:159] neg_lo:[0,1] neg_hi:[0,1]
	v_pk_add_f32 v[166:167], v[136:137], v[162:163]
	v_mov_b32_e32 v161, v136
	v_mov_b32_e32 v165, v167
	v_pk_add_f32 v[158:159], v[160:161], v[164:165] neg_lo:[0,1] neg_hi:[0,1]
	v_pk_add_f32 v[160:161], v[160:161], v[164:165]
	v_mov_b32_e32 v162, v163
	v_pk_add_f32 v[164:165], v[160:161], v[136:137] op_sel:[1,0] op_sel_hi:[0,1] neg_lo:[0,1] neg_hi:[0,1]
	v_pk_add_f32 v[168:169], v[166:167], v[164:165] op_sel_hi:[1,0] neg_lo:[0,1] neg_hi:[0,1]
	v_pk_mov_b32 v[164:165], v[136:137], v[164:165] op_sel:[1,0]
	v_mov_b32_e32 v163, v136
	v_mul_f32_e32 v136, 0xbfb8aa3b, v139
	v_fma_f32 v137, v139, s24, -v136
	v_rndne_f32_e32 v138, v136
	v_fmac_f32_e32 v137, 0xb2a5705f, v139
	v_sub_f32_e32 v136, v136, v138
	v_add_f32_e32 v136, v136, v137
	v_exp_f32_e32 v136, v136
	v_cvt_i32_f32_e32 v137, v138
	v_mov_b32_e32 v160, v167
	v_pk_add_f32 v[164:165], v[160:161], v[164:165] neg_lo:[0,1] neg_hi:[0,1]
	v_mov_b32_e32 v168, v158
	v_ldexp_f32 v136, v136, v137
	v_cndmask_b32_e32 v136, 0, v136, vcc
	v_cmp_ngt_f32_e32 vcc, s26, v139
	v_pk_add_f32 v[162:163], v[162:163], v[164:165] neg_lo:[0,1] neg_hi:[0,1]
	v_add_f32_e32 v112, 1.0, v112
	v_cndmask_b32_e32 v178, v209, v136, vcc
	v_add_f32_e32 v138, 1.0, v178
	v_add_f32_e32 v136, -1.0, v138
	v_sub_f32_e32 v137, v136, v138
	v_add_f32_e32 v137, 1.0, v137
	v_sub_f32_e32 v136, v178, v136
	v_add_f32_e32 v139, v136, v137
	v_frexp_mant_f32_e32 v136, v138
	v_cmp_gt_f32_e32 vcc, s37, v136
	v_cvt_f64_f32_e32 v[136:137], v138
	v_frexp_exp_i32_f64_e32 v136, v[136:137]
	v_subbrev_co_u32_e32 v152, vcc, 0, v136, vcc
	v_sub_u32_e32 v136, 0, v152
	v_ldexp_f32 v138, v138, v136
	v_ldexp_f32 v136, v139, v136
	v_add_f32_e32 v139, -1.0, v138
	v_add_f32_e32 v137, 1.0, v139
	v_sub_f32_e32 v137, v138, v137
	v_add_f32_e32 v149, v136, v137
	v_add_f32_e32 v137, v139, v149
	v_sub_f32_e32 v139, v139, v137
	v_add_f32_e32 v149, v149, v139
	v_add_f32_e32 v139, 1.0, v138
	v_add_f32_e32 v155, -1.0, v139
	v_sub_f32_e32 v138, v138, v155
	v_add_f32_e32 v136, v136, v138
	v_add_f32_e32 v155, v139, v136
	v_pk_add_f32 v[164:165], v[168:169], v[162:163]
	v_rcp_f32_e32 v163, v155
	v_sub_f32_e32 v138, v139, v155
	v_add_f32_e32 v160, v136, v138
	v_rcp_f32_e32 v247, v112
	v_mul_f32_e32 v170, v137, v163
	v_mul_f32_e32 v138, v155, v170
	v_fma_f32 v166, v170, v155, -v138
	v_fmac_f32_e32 v166, v170, v160
	v_add_f32_e32 v136, v138, v166
	v_sub_f32_e32 v139, v137, v136
	v_pk_add_f32 v[168:169], v[136:137], v[138:139] neg_lo:[0,1] neg_hi:[0,1]
	v_mov_b32_e32 v167, v136
	v_pk_add_f32 v[136:137], v[168:169], v[166:167] neg_lo:[0,1] neg_hi:[0,1]
	s_waitcnt vmcnt(0)
	v_add_f32_e32 v112, v117, v89
	v_add_f32_e32 v137, v149, v137
	v_add_f32_e32 v136, v136, v137
	v_add_f32_e32 v137, v139, v136
	v_mul_f32_e32 v149, v163, v137
	v_mul_f32_e32 v138, v155, v149
	v_fma_f32 v166, v149, v155, -v138
	v_fmac_f32_e32 v166, v149, v160
	v_sub_f32_e32 v139, v139, v137
	v_add_f32_e32 v155, v136, v139
	v_add_f32_e32 v136, v138, v166
	v_sub_f32_e32 v139, v137, v136
	v_pk_add_f32 v[168:169], v[136:137], v[138:139] neg_lo:[0,1] neg_hi:[0,1]
	v_mov_b32_e32 v167, v136
	v_pk_add_f32 v[136:137], v[168:169], v[166:167] neg_lo:[0,1] neg_hi:[0,1]
	v_mul_f32_e32 v112, 0xbfb8aa3b, v112
	v_add_f32_e32 v137, v155, v137
	v_add_f32_e32 v136, v136, v137
	v_add_f32_e32 v137, v170, v149
	v_add_f32_e32 v136, v139, v136
	v_sub_f32_e32 v138, v137, v170
	v_mul_f32_e32 v136, v163, v136
	v_sub_f32_e32 v138, v149, v138
	v_add_f32_e32 v138, v138, v136
	v_add_f32_e32 v139, v137, v138
	v_mul_f32_e32 v155, v139, v139
	v_fmamk_f32 v136, v155, 0x3e9b6dac, v195
	v_fmaak_f32 v149, v155, v136, 0x3f2aaada
	v_cvt_f32_i32_e32 v136, v152
	v_sub_f32_e32 v137, v139, v137
	v_sub_f32_e32 v137, v138, v137
	v_ldexp_f32 v152, v137, 1
	v_mul_f32_e32 v137, v139, v155
	v_ldexp_f32 v167, v139, 1
	v_pk_mul_f32 v[138:139], v[136:137], v[148:149]
	v_add_f32_e32 v72, 1.0, v72
	v_fma_f32 v166, v136, s38, -v138
	v_fmac_f32_e32 v166, 0xb102e308, v136
	v_pk_add_f32 v[136:137], v[138:139], v[166:167]
	v_mov_b32_e32 v168, v138
	v_sub_f32_e32 v149, v137, v167
	v_sub_f32_e32 v149, v139, v149
	v_add_f32_e32 v169, v152, v149
	v_pk_add_f32 v[170:171], v[136:137], v[138:139] neg_lo:[0,1] neg_hi:[0,1]
	v_pk_add_f32 v[200:201], v[136:137], v[168:169]
	v_mov_b32_e32 v167, v136
	v_mov_b32_e32 v171, v201
	v_pk_add_f32 v[138:139], v[166:167], v[170:171] neg_lo:[0,1] neg_hi:[0,1]
	v_pk_add_f32 v[170:171], v[166:167], v[170:171]
	v_mov_b32_e32 v168, v169
	v_pk_add_f32 v[166:167], v[170:171], v[136:137] op_sel:[1,0] op_sel_hi:[0,1] neg_lo:[0,1] neg_hi:[0,1]
	v_pk_add_f32 v[206:207], v[200:201], v[166:167] op_sel_hi:[1,0] neg_lo:[0,1] neg_hi:[0,1]
	v_pk_mov_b32 v[166:167], v[136:137], v[166:167] op_sel:[1,0]
	v_mov_b32_e32 v169, v136
	v_lshl_add_u64 v[136:137], v[182:183], 1, v[140:141]
	v_add_co_u32_e32 v200, vcc, s33, v136
	v_mov_b32_e32 v170, v201
	s_nop 0
	v_addc_co_u32_e32 v201, vcc, 0, v137, vcc
	global_load_dwordx2 v[182:183], v[136:137], off
	v_pk_add_f32 v[166:167], v[170:171], v[166:167] neg_lo:[0,1] neg_hi:[0,1]
	global_load_dwordx2 v[200:201], v[200:201], off
	v_pk_add_f32 v[166:167], v[168:169], v[166:167] neg_lo:[0,1] neg_hi:[0,1]
	v_mov_b32_e32 v206, v138
	v_pk_add_f32 v[168:169], v[206:207], v[166:167]
	v_rcp_f32_e32 v167, v128
	v_add_f32_e32 v128, v133, v89
	v_mul_f32_e32 v128, 0xbfb8aa3b, v128
	v_exp_f32_e32 v128, v128
	v_add_f32_e32 v121, v121, v93
	v_exp_f32_e32 v112, v112
	v_rcp_f32_e32 v203, v72
	v_add_f32_e32 v128, 1.0, v128
	v_rcp_f32_e32 v128, v128
	v_add_f32_e32 v72, v77, v89
	v_mul_f32_e32 v121, 0xbfb8aa3b, v121
	v_mul_f32_e32 v72, 0xbfb8aa3b, v72
	v_mul_f32_e32 v241, 0xc1000000, v128
	v_add_f32_e32 v128, v134, v90
	v_exp_f32_e32 v121, v121
	v_exp_f32_e32 v72, v72
	v_mul_f32_e32 v128, 0xbfb8aa3b, v128
	v_exp_f32_e32 v128, v128
	v_add_f32_e32 v120, v120, v92
	v_add_f32_e32 v112, 1.0, v112
	v_add_f32_e32 v96, v96, v92
	v_mul_f32_e32 v120, 0xbfb8aa3b, v120
	v_rcp_f32_e32 v112, v112
	v_mul_f32_e32 v96, 0xbfb8aa3b, v96
	v_exp_f32_e32 v120, v120
	v_add_f32_e32 v121, 1.0, v121
	v_add_f32_e32 v104, v104, v92
	v_exp_f32_e32 v96, v96
	v_add_f32_e32 v73, v73, v93
	v_add_f32_e32 v72, 1.0, v72
	v_rcp_f32_e32 v244, v121
	v_add_f32_e32 v121, v122, v94
	v_mul_f32_e32 v104, 0xbfb8aa3b, v104
	v_rcp_f32_e32 v122, v72
	v_mul_f32_e32 v72, 0xbfb8aa3b, v73
	v_add_f32_e32 v128, 1.0, v128
	v_exp_f32_e32 v104, v104
	v_exp_f32_e32 v72, v72
	v_rcp_f32_e32 v128, v128
	v_mul_f32_e32 v250, 0xc1000000, v112
	v_add_f32_e32 v112, v118, v90
	v_add_f32_e32 v120, 1.0, v120
	v_mul_f32_e32 v112, 0xbfb8aa3b, v112
	v_add_f32_e32 v96, 1.0, v96
	v_add_f32_e32 v129, v129, v93
	v_rcp_f32_e32 v243, v120
	v_add_f32_e32 v120, v125, v89
	v_exp_f32_e32 v112, v112
	v_rcp_f32_e32 v199, v96
	v_add_f32_e32 v96, v101, v89
	v_mul_f32_e32 v129, 0xbfb8aa3b, v129
	v_mul_f32_e32 v120, 0xbfb8aa3b, v120
	v_add_f32_e32 v104, 1.0, v104
	v_mul_f32_e32 v96, 0xbfb8aa3b, v96
	v_add_f32_e32 v72, 1.0, v72
	v_exp_f32_e32 v129, v129
	v_mul_f32_e32 v215, 0xc1000000, v128
	v_add_f32_e32 v128, v135, v91
	v_exp_f32_e32 v120, v120
	v_rcp_f32_e32 v251, v104
	v_add_f32_e32 v104, v109, v89
	v_exp_f32_e32 v96, v96
	v_rcp_f32_e32 v208, v72
	v_add_f32_e32 v72, v78, v90
	v_mul_f32_e32 v128, 0xbfb8aa3b, v128
	v_mul_f32_e32 v104, 0xbfb8aa3b, v104
	v_mul_f32_e32 v72, 0xbfb8aa3b, v72
	v_add_f32_e32 v64, v64, v88
	v_exp_f32_e32 v128, v128
	v_add_f32_e32 v112, 1.0, v112
	v_exp_f32_e32 v104, v104
	v_exp_f32_e32 v72, v72
	v_mul_f32_e32 v64, 0xbfb8aa3b, v64
	v_rcp_f32_e32 v112, v112
	v_exp_f32_e32 v64, v64
	v_add_f32_e32 v129, 1.0, v129
	v_add_f32_e32 v120, 1.0, v120
	v_add_f32_e32 v96, 1.0, v96
	v_rcp_f32_e32 v238, v129
	v_add_f32_e32 v129, v130, v94
	v_rcp_f32_e32 v120, v120
	v_rcp_f32_e32 v96, v96
	v_add_f32_e32 v132, v132, v88
	v_mul_f32_e32 v129, 0xbfb8aa3b, v129
	v_add_f32_e32 v128, 1.0, v128
	v_add_f32_e32 v104, 1.0, v104
	v_add_f32_e32 v73, v74, v94
	v_add_f32_e32 v72, 1.0, v72
	v_mul_f32_e32 v132, 0xbfb8aa3b, v132
	v_exp_f32_e32 v129, v129
	v_rcp_f32_e32 v128, v128
	v_mul_f32_e32 v223, 0xc1000000, v112
	v_add_f32_e32 v112, v119, v91
	v_rcp_f32_e32 v104, v104
	v_add_f32_e32 v98, v98, v94
	v_rcp_f32_e32 v119, v72
	v_mul_f32_e32 v72, 0xbfb8aa3b, v73
	v_add_f32_e32 v68, v68, v92
	v_add_f32_e32 v64, 1.0, v64
	v_exp_f32_e32 v132, v132
	v_mul_f32_e32 v98, 0xbfb8aa3b, v98
	v_exp_f32_e32 v72, v72
	v_rcp_f32_e32 v77, v64
	v_mul_f32_e32 v64, 0xbfb8aa3b, v68
	v_mul_f32_e32 v246, 0xc1000000, v120
	v_add_f32_e32 v120, v126, v90
	v_mul_f32_e32 v101, 0xc1000000, v96
	v_add_f32_e32 v96, v102, v90
	v_exp_f32_e32 v98, v98
	v_exp_f32_e32 v64, v64
	v_mul_f32_e32 v120, 0xbfb8aa3b, v120
	v_mul_f32_e32 v96, 0xbfb8aa3b, v96
	s_waitcnt vmcnt(1)
	v_lshlrev_b32_e32 v163, 16, v182
	v_and_b32_e32 v160, 0xffff0000, v182
	v_add_f32_e32 v129, 1.0, v129
	v_mul_f32_e32 v216, 0xc1000000, v128
	v_ashrrev_i32_e32 v128, 5, v172
	v_lshlrev_b32_e32 v130, 4, v172
	s_waitcnt vmcnt(0)
	v_lshlrev_b32_e32 v182, 16, v201
	v_and_b32_e32 v172, 0xffff0000, v201
	v_exp_f32_e32 v120, v120
	v_mul_f32_e32 v201, 0xc1000000, v104
	v_add_f32_e32 v104, v110, v90
	v_exp_f32_e32 v96, v96
	v_add_f32_e32 v84, v84, v88
	v_add_f32_e32 v132, 1.0, v132
	v_rcp_f32_e32 v214, v129
	v_add_f32_e32 v129, v131, v95
	v_mul_f32_e32 v104, 0xbfb8aa3b, v104
	v_mul_f32_e32 v84, 0xbfb8aa3b, v84
	v_add_f32_e32 v72, 1.0, v72
	v_rcp_f32_e32 v132, v132
	v_mul_f32_e32 v129, 0xbfb8aa3b, v129
	v_exp_f32_e32 v104, v104
	v_add_f32_e32 v98, 1.0, v98
	v_exp_f32_e32 v84, v84
	v_add_f32_e32 v81, v81, v93
	v_rcp_f32_e32 v236, v72
	v_add_f32_e32 v72, v79, v91
	v_add_f32_e32 v64, 1.0, v64
	v_exp_f32_e32 v129, v129
	v_rcp_f32_e32 v230, v98
	v_add_f32_e32 v98, v99, v95
	v_mul_f32_e32 v81, 0xbfb8aa3b, v81
	v_add_f32_e32 v76, v76, v88
	v_mul_f32_e32 v72, 0xbfb8aa3b, v72
	v_rcp_f32_e32 v68, v64
	v_add_f32_e32 v64, v65, v89
	v_add_f32_e32 v120, 1.0, v120
	v_mul_f32_e32 v121, 0xbfb8aa3b, v121
	v_add_f32_e32 v96, 1.0, v96
	v_mul_f32_e32 v98, 0xbfb8aa3b, v98
	v_add_f32_e32 v80, v80, v92
	v_exp_f32_e32 v81, v81
	v_mul_f32_e32 v76, 0xbfb8aa3b, v76
	v_exp_f32_e32 v72, v72
	v_mul_f32_e32 v64, 0xbfb8aa3b, v64
	v_rcp_f32_e32 v120, v120
	v_exp_f32_e32 v121, v121
	v_add_f32_e32 v116, v116, v88
	v_rcp_f32_e32 v96, v96
	v_exp_f32_e32 v98, v98
	v_mul_f32_e32 v80, 0xbfb8aa3b, v80
	v_add_f32_e32 v82, v82, v94
	v_exp_f32_e32 v76, v76
	v_exp_f32_e32 v64, v64
	v_ashrrev_i32_e32 v152, 4, v142
	v_mul_f32_e32 v240, 0xc1000000, v132
	v_and_b32_e32 v132, 0xffffff80, v128
	v_mul_f32_e32 v116, 0xbfb8aa3b, v116
	v_add_f32_e32 v113, v113, v93
	v_add_f32_e32 v104, 1.0, v104
	v_add_f32_e32 v84, 1.0, v84
	v_exp_f32_e32 v80, v80
	v_mul_f32_e32 v82, 0xbfb8aa3b, v82
	v_add_f32_e32 v129, 1.0, v129
	v_add_u32_e32 v128, v132, v152
	v_exp_f32_e32 v116, v116
	v_mul_f32_e32 v113, 0xbfb8aa3b, v113
	v_rcp_f32_e32 v104, v104
	v_rcp_f32_e32 v84, v84
	v_exp_f32_e32 v82, v82
	v_lshlrev_b32_e32 v170, 16, v183
	v_and_b32_e32 v149, 0xffff0000, v183
	v_rcp_f32_e32 v183, v129
	v_ashrrev_i32_e32 v129, 31, v128
	v_and_b32_e32 v133, 0xf8f0, v130
	v_exp_f32_e32 v113, v113
	v_add_f32_e32 v81, 1.0, v81
	v_add_f32_e32 v73, v75, v95
	v_add_f32_e32 v72, 1.0, v72
	v_lshlrev_b64 v[128:129], 16, v[128:129]
	v_add_f32_e32 v121, 1.0, v121
	v_mul_f32_e32 v219, 0xc1000000, v120
	v_add_f32_e32 v120, v127, v91
	v_mul_f32_e32 v231, 0xc1000000, v96
	v_add_f32_e32 v96, v103, v91
	v_add_f32_e32 v98, 1.0, v98
	v_or_b32_e32 v127, 0x400, v133
	v_rcp_f32_e32 v103, v81
	v_add_f32_e32 v81, v86, v90
	v_add_f32_e32 v76, 1.0, v76
	v_rcp_f32_e32 v118, v72
	v_mul_f32_e32 v72, 0xbfb8aa3b, v73
	v_add_f32_e32 v65, v69, v93
	v_add_f32_e32 v64, 1.0, v64
	v_rcp_f32_e32 v218, v121
	v_add_f32_e32 v121, v123, v95
	v_rcp_f32_e32 v229, v98
	v_or3_b32 v98, v128, v127, v146
	v_mov_b32_e32 v99, v129
	v_add_f32_e32 v80, 1.0, v80
	v_mul_f32_e32 v81, 0xbfb8aa3b, v81
	v_rcp_f32_e32 v123, v76
	v_exp_f32_e32 v72, v72
	v_rcp_f32_e32 v76, v64
	v_mul_f32_e32 v64, 0xbfb8aa3b, v65
	v_add_f32_e32 v116, 1.0, v116
	v_mul_f32_e32 v227, 0xc1000000, v104
	v_add_f32_e32 v104, v111, v91
	v_lshl_add_u64 v[110:111], v[98:99], 3, s[14:15]
	v_rcp_f32_e32 v99, v80
	v_mul_f32_e32 v80, 0xc1000000, v84
	v_add_f32_e32 v84, v85, v89
	v_exp_f32_e32 v81, v81
	v_add_f32_e32 v82, 1.0, v82
	v_exp_f32_e32 v64, v64
	v_rcp_f32_e32 v116, v116
	v_add_f32_e32 v113, 1.0, v113
	v_mul_f32_e32 v84, 0xbfb8aa3b, v84
	v_rcp_f32_e32 v234, v82
	v_add_f32_e32 v82, v83, v95
	v_rcp_f32_e32 v248, v113
	v_add_f32_e32 v113, v114, v94
	v_exp_f32_e32 v84, v84
	v_mul_f32_e32 v82, 0xbfb8aa3b, v82
	v_mul_f32_e32 v113, 0xbfb8aa3b, v113
	v_exp_f32_e32 v82, v82
	v_add_f32_e32 v72, 1.0, v72
	v_or_b32_e32 v135, 0x600, v133
	v_exp_f32_e32 v113, v113
	v_add_f32_e32 v81, 1.0, v81
	v_rcp_f32_e32 v79, v72
	v_or3_b32 v72, v128, v135, v146
	v_mov_b32_e32 v73, v129
	v_add_f32_e32 v64, 1.0, v64
	v_mul_f32_e32 v249, 0xc1000000, v116
	v_rcp_f32_e32 v81, v81
	v_lshl_add_u64 v[116:117], v[72:73], 3, s[14:15]
	v_rcp_f32_e32 v189, v64
	v_mov_b32_e32 v64, v180
	v_mov_b32_e32 v65, v156
	v_mov_b32_e32 v72, v181
	v_mov_b32_e32 v73, v157
	v_add_f32_e32 v84, 1.0, v84
	v_pk_add_f32 v[72:73], v[64:65], v[72:73]
	v_mov_b32_e32 v152, v179
	v_rcp_f32_e32 v84, v84
	v_add_f32_e32 v82, 1.0, v82
	v_or_b32_e32 v134, 0x500, v133
	v_pk_add_f32 v[74:75], v[152:153], v[72:73]
	v_mov_b32_e32 v151, v153
	v_mov_b32_e32 v175, v179
	v_add_f32_e32 v113, 1.0, v113
	v_rcp_f32_e32 v233, v82
	v_or3_b32 v82, v128, v134, v146
	v_mov_b32_e32 v83, v129
	v_mov_b32_e32 v157, v75
	v_mov_b32_e32 v181, v74
	v_rcp_f32_e32 v222, v113
	v_add_f32_e32 v113, v115, v95
	v_mul_f32_e32 v235, 0xc1000000, v81
	v_add_f32_e32 v81, v87, v91
	v_lshl_add_u64 v[114:115], v[82:83], 3, s[14:15]
	v_pk_add_f32 v[82:83], v[156:157], v[150:151] neg_lo:[0,1] neg_hi:[0,1]
	v_pk_add_f32 v[86:87], v[180:181], v[174:175] neg_lo:[0,1] neg_hi:[0,1]
	v_add_f32_e32 v124, v124, v88
	v_add_f32_e32 v108, v108, v88
	v_add_f32_e32 v100, v100, v88
	v_mov_b32_e32 v155, v73
	v_mov_b32_e32 v88, v86
	v_mov_b32_e32 v89, v82
	v_mov_b32_e32 v177, v72
	v_mul_f32_e32 v207, 0xc1000000, v84
	v_pk_add_f32 v[84:85], v[154:155], v[82:83] neg_lo:[0,1] neg_hi:[0,1]
	v_pk_add_f32 v[64:65], v[64:65], v[88:89] neg_lo:[0,1] neg_hi:[0,1]
	v_mov_b32_e32 v175, v150
	v_pk_add_f32 v[72:73], v[176:177], v[86:87] neg_lo:[0,1] neg_hi:[0,1]
	v_pk_add_f32 v[64:65], v[174:175], v[64:65] neg_lo:[0,1] neg_hi:[0,1]
	v_mov_b32_e32 v82, v72
	v_mov_b32_e32 v83, v84
	v_pk_add_f32 v[64:65], v[82:83], v[64:65]
	v_mov_b32_e32 v84, v73
	v_pk_add_f32 v[64:65], v[64:65], v[84:85]
	v_cmp_neq_f32_e32 vcc, s27, v173
	v_pk_add_f32 v[64:65], v[74:75], v[64:65]
	v_cmp_lt_f32_e64 s[0:1], |v143|, s39
	v_cndmask_b32_e32 v64, v209, v64, vcc
	v_cmp_neq_f32_e32 vcc, s27, v143
	v_add_f32_e32 v105, v105, v93
	v_mul_f32_e32 v105, 0xbfb8aa3b, v105
	v_cndmask_b32_e32 v65, v209, v65, vcc
	v_cndmask_b32_e64 v65, v65, v143, s[0:1]
	v_mul_f32_e32 v69, v240, v65
	v_mul_f32_e32 v72, 0x3fb8aa3b, v69
	v_exp_f32_e32 v72, v72
	v_add_f32_e32 v69, v69, v69
	v_fmamk_f32 v74, v69, 0x3d2aaaab, v196
	v_fma_f32 v74, v69, v74, 0.5
	v_cmp_lt_f32_e64 vcc, |v173|, s39
	v_fma_f32 v74, v69, v74, 1.0
	v_fma_f32 v73, -v72, v72, 1.0
	v_cndmask_b32_e32 v64, v64, v173, vcc
	v_mul_f32_e64 v74, v74, -v69
	v_cmp_lt_f32_e32 vcc, s40, v69
	v_exp_f32_e32 v105, v105
	v_mul_f32_e32 v124, 0xbfb8aa3b, v124
	v_cndmask_b32_e32 v69, v73, v74, vcc
	v_max_f32_e32 v69, 0, v69
	v_sqrt_f32_e32 v69, v69
	v_add_f32_e32 v105, 1.0, v105
	v_rcp_f32_e32 v252, v105
	v_add_f32_e32 v105, v106, v94
	v_mul_f32_e32 v69, v167, v69
	v_mul_f32_e32 v73, v69, v163
	v_mul_f32_e32 v69, v241, v64
	v_mul_f32_e32 v74, 0x3fb8aa3b, v69
	v_mul_f32_e32 v105, 0xbfb8aa3b, v105
	v_exp_f32_e32 v74, v74
	v_add_f32_e32 v69, v69, v69
	v_exp_f32_e32 v105, v105
	v_fmamk_f32 v78, v69, 0x3d2aaaab, v196
	v_exp_f32_e32 v124, v124
	v_fma_f32 v78, v69, v78, 0.5
	v_mul_f32_e32 v104, 0xbfb8aa3b, v104
	v_fma_f32 v78, v69, v78, 1.0
	v_mul_f32_e32 v108, 0xbfb8aa3b, v108
	v_exp_f32_e32 v104, v104
	v_fma_f32 v75, -v74, v74, 1.0
	v_mul_f32_e64 v78, v78, -v69
	v_cmp_lt_f32_e32 vcc, s40, v69
	v_exp_f32_e32 v108, v108
	v_add_f32_e32 v105, 1.0, v105
	v_cndmask_b32_e32 v69, v75, v78, vcc
	v_add_f32_e32 v124, 1.0, v124
	v_rcp_f32_e32 v226, v105
	v_add_f32_e32 v105, v107, v95
	v_max_f32_e32 v69, 0, v69
	v_rcp_f32_e32 v124, v124
	v_mul_f32_e32 v105, 0xbfb8aa3b, v105
	v_sqrt_f32_e32 v69, v69
	v_add_f32_e32 v104, 1.0, v104
	v_exp_f32_e32 v105, v105
	v_add_f32_e32 v108, 1.0, v108
	v_rcp_f32_e32 v104, v104
	v_rcp_f32_e32 v108, v108
	v_or3_b32 v130, v128, v133, v146
	v_mov_b32_e32 v131, v129
	v_mul_f32_e32 v245, 0xc1000000, v124
	v_mul_f32_e32 v69, v238, v69
	v_lshl_add_u64 v[130:131], v[130:131], 3, s[14:15]
	v_add_f32_e32 v105, 1.0, v105
	v_or_b32_e32 v126, 0x300, v133
	v_mul_f32_e32 v75, v69, v160
	v_mul_f32_e32 v69, v245, v65
	v_rcp_f32_e32 v225, v105
	v_mul_f32_e32 v228, 0xc1000000, v104
	v_or3_b32 v104, v128, v126, v146
	v_mov_b32_e32 v105, v129
	global_store_dwordx4 v[130:131], v[72:75], off
	v_lshlrev_b32_e32 v242, 16, v200
	v_and_b32_e32 v239, 0xffff0000, v200
	v_mul_f32_e32 v72, 0x3fb8aa3b, v69
	v_mul_f32_e32 v200, 0xc1000000, v108
	v_lshl_add_u64 v[108:109], v[104:105], 3, s[14:15]
	v_exp_f32_e32 v104, v72
	v_add_f32_e32 v69, v69, v69
	v_fmamk_f32 v73, v69, 0x3d2aaaab, v196
	v_fma_f32 v73, v69, v73, 0.5
	v_fma_f32 v73, v69, v73, 1.0
	v_fma_f32 v72, -v104, v104, 1.0
	v_mul_f32_e64 v73, v73, -v69
	v_cmp_lt_f32_e32 vcc, s40, v69
	v_mul_f32_e32 v100, 0xbfb8aa3b, v100
	v_exp_f32_e32 v100, v100
	v_cndmask_b32_e32 v69, v72, v73, vcc
	v_max_f32_e32 v69, 0, v69
	v_sqrt_f32_e32 v69, v69
	v_add_f32_e32 v100, 1.0, v100
	v_rcp_f32_e32 v100, v100
	v_mul_f32_e32 v96, 0xbfb8aa3b, v96
	v_mul_f32_e32 v69, v243, v69
	v_mul_f32_e32 v105, v69, v242
	v_mul_f32_e32 v69, v246, v64
	v_mul_f32_e32 v72, 0x3fb8aa3b, v69
	v_exp_f32_e32 v106, v72
	v_add_f32_e32 v69, v69, v69
	v_fmamk_f32 v73, v69, 0x3d2aaaab, v196
	v_fma_f32 v73, v69, v73, 0.5
	v_fma_f32 v73, v69, v73, 1.0
	v_fma_f32 v72, -v106, v106, 1.0
	v_mul_f32_e64 v73, v73, -v69
	v_cmp_lt_f32_e32 vcc, s40, v69
	v_mul_f32_e32 v206, 0xc1000000, v100
	v_exp_f32_e32 v96, v96
	v_cndmask_b32_e32 v69, v72, v73, vcc
	v_max_f32_e32 v69, 0, v69
	v_sqrt_f32_e32 v69, v69
	v_add_f32_e32 v96, 1.0, v96
	v_rcp_f32_e32 v96, v96
	v_add_f32_e32 v97, v97, v93
	v_mul_f32_e32 v69, v244, v69
	v_mul_f32_e32 v107, v69, v239
	v_mul_f32_e32 v69, v249, v65
	v_mul_f32_e32 v72, 0x3fb8aa3b, v69
	v_exp_f32_e32 v100, v72
	v_add_f32_e32 v69, v69, v69
	v_fmamk_f32 v73, v69, 0x3d2aaaab, v196
	v_fma_f32 v73, v69, v73, 0.5
	v_fma_f32 v73, v69, v73, 1.0
	v_fma_f32 v72, -v100, v100, 1.0
	v_mul_f32_e64 v73, v73, -v69
	v_cmp_lt_f32_e32 vcc, s40, v69
	v_mul_f32_e32 v232, 0xc1000000, v96
	v_mul_f32_e32 v81, 0xbfb8aa3b, v81
	v_cndmask_b32_e32 v69, v72, v73, vcc
	v_max_f32_e32 v69, 0, v69
	v_sqrt_f32_e32 v69, v69
	v_exp_f32_e32 v81, v81
	v_mul_f32_e32 v97, 0xbfb8aa3b, v97
	v_exp_f32_e32 v97, v97
	v_mul_f32_e32 v92, v247, v69
	v_mul_f32_e32 v69, v250, v64
	v_mul_f32_e32 v72, 0x3fb8aa3b, v69
	v_exp_f32_e32 v102, v72
	v_add_f32_e32 v69, v69, v69
	v_fmamk_f32 v73, v69, 0x3d2aaaab, v196
	v_fma_f32 v73, v69, v73, 0.5
	v_fma_f32 v73, v69, v73, 1.0
	v_fma_f32 v72, -v102, v102, 1.0
	v_mul_f32_e64 v73, v73, -v69
	v_cmp_lt_f32_e32 vcc, s40, v69
	v_add_f32_e32 v81, 1.0, v81
	v_rcp_f32_e32 v81, v81
	v_cndmask_b32_e32 v69, v72, v73, vcc
	v_max_f32_e32 v69, 0, v69
	v_sqrt_f32_e32 v69, v69
	v_mul_f32_e32 v237, 0xc1000000, v81
	v_add_f32_e32 v97, 1.0, v97
	v_rcp_f32_e32 v97, v97
	v_mul_f32_e32 v93, v248, v69
	v_mul_f32_e32 v69, v200, v65
	v_mul_f32_e32 v72, 0x3fb8aa3b, v69
	v_exp_f32_e32 v96, v72
	v_add_f32_e32 v69, v69, v69
	v_fmamk_f32 v73, v69, 0x3d2aaaab, v196
	v_fma_f32 v73, v69, v73, 0.5
	v_fma_f32 v73, v69, v73, 1.0
	v_fma_f32 v72, -v96, v96, 1.0
	v_mul_f32_e64 v73, v73, -v69
	v_cmp_lt_f32_e32 vcc, s40, v69
	v_pk_mul_f32 v[76:77], v[76:77], s[44:45] op_sel_hi:[1,0]
	v_mov_b32_e32 v160, v171
	v_cndmask_b32_e32 v69, v72, v73, vcc
	v_max_f32_e32 v69, 0, v69
	v_sqrt_f32_e32 v69, v69
	v_mov_b32_e32 v159, v161
	v_mov_b32_e32 v139, v171
	v_mul_f32_e32 v120, 0xbfb8aa3b, v120
	v_mul_f32_e32 v85, v251, v69
	v_mul_f32_e32 v69, v201, v64
	v_mul_f32_e32 v72, 0x3fb8aa3b, v69
	v_exp_f32_e32 v98, v72
	v_add_f32_e32 v69, v69, v69
	v_fmamk_f32 v73, v69, 0x3d2aaaab, v196
	v_fma_f32 v73, v69, v73, 0.5
	v_fma_f32 v73, v69, v73, 1.0
	v_fma_f32 v72, -v98, v98, 1.0
	v_mul_f32_e64 v73, v73, -v69
	v_cmp_lt_f32_e32 vcc, s40, v69
	v_mul_f32_e32 v112, 0xbfb8aa3b, v112
	v_exp_f32_e32 v120, v120
	v_cndmask_b32_e32 v69, v72, v73, vcc
	v_max_f32_e32 v69, 0, v69
	v_sqrt_f32_e32 v69, v69
	v_exp_f32_e32 v112, v112
	v_mul_f32_e32 v121, 0xbfb8aa3b, v121
	v_mul_f32_e32 v113, 0xbfb8aa3b, v113
	v_mul_f32_e32 v89, v252, v69
	v_mul_f32_e32 v69, v206, v65
	v_mul_f32_e32 v72, 0x3fb8aa3b, v69
	v_exp_f32_e32 v84, v72
	v_add_f32_e32 v69, v69, v69
	v_fmamk_f32 v73, v69, 0x3d2aaaab, v196
	v_fma_f32 v73, v69, v73, 0.5
	v_fma_f32 v73, v69, v73, 1.0
	v_fma_f32 v72, -v84, v84, 1.0
	v_mul_f32_e64 v73, v73, -v69
	v_cmp_lt_f32_e32 vcc, s40, v69
	v_add_f32_e32 v120, 1.0, v120
	v_exp_f32_e32 v121, v121
	v_cndmask_b32_e32 v69, v72, v73, vcc
	v_max_f32_e32 v69, 0, v69
	v_sqrt_f32_e32 v69, v69
	v_add_f32_e32 v112, 1.0, v112
	v_exp_f32_e32 v113, v113
	v_rcp_f32_e32 v120, v120
	v_mul_f32_e32 v81, v199, v69
	v_mul_f32_e32 v69, v101, v64
	v_mul_f32_e32 v72, 0x3fb8aa3b, v69
	v_exp_f32_e32 v86, v72
	v_add_f32_e32 v69, v69, v69
	v_fmamk_f32 v73, v69, 0x3d2aaaab, v196
	v_fma_f32 v73, v69, v73, 0.5
	v_fma_f32 v73, v69, v73, 1.0
	v_fma_f32 v72, -v86, v86, 1.0
	v_mul_f32_e64 v73, v73, -v69
	v_cmp_lt_f32_e32 vcc, s40, v69
	v_rcp_f32_e32 v112, v112
	v_add_f32_e32 v121, 1.0, v121
	v_cndmask_b32_e32 v69, v72, v73, vcc
	v_max_f32_e32 v69, 0, v69
	v_sqrt_f32_e32 v69, v69
	v_or_b32_e32 v124, 0x100, v133
	v_add_f32_e32 v113, 1.0, v113
	v_or_b32_e32 v125, 0x200, v133
	v_mul_f32_e32 v87, v97, v69
	v_mul_f32_e32 v69, v80, v65
	v_mul_f32_e32 v72, 0x3fb8aa3b, v69
	v_exp_f32_e32 v80, v72
	v_add_f32_e32 v69, v69, v69
	v_fmamk_f32 v73, v69, 0x3d2aaaab, v196
	v_fma_f32 v73, v69, v73, 0.5
	v_fma_f32 v73, v69, v73, 1.0
	v_fma_f32 v72, -v80, v80, 1.0
	v_mul_f32_e64 v73, v73, -v69
	v_cmp_lt_f32_e32 vcc, s40, v69
	v_rcp_f32_e32 v217, v121
	v_mul_f32_e32 v220, 0xc1000000, v120
	v_cndmask_b32_e32 v69, v72, v73, vcc
	v_max_f32_e32 v69, 0, v69
	v_sqrt_f32_e32 v69, v69
	v_or3_b32 v120, v128, v124, v146
	v_mov_b32_e32 v121, v129
	v_rcp_f32_e32 v221, v113
	v_mul_f32_e32 v75, v99, v69
	v_mul_f32_e32 v69, v207, v64
	v_mul_f32_e32 v72, 0x3fb8aa3b, v69
	v_exp_f32_e32 v82, v72
	v_add_f32_e32 v69, v69, v69
	v_fmamk_f32 v73, v69, 0x3d2aaaab, v196
	v_fma_f32 v73, v69, v73, 0.5
	v_fma_f32 v73, v69, v73, 1.0
	v_fma_f32 v72, -v82, v82, 1.0
	v_mul_f32_e64 v73, v73, -v69
	v_cmp_lt_f32_e32 vcc, s40, v69
	v_mul_f32_e32 v224, 0xc1000000, v112
	v_or3_b32 v112, v128, v125, v146
	v_cndmask_b32_e32 v69, v72, v73, vcc
	v_max_f32_e32 v69, 0, v69
	v_sqrt_f32_e32 v69, v69
	v_pk_mul_f32 v[72:73], v[122:123], s[44:45] op_sel_hi:[1,0]
	v_mov_b32_e32 v113, v129
	v_pk_mul_f32 v[122:123], v[72:73], v[64:65]
	v_mul_f32_e32 v83, v103, v69
	v_mul_f32_e32 v69, 0x3fb8aa3b, v123
	v_exp_f32_e32 v72, v69
	v_pk_add_f32 v[150:151], v[122:123], v[122:123]
	v_pk_mul_f32 v[64:65], v[76:77], v[64:65]
	v_fmamk_f32 v73, v151, 0x3d2aaaab, v196
	v_fma_f32 v73, v151, v73, 0.5
	v_fma_f32 v73, v151, v73, 1.0
	v_fma_f32 v69, -v72, v72, 1.0
	v_mul_f32_e64 v73, v73, -v151
	v_cmp_lt_f32_e64 s[0:1], s40, v151
	v_fmamk_f32 v78, v150, 0x3d2aaaab, v196
	v_fma_f32 v78, v150, v78, 0.5
	v_cndmask_b32_e64 v69, v69, v73, s[0:1]
	v_max_f32_e32 v69, 0, v69
	v_sqrt_f32_e32 v69, v69
	v_fma_f32 v78, v150, v78, 1.0
	v_cmp_lt_f32_e32 vcc, s40, v150
	v_mul_f32_e64 v78, v78, -v150
	v_mul_f32_e32 v73, v203, v69
	v_mul_f32_e32 v69, 0x3fb8aa3b, v122
	v_exp_f32_e32 v74, v69
	v_pk_add_f32 v[122:123], v[64:65], v[64:65]
	v_mul_f32_e32 v64, 0x3fb8aa3b, v64
	v_cmp_lt_f32_e64 s[0:1], s40, v123
	v_fma_f32 v69, -v74, v74, 1.0
	v_cndmask_b32_e32 v69, v69, v78, vcc
	v_max_f32_e32 v69, 0, v69
	v_sqrt_f32_e32 v69, v69
	v_exp_f32_e32 v78, v64
	v_cmp_lt_f32_e32 vcc, s40, v122
	v_lshl_add_u64 v[120:121], v[120:121], 3, s[14:15]
	v_mul_f32_e32 v88, v208, v69
	v_mul_f32_e32 v69, 0x3fb8aa3b, v65
	v_exp_f32_e32 v76, v69
	v_fmamk_f32 v65, v123, 0x3d2aaaab, v196
	v_fma_f32 v65, v123, v65, 0.5
	v_fma_f32 v65, v123, v65, 1.0
	v_fma_f32 v69, -v76, v76, 1.0
	v_mul_f32_e64 v65, v65, -v123
	v_cndmask_b32_e64 v65, v69, v65, s[0:1]
	v_max_f32_e32 v65, 0, v65
	v_sqrt_f32_e32 v65, v65
	v_fma_f32 v64, -v78, v78, 1.0
	v_cmp_lt_f32_e64 s[0:1], |v145|, s39
	v_lshl_add_u64 v[112:113], v[112:113], 3, s[14:15]
	v_mul_f32_e32 v69, v68, v65
	v_fmamk_f32 v65, v122, 0x3d2aaaab, v196
	v_fma_f32 v65, v122, v65, 0.5
	v_fma_f32 v65, v122, v65, 1.0
	v_mul_f32_e64 v65, v65, -v122
	v_cndmask_b32_e32 v64, v64, v65, vcc
	v_max_f32_e32 v64, 0, v64
	v_sqrt_f32_e32 v64, v64
	v_cmp_neq_f32_e32 vcc, s27, v178
	v_mul_f32_e32 v68, v189, v64
	v_add_f32_e32 v64, v66, v90
	v_mul_f32_e32 v64, 0xbfb8aa3b, v64
	v_exp_f32_e32 v64, v64
	v_add_f32_e32 v66, v70, v94
	v_mov_b32_e32 v90, v169
	v_add_f32_e32 v64, 1.0, v64
	v_rcp_f32_e32 v65, v64
	v_mul_f32_e32 v64, 0xbfb8aa3b, v66
	v_add_f32_e32 v66, v71, v95
	v_mul_f32_e32 v66, 0xbfb8aa3b, v66
	v_exp_f32_e32 v64, v64
	v_exp_f32_e32 v66, v66
	v_add_f32_e32 v64, 1.0, v64
	v_add_f32_e32 v66, 1.0, v66
	v_rcp_f32_e32 v70, v64
	v_add_f32_e32 v64, v67, v91
	v_rcp_f32_e32 v71, v66
	v_mov_b32_e32 v66, v168
	v_mov_b32_e32 v67, v164
	v_mov_b32_e32 v91, v165
	v_pk_add_f32 v[90:91], v[66:67], v[90:91]
	v_mul_f32_e32 v64, 0xbfb8aa3b, v64
	v_pk_add_f32 v[94:95], v[160:161], v[90:91]
	v_mov_b32_e32 v163, v91
	v_mov_b32_e32 v165, v95
	v_mov_b32_e32 v169, v94
	v_pk_add_f32 v[122:123], v[164:165], v[158:159] neg_lo:[0,1] neg_hi:[0,1]
	v_pk_add_f32 v[152:153], v[168:169], v[138:139] neg_lo:[0,1] neg_hi:[0,1]
	v_mov_b32_e32 v155, v122
	v_mov_b32_e32 v154, v152
	v_mov_b32_e32 v167, v90
	v_pk_add_f32 v[150:151], v[162:163], v[122:123] neg_lo:[0,1] neg_hi:[0,1]
	v_pk_add_f32 v[66:67], v[66:67], v[154:155] neg_lo:[0,1] neg_hi:[0,1]
	v_mov_b32_e32 v139, v158
	v_pk_add_f32 v[90:91], v[166:167], v[152:153] neg_lo:[0,1] neg_hi:[0,1]
	v_pk_add_f32 v[66:67], v[138:139], v[66:67] neg_lo:[0,1] neg_hi:[0,1]
	v_mov_b32_e32 v122, v90
	v_mov_b32_e32 v123, v150
	v_pk_add_f32 v[66:67], v[122:123], v[66:67]
	v_mov_b32_e32 v150, v91
	v_pk_add_f32 v[66:67], v[66:67], v[150:151]
	v_exp_f32_e32 v64, v64
	v_pk_add_f32 v[66:67], v[94:95], v[66:67]
	v_add_f32_e32 v64, 1.0, v64
	v_cndmask_b32_e32 v66, v209, v66, vcc
	v_cmp_neq_f32_e32 vcc, s27, v145
	v_rcp_f32_e32 v64, v64
	s_nop 0
	v_cndmask_b32_e32 v67, v209, v67, vcc
	v_cndmask_b32_e64 v67, v67, v145, s[0:1]
	v_mul_f32_e32 v77, v215, v67
	v_mul_f32_e32 v90, 0x3fb8aa3b, v77
	v_exp_f32_e32 v150, v90
	v_add_f32_e32 v77, v77, v77
	v_fmamk_f32 v91, v77, 0x3d2aaaab, v196
	v_fma_f32 v91, v77, v91, 0.5
	v_cmp_lt_f32_e64 vcc, |v178|, s39
	v_fma_f32 v91, v77, v91, 1.0
	v_fma_f32 v90, -v150, v150, 1.0
	v_cndmask_b32_e32 v66, v66, v178, vcc
	v_mul_f32_e64 v91, v91, -v77
	v_cmp_lt_f32_e32 vcc, s40, v77
	s_nop 1
	v_cndmask_b32_e32 v77, v90, v91, vcc
	v_max_f32_e32 v77, 0, v77
	v_sqrt_f32_e32 v77, v77
	s_nop 0
	v_mul_f32_e32 v77, v214, v77
	v_mul_f32_e32 v151, v77, v170
	v_mul_f32_e32 v77, v216, v66
	v_mul_f32_e32 v90, 0x3fb8aa3b, v77
	v_exp_f32_e32 v152, v90
	v_add_f32_e32 v77, v77, v77
	v_fmamk_f32 v91, v77, 0x3d2aaaab, v196
	v_fma_f32 v91, v77, v91, 0.5
	v_fma_f32 v91, v77, v91, 1.0
	v_fma_f32 v90, -v152, v152, 1.0
	v_mul_f32_e64 v91, v91, -v77
	v_cmp_lt_f32_e32 vcc, s40, v77
	s_nop 1
	v_cndmask_b32_e32 v77, v90, v91, vcc
	v_max_f32_e32 v77, 0, v77
	v_sqrt_f32_e32 v77, v77
	s_nop 0
	v_mul_f32_e32 v77, v183, v77
	v_mul_f32_e32 v153, v77, v149
	global_store_dwordx4 v[130:131], v[150:153], off offset:16
	v_add_co_u32_e32 v90, vcc, s66, v136
	v_mul_f32_e32 v77, v219, v67
	s_nop 0
	v_addc_co_u32_e32 v91, vcc, 0, v137, vcc
	global_load_dwordx2 v[90:91], v[90:91], off
	v_mul_f32_e32 v94, 0x3fb8aa3b, v77
	v_exp_f32_e32 v150, v94
	v_add_f32_e32 v77, v77, v77
	v_fmamk_f32 v95, v77, 0x3d2aaaab, v196
	v_fma_f32 v95, v77, v95, 0.5
	v_fma_f32 v95, v77, v95, 1.0
	v_fma_f32 v94, -v150, v150, 1.0
	v_mul_f32_e64 v95, v95, -v77
	v_cmp_lt_f32_e32 vcc, s40, v77
	s_nop 1
	v_cndmask_b32_e32 v77, v94, v95, vcc
	v_max_f32_e32 v77, 0, v77
	v_sqrt_f32_e32 v77, v77
	s_nop 0
	v_mul_f32_e32 v77, v218, v77
	v_mul_f32_e32 v151, v77, v182
	v_mul_f32_e32 v77, v220, v66
	v_mul_f32_e32 v94, 0x3fb8aa3b, v77
	v_exp_f32_e32 v152, v94
	v_add_f32_e32 v77, v77, v77
	v_fmamk_f32 v95, v77, 0x3d2aaaab, v196
	v_fma_f32 v95, v77, v95, 0.5
	v_fma_f32 v95, v77, v95, 1.0
	v_fma_f32 v94, -v152, v152, 1.0
	v_mul_f32_e64 v95, v95, -v77
	v_cmp_lt_f32_e32 vcc, s40, v77
	s_nop 1
	v_cndmask_b32_e32 v77, v94, v95, vcc
	v_max_f32_e32 v77, 0, v77
	v_sqrt_f32_e32 v77, v77
	s_nop 0
	v_mul_f32_e32 v77, v217, v77
	v_mul_f32_e32 v153, v77, v172
	global_store_dwordx4 v[120:121], v[104:107], off
	global_store_dwordx4 v[120:121], v[150:153], off offset:16
	v_add_co_u32_e32 v94, vcc, s67, v136
	s_waitcnt vmcnt(2)
	v_lshlrev_b32_e32 v77, 16, v90
	v_addc_co_u32_e32 v95, vcc, 0, v137, vcc
	global_load_dwordx2 v[94:95], v[94:95], off
	v_and_b32_e32 v90, 0xffff0000, v90
	v_mul_f32_e32 v101, v92, v77
	v_mul_f32_e32 v77, v223, v67
	v_mul_f32_e32 v103, v93, v90
	v_mul_f32_e32 v90, 0x3fb8aa3b, v77
	v_exp_f32_e32 v90, v90
	v_add_f32_e32 v77, v77, v77
	v_fmamk_f32 v92, v77, 0x3d2aaaab, v196
	v_fma_f32 v92, v77, v92, 0.5
	v_fma_f32 v92, v77, v92, 1.0
	v_lshlrev_b32_e32 v97, 16, v91
	v_and_b32_e32 v99, 0xffff0000, v91
	v_fma_f32 v91, -v90, v90, 1.0
	v_mul_f32_e64 v92, v92, -v77
	v_cmp_lt_f32_e32 vcc, s40, v77
	s_nop 1
	v_cndmask_b32_e32 v77, v91, v92, vcc
	v_max_f32_e32 v77, 0, v77
	v_sqrt_f32_e32 v77, v77
	s_nop 0
	v_mul_f32_e32 v77, v222, v77
	v_mul_f32_e32 v91, v77, v97
	v_mul_f32_e32 v77, v224, v66
	v_mul_f32_e32 v92, 0x3fb8aa3b, v77
	v_exp_f32_e32 v92, v92
	v_add_f32_e32 v77, v77, v77
	v_fmamk_f32 v97, v77, 0x3d2aaaab, v196
	v_fma_f32 v97, v77, v97, 0.5
	v_fma_f32 v97, v77, v97, 1.0
	v_fma_f32 v93, -v92, v92, 1.0
	v_mul_f32_e64 v97, v97, -v77
	v_cmp_lt_f32_e32 vcc, s40, v77
	s_nop 1
	v_cndmask_b32_e32 v77, v93, v97, vcc
	v_max_f32_e32 v77, 0, v77
	v_sqrt_f32_e32 v77, v77
	s_nop 0
	v_mul_f32_e32 v77, v221, v77
	v_mul_f32_e32 v93, v77, v99
	global_store_dwordx4 v[112:113], v[100:103], off
	global_store_dwordx4 v[112:113], v[90:93], off offset:16
	s_mov_b32 s22, 0x40000
	s_nop 0
	v_add_co_u32_e32 v90, vcc, s22, v136
	s_waitcnt vmcnt(2)
	v_lshlrev_b32_e32 v77, 16, v94
	v_addc_co_u32_e32 v91, vcc, 0, v137, vcc
	global_load_dwordx2 v[100:101], v[90:91], off
	v_mul_f32_e32 v97, v85, v77
	v_mul_f32_e32 v77, v227, v67
	v_and_b32_e32 v90, 0xffff0000, v94
	v_mul_f32_e32 v85, 0x3fb8aa3b, v77
	v_mul_f32_e32 v99, v89, v90
	v_exp_f32_e32 v90, v85
	v_add_f32_e32 v77, v77, v77
	v_fmamk_f32 v89, v77, 0x3d2aaaab, v196
	v_fma_f32 v89, v77, v89, 0.5
	v_fma_f32 v89, v77, v89, 1.0
	v_fma_f32 v85, -v90, v90, 1.0
	v_mul_f32_e64 v89, v89, -v77
	v_cmp_lt_f32_e32 vcc, s40, v77
	v_lshlrev_b32_e32 v91, 16, v95
	v_and_b32_e32 v93, 0xffff0000, v95
	v_cndmask_b32_e32 v77, v85, v89, vcc
	v_max_f32_e32 v77, 0, v77
	v_sqrt_f32_e32 v77, v77
	s_nop 0
	v_mul_f32_e32 v77, v226, v77
	v_mul_f32_e32 v91, v77, v91
	v_mul_f32_e32 v77, v228, v66
	v_mul_f32_e32 v85, 0x3fb8aa3b, v77
	v_exp_f32_e32 v92, v85
	v_add_f32_e32 v77, v77, v77
	v_fmamk_f32 v89, v77, 0x3d2aaaab, v196
	v_fma_f32 v89, v77, v89, 0.5
	v_fma_f32 v89, v77, v89, 1.0
	v_fma_f32 v85, -v92, v92, 1.0
	v_mul_f32_e64 v89, v89, -v77
	v_cmp_lt_f32_e32 vcc, s40, v77
	s_nop 1
	v_cndmask_b32_e32 v77, v85, v89, vcc
	v_max_f32_e32 v77, 0, v77
	v_sqrt_f32_e32 v77, v77
	s_nop 0
	v_mul_f32_e32 v77, v225, v77
	v_mul_f32_e32 v93, v77, v93
	global_store_dwordx4 v[108:109], v[96:99], off
	global_store_dwordx4 v[108:109], v[90:93], off offset:16
	s_mov_b32 s41, 0x50000
	s_nop 0
	v_add_co_u32_e32 v90, vcc, s41, v136
	s_waitcnt vmcnt(2)
	v_lshlrev_b32_e32 v77, 16, v100
	v_addc_co_u32_e32 v91, vcc, 0, v137, vcc
	global_load_dwordx2 v[94:95], v[90:91], off
	v_mul_f32_e32 v85, v81, v77
	v_mul_f32_e32 v77, v231, v67
	v_mul_f32_e32 v81, 0x3fb8aa3b, v77
	v_and_b32_e32 v89, 0xffff0000, v100
	v_exp_f32_e32 v90, v81
	v_add_f32_e32 v77, v77, v77
	v_mul_f32_e32 v87, v87, v89
	v_fmamk_f32 v89, v77, 0x3d2aaaab, v196
	v_fma_f32 v89, v77, v89, 0.5
	v_fma_f32 v89, v77, v89, 1.0
	v_fma_f32 v81, -v90, v90, 1.0
	v_mul_f32_e64 v89, v89, -v77
	v_cmp_lt_f32_e32 vcc, s40, v77
	v_lshlrev_b32_e32 v91, 16, v101
	v_and_b32_e32 v93, 0xffff0000, v101
	v_cndmask_b32_e32 v77, v81, v89, vcc
	v_max_f32_e32 v77, 0, v77
	v_sqrt_f32_e32 v77, v77
	s_nop 0
	v_mul_f32_e32 v77, v230, v77
	v_mul_f32_e32 v91, v77, v91
	v_mul_f32_e32 v77, v232, v66
	v_mul_f32_e32 v81, 0x3fb8aa3b, v77
	v_exp_f32_e32 v92, v81
	v_add_f32_e32 v77, v77, v77
	v_fmamk_f32 v89, v77, 0x3d2aaaab, v196
	v_fma_f32 v89, v77, v89, 0.5
	v_fma_f32 v89, v77, v89, 1.0
	v_fma_f32 v81, -v92, v92, 1.0
	v_mul_f32_e64 v89, v89, -v77
	v_cmp_lt_f32_e32 vcc, s40, v77
	s_nop 1
	v_cndmask_b32_e32 v77, v81, v89, vcc
	v_max_f32_e32 v77, 0, v77
	v_sqrt_f32_e32 v77, v77
	s_nop 0
	v_mul_f32_e32 v77, v229, v77
	v_mul_f32_e32 v93, v77, v93
	global_store_dwordx4 v[110:111], v[84:87], off
	global_store_dwordx4 v[110:111], v[90:93], off offset:16
	s_mov_b32 s23, 0x60000
	v_add_co_u32_e32 v84, vcc, s23, v136
	s_waitcnt vmcnt(2)
	v_lshlrev_b32_e32 v77, 16, v94
	v_addc_co_u32_e32 v85, vcc, 0, v137, vcc
	global_load_dwordx2 v[90:91], v[84:85], off
	v_mul_f32_e32 v81, v75, v77
	v_mul_f32_e32 v75, v235, v67
	v_and_b32_e32 v84, 0xffff0000, v94
	v_mul_f32_e32 v77, 0x3fb8aa3b, v75
	v_mul_f32_e32 v83, v83, v84
	v_exp_f32_e32 v84, v77
	v_add_f32_e32 v75, v75, v75
	v_fmamk_f32 v86, v75, 0x3d2aaaab, v196
	v_fma_f32 v86, v75, v86, 0.5
	v_fma_f32 v86, v75, v86, 1.0
	v_fma_f32 v77, -v84, v84, 1.0
	v_mul_f32_e64 v86, v86, -v75
	v_cmp_lt_f32_e32 vcc, s40, v75
	v_lshlrev_b32_e32 v85, 16, v95
	v_and_b32_e32 v87, 0xffff0000, v95
	v_cndmask_b32_e32 v75, v77, v86, vcc
	v_max_f32_e32 v75, 0, v75
	v_sqrt_f32_e32 v75, v75
	s_nop 0
	v_mul_f32_e32 v75, v234, v75
	v_mul_f32_e32 v85, v75, v85
	v_mul_f32_e32 v75, v237, v66
	v_mul_f32_e32 v77, 0x3fb8aa3b, v75
	v_exp_f32_e32 v86, v77
	v_add_f32_e32 v75, v75, v75
	v_fmamk_f32 v89, v75, 0x3d2aaaab, v196
	v_fma_f32 v89, v75, v89, 0.5
	v_fma_f32 v89, v75, v89, 1.0
	v_fma_f32 v77, -v86, v86, 1.0
	v_mul_f32_e64 v89, v89, -v75
	v_cmp_lt_f32_e32 vcc, s40, v75
	s_nop 1
	v_cndmask_b32_e32 v75, v77, v89, vcc
	v_max_f32_e32 v75, 0, v75
	v_sqrt_f32_e32 v75, v75
	s_nop 0
	v_mul_f32_e32 v75, v233, v75
	v_mul_f32_e32 v87, v75, v87
	global_store_dwordx4 v[114:115], v[80:83], off
	global_store_dwordx4 v[114:115], v[84:87], off offset:16
	s_mov_b32 s42, 0x70000
	v_add_co_u32_e32 v80, vcc, s42, v136
	s_waitcnt vmcnt(2)
	v_lshlrev_b32_e32 v75, 16, v90
	v_addc_co_u32_e32 v81, vcc, 0, v137, vcc
	global_load_dwordx2 v[84:85], v[80:81], off
	v_pk_mul_f32 v[80:81], v[118:119], s[44:45] op_sel_hi:[1,0]
	v_and_b32_e32 v77, 0xffff0000, v90
	v_pk_mul_f32 v[82:83], v[80:81], v[66:67]
	v_mul_f32_e32 v73, v73, v75
	v_mul_f32_e32 v75, v88, v77
	v_mul_f32_e32 v77, 0x3fb8aa3b, v83
	v_exp_f32_e32 v80, v77
	v_pk_add_f32 v[86:87], v[82:83], v[82:83]
	v_lshlrev_b32_e32 v89, 16, v91
	v_fmamk_f32 v81, v87, 0x3d2aaaab, v196
	v_fma_f32 v81, v87, v81, 0.5
	v_fma_f32 v81, v87, v81, 1.0
	v_fma_f32 v77, -v80, v80, 1.0
	v_mul_f32_e64 v81, v81, -v87
	v_cmp_lt_f32_e64 s[0:1], s40, v87
	v_fmamk_f32 v83, v86, 0x3d2aaaab, v196
	v_fma_f32 v83, v86, v83, 0.5
	v_cndmask_b32_e64 v77, v77, v81, s[0:1]
	v_max_f32_e32 v77, 0, v77
	v_sqrt_f32_e32 v77, v77
	v_fma_f32 v83, v86, v83, 1.0
	v_cmp_lt_f32_e32 vcc, s40, v86
	v_mul_f32_e64 v83, v83, -v86
	v_mul_f32_e32 v77, v236, v77
	v_mul_f32_e32 v81, v77, v89
	v_mul_f32_e32 v77, 0x3fb8aa3b, v82
	v_exp_f32_e32 v82, v77
	v_and_b32_e32 v90, 0xffff0000, v91
	v_fma_f32 v77, -v82, v82, 1.0
	v_cndmask_b32_e32 v77, v77, v83, vcc
	v_max_f32_e32 v77, 0, v77
	v_sqrt_f32_e32 v77, v77
	s_nop 0
	v_mul_f32_e32 v77, v79, v77
	v_mul_f32_e32 v83, v77, v90
	global_store_dwordx4 v[116:117], v[72:75], off
	global_store_dwordx4 v[116:117], v[80:83], off offset:16
	v_pk_mul_f32 v[64:65], v[64:65], s[44:45] op_sel_hi:[1,0]
	s_waitcnt vmcnt(2)
	v_lshlrev_b32_e32 v72, 16, v84
	v_pk_mul_f32 v[66:67], v[64:65], v[66:67]
	v_mul_f32_e32 v77, v69, v72
	v_pk_add_f32 v[72:73], v[66:67], v[66:67]
	v_mul_f32_e32 v64, 0x3fb8aa3b, v67
	v_fmamk_f32 v67, v73, 0x3d2aaaab, v196
	v_exp_f32_e32 v64, v64
	v_fma_f32 v67, v73, v67, 0.5
	v_mul_f32_e32 v66, 0x3fb8aa3b, v66
	v_fma_f32 v67, v73, v67, 1.0
	v_exp_f32_e32 v66, v66
	v_mul_f32_e64 v67, v67, -v73
	v_cmp_lt_f32_e32 vcc, s40, v73
	v_fmamk_f32 v73, v72, 0x3d2aaaab, v196
	v_fma_f32 v73, v72, v73, 0.5
	v_fma_f32 v69, -v64, v64, 1.0
	v_fma_f32 v73, v72, v73, 1.0
	v_cndmask_b32_e32 v67, v69, v67, vcc
	v_fma_f32 v69, -v66, v66, 1.0
	v_mul_f32_e64 v73, v73, -v72
	v_cmp_lt_f32_e32 vcc, s40, v72
	v_max_f32_e32 v67, 0, v67
	v_sqrt_f32_e32 v67, v67
	v_cndmask_b32_e32 v69, v69, v73, vcc
	v_max_f32_e32 v69, 0, v69
	v_sqrt_f32_e32 v69, v69
	v_or_b32_e32 v122, 0x700, v133
	v_and_b32_e32 v74, 0xffff0000, v84
	v_lshlrev_b32_e32 v65, 16, v85
	v_mul_f32_e32 v67, v70, v67
	v_or3_b32 v128, v128, v122, v146
	v_and_b32_e32 v75, 0xffff0000, v85
	v_mul_f32_e32 v79, v68, v74
	v_mul_f32_e32 v65, v67, v65
	v_mul_f32_e32 v67, v71, v69
	v_lshl_add_u64 v[68:69], v[128:129], 3, s[14:15]
	v_mul_f32_e32 v67, v67, v75
	global_store_dwordx4 v[68:69], v[76:79], off
	global_store_dwordx4 v[68:69], v[64:67], off offset:16
	v_ashrrev_i32_e32 v143, 31, v142
	v_lshl_add_u64 v[106:107], v[142:143], 0, v[146:147]
	v_lshlrev_b64 v[68:69], 2, v[106:107]
	v_lshl_add_u64 v[64:65], s[4:5], 0, v[68:69]
	global_load_dwordx4 v[72:75], v[64:65], off offset:64
	v_lshl_add_u64 v[64:65], s[6:7], 0, v[68:69]
	v_lshl_add_u64 v[68:69], s[8:9], 0, v[68:69]
	global_load_dwordx4 v[68:71], v[68:69], off offset:64
	v_or_b32_e32 v108, 16, v142
	global_load_dwordx4 v[64:67], v[64:65], off offset:64
	s_waitcnt vmcnt(2)
	v_mul_f32_e32 v76, 0xbfb8aa3b, v72
	v_fma_f32 v77, v72, s24, -v76
	v_rndne_f32_e32 v78, v76
	v_fmac_f32_e32 v77, 0xb2a5705f, v72
	v_sub_f32_e32 v76, v76, v78
	v_add_f32_e32 v76, v76, v77
	v_exp_f32_e32 v76, v76
	v_cvt_i32_f32_e32 v77, v78
	v_cmp_nlt_f32_e32 vcc, s25, v72
	s_waitcnt vmcnt(1)
	v_add_f32_e32 v56, v56, v68
	v_mul_f32_e32 v56, 0xbfb8aa3b, v56
	v_ldexp_f32 v76, v76, v77
	v_cndmask_b32_e32 v76, 0, v76, vcc
	v_cmp_ngt_f32_e32 vcc, s26, v72
	v_exp_f32_e32 v56, v56
	v_add_f32_e32 v57, v57, v69
	v_cndmask_b32_e32 v123, v209, v76, vcc
	v_add_f32_e32 v72, 1.0, v123
	v_add_f32_e32 v76, -1.0, v72
	v_sub_f32_e32 v77, v76, v72
	v_add_f32_e32 v77, 1.0, v77
	v_sub_f32_e32 v76, v123, v76
	v_add_f32_e32 v78, v76, v77
	v_frexp_mant_f32_e32 v76, v72
	v_cmp_gt_f32_e32 vcc, s37, v76
	v_cvt_f64_f32_e32 v[76:77], v72
	v_frexp_exp_i32_f64_e32 v76, v[76:77]
	v_subbrev_co_u32_e32 v84, vcc, 0, v76, vcc
	v_sub_u32_e32 v76, 0, v84
	v_ldexp_f32 v72, v72, v76
	v_ldexp_f32 v76, v78, v76
	v_add_f32_e32 v78, -1.0, v72
	v_add_f32_e32 v77, 1.0, v78
	v_sub_f32_e32 v77, v72, v77
	v_add_f32_e32 v79, v76, v77
	v_add_f32_e32 v77, v78, v79
	v_sub_f32_e32 v78, v78, v77
	v_add_f32_e32 v85, v79, v78
	v_add_f32_e32 v78, 1.0, v72
	v_add_f32_e32 v79, -1.0, v78
	v_sub_f32_e32 v72, v72, v79
	v_add_f32_e32 v72, v76, v72
	v_add_f32_e32 v86, v78, v72
	v_rcp_f32_e32 v87, v86
	v_sub_f32_e32 v76, v78, v86
	v_add_f32_e32 v72, v72, v76
	v_cmp_nlt_f32_e32 vcc, s25, v73
	v_mul_f32_e32 v88, v77, v87
	v_mul_f32_e32 v78, v86, v88
	v_fma_f32 v80, v88, v86, -v78
	v_fmac_f32_e32 v80, v88, v72
	v_add_f32_e32 v76, v78, v80
	v_sub_f32_e32 v79, v77, v76
	v_pk_add_f32 v[82:83], v[76:77], v[78:79] neg_lo:[0,1] neg_hi:[0,1]
	v_mov_b32_e32 v81, v76
	v_pk_add_f32 v[76:77], v[82:83], v[80:81] neg_lo:[0,1] neg_hi:[0,1]
	v_add_f32_e32 v56, 1.0, v56
	v_add_f32_e32 v77, v85, v77
	v_add_f32_e32 v76, v76, v77
	v_add_f32_e32 v77, v79, v76
	v_mul_f32_e32 v85, v87, v77
	v_mul_f32_e32 v78, v86, v85
	v_fma_f32 v80, v85, v86, -v78
	v_fmac_f32_e32 v80, v85, v72
	v_sub_f32_e32 v72, v79, v77
	v_add_f32_e32 v72, v76, v72
	v_add_f32_e32 v76, v78, v80
	v_sub_f32_e32 v79, v77, v76
	v_pk_add_f32 v[82:83], v[76:77], v[78:79] neg_lo:[0,1] neg_hi:[0,1]
	v_mov_b32_e32 v81, v76
	v_pk_add_f32 v[76:77], v[82:83], v[80:81] neg_lo:[0,1] neg_hi:[0,1]
	v_rcp_f32_e32 v145, v56
	v_add_f32_e32 v72, v72, v77
	v_add_f32_e32 v72, v76, v72
	v_add_f32_e32 v77, v88, v85
	v_add_f32_e32 v72, v79, v72
	v_sub_f32_e32 v76, v77, v88
	v_mul_f32_e32 v72, v87, v72
	v_sub_f32_e32 v76, v85, v76
	v_add_f32_e32 v72, v76, v72
	v_add_f32_e32 v78, v77, v72
	v_mul_f32_e32 v80, v78, v78
	v_fmamk_f32 v76, v80, 0x3e9b6dac, v195
	v_fmaak_f32 v149, v80, v76, 0x3f2aaada
	v_cvt_f32_i32_e32 v76, v84
	v_sub_f32_e32 v77, v78, v77
	v_sub_f32_e32 v72, v72, v77
	v_mul_f32_e32 v77, v78, v80
	v_pk_mul_f32 v[80:81], v[76:77], v[148:149]
	v_ldexp_f32 v79, v78, 1
	v_fma_f32 v78, v76, s38, -v80
	v_fmac_f32_e32 v78, 0xb102e308, v76
	v_pk_add_f32 v[82:83], v[80:81], v[78:79]
	v_ldexp_f32 v72, v72, 1
	v_sub_f32_e32 v76, v83, v79
	v_sub_f32_e32 v76, v81, v76
	v_add_f32_e32 v85, v72, v76
	v_mov_b32_e32 v84, v80
	v_pk_add_f32 v[80:81], v[82:83], v[80:81] neg_lo:[0,1] neg_hi:[0,1]
	v_pk_add_f32 v[86:87], v[82:83], v[84:85]
	v_mov_b32_e32 v79, v82
	v_mov_b32_e32 v81, v87
	v_pk_add_f32 v[76:77], v[78:79], v[80:81] neg_lo:[0,1] neg_hi:[0,1]
	v_pk_add_f32 v[78:79], v[78:79], v[80:81]
	v_mov_b32_e32 v84, v85
	v_pk_add_f32 v[80:81], v[78:79], v[82:83] op_sel:[1,0] op_sel_hi:[0,1] neg_lo:[0,1] neg_hi:[0,1]
	v_pk_add_f32 v[88:89], v[86:87], v[80:81] op_sel_hi:[1,0] neg_lo:[0,1] neg_hi:[0,1]
	v_mov_b32_e32 v78, v87
	v_pk_mov_b32 v[80:81], v[82:83], v[80:81] op_sel:[1,0]
	v_mov_b32_e32 v85, v82
	v_pk_add_f32 v[80:81], v[78:79], v[80:81] neg_lo:[0,1] neg_hi:[0,1]
	v_mov_b32_e32 v88, v76
	v_pk_add_f32 v[80:81], v[84:85], v[80:81] neg_lo:[0,1] neg_hi:[0,1]
	v_mul_f32_e32 v72, 0xbfb8aa3b, v73
	v_pk_add_f32 v[82:83], v[88:89], v[80:81]
	v_fma_f32 v78, v73, s24, -v72
	v_rndne_f32_e32 v81, v72
	v_fmac_f32_e32 v78, 0xb2a5705f, v73
	v_sub_f32_e32 v72, v72, v81
	v_add_f32_e32 v72, v72, v78
	v_exp_f32_e32 v72, v72
	v_cvt_i32_f32_e32 v78, v81
	s_waitcnt vmcnt(0)
	v_add_f32_e32 v56, v61, v65
	v_mul_f32_e32 v56, 0xbfb8aa3b, v56
	v_exp_f32_e32 v56, v56
	v_ldexp_f32 v72, v72, v78
	v_cndmask_b32_e32 v72, 0, v72, vcc
	v_cmp_ngt_f32_e32 vcc, s26, v73
	v_add_f32_e32 v56, 1.0, v56
	v_add_f32_e32 v48, v48, v68
	v_cndmask_b32_e32 v129, v209, v72, vcc
	v_add_f32_e32 v78, 1.0, v129
	v_add_f32_e32 v72, -1.0, v78
	v_sub_f32_e32 v73, v72, v78
	v_add_f32_e32 v73, 1.0, v73
	v_sub_f32_e32 v72, v129, v72
	v_add_f32_e32 v81, v72, v73
	v_frexp_mant_f32_e32 v72, v78
	v_cmp_gt_f32_e32 vcc, s37, v72
	v_cvt_f64_f32_e32 v[72:73], v78
	v_frexp_exp_i32_f64_e32 v72, v[72:73]
	v_subbrev_co_u32_e32 v90, vcc, 0, v72, vcc
	v_sub_u32_e32 v72, 0, v90
	v_ldexp_f32 v78, v78, v72
	v_ldexp_f32 v72, v81, v72
	v_add_f32_e32 v81, -1.0, v78
	v_add_f32_e32 v73, 1.0, v81
	v_sub_f32_e32 v73, v78, v73
	v_add_f32_e32 v84, v72, v73
	v_add_f32_e32 v73, v81, v84
	v_sub_f32_e32 v81, v81, v73
	v_add_f32_e32 v81, v84, v81
	v_add_f32_e32 v84, 1.0, v78
	v_add_f32_e32 v85, -1.0, v84
	v_sub_f32_e32 v78, v78, v85
	v_add_f32_e32 v72, v72, v78
	v_add_f32_e32 v78, v84, v72
	v_rcp_f32_e32 v92, v78
	v_sub_f32_e32 v84, v84, v78
	v_add_f32_e32 v91, v72, v84
	v_cmp_nlt_f32_e32 vcc, s25, v74
	v_mul_f32_e32 v93, v73, v92
	v_mul_f32_e32 v84, v78, v93
	v_fma_f32 v86, v93, v78, -v84
	v_fmac_f32_e32 v86, v93, v91
	v_add_f32_e32 v72, v84, v86
	v_sub_f32_e32 v85, v73, v72
	v_pk_add_f32 v[88:89], v[72:73], v[84:85] neg_lo:[0,1] neg_hi:[0,1]
	v_mov_b32_e32 v87, v72
	v_pk_add_f32 v[72:73], v[88:89], v[86:87] neg_lo:[0,1] neg_hi:[0,1]
	v_mul_f32_e32 v48, 0xbfb8aa3b, v48
	v_add_f32_e32 v73, v81, v73
	v_add_f32_e32 v72, v72, v73
	v_add_f32_e32 v73, v85, v72
	v_mul_f32_e32 v81, v92, v73
	v_mul_f32_e32 v84, v78, v81
	v_fma_f32 v86, v81, v78, -v84
	v_fmac_f32_e32 v86, v81, v91
	v_sub_f32_e32 v78, v85, v73
	v_add_f32_e32 v78, v72, v78
	v_add_f32_e32 v72, v84, v86
	v_sub_f32_e32 v85, v73, v72
	v_pk_add_f32 v[88:89], v[72:73], v[84:85] neg_lo:[0,1] neg_hi:[0,1]
	v_mov_b32_e32 v87, v72
	v_pk_add_f32 v[72:73], v[88:89], v[86:87] neg_lo:[0,1] neg_hi:[0,1]
	v_exp_f32_e32 v48, v48
	v_add_f32_e32 v73, v78, v73
	v_add_f32_e32 v72, v72, v73
	v_add_f32_e32 v73, v93, v81
	v_add_f32_e32 v72, v85, v72
	v_sub_f32_e32 v78, v73, v93
	v_mul_f32_e32 v72, v92, v72
	v_sub_f32_e32 v78, v81, v78
	v_add_f32_e32 v78, v78, v72
	v_add_f32_e32 v81, v73, v78
	v_mul_f32_e32 v84, v81, v81
	v_fmamk_f32 v72, v84, 0x3e9b6dac, v195
	v_fmaak_f32 v149, v84, v72, 0x3f2aaada
	v_cvt_f32_i32_e32 v72, v90
	v_sub_f32_e32 v73, v81, v73
	v_sub_f32_e32 v73, v78, v73
	v_ldexp_f32 v78, v73, 1
	v_mul_f32_e32 v73, v81, v84
	v_pk_mul_f32 v[86:87], v[72:73], v[148:149]
	v_ldexp_f32 v85, v81, 1
	v_fma_f32 v84, v72, s38, -v86
	v_fmac_f32_e32 v84, 0xb102e308, v72
	v_pk_add_f32 v[72:73], v[86:87], v[84:85]
	v_mov_b32_e32 v88, v86
	v_sub_f32_e32 v81, v73, v85
	v_sub_f32_e32 v81, v87, v81
	v_add_f32_e32 v89, v78, v81
	v_pk_add_f32 v[86:87], v[72:73], v[86:87] neg_lo:[0,1] neg_hi:[0,1]
	v_pk_add_f32 v[90:91], v[72:73], v[88:89]
	v_mov_b32_e32 v85, v72
	v_mov_b32_e32 v87, v91
	v_pk_add_f32 v[102:103], v[84:85], v[86:87]
	v_pk_add_f32 v[98:99], v[84:85], v[86:87] neg_lo:[0,1] neg_hi:[0,1]
	v_pk_add_f32 v[84:85], v[102:103], v[72:73] op_sel:[1,0] op_sel_hi:[0,1] neg_lo:[0,1] neg_hi:[0,1]
	v_pk_add_f32 v[86:87], v[90:91], v[84:85] op_sel_hi:[1,0] neg_lo:[0,1] neg_hi:[0,1]
	v_pk_mov_b32 v[84:85], v[72:73], v[84:85] op_sel:[1,0]
	v_mov_b32_e32 v88, v89
	v_mov_b32_e32 v89, v72
	v_mul_f32_e32 v72, 0xbfb8aa3b, v74
	v_fma_f32 v73, v74, s24, -v72
	v_rndne_f32_e32 v78, v72
	v_fmac_f32_e32 v73, 0xb2a5705f, v74
	v_sub_f32_e32 v72, v72, v78
	v_add_f32_e32 v72, v72, v73
	v_exp_f32_e32 v72, v72
	v_cvt_i32_f32_e32 v73, v78
	v_mov_b32_e32 v102, v91
	v_pk_add_f32 v[84:85], v[102:103], v[84:85] neg_lo:[0,1] neg_hi:[0,1]
	v_mov_b32_e32 v86, v98
	v_ldexp_f32 v72, v72, v73
	v_cndmask_b32_e32 v72, 0, v72, vcc
	v_cmp_ngt_f32_e32 vcc, s26, v74
	v_pk_add_f32 v[100:101], v[88:89], v[84:85] neg_lo:[0,1] neg_hi:[0,1]
	v_add_f32_e32 v48, 1.0, v48
	v_cndmask_b32_e32 v102, v209, v72, vcc
	v_add_f32_e32 v74, 1.0, v102
	v_add_f32_e32 v72, -1.0, v74
	v_sub_f32_e32 v73, v72, v74
	v_add_f32_e32 v73, 1.0, v73
	v_sub_f32_e32 v72, v102, v72
	v_add_f32_e32 v78, v72, v73
	v_frexp_mant_f32_e32 v72, v74
	v_cmp_gt_f32_e32 vcc, s37, v72
	v_cvt_f64_f32_e32 v[72:73], v74
	v_frexp_exp_i32_f64_e32 v72, v[72:73]
	v_subbrev_co_u32_e32 v81, vcc, 0, v72, vcc
	v_sub_u32_e32 v72, 0, v81
	v_ldexp_f32 v74, v74, v72
	v_ldexp_f32 v72, v78, v72
	v_add_f32_e32 v78, -1.0, v74
	v_add_f32_e32 v73, 1.0, v78
	v_sub_f32_e32 v73, v74, v73
	v_add_f32_e32 v84, v72, v73
	v_add_f32_e32 v73, v78, v84
	v_sub_f32_e32 v78, v78, v73
	v_add_f32_e32 v78, v84, v78
	v_add_f32_e32 v84, 1.0, v74
	v_add_f32_e32 v85, -1.0, v84
	v_sub_f32_e32 v74, v74, v85
	v_add_f32_e32 v72, v72, v74
	v_add_f32_e32 v74, v84, v72
	v_rcp_f32_e32 v91, v74
	v_sub_f32_e32 v84, v84, v74
	v_add_f32_e32 v90, v72, v84
	v_pk_add_f32 v[104:105], v[86:87], v[100:101]
	v_mul_f32_e32 v92, v73, v91
	v_mul_f32_e32 v84, v74, v92
	v_fma_f32 v86, v92, v74, -v84
	v_fmac_f32_e32 v86, v92, v90
	v_add_f32_e32 v72, v84, v86
	v_sub_f32_e32 v85, v73, v72
	v_pk_add_f32 v[88:89], v[72:73], v[84:85] neg_lo:[0,1] neg_hi:[0,1]
	v_mov_b32_e32 v87, v72
	v_pk_add_f32 v[72:73], v[88:89], v[86:87] neg_lo:[0,1] neg_hi:[0,1]
	v_cmp_nlt_f32_e32 vcc, s25, v75
	v_add_f32_e32 v73, v78, v73
	v_add_f32_e32 v72, v72, v73
	v_add_f32_e32 v73, v85, v72
	v_mul_f32_e32 v78, v91, v73
	v_mul_f32_e32 v84, v74, v78
	v_fma_f32 v86, v78, v74, -v84
	v_fmac_f32_e32 v86, v78, v90
	v_sub_f32_e32 v74, v85, v73
	v_add_f32_e32 v74, v72, v74
	v_add_f32_e32 v72, v84, v86
	v_sub_f32_e32 v85, v73, v72
	v_pk_add_f32 v[88:89], v[72:73], v[84:85] neg_lo:[0,1] neg_hi:[0,1]
	v_mov_b32_e32 v87, v72
	v_pk_add_f32 v[72:73], v[88:89], v[86:87] neg_lo:[0,1] neg_hi:[0,1]
	v_add_f32_e32 v24, v24, v68
	v_add_f32_e32 v73, v74, v73
	v_add_f32_e32 v72, v72, v73
	v_add_f32_e32 v73, v92, v78
	v_add_f32_e32 v72, v85, v72
	v_sub_f32_e32 v74, v73, v92
	v_mul_f32_e32 v72, v91, v72
	v_sub_f32_e32 v74, v78, v74
	v_add_f32_e32 v74, v74, v72
	v_add_f32_e32 v78, v73, v74
	v_mul_f32_e32 v84, v78, v78
	v_fmamk_f32 v72, v84, 0x3e9b6dac, v195
	v_fmaak_f32 v149, v84, v72, 0x3f2aaada
	v_cvt_f32_i32_e32 v72, v81
	v_sub_f32_e32 v73, v78, v73
	v_sub_f32_e32 v73, v74, v73
	v_ldexp_f32 v74, v73, 1
	v_mul_f32_e32 v73, v78, v84
	v_pk_mul_f32 v[84:85], v[72:73], v[148:149]
	v_ldexp_f32 v87, v78, 1
	v_fma_f32 v86, v72, s38, -v84
	v_fmac_f32_e32 v86, 0xb102e308, v72
	v_pk_add_f32 v[72:73], v[84:85], v[86:87]
	v_mov_b32_e32 v88, v84
	v_sub_f32_e32 v78, v73, v87
	v_sub_f32_e32 v78, v85, v78
	v_add_f32_e32 v89, v74, v78
	v_pk_add_f32 v[90:91], v[72:73], v[84:85] neg_lo:[0,1] neg_hi:[0,1]
	v_pk_add_f32 v[92:93], v[72:73], v[88:89]
	v_mov_b32_e32 v87, v72
	v_mov_b32_e32 v91, v93
	v_pk_add_f32 v[84:85], v[86:87], v[90:91] neg_lo:[0,1] neg_hi:[0,1]
	v_pk_add_f32 v[86:87], v[86:87], v[90:91]
	v_mov_b32_e32 v88, v89
	v_pk_add_f32 v[90:91], v[86:87], v[72:73] op_sel:[1,0] op_sel_hi:[0,1] neg_lo:[0,1] neg_hi:[0,1]
	v_pk_add_f32 v[94:95], v[92:93], v[90:91] op_sel_hi:[1,0] neg_lo:[0,1] neg_hi:[0,1]
	v_pk_mov_b32 v[90:91], v[72:73], v[90:91] op_sel:[1,0]
	v_mov_b32_e32 v89, v72
	v_mul_f32_e32 v72, 0xbfb8aa3b, v75
	v_fma_f32 v73, v75, s24, -v72
	v_rndne_f32_e32 v74, v72
	v_fmac_f32_e32 v73, 0xb2a5705f, v75
	v_sub_f32_e32 v72, v72, v74
	v_add_f32_e32 v72, v72, v73
	v_exp_f32_e32 v72, v72
	v_cvt_i32_f32_e32 v73, v74
	v_mov_b32_e32 v86, v93
	v_pk_add_f32 v[90:91], v[86:87], v[90:91] neg_lo:[0,1] neg_hi:[0,1]
	v_mov_b32_e32 v94, v84
	v_ldexp_f32 v72, v72, v73
	v_cndmask_b32_e32 v72, 0, v72, vcc
	v_cmp_ngt_f32_e32 vcc, s26, v75
	v_pk_add_f32 v[88:89], v[88:89], v[90:91] neg_lo:[0,1] neg_hi:[0,1]
	v_rcp_f32_e32 v151, v48
	v_cndmask_b32_e32 v128, v209, v72, vcc
	v_add_f32_e32 v74, 1.0, v128
	v_add_f32_e32 v72, -1.0, v74
	v_sub_f32_e32 v73, v72, v74
	v_add_f32_e32 v73, 1.0, v73
	v_sub_f32_e32 v72, v128, v72
	v_add_f32_e32 v75, v72, v73
	v_frexp_mant_f32_e32 v72, v74
	v_cmp_gt_f32_e32 vcc, s37, v72
	v_cvt_f64_f32_e32 v[72:73], v74
	v_frexp_exp_i32_f64_e32 v72, v[72:73]
	v_subbrev_co_u32_e32 v78, vcc, 0, v72, vcc
	v_sub_u32_e32 v72, 0, v78
	v_ldexp_f32 v74, v74, v72
	v_ldexp_f32 v72, v75, v72
	v_add_f32_e32 v75, -1.0, v74
	v_add_f32_e32 v73, 1.0, v75
	v_sub_f32_e32 v73, v74, v73
	v_add_f32_e32 v81, v72, v73
	v_add_f32_e32 v73, v75, v81
	v_sub_f32_e32 v75, v75, v73
	v_add_f32_e32 v81, v81, v75
	v_add_f32_e32 v75, 1.0, v74
	v_add_f32_e32 v86, -1.0, v75
	v_sub_f32_e32 v74, v74, v86
	v_add_f32_e32 v72, v72, v74
	v_add_f32_e32 v86, v75, v72
	v_rcp_f32_e32 v96, v86
	v_sub_f32_e32 v74, v75, v86
	v_pk_add_f32 v[90:91], v[94:95], v[88:89]
	v_add_f32_e32 v89, v72, v74
	v_mul_f32_e32 v97, v73, v96
	v_mul_f32_e32 v74, v86, v97
	v_fma_f32 v92, v97, v86, -v74
	v_fmac_f32_e32 v92, v97, v89
	v_add_f32_e32 v72, v74, v92
	v_sub_f32_e32 v75, v73, v72
	v_pk_add_f32 v[94:95], v[72:73], v[74:75] neg_lo:[0,1] neg_hi:[0,1]
	v_mov_b32_e32 v93, v72
	v_pk_add_f32 v[72:73], v[94:95], v[92:93] neg_lo:[0,1] neg_hi:[0,1]
	v_add_f32_e32 v48, v53, v65
	v_add_f32_e32 v73, v81, v73
	v_add_f32_e32 v72, v72, v73
	v_add_f32_e32 v73, v75, v72
	v_mul_f32_e32 v81, v96, v73
	v_mul_f32_e32 v74, v86, v81
	v_fma_f32 v92, v81, v86, -v74
	v_fmac_f32_e32 v92, v81, v89
	v_sub_f32_e32 v75, v75, v73
	v_add_f32_e32 v86, v72, v75
	v_add_f32_e32 v72, v74, v92
	v_sub_f32_e32 v75, v73, v72
	v_pk_add_f32 v[94:95], v[72:73], v[74:75] neg_lo:[0,1] neg_hi:[0,1]
	v_mov_b32_e32 v93, v72
	v_pk_add_f32 v[72:73], v[94:95], v[92:93] neg_lo:[0,1] neg_hi:[0,1]
	v_mul_f32_e32 v24, 0xbfb8aa3b, v24
	v_add_f32_e32 v73, v86, v73
	v_add_f32_e32 v72, v72, v73
	v_add_f32_e32 v73, v97, v81
	v_add_f32_e32 v72, v75, v72
	v_sub_f32_e32 v74, v73, v97
	v_mul_f32_e32 v72, v96, v72
	v_sub_f32_e32 v74, v81, v74
	v_add_f32_e32 v74, v74, v72
	v_add_f32_e32 v75, v73, v74
	v_mul_f32_e32 v81, v75, v75
	v_fmamk_f32 v72, v81, 0x3e9b6dac, v195
	v_fmaak_f32 v149, v81, v72, 0x3f2aaada
	v_cvt_f32_i32_e32 v72, v78
	v_sub_f32_e32 v73, v75, v73
	v_sub_f32_e32 v73, v74, v73
	v_ldexp_f32 v78, v73, 1
	v_mul_f32_e32 v73, v75, v81
	v_ldexp_f32 v93, v75, 1
	v_pk_mul_f32 v[74:75], v[72:73], v[148:149]
	v_mul_f32_e32 v48, 0xbfb8aa3b, v48
	v_fma_f32 v92, v72, s38, -v74
	v_fmac_f32_e32 v92, 0xb102e308, v72
	v_pk_add_f32 v[72:73], v[74:75], v[92:93]
	v_mov_b32_e32 v94, v74
	v_sub_f32_e32 v81, v73, v93
	v_sub_f32_e32 v81, v75, v81
	v_add_f32_e32 v95, v78, v81
	v_pk_add_f32 v[96:97], v[72:73], v[74:75] neg_lo:[0,1] neg_hi:[0,1]
	v_pk_add_f32 v[110:111], v[72:73], v[94:95]
	v_mov_b32_e32 v93, v72
	v_mov_b32_e32 v97, v111
	v_pk_add_f32 v[74:75], v[92:93], v[96:97] neg_lo:[0,1] neg_hi:[0,1]
	v_pk_add_f32 v[96:97], v[92:93], v[96:97]
	v_mov_b32_e32 v94, v95
	v_pk_add_f32 v[92:93], v[96:97], v[72:73] op_sel:[1,0] op_sel_hi:[0,1] neg_lo:[0,1] neg_hi:[0,1]
	v_pk_add_f32 v[112:113], v[110:111], v[92:93] op_sel_hi:[1,0] neg_lo:[0,1] neg_hi:[0,1]
	v_pk_mov_b32 v[92:93], v[72:73], v[92:93] op_sel:[1,0]
	v_mov_b32_e32 v95, v72
	v_lshl_add_u64 v[72:73], v[106:107], 1, v[140:141]
	v_ashrrev_i32_e32 v78, 4, v108
	v_add_co_u32_e32 v108, vcc, s33, v72
	v_mov_b32_e32 v96, v111
	s_nop 0
	v_addc_co_u32_e32 v109, vcc, 0, v73, vcc
	global_load_dwordx2 v[110:111], v[108:109], off offset:32
	global_load_dwordx2 v[106:107], v[72:73], off offset:32
	v_rcp_f32_e32 v108, v56
	v_mul_f32_e32 v56, 0xbfb8aa3b, v57
	v_exp_f32_e32 v56, v56
	v_exp_f32_e32 v24, v24
	v_exp_f32_e32 v48, v48
	v_add_f32_e32 v57, v58, v70
	v_add_f32_e32 v56, 1.0, v56
	v_rcp_f32_e32 v143, v56
	v_add_f32_e32 v56, v62, v66
	v_mul_f32_e32 v56, 0xbfb8aa3b, v56
	v_exp_f32_e32 v56, v56
	v_pk_add_f32 v[92:93], v[96:97], v[92:93] neg_lo:[0,1] neg_hi:[0,1]
	v_add_f32_e32 v24, 1.0, v24
	v_pk_add_f32 v[92:93], v[94:95], v[92:93] neg_lo:[0,1] neg_hi:[0,1]
	v_add_f32_e32 v56, 1.0, v56
	v_rcp_f32_e32 v61, v56
	v_mul_f32_e32 v56, 0xbfb8aa3b, v57
	v_exp_f32_e32 v56, v56
	v_mov_b32_e32 v112, v74
	v_add_f32_e32 v49, v49, v69
	v_add_f32_e32 v48, 1.0, v48
	v_rcp_f32_e32 v156, v24
	v_add_f32_e32 v24, v29, v65
	v_pk_add_f32 v[94:95], v[112:113], v[92:93]
	v_mul_f32_e32 v24, 0xbfb8aa3b, v24
	v_exp_f32_e32 v24, v24
	v_add_f32_e32 v56, 1.0, v56
	v_add_f32_e32 v60, v60, v64
	v_rcp_f32_e32 v137, v56
	v_add_f32_e32 v56, v63, v67
	v_mul_f32_e32 v60, 0xbfb8aa3b, v60
	v_mul_f32_e32 v56, 0xbfb8aa3b, v56
	v_exp_f32_e32 v60, v60
	v_exp_f32_e32 v56, v56
	v_add_f32_e32 v25, v25, v69
	v_add_f32_e32 v24, 1.0, v24
	v_add_f32_e32 v40, v40, v68
	v_rcp_f32_e32 v116, v24
	v_mul_f32_e32 v24, 0xbfb8aa3b, v25
	v_mul_f32_e32 v40, 0xbfb8aa3b, v40
	v_exp_f32_e32 v24, v24
	v_exp_f32_e32 v40, v40
	v_add_f32_e32 v60, 1.0, v60
	v_add_f32_e32 v57, v59, v71
	v_add_f32_e32 v56, 1.0, v56
	v_rcp_f32_e32 v109, v60
	v_rcp_f32_e32 v60, v56
	v_mul_f32_e32 v56, 0xbfb8aa3b, v57
	v_exp_f32_e32 v56, v56
	v_add_f32_e32 v24, 1.0, v24
	v_add_f32_e32 v50, v50, v70
	v_add_f32_e32 v40, 1.0, v40
	v_rcp_f32_e32 v25, v24
	v_add_f32_e32 v24, v30, v66
	v_rcp_f32_e32 v153, v40
	v_add_f32_e32 v40, v45, v65
	v_mul_f32_e32 v24, 0xbfb8aa3b, v24
	v_add_f32_e32 v16, v16, v68
	v_mul_f32_e32 v40, 0xbfb8aa3b, v40
	v_exp_f32_e32 v24, v24
	v_mul_f32_e32 v16, 0xbfb8aa3b, v16
	v_add_f32_e32 v56, 1.0, v56
	v_exp_f32_e32 v40, v40
	v_exp_f32_e32 v16, v16
	v_rcp_f32_e32 v136, v56
	v_add_u32_e32 v56, v78, v132
	v_ashrrev_i32_e32 v57, 31, v56
	v_lshlrev_b64 v[56:57], 16, v[56:57]
	v_add_f32_e32 v26, v26, v70
	v_add_f32_e32 v24, 1.0, v24
	v_or3_b32 v58, v56, v133, v146
	v_add_f32_e32 v41, v41, v69
	v_add_f32_e32 v40, 1.0, v40
	v_add_f32_e32 v16, 1.0, v16
	v_rcp_f32_e32 v112, v40
	v_mul_f32_e32 v40, 0xbfb8aa3b, v41
	v_rcp_f32_e32 v29, v16
	v_add_f32_e32 v16, v21, v65
	s_waitcnt vmcnt(1)
	v_lshlrev_b32_e32 v149, 16, v110
	v_and_b32_e32 v93, 0xffff0000, v110
	v_rcp_f32_e32 v110, v48
	v_mul_f32_e32 v48, 0xbfb8aa3b, v49
	v_exp_f32_e32 v48, v48
	v_exp_f32_e32 v40, v40
	v_mul_f32_e32 v16, 0xbfb8aa3b, v16
	v_exp_f32_e32 v16, v16
	v_add_f32_e32 v48, 1.0, v48
	v_rcp_f32_e32 v150, v48
	v_add_f32_e32 v48, v54, v66
	v_mul_f32_e32 v48, 0xbfb8aa3b, v48
	v_exp_f32_e32 v48, v48
	v_add_f32_e32 v40, 1.0, v40
	v_rcp_f32_e32 v152, v40
	v_add_f32_e32 v40, v46, v66
	v_add_f32_e32 v48, 1.0, v48
	v_rcp_f32_e32 v49, v48
	v_mul_f32_e32 v48, 0xbfb8aa3b, v50
	v_exp_f32_e32 v48, v48
	v_add_f32_e32 v17, v17, v69
	v_add_f32_e32 v16, 1.0, v16
	v_add_f32_e32 v8, v8, v68
	v_add_f32_e32 v48, 1.0, v48
	v_rcp_f32_e32 v133, v48
	v_add_f32_e32 v48, v55, v67
	v_rcp_f32_e32 v55, v24
	v_mul_f32_e32 v24, 0xbfb8aa3b, v26
	v_exp_f32_e32 v24, v24
	v_mul_f32_e32 v40, 0xbfb8aa3b, v40
	v_rcp_f32_e32 v118, v16
	v_mul_f32_e32 v16, 0xbfb8aa3b, v17
	v_add_f32_e32 v24, 1.0, v24
	v_rcp_f32_e32 v141, v24
	v_add_f32_e32 v24, v31, v67
	v_mul_f32_e32 v24, 0xbfb8aa3b, v24
	v_exp_f32_e32 v24, v24
	v_mul_f32_e32 v8, 0xbfb8aa3b, v8
	v_exp_f32_e32 v40, v40
	v_exp_f32_e32 v16, v16
	v_exp_f32_e32 v8, v8
	v_add_f32_e32 v26, v27, v71
	v_add_f32_e32 v24, 1.0, v24
	v_add_f32_e32 v41, v42, v70
	v_add_f32_e32 v40, 1.0, v40
	v_rcp_f32_e32 v54, v24
	v_mul_f32_e32 v24, 0xbfb8aa3b, v26
	v_or3_b32 v26, v56, v127, v146
	v_mov_b32_e32 v27, v57
	v_add_f32_e32 v16, 1.0, v16
	v_add_f32_e32 v8, 1.0, v8
	s_waitcnt vmcnt(0)
	v_lshlrev_b32_e32 v130, 16, v107
	v_and_b32_e32 v96, 0xffff0000, v107
	v_rcp_f32_e32 v107, v40
	v_mul_f32_e32 v40, 0xbfb8aa3b, v41
	v_add_f32_e32 v41, v43, v71
	v_lshl_add_u64 v[42:43], v[26:27], 3, s[14:15]
	v_rcp_f32_e32 v27, v16
	v_add_f32_e32 v16, v22, v66
	v_rcp_f32_e32 v157, v8
	v_add_f32_e32 v8, v13, v65
	v_mul_f32_e32 v16, 0xbfb8aa3b, v16
	v_mul_f32_e32 v8, 0xbfb8aa3b, v8
	v_exp_f32_e32 v16, v16
	v_exp_f32_e32 v8, v8
	v_add_f32_e32 v17, v18, v70
	v_add_f32_e32 v9, v9, v69
	v_add_f32_e32 v16, 1.0, v16
	v_add_f32_e32 v8, 1.0, v8
	v_rcp_f32_e32 v53, v16
	v_mul_f32_e32 v16, 0xbfb8aa3b, v17
	v_rcp_f32_e32 v120, v8
	v_mul_f32_e32 v8, 0xbfb8aa3b, v9
	v_exp_f32_e32 v16, v16
	v_exp_f32_e32 v8, v8
	v_add_f32_e32 v52, v52, v64
	v_mul_f32_e32 v52, 0xbfb8aa3b, v52
	v_add_f32_e32 v16, 1.0, v16
	v_add_f32_e32 v8, 1.0, v8
	v_rcp_f32_e32 v142, v16
	v_add_f32_e32 v16, v23, v67
	v_rcp_f32_e32 v31, v8
	v_add_f32_e32 v8, v14, v66
	v_mul_f32_e32 v16, 0xbfb8aa3b, v16
	v_mul_f32_e32 v8, 0xbfb8aa3b, v8
	v_add_f32_e32 v0, v0, v64
	v_exp_f32_e32 v52, v52
	v_exp_f32_e32 v40, v40
	v_exp_f32_e32 v16, v16
	v_exp_f32_e32 v8, v8
	v_mul_f32_e32 v0, 0xbfb8aa3b, v0
	v_exp_f32_e32 v0, v0
	v_add_f32_e32 v52, 1.0, v52
	v_add_f32_e32 v40, 1.0, v40
	v_add_f32_e32 v17, v19, v71
	v_add_f32_e32 v16, 1.0, v16
	v_add_f32_e32 v9, v10, v70
	v_add_f32_e32 v8, 1.0, v8
	v_lshlrev_b32_e32 v132, 16, v111
	v_and_b32_e32 v131, 0xffff0000, v111
	v_rcp_f32_e32 v111, v52
	v_rcp_f32_e32 v139, v40
	v_add_f32_e32 v40, v47, v67
	v_rcp_f32_e32 v52, v16
	v_mul_f32_e32 v16, 0xbfb8aa3b, v17
	v_rcp_f32_e32 v47, v8
	v_mul_f32_e32 v8, 0xbfb8aa3b, v9
	v_add_f32_e32 v4, v4, v68
	v_add_f32_e32 v0, 1.0, v0
	v_exp_f32_e32 v16, v16
	v_exp_f32_e32 v8, v8
	v_rcp_f32_e32 v13, v0
	v_mul_f32_e32 v0, 0xbfb8aa3b, v4
	v_exp_f32_e32 v0, v0
	v_add_f32_e32 v16, 1.0, v16
	v_add_f32_e32 v8, 1.0, v8
	v_rcp_f32_e32 v127, v16
	v_or3_b32 v16, v56, v134, v146
	v_rcp_f32_e32 v134, v8
	v_add_f32_e32 v8, v15, v67
	v_add_f32_e32 v0, 1.0, v0
	v_add_f32_e32 v12, v12, v64
	v_mul_f32_e32 v8, 0xbfb8aa3b, v8
	v_rcp_f32_e32 v14, v0
	v_add_f32_e32 v0, v1, v65
	v_mul_f32_e32 v12, 0xbfb8aa3b, v12
	v_exp_f32_e32 v8, v8
	v_mul_f32_e32 v0, 0xbfb8aa3b, v0
	v_exp_f32_e32 v12, v12
	v_exp_f32_e32 v0, v0
	v_add_f32_e32 v9, v11, v71
	v_add_f32_e32 v8, 1.0, v8
	v_add_f32_e32 v36, v36, v64
	v_add_f32_e32 v32, v32, v68
	v_add_f32_e32 v12, 1.0, v12
	v_rcp_f32_e32 v46, v8
	v_mul_f32_e32 v8, 0xbfb8aa3b, v9
	v_add_f32_e32 v1, v5, v69
	v_add_f32_e32 v0, 1.0, v0
	v_mul_f32_e32 v36, 0xbfb8aa3b, v36
	v_mul_f32_e32 v32, 0xbfb8aa3b, v32
	v_rcp_f32_e32 v121, v12
	v_exp_f32_e32 v8, v8
	v_rcp_f32_e32 v12, v0
	v_mul_f32_e32 v0, 0xbfb8aa3b, v1
	v_exp_f32_e32 v36, v36
	v_exp_f32_e32 v32, v32
	v_exp_f32_e32 v0, v0
	v_add_f32_e32 v44, v44, v64
	v_add_f32_e32 v20, v20, v64
	v_mul_f32_e32 v44, 0xbfb8aa3b, v44
	v_mul_f32_e32 v20, 0xbfb8aa3b, v20
	v_add_f32_e32 v8, 1.0, v8
	v_exp_f32_e32 v44, v44
	v_add_f32_e32 v36, 1.0, v36
	v_add_f32_e32 v32, 1.0, v32
	v_exp_f32_e32 v20, v20
	v_rcp_f32_e32 v15, v8
	v_or3_b32 v8, v56, v135, v146
	v_mov_b32_e32 v9, v57
	v_add_f32_e32 v0, 1.0, v0
	v_rcp_f32_e32 v115, v36
	v_rcp_f32_e32 v155, v32
	v_add_f32_e32 v32, v37, v65
	v_lshl_add_u64 v[36:37], v[8:9], 3, s[14:15]
	v_rcp_f32_e32 v4, v0
	v_mov_b32_e32 v0, v104
	v_mov_b32_e32 v1, v82
	v_mov_b32_e32 v8, v105
	v_mov_b32_e32 v9, v83
	v_pk_add_f32 v[8:9], v[0:1], v[8:9]
	v_mov_b32_e32 v78, v103
	v_pk_add_f32 v[10:11], v[78:79], v[8:9]
	v_mov_b32_e32 v77, v79
	v_mov_b32_e32 v99, v103
	v_add_f32_e32 v44, 1.0, v44
	v_add_f32_e32 v20, 1.0, v20
	v_mov_b32_e32 v17, v57
	v_mov_b32_e32 v83, v11
	v_mov_b32_e32 v105, v10
	v_rcp_f32_e32 v113, v44
	v_rcp_f32_e32 v119, v20
	v_lshl_add_u64 v[44:45], v[16:17], 3, s[14:15]
	v_pk_add_f32 v[16:17], v[82:83], v[76:77] neg_lo:[0,1] neg_hi:[0,1]
	v_pk_add_f32 v[20:21], v[104:105], v[98:99] neg_lo:[0,1] neg_hi:[0,1]
	v_mov_b32_e32 v81, v9
	v_mov_b32_e32 v22, v20
	v_mov_b32_e32 v23, v16
	v_mov_b32_e32 v101, v8
	v_mul_f32_e32 v32, 0xbfb8aa3b, v32
	v_pk_add_f32 v[18:19], v[80:81], v[16:17] neg_lo:[0,1] neg_hi:[0,1]
	v_pk_add_f32 v[0:1], v[0:1], v[22:23] neg_lo:[0,1] neg_hi:[0,1]
	v_mov_b32_e32 v99, v76
	v_pk_add_f32 v[8:9], v[100:101], v[20:21] neg_lo:[0,1] neg_hi:[0,1]
	v_exp_f32_e32 v32, v32
	v_pk_add_f32 v[0:1], v[98:99], v[0:1] neg_lo:[0,1] neg_hi:[0,1]
	v_mov_b32_e32 v16, v8
	v_mov_b32_e32 v17, v18
	v_pk_add_f32 v[0:1], v[16:17], v[0:1]
	v_mov_b32_e32 v18, v9
	v_pk_add_f32 v[0:1], v[0:1], v[18:19]
	v_cmp_neq_f32_e32 vcc, s27, v129
	v_pk_add_f32 v[0:1], v[10:11], v[0:1]
	v_add_f32_e32 v33, v33, v69
	v_add_f32_e32 v32, 1.0, v32
	v_cndmask_b32_e32 v0, v209, v0, vcc
	v_cmp_neq_f32_e32 vcc, s27, v123
	v_rcp_f32_e32 v114, v32
	v_mul_f32_e32 v32, 0xbfb8aa3b, v33
	v_cndmask_b32_e32 v1, v209, v1, vcc
	v_cmp_lt_f32_e64 vcc, |v129|, s39
	v_cmp_lt_f32_e64 s[0:1], |v123|, s39
	v_exp_f32_e32 v32, v32
	v_cndmask_b32_e32 v0, v0, v129, vcc
	v_cndmask_b32_e64 v1, v1, v123, s[0:1]
	v_pk_mul_f32 v[8:9], v[108:109], s[44:45] op_sel_hi:[1,0]
	v_add_f32_e32 v32, 1.0, v32
	v_pk_mul_f32 v[10:11], v[8:9], v[0:1]
	v_rcp_f32_e32 v154, v32
	v_mul_f32_e32 v5, 0x3fb8aa3b, v11
	v_exp_f32_e32 v8, v5
	v_pk_add_f32 v[16:17], v[10:11], v[10:11]
	v_add_f32_e32 v32, v38, v66
	v_fmamk_f32 v9, v17, 0x3d2aaaab, v196
	v_fma_f32 v9, v17, v9, 0.5
	v_mul_f32_e32 v32, 0xbfb8aa3b, v32
	v_fma_f32 v9, v17, v9, 1.0
	v_exp_f32_e32 v32, v32
	v_fma_f32 v5, -v8, v8, 1.0
	v_mul_f32_e64 v9, v9, -v17
	v_cmp_lt_f32_e64 s[0:1], s40, v17
	v_add_f32_e32 v33, v34, v70
	v_add_f32_e32 v32, 1.0, v32
	v_cndmask_b32_e64 v5, v5, v9, s[0:1]
	v_max_f32_e32 v5, 0, v5
	v_sqrt_f32_e32 v5, v5
	v_rcp_f32_e32 v63, v32
	v_mul_f32_e32 v32, 0xbfb8aa3b, v33
	v_exp_f32_e32 v32, v32
	v_lshlrev_b32_e32 v89, 16, v106
	v_mul_f32_e32 v5, v145, v5
	v_mul_f32_e32 v9, v5, v89
	v_mul_f32_e32 v5, 0x3fb8aa3b, v10
	v_exp_f32_e32 v10, v5
	v_add_f32_e32 v32, 1.0, v32
	v_fmamk_f32 v11, v16, 0x3d2aaaab, v196
	v_rcp_f32_e32 v140, v32
	v_add_f32_e32 v32, v39, v67
	v_fma_f32 v11, v16, v11, 0.5
	v_mul_f32_e32 v40, 0xbfb8aa3b, v40
	v_mul_f32_e32 v32, 0xbfb8aa3b, v32
	v_fma_f32 v11, v16, v11, 1.0
	v_exp_f32_e32 v40, v40
	v_exp_f32_e32 v32, v32
	v_cmp_lt_f32_e32 vcc, s40, v16
	v_fma_f32 v5, -v10, v10, 1.0
	v_mul_f32_e64 v11, v11, -v16
	v_cndmask_b32_e32 v5, v5, v11, vcc
	v_max_f32_e32 v5, 0, v5
	v_sqrt_f32_e32 v5, v5
	v_add_f32_e32 v50, v51, v71
	v_add_f32_e32 v40, 1.0, v40
	v_add_f32_e32 v33, v35, v71
	v_add_f32_e32 v32, 1.0, v32
	v_and_b32_e32 v86, 0xffff0000, v106
	v_mul_f32_e32 v50, 0xbfb8aa3b, v50
	v_rcp_f32_e32 v106, v40
	v_mul_f32_e32 v40, 0xbfb8aa3b, v41
	v_rcp_f32_e32 v62, v32
	v_mul_f32_e32 v32, 0xbfb8aa3b, v33
	v_exp_f32_e32 v50, v50
	v_exp_f32_e32 v40, v40
	v_exp_f32_e32 v32, v32
	v_mov_b32_e32 v59, v57
	v_mul_f32_e32 v5, v143, v5
	v_lshl_add_u64 v[58:59], v[58:59], 3, s[14:15]
	v_mul_f32_e32 v11, v5, v86
	global_store_dwordx4 v[58:59], v[8:11], off
	v_add_f32_e32 v50, 1.0, v50
	v_add_f32_e32 v40, 1.0, v40
	v_pk_mul_f32 v[8:9], v[110:111], s[44:45] op_sel_hi:[1,0]
	v_add_f32_e32 v32, 1.0, v32
	v_pk_mul_f32 v[8:9], v[8:9], v[0:1]
	v_rcp_f32_e32 v138, v50
	v_or3_b32 v50, v56, v124, v146
	v_rcp_f32_e32 v124, v40
	v_or3_b32 v40, v56, v125, v146
	v_rcp_f32_e32 v125, v32
	v_or3_b32 v32, v56, v126, v146
	v_mov_b32_e32 v33, v57
	v_mul_f32_e32 v5, 0x3fb8aa3b, v9
	v_lshl_add_u64 v[38:39], v[32:33], 3, s[14:15]
	v_exp_f32_e32 v32, v5
	v_pk_add_f32 v[10:11], v[8:9], v[8:9]
	v_add_f32_e32 v28, v28, v64
	v_fmamk_f32 v9, v11, 0x3d2aaaab, v196
	v_fma_f32 v9, v11, v9, 0.5
	v_fma_f32 v9, v11, v9, 1.0
	v_fma_f32 v5, -v32, v32, 1.0
	v_mul_f32_e64 v9, v9, -v11
	v_cmp_lt_f32_e64 s[0:1], s40, v11
	v_cmp_lt_f32_e32 vcc, s40, v10
	v_mul_f32_e32 v28, 0xbfb8aa3b, v28
	v_cndmask_b32_e64 v5, v5, v9, s[0:1]
	v_max_f32_e32 v5, 0, v5
	v_sqrt_f32_e32 v5, v5
	v_exp_f32_e32 v28, v28
	v_exp_f32_e32 v24, v24
	v_pk_mul_f32 v[12:13], v[12:13], s[44:45] op_sel_hi:[1,0]
	v_mul_f32_e32 v5, v151, v5
	v_mul_f32_e32 v33, v5, v149
	v_mul_f32_e32 v5, 0x3fb8aa3b, v8
	v_exp_f32_e32 v34, v5
	v_fmamk_f32 v8, v10, 0x3d2aaaab, v196
	v_fma_f32 v8, v10, v8, 0.5
	v_fma_f32 v8, v10, v8, 1.0
	v_fma_f32 v5, -v34, v34, 1.0
	v_mul_f32_e64 v8, v8, -v10
	v_cndmask_b32_e32 v5, v5, v8, vcc
	v_max_f32_e32 v5, 0, v5
	v_sqrt_f32_e32 v5, v5
	v_pk_mul_f32 v[8:9], v[112:113], s[44:45] op_sel_hi:[1,0]
	v_add_f32_e32 v28, 1.0, v28
	v_pk_mul_f32 v[8:9], v[8:9], v[0:1]
	v_mul_f32_e32 v5, v150, v5
	v_mul_f32_e32 v35, v5, v93
	v_mul_f32_e32 v5, 0x3fb8aa3b, v9
	v_rcp_f32_e32 v117, v28
	v_exp_f32_e32 v28, v5
	v_pk_add_f32 v[10:11], v[8:9], v[8:9]
	v_add_f32_e32 v24, 1.0, v24
	v_fmamk_f32 v9, v11, 0x3d2aaaab, v196
	v_fma_f32 v9, v11, v9, 0.5
	v_fma_f32 v9, v11, v9, 1.0
	v_fma_f32 v5, -v28, v28, 1.0
	v_mul_f32_e64 v9, v9, -v11
	v_cmp_lt_f32_e64 s[0:1], s40, v11
	v_cmp_lt_f32_e32 vcc, s40, v10
	v_rcp_f32_e32 v126, v24
	v_cndmask_b32_e64 v5, v5, v9, s[0:1]
	v_max_f32_e32 v5, 0, v5
	v_sqrt_f32_e32 v5, v5
	v_mov_b32_e32 v86, v97
	v_mov_b32_e32 v85, v87
	v_mov_b32_e32 v75, v97
	v_mul_f32_e32 v68, v153, v5
	v_mul_f32_e32 v5, 0x3fb8aa3b, v8
	v_exp_f32_e32 v30, v5
	v_fmamk_f32 v8, v10, 0x3d2aaaab, v196
	v_fma_f32 v8, v10, v8, 0.5
	v_fma_f32 v8, v10, v8, 1.0
	v_fma_f32 v5, -v30, v30, 1.0
	v_mul_f32_e64 v8, v8, -v10
	v_cndmask_b32_e32 v5, v5, v8, vcc
	v_max_f32_e32 v5, 0, v5
	v_sqrt_f32_e32 v5, v5
	v_pk_mul_f32 v[8:9], v[114:115], s[44:45] op_sel_hi:[1,0]
	v_pk_mul_f32 v[60:61], v[60:61], s[44:45] op_sel_hi:[1,0]
	v_pk_mul_f32 v[8:9], v[8:9], v[0:1]
	v_mul_f32_e32 v69, v152, v5
	v_mul_f32_e32 v5, 0x3fb8aa3b, v9
	v_exp_f32_e32 v24, v5
	v_pk_add_f32 v[10:11], v[8:9], v[8:9]
	v_mul_f32_e32 v48, 0xbfb8aa3b, v48
	v_fmamk_f32 v9, v11, 0x3d2aaaab, v196
	v_fma_f32 v9, v11, v9, 0.5
	v_fma_f32 v9, v11, v9, 1.0
	v_fma_f32 v5, -v24, v24, 1.0
	v_mul_f32_e64 v9, v9, -v11
	v_cmp_lt_f32_e64 s[0:1], s40, v11
	v_cmp_lt_f32_e32 vcc, s40, v10
	v_exp_f32_e32 v48, v48
	v_cndmask_b32_e64 v5, v5, v9, s[0:1]
	v_max_f32_e32 v5, 0, v5
	v_sqrt_f32_e32 v5, v5
	v_add_f32_e32 v48, 1.0, v48
	v_mov_b32_e32 v51, v57
	v_mov_b32_e32 v41, v57
	v_mul_f32_e32 v64, v155, v5
	v_mul_f32_e32 v5, 0x3fb8aa3b, v8
	v_exp_f32_e32 v26, v5
	v_fmamk_f32 v8, v10, 0x3d2aaaab, v196
	v_fma_f32 v8, v10, v8, 0.5
	v_fma_f32 v8, v10, v8, 1.0
	v_fma_f32 v5, -v26, v26, 1.0
	v_mul_f32_e64 v8, v8, -v10
	v_cndmask_b32_e32 v5, v5, v8, vcc
	v_max_f32_e32 v5, 0, v5
	v_sqrt_f32_e32 v5, v5
	v_pk_mul_f32 v[8:9], v[116:117], s[44:45] op_sel_hi:[1,0]
	v_rcp_f32_e32 v48, v48
	v_pk_mul_f32 v[8:9], v[8:9], v[0:1]
	v_mul_f32_e32 v65, v154, v5
	v_mul_f32_e32 v5, 0x3fb8aa3b, v9
	v_exp_f32_e32 v20, v5
	v_pk_add_f32 v[10:11], v[8:9], v[8:9]
	v_lshl_add_u64 v[50:51], v[50:51], 3, s[14:15]
	v_fmamk_f32 v9, v11, 0x3d2aaaab, v196
	v_fma_f32 v9, v11, v9, 0.5
	v_fma_f32 v9, v11, v9, 1.0
	v_fma_f32 v5, -v20, v20, 1.0
	v_mul_f32_e64 v9, v9, -v11
	v_cmp_lt_f32_e64 s[0:1], s40, v11
	v_cmp_lt_f32_e32 vcc, s40, v10
	v_lshl_add_u64 v[40:41], v[40:41], 3, s[14:15]
	v_cndmask_b32_e64 v5, v5, v9, s[0:1]
	v_max_f32_e32 v5, 0, v5
	v_sqrt_f32_e32 v5, v5
	s_nop 0
	v_mul_f32_e32 v21, v156, v5
	v_mul_f32_e32 v5, 0x3fb8aa3b, v8
	v_exp_f32_e32 v22, v5
	v_fmamk_f32 v8, v10, 0x3d2aaaab, v196
	v_fma_f32 v8, v10, v8, 0.5
	v_fma_f32 v8, v10, v8, 1.0
	v_fma_f32 v5, -v22, v22, 1.0
	v_mul_f32_e64 v8, v8, -v10
	v_cndmask_b32_e32 v5, v5, v8, vcc
	v_max_f32_e32 v5, 0, v5
	v_sqrt_f32_e32 v5, v5
	v_pk_mul_f32 v[8:9], v[118:119], s[44:45] op_sel_hi:[1,0]
	v_mul_f32_e32 v23, v25, v5
	v_pk_mul_f32 v[8:9], v[8:9], v[0:1]
	s_nop 0
	v_mul_f32_e32 v5, 0x3fb8aa3b, v9
	v_exp_f32_e32 v16, v5
	v_pk_add_f32 v[10:11], v[8:9], v[8:9]
	v_fma_f32 v5, -v16, v16, 1.0
	v_fmamk_f32 v9, v11, 0x3d2aaaab, v196
	v_fma_f32 v9, v11, v9, 0.5
	v_fma_f32 v9, v11, v9, 1.0
	v_mul_f32_e64 v9, v9, -v11
	v_cmp_lt_f32_e64 s[0:1], s40, v11
	v_cmp_lt_f32_e32 vcc, s40, v10
	s_nop 0
	v_cndmask_b32_e64 v5, v5, v9, s[0:1]
	v_max_f32_e32 v5, 0, v5
	v_sqrt_f32_e32 v5, v5
	s_nop 0
	v_mul_f32_e32 v17, v29, v5
	v_mul_f32_e32 v5, 0x3fb8aa3b, v8
	v_exp_f32_e32 v18, v5
	v_fmamk_f32 v8, v10, 0x3d2aaaab, v196
	v_fma_f32 v8, v10, v8, 0.5
	v_fma_f32 v8, v10, v8, 1.0
	v_fma_f32 v5, -v18, v18, 1.0
	v_mul_f32_e64 v8, v8, -v10
	v_cndmask_b32_e32 v5, v5, v8, vcc
	v_max_f32_e32 v5, 0, v5
	v_sqrt_f32_e32 v5, v5
	v_pk_mul_f32 v[8:9], v[120:121], s[44:45] op_sel_hi:[1,0]
	v_mul_f32_e32 v19, v27, v5
	v_pk_mul_f32 v[10:11], v[8:9], v[0:1]
	v_pk_mul_f32 v[0:1], v[12:13], v[0:1]
	v_mul_f32_e32 v5, 0x3fb8aa3b, v11
	v_exp_f32_e32 v8, v5
	v_pk_add_f32 v[76:77], v[10:11], v[10:11]
	v_fma_f32 v5, -v8, v8, 1.0
	v_fmamk_f32 v9, v77, 0x3d2aaaab, v196
	v_fma_f32 v9, v77, v9, 0.5
	v_fma_f32 v9, v77, v9, 1.0
	v_mul_f32_e64 v9, v9, -v77
	v_cmp_lt_f32_e64 s[0:1], s40, v77
	v_fmamk_f32 v11, v76, 0x3d2aaaab, v196
	v_fma_f32 v11, v76, v11, 0.5
	v_cndmask_b32_e64 v5, v5, v9, s[0:1]
	v_max_f32_e32 v5, 0, v5
	v_sqrt_f32_e32 v5, v5
	v_fma_f32 v11, v76, v11, 1.0
	v_cmp_lt_f32_e32 vcc, s40, v76
	v_mul_f32_e64 v11, v11, -v76
	v_mul_f32_e32 v9, v157, v5
	v_mul_f32_e32 v5, 0x3fb8aa3b, v10
	v_exp_f32_e32 v10, v5
	v_pk_add_f32 v[76:77], v[0:1], v[0:1]
	v_mul_f32_e32 v0, 0x3fb8aa3b, v0
	v_cmp_lt_f32_e64 s[0:1], s40, v77
	v_fma_f32 v5, -v10, v10, 1.0
	v_cndmask_b32_e32 v5, v5, v11, vcc
	v_max_f32_e32 v5, 0, v5
	v_sqrt_f32_e32 v5, v5
	v_cmp_lt_f32_e32 vcc, s40, v76
	v_mul_f32_e32 v11, v31, v5
	v_mul_f32_e32 v5, 0x3fb8aa3b, v1
	v_exp_f32_e32 v12, v5
	v_fmamk_f32 v1, v77, 0x3d2aaaab, v196
	v_fma_f32 v1, v77, v1, 0.5
	v_fma_f32 v1, v77, v1, 1.0
	v_fma_f32 v5, -v12, v12, 1.0
	v_mul_f32_e64 v1, v1, -v77
	v_cndmask_b32_e64 v1, v5, v1, s[0:1]
	v_max_f32_e32 v1, 0, v1
	v_sqrt_f32_e32 v1, v1
	v_cmp_lt_f32_e64 s[0:1], |v102|, s39
	v_mul_f32_e32 v5, v14, v1
	v_exp_f32_e32 v14, v0
	v_fmamk_f32 v1, v76, 0x3d2aaaab, v196
	v_fma_f32 v1, v76, v1, 0.5
	v_fma_f32 v1, v76, v1, 1.0
	v_fma_f32 v0, -v14, v14, 1.0
	v_mul_f32_e64 v1, v1, -v76
	v_cndmask_b32_e32 v0, v0, v1, vcc
	v_max_f32_e32 v0, 0, v0
	v_sqrt_f32_e32 v0, v0
	v_cmp_neq_f32_e32 vcc, s27, v128
	v_mul_f32_e32 v4, v4, v0
	v_add_f32_e32 v0, v2, v66
	v_mul_f32_e32 v0, 0xbfb8aa3b, v0
	v_exp_f32_e32 v0, v0
	v_add_f32_e32 v2, v6, v70
	v_mov_b32_e32 v66, v95
	v_add_f32_e32 v0, 1.0, v0
	v_rcp_f32_e32 v1, v0
	v_mul_f32_e32 v0, 0xbfb8aa3b, v2
	v_add_f32_e32 v2, v7, v71
	v_mul_f32_e32 v2, 0xbfb8aa3b, v2
	v_exp_f32_e32 v0, v0
	v_exp_f32_e32 v2, v2
	v_add_f32_e32 v0, 1.0, v0
	v_add_f32_e32 v2, 1.0, v2
	v_rcp_f32_e32 v6, v0
	v_add_f32_e32 v0, v3, v67
	v_rcp_f32_e32 v7, v2
	v_mov_b32_e32 v2, v94
	v_mov_b32_e32 v3, v90
	v_mov_b32_e32 v67, v91
	v_pk_add_f32 v[66:67], v[2:3], v[66:67]
	v_mul_f32_e32 v0, 0xbfb8aa3b, v0
	v_pk_add_f32 v[70:71], v[86:87], v[66:67]
	v_mov_b32_e32 v89, v67
	v_mov_b32_e32 v91, v71
	v_mov_b32_e32 v95, v70
	v_pk_add_f32 v[76:77], v[90:91], v[84:85] neg_lo:[0,1] neg_hi:[0,1]
	v_pk_add_f32 v[80:81], v[94:95], v[74:75] neg_lo:[0,1] neg_hi:[0,1]
	v_mov_b32_e32 v83, v76
	v_mov_b32_e32 v82, v80
	v_mov_b32_e32 v93, v66
	v_pk_add_f32 v[78:79], v[88:89], v[76:77] neg_lo:[0,1] neg_hi:[0,1]
	v_pk_add_f32 v[2:3], v[2:3], v[82:83] neg_lo:[0,1] neg_hi:[0,1]
	v_mov_b32_e32 v75, v84
	v_pk_add_f32 v[66:67], v[92:93], v[80:81] neg_lo:[0,1] neg_hi:[0,1]
	v_pk_add_f32 v[2:3], v[74:75], v[2:3] neg_lo:[0,1] neg_hi:[0,1]
	v_mov_b32_e32 v74, v66
	v_mov_b32_e32 v75, v78
	v_pk_add_f32 v[2:3], v[74:75], v[2:3]
	v_mov_b32_e32 v78, v67
	v_pk_add_f32 v[2:3], v[2:3], v[78:79]
	v_exp_f32_e32 v0, v0
	v_pk_add_f32 v[2:3], v[70:71], v[2:3]
	v_add_f32_e32 v0, 1.0, v0
	v_cndmask_b32_e32 v2, v209, v2, vcc
	v_cmp_neq_f32_e32 vcc, s27, v102
	v_rcp_f32_e32 v0, v0
	s_nop 0
	v_cndmask_b32_e32 v3, v209, v3, vcc
	v_cmp_lt_f32_e64 vcc, |v128|, s39
	v_cndmask_b32_e64 v3, v3, v102, s[0:1]
	s_nop 0
	v_cndmask_b32_e32 v2, v2, v128, vcc
	v_pk_mul_f32 v[60:61], v[60:61], v[2:3]
	s_nop 0
	v_mul_f32_e32 v13, 0x3fb8aa3b, v61
	v_exp_f32_e32 v74, v13
	v_pk_add_f32 v[66:67], v[60:61], v[60:61]
	v_fma_f32 v13, -v74, v74, 1.0
	v_fmamk_f32 v25, v67, 0x3d2aaaab, v196
	v_fma_f32 v25, v67, v25, 0.5
	v_fma_f32 v25, v67, v25, 1.0
	v_mul_f32_e64 v25, v25, -v67
	v_cmp_lt_f32_e64 s[0:1], s40, v67
	v_cmp_lt_f32_e32 vcc, s40, v66
	s_nop 0
	v_cndmask_b32_e64 v13, v13, v25, s[0:1]
	v_max_f32_e32 v13, 0, v13
	v_sqrt_f32_e32 v13, v13
	v_fmamk_f32 v25, v66, 0x3d2aaaab, v196
	v_fma_f32 v25, v66, v25, 0.5
	v_fma_f32 v25, v66, v25, 1.0
	v_mul_f32_e32 v13, v137, v13
	v_mul_f32_e32 v75, v13, v130
	v_mul_f32_e32 v13, 0x3fb8aa3b, v60
	v_exp_f32_e32 v76, v13
	v_mul_f32_e64 v25, v25, -v66
	v_fma_f32 v13, -v76, v76, 1.0
	v_cndmask_b32_e32 v13, v13, v25, vcc
	v_max_f32_e32 v13, 0, v13
	v_sqrt_f32_e32 v13, v13
	s_nop 0
	v_mul_f32_e32 v13, v136, v13
	v_mul_f32_e32 v77, v13, v96
	global_store_dwordx4 v[58:59], v[74:77], off offset:16
	v_add_co_u32_e32 v58, vcc, s66, v72
	v_pk_mul_f32 v[48:49], v[48:49], s[44:45] op_sel_hi:[1,0]
	s_nop 0
	v_addc_co_u32_e32 v59, vcc, 0, v73, vcc
	global_load_dwordx2 v[66:67], v[58:59], off offset:32
	v_pk_mul_f32 v[48:49], v[48:49], v[2:3]
	s_nop 0
	v_mul_f32_e32 v13, 0x3fb8aa3b, v49
	v_exp_f32_e32 v58, v13
	v_pk_add_f32 v[70:71], v[48:49], v[48:49]
	v_mul_f32_e32 v27, 0x3fb8aa3b, v48
	v_fmamk_f32 v25, v71, 0x3d2aaaab, v196
	v_exp_f32_e32 v60, v27
	v_fma_f32 v25, v71, v25, 0.5
	v_fmamk_f32 v27, v70, 0x3d2aaaab, v196
	v_fma_f32 v25, v71, v25, 1.0
	v_fma_f32 v27, v70, v27, 0.5
	v_fma_f32 v13, -v58, v58, 1.0
	v_mul_f32_e64 v25, v25, -v71
	v_cmp_lt_f32_e32 vcc, s40, v71
	v_fma_f32 v27, v70, v27, 1.0
	v_mul_f32_e64 v27, v27, -v70
	v_cndmask_b32_e32 v13, v13, v25, vcc
	v_fma_f32 v25, -v60, v60, 1.0
	v_cmp_lt_f32_e32 vcc, s40, v70
	v_max_f32_e32 v13, 0, v13
	v_sqrt_f32_e32 v13, v13
	v_cndmask_b32_e32 v25, v25, v27, vcc
	v_max_f32_e32 v25, 0, v25
	v_sqrt_f32_e32 v25, v25
	v_mul_f32_e32 v13, v133, v13
	v_mul_f32_e32 v59, v13, v132
	v_mul_f32_e32 v13, v138, v25
	v_mul_f32_e32 v61, v13, v131
	global_store_dwordx4 v[50:51], v[32:35], off
	global_store_dwordx4 v[50:51], v[58:61], off offset:16
	s_nop 0
	v_add_co_u32_e32 v32, vcc, s67, v72
	s_waitcnt vmcnt(2)
	v_lshlrev_b32_e32 v13, 16, v66
	v_addc_co_u32_e32 v33, vcc, 0, v73, vcc
	global_load_dwordx2 v[48:49], v[32:33], off offset:32
	v_pk_mul_f32 v[32:33], v[106:107], s[44:45] op_sel_hi:[1,0]
	v_mul_f32_e32 v29, v68, v13
	v_pk_mul_f32 v[34:35], v[32:33], v[2:3]
	v_and_b32_e32 v25, 0xffff0000, v66
	v_mul_f32_e32 v13, 0x3fb8aa3b, v35
	v_exp_f32_e32 v32, v13
	v_pk_add_f32 v[50:51], v[34:35], v[34:35]
	v_mul_f32_e32 v31, v69, v25
	v_fmamk_f32 v25, v51, 0x3d2aaaab, v196
	v_fma_f32 v25, v51, v25, 0.5
	v_fma_f32 v25, v51, v25, 1.0
	v_fma_f32 v13, -v32, v32, 1.0
	v_mul_f32_e64 v25, v25, -v51
	v_cmp_lt_f32_e64 s[0:1], s40, v51
	v_lshlrev_b32_e32 v27, 16, v67
	v_cmp_lt_f32_e32 vcc, s40, v50
	v_cndmask_b32_e64 v13, v13, v25, s[0:1]
	v_max_f32_e32 v13, 0, v13
	v_sqrt_f32_e32 v13, v13
	v_fmamk_f32 v25, v50, 0x3d2aaaab, v196
	v_fma_f32 v25, v50, v25, 0.5
	v_fma_f32 v25, v50, v25, 1.0
	v_mul_f32_e32 v13, v139, v13
	v_mul_f32_e32 v33, v13, v27
	v_mul_f32_e32 v13, 0x3fb8aa3b, v34
	v_exp_f32_e32 v34, v13
	v_mul_f32_e64 v25, v25, -v50
	v_and_b32_e32 v58, 0xffff0000, v67
	v_fma_f32 v13, -v34, v34, 1.0
	v_cndmask_b32_e32 v13, v13, v25, vcc
	v_max_f32_e32 v13, 0, v13
	v_sqrt_f32_e32 v13, v13
	s_nop 0
	v_mul_f32_e32 v13, v124, v13
	v_mul_f32_e32 v35, v13, v58
	global_store_dwordx4 v[40:41], v[28:31], off
	global_store_dwordx4 v[40:41], v[32:35], off offset:16
	s_nop 0
	v_add_co_u32_e32 v28, vcc, s22, v72
	s_waitcnt vmcnt(2)
	v_lshlrev_b32_e32 v13, 16, v48
	v_addc_co_u32_e32 v29, vcc, 0, v73, vcc
	global_load_dwordx2 v[32:33], v[28:29], off offset:32
	v_pk_mul_f32 v[28:29], v[62:63], s[44:45] op_sel_hi:[1,0]
	v_mul_f32_e32 v25, v64, v13
	v_pk_mul_f32 v[30:31], v[28:29], v[2:3]
	v_lshlrev_b32_e32 v40, 16, v49
	v_mul_f32_e32 v13, 0x3fb8aa3b, v31
	v_exp_f32_e32 v28, v13
	v_pk_add_f32 v[34:35], v[30:31], v[30:31]
	v_and_b32_e32 v27, 0xffff0000, v48
	v_fmamk_f32 v29, v35, 0x3d2aaaab, v196
	v_fma_f32 v29, v35, v29, 0.5
	v_fma_f32 v29, v35, v29, 1.0
	v_fma_f32 v13, -v28, v28, 1.0
	v_mul_f32_e64 v29, v29, -v35
	v_cmp_lt_f32_e64 s[0:1], s40, v35
	v_fmamk_f32 v31, v34, 0x3d2aaaab, v196
	v_fma_f32 v31, v34, v31, 0.5
	v_cndmask_b32_e64 v13, v13, v29, s[0:1]
	v_max_f32_e32 v13, 0, v13
	v_sqrt_f32_e32 v13, v13
	v_fma_f32 v31, v34, v31, 1.0
	v_cmp_lt_f32_e32 vcc, s40, v34
	v_mul_f32_e64 v31, v31, -v34
	v_mul_f32_e32 v13, v140, v13
	v_mul_f32_e32 v29, v13, v40
	v_mul_f32_e32 v13, 0x3fb8aa3b, v30
	v_exp_f32_e32 v30, v13
	v_and_b32_e32 v41, 0xffff0000, v49
	v_mul_f32_e32 v27, v65, v27
	v_fma_f32 v13, -v30, v30, 1.0
	v_cndmask_b32_e32 v13, v13, v31, vcc
	v_max_f32_e32 v13, 0, v13
	v_sqrt_f32_e32 v13, v13
	s_nop 0
	v_mul_f32_e32 v13, v125, v13
	v_mul_f32_e32 v31, v13, v41
	global_store_dwordx4 v[38:39], v[24:27], off
	global_store_dwordx4 v[38:39], v[28:31], off offset:16
	s_nop 0
	v_add_co_u32_e32 v24, vcc, s41, v72
	s_waitcnt vmcnt(2)
	v_lshlrev_b32_e32 v13, 16, v32
	v_addc_co_u32_e32 v25, vcc, 0, v73, vcc
	global_load_dwordx2 v[28:29], v[24:25], off offset:32
	v_and_b32_e32 v24, 0xffff0000, v32
	v_mul_f32_e32 v23, v23, v24
	v_pk_mul_f32 v[24:25], v[54:55], s[44:45] op_sel_hi:[1,0]
	v_mul_f32_e32 v21, v21, v13
	v_pk_mul_f32 v[26:27], v[24:25], v[2:3]
	v_lshlrev_b32_e32 v32, 16, v33
	v_mul_f32_e32 v13, 0x3fb8aa3b, v27
	v_exp_f32_e32 v24, v13
	v_pk_add_f32 v[30:31], v[26:27], v[26:27]
	v_and_b32_e32 v33, 0xffff0000, v33
	v_fmamk_f32 v25, v31, 0x3d2aaaab, v196
	v_fma_f32 v25, v31, v25, 0.5
	v_fma_f32 v25, v31, v25, 1.0
	v_fma_f32 v13, -v24, v24, 1.0
	v_mul_f32_e64 v25, v25, -v31
	v_cmp_lt_f32_e64 s[0:1], s40, v31
	v_fmamk_f32 v27, v30, 0x3d2aaaab, v196
	v_fma_f32 v27, v30, v27, 0.5
	v_cndmask_b32_e64 v13, v13, v25, s[0:1]
	v_max_f32_e32 v13, 0, v13
	v_sqrt_f32_e32 v13, v13
	v_fma_f32 v27, v30, v27, 1.0
	v_cmp_lt_f32_e32 vcc, s40, v30
	v_mul_f32_e64 v27, v27, -v30
	v_mul_f32_e32 v13, v141, v13
	v_mul_f32_e32 v25, v13, v32
	v_mul_f32_e32 v13, 0x3fb8aa3b, v26
	v_exp_f32_e32 v26, v13
	s_nop 0
	v_fma_f32 v13, -v26, v26, 1.0
	v_cndmask_b32_e32 v13, v13, v27, vcc
	v_max_f32_e32 v13, 0, v13
	v_sqrt_f32_e32 v13, v13
	s_nop 0
	v_mul_f32_e32 v13, v126, v13
	v_mul_f32_e32 v27, v13, v33
	global_store_dwordx4 v[42:43], v[20:23], off
	global_store_dwordx4 v[42:43], v[24:27], off offset:16
	s_nop 0
	v_add_co_u32_e32 v20, vcc, s23, v72
	s_waitcnt vmcnt(2)
	v_lshlrev_b32_e32 v13, 16, v28
	v_addc_co_u32_e32 v21, vcc, 0, v73, vcc
	global_load_dwordx2 v[24:25], v[20:21], off offset:32
	v_and_b32_e32 v20, 0xffff0000, v28
	v_mul_f32_e32 v19, v19, v20
	v_pk_mul_f32 v[20:21], v[52:53], s[44:45] op_sel_hi:[1,0]
	v_mul_f32_e32 v17, v17, v13
	v_pk_mul_f32 v[22:23], v[20:21], v[2:3]
	v_lshlrev_b32_e32 v28, 16, v29
	v_mul_f32_e32 v13, 0x3fb8aa3b, v23
	v_exp_f32_e32 v20, v13
	v_pk_add_f32 v[26:27], v[22:23], v[22:23]
	v_and_b32_e32 v29, 0xffff0000, v29
	v_fmamk_f32 v21, v27, 0x3d2aaaab, v196
	v_fma_f32 v21, v27, v21, 0.5
	v_fma_f32 v21, v27, v21, 1.0
	v_fma_f32 v13, -v20, v20, 1.0
	v_mul_f32_e64 v21, v21, -v27
	v_cmp_lt_f32_e64 s[0:1], s40, v27
	v_fmamk_f32 v23, v26, 0x3d2aaaab, v196
	v_fma_f32 v23, v26, v23, 0.5
	v_cndmask_b32_e64 v13, v13, v21, s[0:1]
	v_max_f32_e32 v13, 0, v13
	v_sqrt_f32_e32 v13, v13
	v_fma_f32 v23, v26, v23, 1.0
	v_cmp_lt_f32_e32 vcc, s40, v26
	v_mul_f32_e64 v23, v23, -v26
	v_mul_f32_e32 v13, v142, v13
	v_mul_f32_e32 v21, v13, v28
	v_mul_f32_e32 v13, 0x3fb8aa3b, v22
	v_exp_f32_e32 v22, v13
	s_nop 0
	v_fma_f32 v13, -v22, v22, 1.0
	v_cndmask_b32_e32 v13, v13, v23, vcc
	v_max_f32_e32 v13, 0, v13
	v_sqrt_f32_e32 v13, v13
	s_nop 0
	v_mul_f32_e32 v13, v127, v13
	v_mul_f32_e32 v23, v13, v29
	global_store_dwordx4 v[44:45], v[16:19], off
	global_store_dwordx4 v[44:45], v[20:23], off offset:16
	s_nop 0
	v_add_co_u32_e32 v16, vcc, s42, v72
	s_waitcnt vmcnt(2)
	v_lshlrev_b32_e32 v13, 16, v24
	v_addc_co_u32_e32 v17, vcc, 0, v73, vcc
	global_load_dwordx2 v[20:21], v[16:17], off offset:32
	v_and_b32_e32 v16, 0xffff0000, v24
	v_mul_f32_e32 v11, v11, v16
	v_pk_mul_f32 v[16:17], v[46:47], s[44:45] op_sel_hi:[1,0]
	v_mul_f32_e32 v9, v9, v13
	v_pk_mul_f32 v[18:19], v[16:17], v[2:3]
	v_lshlrev_b32_e32 v24, 16, v25
	v_mul_f32_e32 v13, 0x3fb8aa3b, v19
	v_exp_f32_e32 v16, v13
	v_pk_add_f32 v[22:23], v[18:19], v[18:19]
	v_and_b32_e32 v25, 0xffff0000, v25
	v_fmamk_f32 v17, v23, 0x3d2aaaab, v196
	v_fma_f32 v17, v23, v17, 0.5
	v_fma_f32 v17, v23, v17, 1.0
	v_fma_f32 v13, -v16, v16, 1.0
	v_mul_f32_e64 v17, v17, -v23
	v_cmp_lt_f32_e64 s[0:1], s40, v23
	v_fmamk_f32 v19, v22, 0x3d2aaaab, v196
	v_fma_f32 v19, v22, v19, 0.5
	v_cndmask_b32_e64 v13, v13, v17, s[0:1]
	v_max_f32_e32 v13, 0, v13
	v_sqrt_f32_e32 v13, v13
	v_fma_f32 v19, v22, v19, 1.0
	v_cmp_lt_f32_e32 vcc, s40, v22
	v_mul_f32_e64 v19, v19, -v22
	v_mul_f32_e32 v13, v134, v13
	v_mul_f32_e32 v17, v13, v24
	v_mul_f32_e32 v13, 0x3fb8aa3b, v18
	v_exp_f32_e32 v18, v13
	s_nop 0
	v_fma_f32 v13, -v18, v18, 1.0
	v_cndmask_b32_e32 v13, v13, v19, vcc
	v_max_f32_e32 v13, 0, v13
	v_sqrt_f32_e32 v13, v13
	s_nop 0
	v_mul_f32_e32 v13, v15, v13
	v_mul_f32_e32 v19, v13, v25
	global_store_dwordx4 v[36:37], v[8:11], off
	global_store_dwordx4 v[36:37], v[16:19], off offset:16
	v_pk_mul_f32 v[0:1], v[0:1], s[44:45] op_sel_hi:[1,0]
	s_waitcnt vmcnt(2)
	v_lshlrev_b32_e32 v8, 16, v20
	v_pk_mul_f32 v[2:3], v[0:1], v[2:3]
	v_mul_f32_e32 v13, v5, v8
	v_pk_add_f32 v[8:9], v[2:3], v[2:3]
	v_mul_f32_e32 v0, 0x3fb8aa3b, v3
	v_fmamk_f32 v3, v9, 0x3d2aaaab, v196
	v_exp_f32_e32 v0, v0
	v_fma_f32 v3, v9, v3, 0.5
	v_mul_f32_e32 v2, 0x3fb8aa3b, v2
	v_fma_f32 v3, v9, v3, 1.0
	v_exp_f32_e32 v2, v2
	v_mul_f32_e64 v3, v3, -v9
	v_cmp_lt_f32_e32 vcc, s40, v9
	v_fmamk_f32 v9, v8, 0x3d2aaaab, v196
	v_fma_f32 v9, v8, v9, 0.5
	v_fma_f32 v5, -v0, v0, 1.0
	v_fma_f32 v9, v8, v9, 1.0
	v_cndmask_b32_e32 v3, v5, v3, vcc
	v_fma_f32 v5, -v2, v2, 1.0
	v_mul_f32_e64 v9, v9, -v8
	v_cmp_lt_f32_e32 vcc, s40, v8
	v_max_f32_e32 v3, 0, v3
	v_sqrt_f32_e32 v3, v3
	v_cndmask_b32_e32 v5, v5, v9, vcc
	v_max_f32_e32 v5, 0, v5
	v_sqrt_f32_e32 v5, v5
	v_and_b32_e32 v10, 0xffff0000, v20
	v_lshlrev_b32_e32 v1, 16, v21
	v_mul_f32_e32 v3, v6, v3
	v_or3_b32 v56, v56, v122, v146
	v_and_b32_e32 v11, 0xffff0000, v21
	v_mul_f32_e32 v15, v4, v10
	v_mul_f32_e32 v1, v3, v1
	v_mul_f32_e32 v3, v7, v5
	v_lshl_add_u64 v[4:5], v[56:57], 3, s[14:15]
	v_mul_f32_e32 v3, v3, v11
	global_store_dwordx4 v[4:5], v[12:15], off
	global_store_dwordx4 v[4:5], v[0:3], off offset:16
	s_mov_b64 s[22:23], s[20:21]
	v_readlane_b32 s68, v253, 18
	v_readlane_b32 s75, v253, 20
	s_barrier
	s_cmpk_gt_i32 s36, 0x1ff
	s_cbranch_scc0 .LBB0_741
	s_branch .LBB0_761

.LBB0_788:
	s_ashr_i32 s29, s28, 31
	s_lshl_b64 s[28:29], s[28:29], 20
	s_add_u32 s28, s35, s28
	s_addc_u32 s29, s36, s29
	s_ashr_i32 s27, s26, 31
	v_lshlrev_b32_e32 v3, 6, v1
	s_lshl_b64 s[26:27], s[26:27], 20
	v_and_b32_e32 v2, 48, v1
	v_and_b32_e32 v4, 0x3c0, v3
	v_lshlrev_b32_e32 v1, 2, v1
	s_add_u32 s30, s10, s26
	v_or_b32_e32 v5, v4, v2
	v_and_b32_e32 v1, 32, v1
	v_lshlrev_b32_e32 v0, 13, v0
	s_mov_b32 s26, 0x18000
	v_and_b32_e32 v135, 0x6000, v0
	v_bitop3_b32 v0, v5, s26, v1 bitop3:0xde
	s_mov_b32 s26, 0x10400
	s_addc_u32 s31, s11, s27
	v_bitop3_b32 v149, v5, s26, v1 bitop3:0xde
	s_add_i32 s26, s55, s58
	s_ashr_i32 s27, s26, 31
	s_waitcnt vmcnt(0)
	s_add_i32 s47, s1, 0x10000
	s_add_i32 s48, s1, 0x18000
	s_add_i32 s49, s1, 0x12000
	s_add_i32 s50, s1, 0x1a000
	s_add_i32 s51, s1, 0x14000
	s_add_i32 s52, s1, 0x1c000
	s_add_i32 s53, s1, 0x16000
	s_add_i32 s54, s1, 0x1e000
	s_lshl_b64 s[26:27], s[26:27], 20
	v_bitop3_b32 v134, v4, v1, v2 bitop3:0x36
	v_and_b32_e32 v136, 0xffffc000, v3
	s_add_u32 s55, s6, s26
	v_mov_b32_e32 v4, 0
	v_or_b32_e32 v137, 0x800, v136
	v_or_b32_e32 v138, 0x1000, v136
	v_or_b32_e32 v139, 0x1800, v136
	v_or_b32_e32 v140, 0x2000, v136
	v_or_b32_e32 v141, 0x2800, v136
	v_or_b32_e32 v142, 0x3000, v136
	v_or_b32_e32 v143, 0x3800, v136
	v_bitop3_b32 v145, v5, s33, v1 bitop3:0xde
	s_addc_u32 s58, s7, s27
	s_mov_b64 s[26:27], 0
	s_mov_b32 s62, 1
	v_add_u32_e32 v150, v0, v135
	v_mov_b32_e32 v5, v4
	v_mov_b32_e32 v6, v4
	v_mov_b32_e32 v7, v4
	v_mov_b32_e32 v12, v4
	v_mov_b32_e32 v13, v4
	v_mov_b32_e32 v14, v4
	v_mov_b32_e32 v15, v4
	v_mov_b32_e32 v16, v4
	v_mov_b32_e32 v17, v4
	v_mov_b32_e32 v18, v4
	v_mov_b32_e32 v19, v4
	v_mov_b32_e32 v20, v4
	v_mov_b32_e32 v21, v4
	v_mov_b32_e32 v22, v4
	v_mov_b32_e32 v23, v4
	v_mov_b32_e32 v24, v4
	v_mov_b32_e32 v25, v4
	v_mov_b32_e32 v26, v4
	v_mov_b32_e32 v27, v4
	v_mov_b32_e32 v28, v4
	v_mov_b32_e32 v29, v4
	v_mov_b32_e32 v30, v4
	v_mov_b32_e32 v31, v4
	v_mov_b32_e32 v32, v4
	v_mov_b32_e32 v33, v4
	v_mov_b32_e32 v34, v4
	v_mov_b32_e32 v35, v4
	v_mov_b32_e32 v36, v4
	v_mov_b32_e32 v37, v4
	v_mov_b32_e32 v38, v4
	v_mov_b32_e32 v39, v4
	v_mov_b32_e32 v40, v4
	v_mov_b32_e32 v41, v4
	v_mov_b32_e32 v42, v4
	v_mov_b32_e32 v43, v4
	v_mov_b32_e32 v44, v4
	v_mov_b32_e32 v45, v4
	v_mov_b32_e32 v46, v4
	v_mov_b32_e32 v47, v4
	v_mov_b32_e32 v48, v4
	v_mov_b32_e32 v49, v4
	v_mov_b32_e32 v50, v4
	v_mov_b32_e32 v51, v4
	v_mov_b32_e32 v52, v4
	v_mov_b32_e32 v53, v4
	v_mov_b32_e32 v54, v4
	v_mov_b32_e32 v55, v4
	v_mov_b32_e32 v56, v4
	v_mov_b32_e32 v57, v4
	v_mov_b32_e32 v58, v4
	v_mov_b32_e32 v59, v4
	v_mov_b32_e32 v60, v4
	v_mov_b32_e32 v61, v4
	v_mov_b32_e32 v62, v4
	v_mov_b32_e32 v63, v4
	v_mov_b32_e32 v64, v4
	v_mov_b32_e32 v65, v4
	v_mov_b32_e32 v66, v4
	v_mov_b32_e32 v67, v4
	v_mov_b32_e32 v68, v4
	v_mov_b32_e32 v69, v4
	v_mov_b32_e32 v70, v4
	v_mov_b32_e32 v71, v4
	v_mov_b32_e32 v72, v4
	v_mov_b32_e32 v73, v4
	v_mov_b32_e32 v74, v4
	v_mov_b32_e32 v75, v4
	v_mov_b32_e32 v76, v4
	v_mov_b32_e32 v77, v4
	v_mov_b32_e32 v78, v4
	v_mov_b32_e32 v79, v4
	v_mov_b32_e32 v80, v4
	v_mov_b32_e32 v81, v4
	v_mov_b32_e32 v82, v4
	v_mov_b32_e32 v83, v4
	v_mov_b32_e32 v84, v4
	v_mov_b32_e32 v85, v4
	v_mov_b32_e32 v86, v4
	v_mov_b32_e32 v87, v4
	v_mov_b32_e32 v88, v4
	v_mov_b32_e32 v89, v4
	v_mov_b32_e32 v90, v4
	v_mov_b32_e32 v91, v4
	v_mov_b32_e32 v92, v4
	v_mov_b32_e32 v93, v4
	v_mov_b32_e32 v94, v4
	v_mov_b32_e32 v95, v4
	v_mov_b32_e32 v96, v4
	v_mov_b32_e32 v97, v4
	v_mov_b32_e32 v98, v4
	v_mov_b32_e32 v99, v4
	v_mov_b32_e32 v100, v4
	v_mov_b32_e32 v101, v4
	v_mov_b32_e32 v102, v4
	v_mov_b32_e32 v103, v4
	v_mov_b32_e32 v104, v4
	v_mov_b32_e32 v105, v4
	v_mov_b32_e32 v106, v4
	v_mov_b32_e32 v107, v4
	v_mov_b32_e32 v108, v4
	v_mov_b32_e32 v109, v4
	v_mov_b32_e32 v110, v4
	v_mov_b32_e32 v111, v4
	v_mov_b32_e32 v112, v4
	v_mov_b32_e32 v113, v4
	v_mov_b32_e32 v114, v4
	v_mov_b32_e32 v115, v4
	v_mov_b32_e32 v116, v4
	v_mov_b32_e32 v117, v4
	v_mov_b32_e32 v118, v4
	v_mov_b32_e32 v119, v4
	v_mov_b32_e32 v120, v4
	v_mov_b32_e32 v121, v4
	v_mov_b32_e32 v122, v4
	v_mov_b32_e32 v123, v4
	v_mov_b32_e32 v124, v4
	v_mov_b32_e32 v125, v4
	v_mov_b32_e32 v126, v4
	v_mov_b32_e32 v127, v4
	v_mov_b32_e32 v8, v4
	v_mov_b32_e32 v9, v4
	v_mov_b32_e32 v10, v4
	v_mov_b32_e32 v11, v4
	v_mov_b32_e32 v0, v4
	v_mov_b32_e32 v1, v4
	v_mov_b32_e32 v2, v4
	v_mov_b32_e32 v3, v4
	s_waitcnt lgkmcnt(0)
	s_barrier
	s_add_u32 s63, s55, s26
	s_addc_u32 s70, s58, s27
	s_add_u32 s64, s63, 0x1b900080
	s_addc_u32 s65, s70, 0
	s_add_u32 s71, s2, s26
	s_addc_u32 s72, s3, s27
	s_add_u32 s68, s71, 0x80
	s_addc_u32 s69, s72, 0
	v_add_u32_e32 v151, v134, v135
	v_add_u32_e32 v189, v134, v136
	ds_read_b128 v[152:155], v151 offset:32768
	ds_read_b128 v[156:159], v189
	s_mov_b32 m0, s47
	s_nop 0
	global_load_lds_dwordx4 v128, s[64:65]
	ds_read_b128 v[160:163], v151 offset:34816
	s_mov_b32 m0, s48
	s_nop 0
	global_load_lds_dwordx4 v128, s[68:69]
	ds_read_b128 v[164:167], v189 offset:2048
	ds_read_b128 v[168:171], v151 offset:36864
	s_mov_b32 m0, s49
	s_nop 0
	global_load_lds_dwordx4 v130, s[64:65]
	ds_read_b128 v[172:175], v151 offset:38912
	ds_read_b128 v[176:179], v189 offset:4096
	ds_read_b128 v[180:183], v189 offset:6144
	s_branch .Lmy_rot_789
.LBB0_789:
	s_add_u32 s63, s55, s26
	s_addc_u32 s70, s58, s27
	s_add_u32 s64, s63, 0x1b900080
	s_addc_u32 s65, s70, 0
	s_add_u32 s71, s2, s26
	s_addc_u32 s72, s3, s27
	s_add_u32 s68, s71, 0x80
	s_addc_u32 s69, s72, 0
	v_add_u32_e32 v151, v134, v135
	v_add_u32_e32 v189, v134, v136
	ds_read_b128 v[152:155], v151 offset:32768
	ds_read_b128 v[156:159], v189
	s_mov_b32 m0, s47
	v_mfma_f32_16x16x32_bf16 v[28:31], v[160:163], v[176:179], v[28:31]
	global_load_lds_dwordx4 v128, s[64:65]
	v_mfma_f32_16x16x32_bf16 v[12:15], v[160:163], v[180:183], v[12:15]
	ds_read_b128 v[160:163], v151 offset:34816
	v_mfma_f32_16x16x32_bf16 v[24:27], v[164:167], v[176:179], v[24:27]
	s_mov_b32 m0, s48
	v_mfma_f32_16x16x32_bf16 v[4:7], v[164:167], v[180:183], v[4:7]
	global_load_lds_dwordx4 v128, s[68:69]
	ds_read_b128 v[164:167], v189 offset:2048
	v_mfma_f32_16x16x32_bf16 v[20:23], v[168:171], v[176:179], v[20:23]
	v_mfma_f32_16x16x32_bf16 v[8:11], v[168:171], v[180:183], v[8:11]
	ds_read_b128 v[168:171], v151 offset:36864
	s_mov_b32 m0, s49
	v_mfma_f32_16x16x32_bf16 v[16:19], v[172:175], v[176:179], v[16:19]
	global_load_lds_dwordx4 v130, s[64:65]
	v_mfma_f32_16x16x32_bf16 v[0:3], v[172:175], v[180:183], v[0:3]
	ds_read_b128 v[172:175], v151 offset:38912
	ds_read_b128 v[176:179], v189 offset:4096
	ds_read_b128 v[180:183], v189 offset:6144
.Lmy_rot_789:
	s_waitcnt lgkmcnt(6)
	v_mfma_f32_16x16x32_bf16 v[124:127], v[152:155], v[156:159], v[124:127]
	s_waitcnt lgkmcnt(5)
	s_mov_b32 m0, s50
	v_mfma_f32_16x16x32_bf16 v[120:123], v[160:163], v[156:159], v[120:123]
	global_load_lds_dwordx4 v130, s[68:69]
	s_waitcnt lgkmcnt(4)
	v_mfma_f32_16x16x32_bf16 v[108:111], v[152:155], v[164:167], v[108:111]
	v_mfma_f32_16x16x32_bf16 v[104:107], v[160:163], v[164:167], v[104:107]
	s_waitcnt lgkmcnt(3)
	s_mov_b32 m0, s51
	v_mfma_f32_16x16x32_bf16 v[116:119], v[168:171], v[156:159], v[116:119]
	global_load_lds_dwordx4 v132, s[64:65]
	v_mfma_f32_16x16x32_bf16 v[100:103], v[168:171], v[164:167], v[100:103]
	s_waitcnt lgkmcnt(2)
	v_mfma_f32_16x16x32_bf16 v[112:115], v[172:175], v[156:159], v[112:115]
	ds_read_b128 v[156:159], v189 offset:8192
	s_mov_b32 m0, s52
	v_mfma_f32_16x16x32_bf16 v[96:99], v[172:175], v[164:167], v[96:99]
	global_load_lds_dwordx4 v132, s[68:69]
	ds_read_b128 v[164:167], v189 offset:10240
	s_waitcnt lgkmcnt(3)
	v_mfma_f32_16x16x32_bf16 v[92:95], v[152:155], v[176:179], v[92:95]
	v_mfma_f32_16x16x32_bf16 v[88:91], v[160:163], v[176:179], v[88:91]
	s_mov_b32 m0, s53
	v_mfma_f32_16x16x32_bf16 v[84:87], v[168:171], v[176:179], v[84:87]
	global_load_lds_dwordx4 v146, s[64:65]
	v_mfma_f32_16x16x32_bf16 v[80:83], v[172:175], v[176:179], v[80:83]
	ds_read_b128 v[176:179], v189 offset:12288
	s_waitcnt lgkmcnt(3)
	v_mfma_f32_16x16x32_bf16 v[76:79], v[152:155], v[180:183], v[76:79]
	s_mov_b32 m0, s54
	v_mfma_f32_16x16x32_bf16 v[72:75], v[160:163], v[180:183], v[72:75]
	global_load_lds_dwordx4 v146, s[68:69]
	v_mfma_f32_16x16x32_bf16 v[68:71], v[168:171], v[180:183], v[68:71]
	v_mfma_f32_16x16x32_bf16 v[64:67], v[172:175], v[180:183], v[64:67]
	ds_read_b128 v[180:183], v189 offset:14336
	s_waitcnt lgkmcnt(3)
	v_mfma_f32_16x16x32_bf16 v[56:59], v[160:163], v[156:159], v[56:59]
	s_waitcnt lgkmcnt(2)
	v_mfma_f32_16x16x32_bf16 v[40:43], v[160:163], v[164:167], v[40:43]
	s_waitcnt lgkmcnt(1)
	v_mfma_f32_16x16x32_bf16 v[24:27], v[160:163], v[176:179], v[24:27]
	s_waitcnt lgkmcnt(0)
	v_mfma_f32_16x16x32_bf16 v[4:7], v[160:163], v[180:183], v[4:7]
	ds_read_b128 v[160:163], v151 offset:33792
	v_mfma_f32_16x16x32_bf16 v[60:63], v[152:155], v[156:159], v[60:63]
	v_mfma_f32_16x16x32_bf16 v[44:47], v[152:155], v[164:167], v[44:47]
	v_mfma_f32_16x16x32_bf16 v[28:31], v[152:155], v[176:179], v[28:31]
	v_mfma_f32_16x16x32_bf16 v[12:15], v[152:155], v[180:183], v[12:15]
	ds_read_b128 v[152:155], v189 offset:1024
	v_mfma_f32_16x16x32_bf16 v[36:39], v[168:171], v[164:167], v[36:39]
	v_mfma_f32_16x16x32_bf16 v[32:35], v[172:175], v[164:167], v[32:35]
	ds_read_b128 v[164:167], v151 offset:35840
	v_mfma_f32_16x16x32_bf16 v[52:55], v[168:171], v[156:159], v[52:55]
	v_mfma_f32_16x16x32_bf16 v[48:51], v[172:175], v[156:159], v[48:51]
	ds_read_b128 v[156:159], v189 offset:3072
	v_mfma_f32_16x16x32_bf16 v[20:23], v[168:171], v[176:179], v[20:23]
	v_mfma_f32_16x16x32_bf16 v[16:19], v[172:175], v[176:179], v[16:19]
	ds_read_b128 v[176:179], v189 offset:5120
	v_mfma_f32_16x16x32_bf16 v[8:11], v[168:171], v[180:183], v[8:11]
	ds_read_b128 v[168:171], v151 offset:37888
	v_mfma_f32_16x16x32_bf16 v[0:3], v[172:175], v[180:183], v[0:3]
	ds_read_b128 v[172:175], v151 offset:39936
	ds_read_b128 v[180:183], v189 offset:7168
	s_waitcnt lgkmcnt(6)
	v_mfma_f32_16x16x32_bf16 v[124:127], v[160:163], v[152:155], v[124:127]
	s_waitcnt lgkmcnt(5)
	v_mfma_f32_16x16x32_bf16 v[120:123], v[164:167], v[152:155], v[120:123]
	s_waitcnt lgkmcnt(4)
	v_mfma_f32_16x16x32_bf16 v[108:111], v[160:163], v[156:159], v[108:111]
	v_mfma_f32_16x16x32_bf16 v[104:107], v[164:167], v[156:159], v[104:107]
	s_waitcnt lgkmcnt(3)
	v_mfma_f32_16x16x32_bf16 v[92:95], v[160:163], v[176:179], v[92:95]
	v_mfma_f32_16x16x32_bf16 v[88:91], v[164:167], v[176:179], v[88:91]
	s_waitcnt lgkmcnt(2)
	v_mfma_f32_16x16x32_bf16 v[116:119], v[168:171], v[152:155], v[116:119]
	s_waitcnt lgkmcnt(1)
	v_mfma_f32_16x16x32_bf16 v[112:115], v[172:175], v[152:155], v[112:115]
	ds_read_b128 v[152:155], v189 offset:9216
	v_mfma_f32_16x16x32_bf16 v[100:103], v[168:171], v[156:159], v[100:103]
	v_mfma_f32_16x16x32_bf16 v[96:99], v[172:175], v[156:159], v[96:99]
	ds_read_b128 v[156:159], v189 offset:11264
	v_mfma_f32_16x16x32_bf16 v[84:87], v[168:171], v[176:179], v[84:87]
	v_mfma_f32_16x16x32_bf16 v[80:83], v[172:175], v[176:179], v[80:83]
	ds_read_b128 v[176:179], v189 offset:13312
	s_waitcnt lgkmcnt(3)
	v_mfma_f32_16x16x32_bf16 v[76:79], v[160:163], v[180:183], v[76:79]
	v_mfma_f32_16x16x32_bf16 v[72:75], v[164:167], v[180:183], v[72:75]
	v_mfma_f32_16x16x32_bf16 v[68:71], v[168:171], v[180:183], v[68:71]
	v_mfma_f32_16x16x32_bf16 v[64:67], v[172:175], v[180:183], v[64:67]
	ds_read_b128 v[180:183], v189 offset:15360
	s_waitcnt lgkmcnt(3)
	v_mfma_f32_16x16x32_bf16 v[60:63], v[160:163], v[152:155], v[60:63]
	v_mfma_f32_16x16x32_bf16 v[56:59], v[164:167], v[152:155], v[56:59]
	v_mfma_f32_16x16x32_bf16 v[52:55], v[168:171], v[152:155], v[52:55]
	v_mfma_f32_16x16x32_bf16 v[48:51], v[172:175], v[152:155], v[48:51]
	s_waitcnt lgkmcnt(2)
	v_mfma_f32_16x16x32_bf16 v[44:47], v[160:163], v[156:159], v[44:47]
	v_mfma_f32_16x16x32_bf16 v[40:43], v[164:167], v[156:159], v[40:43]
	v_mfma_f32_16x16x32_bf16 v[36:39], v[168:171], v[156:159], v[36:39]
	v_mfma_f32_16x16x32_bf16 v[32:35], v[172:175], v[156:159], v[32:35]
	s_add_u32 s63, s63, 0x1b900100
	s_addc_u32 s64, s70, 0
	s_add_u32 s68, s71, 0x100
	s_addc_u32 s69, s72, 0
	s_cmp_lt_u32 s62, 31
	s_cselect_b32 s65, s64, s29
	s_cselect_b32 s64, s63, s28
	s_waitcnt vmcnt(0)
	s_waitcnt lgkmcnt(0)
	s_barrier
	s_cselect_b32 s69, s69, s31
	s_cselect_b32 s68, s68, s30
	ds_read_b128 v[152:155], v150
	v_add_u32_e32 v151, v145, v136
	ds_read_b128 v[156:159], v151
	s_mov_b32 m0, s1
	v_mfma_f32_16x16x32_bf16 v[28:31], v[160:163], v[176:179], v[28:31]
	global_load_lds_dwordx4 v128, s[64:65]
	v_mfma_f32_16x16x32_bf16 v[12:15], v[160:163], v[180:183], v[12:15]
	ds_read_b128 v[160:163], v150 offset:2048
	v_mfma_f32_16x16x32_bf16 v[24:27], v[164:167], v[176:179], v[24:27]
	s_mov_b32 m0, s40
	v_mfma_f32_16x16x32_bf16 v[4:7], v[164:167], v[180:183], v[4:7]
	global_load_lds_dwordx4 v128, s[68:69]
	v_add_u32_e32 v151, v145, v137
	ds_read_b128 v[164:167], v151
	v_mfma_f32_16x16x32_bf16 v[20:23], v[168:171], v[176:179], v[20:23]
	v_mfma_f32_16x16x32_bf16 v[8:11], v[168:171], v[180:183], v[8:11]
	ds_read_b128 v[168:171], v150 offset:4096
	s_mov_b32 m0, s41
	v_mfma_f32_16x16x32_bf16 v[16:19], v[172:175], v[176:179], v[16:19]
	global_load_lds_dwordx4 v130, s[64:65]
	v_mfma_f32_16x16x32_bf16 v[0:3], v[172:175], v[180:183], v[0:3]
	ds_read_b128 v[172:175], v150 offset:6144
	v_add_u32_e32 v151, v145, v138
	ds_read_b128 v[176:179], v151
	v_add_u32_e32 v151, v145, v139
	ds_read_b128 v[180:183], v151
	s_waitcnt lgkmcnt(6)
	v_mfma_f32_16x16x32_bf16 v[124:127], v[152:155], v[156:159], v[124:127]
	s_waitcnt lgkmcnt(5)
	s_mov_b32 m0, s42
	v_mfma_f32_16x16x32_bf16 v[120:123], v[160:163], v[156:159], v[120:123]
	global_load_lds_dwordx4 v130, s[68:69]
	s_waitcnt lgkmcnt(4)
	v_mfma_f32_16x16x32_bf16 v[108:111], v[152:155], v[164:167], v[108:111]
	v_mfma_f32_16x16x32_bf16 v[104:107], v[160:163], v[164:167], v[104:107]
	s_waitcnt lgkmcnt(3)
	s_mov_b32 m0, s43
	v_mfma_f32_16x16x32_bf16 v[116:119], v[168:171], v[156:159], v[116:119]
	global_load_lds_dwordx4 v132, s[64:65]
	v_mfma_f32_16x16x32_bf16 v[100:103], v[168:171], v[164:167], v[100:103]
	s_waitcnt lgkmcnt(2)
	v_mfma_f32_16x16x32_bf16 v[112:115], v[172:175], v[156:159], v[112:115]
	v_add_u32_e32 v151, v145, v140
	ds_read_b128 v[156:159], v151
	s_mov_b32 m0, s44
	v_mfma_f32_16x16x32_bf16 v[96:99], v[172:175], v[164:167], v[96:99]
	global_load_lds_dwordx4 v132, s[68:69]
	v_add_u32_e32 v151, v145, v141
	ds_read_b128 v[164:167], v151
	s_waitcnt lgkmcnt(3)
	v_mfma_f32_16x16x32_bf16 v[92:95], v[152:155], v[176:179], v[92:95]
	v_mfma_f32_16x16x32_bf16 v[88:91], v[160:163], v[176:179], v[88:91]
	s_mov_b32 m0, s45
	v_mfma_f32_16x16x32_bf16 v[84:87], v[168:171], v[176:179], v[84:87]
	global_load_lds_dwordx4 v146, s[64:65]
	v_mfma_f32_16x16x32_bf16 v[80:83], v[172:175], v[176:179], v[80:83]
	v_add_u32_e32 v151, v145, v142
	ds_read_b128 v[176:179], v151
	s_waitcnt lgkmcnt(3)
	v_mfma_f32_16x16x32_bf16 v[76:79], v[152:155], v[180:183], v[76:79]
	s_mov_b32 m0, s46
	v_mfma_f32_16x16x32_bf16 v[72:75], v[160:163], v[180:183], v[72:75]
	global_load_lds_dwordx4 v146, s[68:69]
	v_mfma_f32_16x16x32_bf16 v[68:71], v[168:171], v[180:183], v[68:71]
	v_mfma_f32_16x16x32_bf16 v[64:67], v[172:175], v[180:183], v[64:67]
	v_add_u32_e32 v151, v145, v143
	ds_read_b128 v[180:183], v151
	s_waitcnt lgkmcnt(3)
	v_mfma_f32_16x16x32_bf16 v[56:59], v[160:163], v[156:159], v[56:59]
	s_waitcnt lgkmcnt(2)
	v_mfma_f32_16x16x32_bf16 v[40:43], v[160:163], v[164:167], v[40:43]
	s_waitcnt lgkmcnt(1)
	v_mfma_f32_16x16x32_bf16 v[24:27], v[160:163], v[176:179], v[24:27]
	s_waitcnt lgkmcnt(0)
	v_mfma_f32_16x16x32_bf16 v[4:7], v[160:163], v[180:183], v[4:7]
	ds_read_b128 v[160:163], v150 offset:1024
	v_mfma_f32_16x16x32_bf16 v[60:63], v[152:155], v[156:159], v[60:63]
	v_mfma_f32_16x16x32_bf16 v[44:47], v[152:155], v[164:167], v[44:47]
	v_mfma_f32_16x16x32_bf16 v[28:31], v[152:155], v[176:179], v[28:31]
	v_mfma_f32_16x16x32_bf16 v[12:15], v[152:155], v[180:183], v[12:15]
	v_add_u32_e32 v151, v149, v136
	ds_read_b128 v[152:155], v151
	v_mfma_f32_16x16x32_bf16 v[36:39], v[168:171], v[164:167], v[36:39]
	v_mfma_f32_16x16x32_bf16 v[32:35], v[172:175], v[164:167], v[32:35]
	ds_read_b128 v[164:167], v150 offset:3072
	v_mfma_f32_16x16x32_bf16 v[52:55], v[168:171], v[156:159], v[52:55]
	v_mfma_f32_16x16x32_bf16 v[48:51], v[172:175], v[156:159], v[48:51]
	v_add_u32_e32 v151, v149, v137
	ds_read_b128 v[156:159], v151
	v_mfma_f32_16x16x32_bf16 v[20:23], v[168:171], v[176:179], v[20:23]
	v_mfma_f32_16x16x32_bf16 v[16:19], v[172:175], v[176:179], v[16:19]
	v_add_u32_e32 v151, v149, v138
	ds_read_b128 v[176:179], v151
	v_mfma_f32_16x16x32_bf16 v[8:11], v[168:171], v[180:183], v[8:11]
	ds_read_b128 v[168:171], v150 offset:5120
	v_mfma_f32_16x16x32_bf16 v[0:3], v[172:175], v[180:183], v[0:3]
	ds_read_b128 v[172:175], v150 offset:7168
	v_add_u32_e32 v151, v149, v139
	ds_read_b128 v[180:183], v151
	s_waitcnt lgkmcnt(6)
	v_mfma_f32_16x16x32_bf16 v[124:127], v[160:163], v[152:155], v[124:127]
	s_waitcnt lgkmcnt(5)
	v_mfma_f32_16x16x32_bf16 v[120:123], v[164:167], v[152:155], v[120:123]
	s_waitcnt lgkmcnt(4)
	v_mfma_f32_16x16x32_bf16 v[108:111], v[160:163], v[156:159], v[108:111]
	v_mfma_f32_16x16x32_bf16 v[104:107], v[164:167], v[156:159], v[104:107]
	s_waitcnt lgkmcnt(3)
	v_mfma_f32_16x16x32_bf16 v[92:95], v[160:163], v[176:179], v[92:95]
	v_mfma_f32_16x16x32_bf16 v[88:91], v[164:167], v[176:179], v[88:91]
	s_waitcnt lgkmcnt(2)
	v_mfma_f32_16x16x32_bf16 v[116:119], v[168:171], v[152:155], v[116:119]
	s_waitcnt lgkmcnt(1)
	v_mfma_f32_16x16x32_bf16 v[112:115], v[172:175], v[152:155], v[112:115]
	v_add_u32_e32 v151, v149, v140
	ds_read_b128 v[152:155], v151
	v_mfma_f32_16x16x32_bf16 v[100:103], v[168:171], v[156:159], v[100:103]
	v_mfma_f32_16x16x32_bf16 v[96:99], v[172:175], v[156:159], v[96:99]
	v_add_u32_e32 v151, v149, v141
	ds_read_b128 v[156:159], v151
	v_mfma_f32_16x16x32_bf16 v[84:87], v[168:171], v[176:179], v[84:87]
	v_mfma_f32_16x16x32_bf16 v[80:83], v[172:175], v[176:179], v[80:83]
	v_add_u32_e32 v151, v149, v142
	ds_read_b128 v[176:179], v151
	s_waitcnt lgkmcnt(3)
	v_mfma_f32_16x16x32_bf16 v[76:79], v[160:163], v[180:183], v[76:79]
	v_mfma_f32_16x16x32_bf16 v[72:75], v[164:167], v[180:183], v[72:75]
	v_mfma_f32_16x16x32_bf16 v[68:71], v[168:171], v[180:183], v[68:71]
	v_mfma_f32_16x16x32_bf16 v[64:67], v[172:175], v[180:183], v[64:67]
	v_add_u32_e32 v151, v149, v143
	ds_read_b128 v[180:183], v151
	s_waitcnt lgkmcnt(3)
	v_mfma_f32_16x16x32_bf16 v[60:63], v[160:163], v[152:155], v[60:63]
	v_mfma_f32_16x16x32_bf16 v[56:59], v[164:167], v[152:155], v[56:59]
	v_mfma_f32_16x16x32_bf16 v[52:55], v[168:171], v[152:155], v[52:55]
	v_mfma_f32_16x16x32_bf16 v[48:51], v[172:175], v[152:155], v[48:51]
	s_waitcnt lgkmcnt(2)
	v_mfma_f32_16x16x32_bf16 v[44:47], v[160:163], v[156:159], v[44:47]
	v_mfma_f32_16x16x32_bf16 v[40:43], v[164:167], v[156:159], v[40:43]
	v_mfma_f32_16x16x32_bf16 v[36:39], v[168:171], v[156:159], v[36:39]
	v_mfma_f32_16x16x32_bf16 v[32:35], v[172:175], v[156:159], v[32:35]
	s_waitcnt vmcnt(0)
	s_add_u32 s26, s26, 0x100
	s_addc_u32 s27, s27, 0
	s_add_i32 s62, s62, 2
	s_cmpk_lg_i32 s26, 0x1000
	s_waitcnt lgkmcnt(0)
	s_barrier
	s_cbranch_scc1 .LBB0_789
	v_mfma_f32_16x16x32_bf16 v[28:31], v[160:163], v[176:179], v[28:31]
	v_mfma_f32_16x16x32_bf16 v[12:15], v[160:163], v[180:183], v[12:15]
	v_mfma_f32_16x16x32_bf16 v[24:27], v[164:167], v[176:179], v[24:27]
	v_mfma_f32_16x16x32_bf16 v[4:7], v[164:167], v[180:183], v[4:7]
	v_mfma_f32_16x16x32_bf16 v[20:23], v[168:171], v[176:179], v[20:23]
	v_mfma_f32_16x16x32_bf16 v[8:11], v[168:171], v[180:183], v[8:11]
	v_mfma_f32_16x16x32_bf16 v[16:19], v[172:175], v[176:179], v[16:19]
	v_mfma_f32_16x16x32_bf16 v[0:3], v[172:175], v[180:183], v[0:3]
	s_nop 15
	s_nop 15
	v_mov_b32_e32 v128, v184
	s_movk_i32 s3, 0xff80
	v_and_b32_e32 v130, 15, v128
	v_ashrrev_i32_e32 v131, 1, v128
	v_and_or_b32 v141, v131, s3, v130
	v_lshl_add_u32 v140, v141, 2, v202
	ds_read_b32 v134, v140
	s_lshl_b32 s2, s0, 8
	v_add_u32_e32 v130, s39, v141
	v_and_b32_e32 v129, 0xc0, v128
	s_cmp_gt_i32 s0, 7
	v_lshrrev_b32_e32 v128, 2, v128
	v_ashrrev_i32_e32 v131, 31, v130
	s_cselect_b64 s[0:1], -1, 0
	v_and_b32_e32 v128, 12, v128
	v_lshlrev_b64 v[138:139], 12, v[130:131]
	v_or3_b32 v128, v129, s2, v128
	v_lshl_add_u64 v[132:133], s[20:21], 0, v[138:139]
	s_waitcnt lgkmcnt(0)
	v_pk_mul_f32 v[136:137], v[124:125], v[134:135] op_sel_hi:[1,0]
	v_pk_mul_f32 v[126:127], v[126:127], v[134:135] op_sel_hi:[1,0]
	s_mov_b64 s[2:3], -1
	s_and_b64 vcc, exec, s[0:1]
	s_cbranch_vccz .LBB0_792
	v_mov_b32_e32 v129, v147
	v_cvt_pk_bf16_f32 v124, v136, v137
	v_cvt_pk_bf16_f32 v125, v126, v127
	v_lshl_add_u64 v[142:143], v[128:129], 1, v[132:133]
	global_store_dwordx2 v[142:143], v[124:125], off offset:-4096
	s_mov_b64 s[2:3], 0
